# gdb chunk solve: one wave per task carries both the u and w columns as packed halves (v_pk_fma_f32), M rows read from LDS once per task; solving waves 0,3,5,6 on four SIMDs; bit-identical
# speedup vs baseline: 1.0244x; 1.0033x over previous
; #define LAS __attribute__((address_space(3)))
; __device__ __forceinline__ void phase_gdb(const int wvs, const Params& p, LAS unsigned char* lds, int nwg) {
;     ...
;     { float x[64]; const bool isw = t >= 64;
; #pragma unroll
;       for (int i = 0; i < 64; ++i) { const float v = (float)R[i * RP + t]; x[i] = v * bs[i] * (isw ? __expf(gcs[i]) : 1.0f); asm volatile("" : "+v"(x[i])); if ((i & 7) == 7) __builtin_amdgcn_sched_barrier(0); }
; #pragma unroll
;       for (int i = 1; i < 64; ++i) {
; #pragma unroll
;         for (int j4 = 0; j4 < (i + 3) / 4; ++j4) { const f32x4 m4 = *(const LAS f32x4*)(M + i * 64 + j4 * 4);
; #pragma unroll
;           for (int jj = 0; jj < 4; ++jj) if (j4 * 4 + jj < i) x[i] -= m4[jj] * x[j4 * 4 + jj]; }
.LBB0_899:
	s_waitcnt lgkmcnt(0)
	s_barrier
	v_readfirstlane_b32 s8, v193
	s_nop 1
	s_lshr_b32 s9, s8, 6
	s_lshr_b32 s18, s9, 1
	s_add_u32 s18, s18, 1
	s_bfe_u32 s18, s18, 0x10001
	s_and_b32 s19, s9, 1
	s_cmp_lg_u32 s18, s19
	s_cbranch_scc1 .Lgdb_wskip
	v_mov_b32_e32 v253, 0x80
	v_cndmask_b32_e64 v253, 0, v253, s[4:5]
	v_sub_u32_e32 v253, v232, v253
	v_and_b32_e32 v252, 63, v224
	v_lshl_add_u32 v252, v252, 2, v228
	ds_read_b32 v242, v252 offset:34048
	ds_read_b32 v243, v252 offset:34304
	ds_read_u16 v64, v253 offset:16384
	ds_read_u16 v65, v253 offset:16512
	ds_read_u16 v66, v253 offset:16656
	ds_read_u16 v67, v253 offset:16784
	ds_read_u16 v68, v253 offset:16928
	ds_read_u16 v69, v253 offset:17056
	ds_read_u16 v70, v253 offset:17200
	ds_read_u16 v71, v253 offset:17328
	ds_read_u16 v72, v253 offset:17472
	ds_read_u16 v73, v253 offset:17600
	ds_read_u16 v74, v253 offset:17744
	ds_read_u16 v75, v253 offset:17872
	s_waitcnt lgkmcnt(12)
	v_mul_f32_e32 v243, 0x3fb8aa3b, v243
	v_exp_f32_e32 v243, v243
	s_nop 0
	v_readlane_b32 s8, v242, 0
	v_readlane_b32 s9, v243, 0
	v_readlane_b32 s18, v242, 1
	v_readlane_b32 s19, v243, 1
	v_readlane_b32 s20, v242, 2
	v_readlane_b32 s21, v243, 2
	v_readlane_b32 s22, v242, 3
	v_readlane_b32 s23, v243, 3
	s_waitcnt lgkmcnt(10)
	v_cvt_f32_f16_e32 v64, v64
	v_cvt_f32_f16_e32 v65, v65
	s_waitcnt lgkmcnt(8)
	v_cvt_f32_f16_e32 v66, v66
	v_cvt_f32_f16_e32 v67, v67
	s_waitcnt lgkmcnt(6)
	v_cvt_f32_f16_e32 v68, v68
	v_cvt_f32_f16_e32 v69, v69
	s_waitcnt lgkmcnt(4)
	v_cvt_f32_f16_e32 v70, v70
	v_cvt_f32_f16_e32 v71, v71
	v_pk_mul_f32 v[64:65], v[64:65], s[8:9] op_sel_hi:[1,0]
	v_mul_f32_e32 v65, s9, v65
	v_pk_mul_f32 v[66:67], v[66:67], s[18:19] op_sel_hi:[1,0]
	v_mul_f32_e32 v67, s19, v67
	v_pk_mul_f32 v[68:69], v[68:69], s[20:21] op_sel_hi:[1,0]
	v_mul_f32_e32 v69, s21, v69
	v_pk_mul_f32 v[70:71], v[70:71], s[22:23] op_sel_hi:[1,0]
	v_mul_f32_e32 v71, s23, v71
	ds_read_u16 v76, v253 offset:18016
	ds_read_u16 v77, v253 offset:18144
	ds_read_u16 v78, v253 offset:18288
	ds_read_u16 v79, v253 offset:18416
	ds_read_u16 v80, v253 offset:18560
	ds_read_u16 v81, v253 offset:18688
	ds_read_u16 v82, v253 offset:18832
	ds_read_u16 v83, v253 offset:18960
	v_readlane_b32 s8, v242, 4
	v_readlane_b32 s9, v243, 4
	v_readlane_b32 s18, v242, 5
	v_readlane_b32 s19, v243, 5
	v_readlane_b32 s20, v242, 6
	v_readlane_b32 s21, v243, 6
	v_readlane_b32 s22, v242, 7
	v_readlane_b32 s23, v243, 7
	s_waitcnt lgkmcnt(10)
	v_cvt_f32_f16_e32 v72, v72
	v_cvt_f32_f16_e32 v73, v73
	s_waitcnt lgkmcnt(8)
	v_cvt_f32_f16_e32 v74, v74
	v_cvt_f32_f16_e32 v75, v75
	s_waitcnt lgkmcnt(6)
	v_cvt_f32_f16_e32 v76, v76
	v_cvt_f32_f16_e32 v77, v77
	s_waitcnt lgkmcnt(4)
	v_cvt_f32_f16_e32 v78, v78
	v_cvt_f32_f16_e32 v79, v79
	v_pk_mul_f32 v[72:73], v[72:73], s[8:9] op_sel_hi:[1,0]
	v_mul_f32_e32 v73, s9, v73
	v_pk_mul_f32 v[74:75], v[74:75], s[18:19] op_sel_hi:[1,0]
	v_mul_f32_e32 v75, s19, v75
	v_pk_mul_f32 v[76:77], v[76:77], s[20:21] op_sel_hi:[1,0]
	v_mul_f32_e32 v77, s21, v77
	v_pk_mul_f32 v[78:79], v[78:79], s[22:23] op_sel_hi:[1,0]
	v_mul_f32_e32 v79, s23, v79
	ds_read_u16 v84, v253 offset:19104
	ds_read_u16 v85, v253 offset:19232
	ds_read_u16 v86, v253 offset:19376
	ds_read_u16 v87, v253 offset:19504
	ds_read_u16 v88, v253 offset:19648
	ds_read_u16 v89, v253 offset:19776
	ds_read_u16 v90, v253 offset:19920
	ds_read_u16 v91, v253 offset:20048
	v_readlane_b32 s8, v242, 8
	v_readlane_b32 s9, v243, 8
	v_readlane_b32 s18, v242, 9
	v_readlane_b32 s19, v243, 9
	v_readlane_b32 s20, v242, 10
	v_readlane_b32 s21, v243, 10
	v_readlane_b32 s22, v242, 11
	v_readlane_b32 s23, v243, 11
	s_waitcnt lgkmcnt(10)
	v_cvt_f32_f16_e32 v80, v80
	v_cvt_f32_f16_e32 v81, v81
	s_waitcnt lgkmcnt(8)
	v_cvt_f32_f16_e32 v82, v82
	v_cvt_f32_f16_e32 v83, v83
	s_waitcnt lgkmcnt(6)
	v_cvt_f32_f16_e32 v84, v84
	v_cvt_f32_f16_e32 v85, v85
	s_waitcnt lgkmcnt(4)
	v_cvt_f32_f16_e32 v86, v86
	v_cvt_f32_f16_e32 v87, v87
	v_pk_mul_f32 v[80:81], v[80:81], s[8:9] op_sel_hi:[1,0]
	v_mul_f32_e32 v81, s9, v81
	v_pk_mul_f32 v[82:83], v[82:83], s[18:19] op_sel_hi:[1,0]
	v_mul_f32_e32 v83, s19, v83
	v_pk_mul_f32 v[84:85], v[84:85], s[20:21] op_sel_hi:[1,0]
	v_mul_f32_e32 v85, s21, v85
	v_pk_mul_f32 v[86:87], v[86:87], s[22:23] op_sel_hi:[1,0]
	v_mul_f32_e32 v87, s23, v87
	ds_read_u16 v92, v253 offset:20192
	ds_read_u16 v93, v253 offset:20320
	ds_read_u16 v94, v253 offset:20464
	ds_read_u16 v95, v253 offset:20592
	ds_read_u16 v96, v253 offset:20736
	ds_read_u16 v97, v253 offset:20864
	ds_read_u16 v98, v253 offset:21008
	ds_read_u16 v99, v253 offset:21136
	v_readlane_b32 s8, v242, 12
	v_readlane_b32 s9, v243, 12
	v_readlane_b32 s18, v242, 13
	v_readlane_b32 s19, v243, 13
	v_readlane_b32 s20, v242, 14
	v_readlane_b32 s21, v243, 14
	v_readlane_b32 s22, v242, 15
	v_readlane_b32 s23, v243, 15
	s_waitcnt lgkmcnt(10)
	v_cvt_f32_f16_e32 v88, v88
	v_cvt_f32_f16_e32 v89, v89
	s_waitcnt lgkmcnt(8)
	v_cvt_f32_f16_e32 v90, v90
	v_cvt_f32_f16_e32 v91, v91
	s_waitcnt lgkmcnt(6)
	v_cvt_f32_f16_e32 v92, v92
	v_cvt_f32_f16_e32 v93, v93
	s_waitcnt lgkmcnt(4)
	v_cvt_f32_f16_e32 v94, v94
	v_cvt_f32_f16_e32 v95, v95
	v_pk_mul_f32 v[88:89], v[88:89], s[8:9] op_sel_hi:[1,0]
	v_mul_f32_e32 v89, s9, v89
	v_pk_mul_f32 v[90:91], v[90:91], s[18:19] op_sel_hi:[1,0]
	v_mul_f32_e32 v91, s19, v91
	v_pk_mul_f32 v[92:93], v[92:93], s[20:21] op_sel_hi:[1,0]
	v_mul_f32_e32 v93, s21, v93
	v_pk_mul_f32 v[94:95], v[94:95], s[22:23] op_sel_hi:[1,0]
	v_mul_f32_e32 v95, s23, v95
	ds_read_u16 v100, v253 offset:21280
	ds_read_u16 v101, v253 offset:21408
	ds_read_u16 v102, v253 offset:21552
	ds_read_u16 v103, v253 offset:21680
	ds_read_u16 v104, v253 offset:21824
	ds_read_u16 v105, v253 offset:21952
	ds_read_u16 v106, v253 offset:22096
	ds_read_u16 v107, v253 offset:22224
	v_readlane_b32 s8, v242, 16
	v_readlane_b32 s9, v243, 16
	v_readlane_b32 s18, v242, 17
	v_readlane_b32 s19, v243, 17
	v_readlane_b32 s20, v242, 18
	v_readlane_b32 s21, v243, 18
	v_readlane_b32 s22, v242, 19
	v_readlane_b32 s23, v243, 19
	s_waitcnt lgkmcnt(10)
; #define LAS __attribute__((address_space(3)))
; __device__ __forceinline__ void phase_gdb(const int wvs, const Params& p, LAS unsigned char* lds, int nwg) {
;     ...
;     { float x[64]; const bool isw = t >= 64;
; #pragma unroll
;       for (int i = 0; i < 64; ++i) { const float v = (float)R[i * RP + t]; x[i] = v * bs[i] * (isw ? __expf(gcs[i]) : 1.0f); asm volatile("" : "+v"(x[i])); if ((i & 7) == 7) __builtin_amdgcn_sched_barrier(0); }
; #pragma unroll
;       for (int i = 1; i < 64; ++i) {
; #pragma unroll
;         for (int j4 = 0; j4 < (i + 3) / 4; ++j4) { const f32x4 m4 = *(const LAS f32x4*)(M + i * 64 + j4 * 4);
; #pragma unroll
;           for (int jj = 0; jj < 4; ++jj) if (j4 * 4 + jj < i) x[i] -= m4[jj] * x[j4 * 4 + jj]; }
	v_cvt_f32_f16_e32 v96, v96
	v_cvt_f32_f16_e32 v97, v97
	s_waitcnt lgkmcnt(8)
	v_cvt_f32_f16_e32 v98, v98
	v_cvt_f32_f16_e32 v99, v99
	s_waitcnt lgkmcnt(6)
	v_cvt_f32_f16_e32 v100, v100
	v_cvt_f32_f16_e32 v101, v101
	s_waitcnt lgkmcnt(4)
	v_cvt_f32_f16_e32 v102, v102
	v_cvt_f32_f16_e32 v103, v103
	v_pk_mul_f32 v[96:97], v[96:97], s[8:9] op_sel_hi:[1,0]
	v_mul_f32_e32 v97, s9, v97
	v_pk_mul_f32 v[98:99], v[98:99], s[18:19] op_sel_hi:[1,0]
	v_mul_f32_e32 v99, s19, v99
	v_pk_mul_f32 v[100:101], v[100:101], s[20:21] op_sel_hi:[1,0]
	v_mul_f32_e32 v101, s21, v101
	v_pk_mul_f32 v[102:103], v[102:103], s[22:23] op_sel_hi:[1,0]
	v_mul_f32_e32 v103, s23, v103
	ds_read_u16 v108, v253 offset:22368
	ds_read_u16 v109, v253 offset:22496
	ds_read_u16 v110, v253 offset:22640
	ds_read_u16 v111, v253 offset:22768
	ds_read_u16 v112, v253 offset:22912
	ds_read_u16 v113, v253 offset:23040
	ds_read_u16 v114, v253 offset:23184
	ds_read_u16 v115, v253 offset:23312
	v_readlane_b32 s8, v242, 20
	v_readlane_b32 s9, v243, 20
	v_readlane_b32 s18, v242, 21
	v_readlane_b32 s19, v243, 21
	v_readlane_b32 s20, v242, 22
	v_readlane_b32 s21, v243, 22
	v_readlane_b32 s22, v242, 23
	v_readlane_b32 s23, v243, 23
	s_waitcnt lgkmcnt(10)
	v_cvt_f32_f16_e32 v104, v104
	v_cvt_f32_f16_e32 v105, v105
	s_waitcnt lgkmcnt(8)
	v_cvt_f32_f16_e32 v106, v106
	v_cvt_f32_f16_e32 v107, v107
	s_waitcnt lgkmcnt(6)
	v_cvt_f32_f16_e32 v108, v108
	v_cvt_f32_f16_e32 v109, v109
	s_waitcnt lgkmcnt(4)
	v_cvt_f32_f16_e32 v110, v110
	v_cvt_f32_f16_e32 v111, v111
	v_pk_mul_f32 v[104:105], v[104:105], s[8:9] op_sel_hi:[1,0]
	v_mul_f32_e32 v105, s9, v105
	v_pk_mul_f32 v[106:107], v[106:107], s[18:19] op_sel_hi:[1,0]
	v_mul_f32_e32 v107, s19, v107
	v_pk_mul_f32 v[108:109], v[108:109], s[20:21] op_sel_hi:[1,0]
	v_mul_f32_e32 v109, s21, v109
	v_pk_mul_f32 v[110:111], v[110:111], s[22:23] op_sel_hi:[1,0]
	v_mul_f32_e32 v111, s23, v111
	ds_read_u16 v116, v253 offset:23456
	ds_read_u16 v117, v253 offset:23584
	ds_read_u16 v118, v253 offset:23728
	ds_read_u16 v119, v253 offset:23856
	ds_read_u16 v120, v253 offset:24000
	ds_read_u16 v121, v253 offset:24128
	ds_read_u16 v122, v253 offset:24272
	ds_read_u16 v123, v253 offset:24400
	v_readlane_b32 s8, v242, 24
	v_readlane_b32 s9, v243, 24
	v_readlane_b32 s18, v242, 25
	v_readlane_b32 s19, v243, 25
	v_readlane_b32 s20, v242, 26
	v_readlane_b32 s21, v243, 26
	v_readlane_b32 s22, v242, 27
	v_readlane_b32 s23, v243, 27
	s_waitcnt lgkmcnt(10)
	v_cvt_f32_f16_e32 v112, v112
	v_cvt_f32_f16_e32 v113, v113
	s_waitcnt lgkmcnt(8)
	v_cvt_f32_f16_e32 v114, v114
	v_cvt_f32_f16_e32 v115, v115
	s_waitcnt lgkmcnt(6)
	v_cvt_f32_f16_e32 v116, v116
	v_cvt_f32_f16_e32 v117, v117
	s_waitcnt lgkmcnt(4)
	v_cvt_f32_f16_e32 v118, v118
	v_cvt_f32_f16_e32 v119, v119
	v_pk_mul_f32 v[112:113], v[112:113], s[8:9] op_sel_hi:[1,0]
	v_mul_f32_e32 v113, s9, v113
	v_pk_mul_f32 v[114:115], v[114:115], s[18:19] op_sel_hi:[1,0]
	v_mul_f32_e32 v115, s19, v115
	v_pk_mul_f32 v[116:117], v[116:117], s[20:21] op_sel_hi:[1,0]
	v_mul_f32_e32 v117, s21, v117
	v_pk_mul_f32 v[118:119], v[118:119], s[22:23] op_sel_hi:[1,0]
	v_mul_f32_e32 v119, s23, v119
	ds_read_u16 v124, v253 offset:24544
	ds_read_u16 v125, v253 offset:24672
	ds_read_u16 v126, v253 offset:24816
	ds_read_u16 v127, v253 offset:24944
	ds_read_u16 v128, v253 offset:25088
	ds_read_u16 v129, v253 offset:25216
	ds_read_u16 v130, v253 offset:25360
	ds_read_u16 v131, v253 offset:25488
	v_readlane_b32 s8, v242, 28
	v_readlane_b32 s9, v243, 28
	v_readlane_b32 s18, v242, 29
	v_readlane_b32 s19, v243, 29
	v_readlane_b32 s20, v242, 30
	v_readlane_b32 s21, v243, 30
	v_readlane_b32 s22, v242, 31
	v_readlane_b32 s23, v243, 31
	s_waitcnt lgkmcnt(10)
	v_cvt_f32_f16_e32 v120, v120
	v_cvt_f32_f16_e32 v121, v121
	s_waitcnt lgkmcnt(8)
	v_cvt_f32_f16_e32 v122, v122
	v_cvt_f32_f16_e32 v123, v123
	s_waitcnt lgkmcnt(6)
	v_cvt_f32_f16_e32 v124, v124
	v_cvt_f32_f16_e32 v125, v125
	s_waitcnt lgkmcnt(4)
	v_cvt_f32_f16_e32 v126, v126
	v_cvt_f32_f16_e32 v127, v127
	v_pk_mul_f32 v[120:121], v[120:121], s[8:9] op_sel_hi:[1,0]
	v_mul_f32_e32 v121, s9, v121
	v_pk_mul_f32 v[122:123], v[122:123], s[18:19] op_sel_hi:[1,0]
	v_mul_f32_e32 v123, s19, v123
	v_pk_mul_f32 v[124:125], v[124:125], s[20:21] op_sel_hi:[1,0]
	v_mul_f32_e32 v125, s21, v125
	v_pk_mul_f32 v[126:127], v[126:127], s[22:23] op_sel_hi:[1,0]
	v_mul_f32_e32 v127, s23, v127
	ds_read_u16 v132, v253 offset:25632
	ds_read_u16 v133, v253 offset:25760
	ds_read_u16 v134, v253 offset:25904
	ds_read_u16 v135, v253 offset:26032
	ds_read_u16 v136, v253 offset:26176
	ds_read_u16 v137, v253 offset:26304
	ds_read_u16 v138, v253 offset:26448
	ds_read_u16 v139, v253 offset:26576
	v_readlane_b32 s8, v242, 32
	v_readlane_b32 s9, v243, 32
	v_readlane_b32 s18, v242, 33
	v_readlane_b32 s19, v243, 33
	v_readlane_b32 s20, v242, 34
	v_readlane_b32 s21, v243, 34
	v_readlane_b32 s22, v242, 35
	v_readlane_b32 s23, v243, 35
	s_waitcnt lgkmcnt(10)
	v_cvt_f32_f16_e32 v128, v128
	v_cvt_f32_f16_e32 v129, v129
	s_waitcnt lgkmcnt(8)
	v_cvt_f32_f16_e32 v130, v130
	v_cvt_f32_f16_e32 v131, v131
	s_waitcnt lgkmcnt(6)
	v_cvt_f32_f16_e32 v132, v132
	v_cvt_f32_f16_e32 v133, v133
	s_waitcnt lgkmcnt(4)
; #define LAS __attribute__((address_space(3)))
; __device__ __forceinline__ void phase_gdb(const int wvs, const Params& p, LAS unsigned char* lds, int nwg) {
;     ...
;     { float x[64]; const bool isw = t >= 64;
; #pragma unroll
;       for (int i = 0; i < 64; ++i) { const float v = (float)R[i * RP + t]; x[i] = v * bs[i] * (isw ? __expf(gcs[i]) : 1.0f); asm volatile("" : "+v"(x[i])); if ((i & 7) == 7) __builtin_amdgcn_sched_barrier(0); }
; #pragma unroll
;       for (int i = 1; i < 64; ++i) {
; #pragma unroll
;         for (int j4 = 0; j4 < (i + 3) / 4; ++j4) { const f32x4 m4 = *(const LAS f32x4*)(M + i * 64 + j4 * 4);
; #pragma unroll
;           for (int jj = 0; jj < 4; ++jj) if (j4 * 4 + jj < i) x[i] -= m4[jj] * x[j4 * 4 + jj]; }
	v_cvt_f32_f16_e32 v134, v134
	v_cvt_f32_f16_e32 v135, v135
	v_pk_mul_f32 v[128:129], v[128:129], s[8:9] op_sel_hi:[1,0]
	v_mul_f32_e32 v129, s9, v129
	v_pk_mul_f32 v[130:131], v[130:131], s[18:19] op_sel_hi:[1,0]
	v_mul_f32_e32 v131, s19, v131
	v_pk_mul_f32 v[132:133], v[132:133], s[20:21] op_sel_hi:[1,0]
	v_mul_f32_e32 v133, s21, v133
	v_pk_mul_f32 v[134:135], v[134:135], s[22:23] op_sel_hi:[1,0]
	v_mul_f32_e32 v135, s23, v135
	ds_read_u16 v140, v253 offset:26720
	ds_read_u16 v141, v253 offset:26848
	ds_read_u16 v142, v253 offset:26992
	ds_read_u16 v143, v253 offset:27120
	ds_read_u16 v144, v253 offset:27264
	ds_read_u16 v145, v253 offset:27392
	ds_read_u16 v146, v253 offset:27536
	ds_read_u16 v147, v253 offset:27664
	v_readlane_b32 s8, v242, 36
	v_readlane_b32 s9, v243, 36
	v_readlane_b32 s18, v242, 37
	v_readlane_b32 s19, v243, 37
	v_readlane_b32 s20, v242, 38
	v_readlane_b32 s21, v243, 38
	v_readlane_b32 s22, v242, 39
	v_readlane_b32 s23, v243, 39
	s_waitcnt lgkmcnt(10)
	v_cvt_f32_f16_e32 v136, v136
	v_cvt_f32_f16_e32 v137, v137
	s_waitcnt lgkmcnt(8)
	v_cvt_f32_f16_e32 v138, v138
	v_cvt_f32_f16_e32 v139, v139
	s_waitcnt lgkmcnt(6)
	v_cvt_f32_f16_e32 v140, v140
	v_cvt_f32_f16_e32 v141, v141
	s_waitcnt lgkmcnt(4)
	v_cvt_f32_f16_e32 v142, v142
	v_cvt_f32_f16_e32 v143, v143
	v_pk_mul_f32 v[136:137], v[136:137], s[8:9] op_sel_hi:[1,0]
	v_mul_f32_e32 v137, s9, v137
	v_pk_mul_f32 v[138:139], v[138:139], s[18:19] op_sel_hi:[1,0]
	v_mul_f32_e32 v139, s19, v139
	v_pk_mul_f32 v[140:141], v[140:141], s[20:21] op_sel_hi:[1,0]
	v_mul_f32_e32 v141, s21, v141
	v_pk_mul_f32 v[142:143], v[142:143], s[22:23] op_sel_hi:[1,0]
	v_mul_f32_e32 v143, s23, v143
	ds_read_u16 v148, v253 offset:27808
	ds_read_u16 v149, v253 offset:27936
	ds_read_u16 v150, v253 offset:28080
	ds_read_u16 v151, v253 offset:28208
	ds_read_u16 v152, v253 offset:28352
	ds_read_u16 v153, v253 offset:28480
	ds_read_u16 v154, v253 offset:28624
	ds_read_u16 v155, v253 offset:28752
	v_readlane_b32 s8, v242, 40
	v_readlane_b32 s9, v243, 40
	v_readlane_b32 s18, v242, 41
	v_readlane_b32 s19, v243, 41
	v_readlane_b32 s20, v242, 42
	v_readlane_b32 s21, v243, 42
	v_readlane_b32 s22, v242, 43
	v_readlane_b32 s23, v243, 43
	s_waitcnt lgkmcnt(10)
	v_cvt_f32_f16_e32 v144, v144
	v_cvt_f32_f16_e32 v145, v145
	s_waitcnt lgkmcnt(8)
	v_cvt_f32_f16_e32 v146, v146
	v_cvt_f32_f16_e32 v147, v147
	s_waitcnt lgkmcnt(6)
	v_cvt_f32_f16_e32 v148, v148
	v_cvt_f32_f16_e32 v149, v149
	s_waitcnt lgkmcnt(4)
	v_cvt_f32_f16_e32 v150, v150
	v_cvt_f32_f16_e32 v151, v151
	v_pk_mul_f32 v[144:145], v[144:145], s[8:9] op_sel_hi:[1,0]
	v_mul_f32_e32 v145, s9, v145
	v_pk_mul_f32 v[146:147], v[146:147], s[18:19] op_sel_hi:[1,0]
	v_mul_f32_e32 v147, s19, v147
	v_pk_mul_f32 v[148:149], v[148:149], s[20:21] op_sel_hi:[1,0]
	v_mul_f32_e32 v149, s21, v149
	v_pk_mul_f32 v[150:151], v[150:151], s[22:23] op_sel_hi:[1,0]
	v_mul_f32_e32 v151, s23, v151
	ds_read_u16 v156, v253 offset:28896
	ds_read_u16 v157, v253 offset:29024
	ds_read_u16 v158, v253 offset:29168
	ds_read_u16 v159, v253 offset:29296
	ds_read_u16 v160, v253 offset:29440
	ds_read_u16 v161, v253 offset:29568
	ds_read_u16 v162, v253 offset:29712
	ds_read_u16 v163, v253 offset:29840
	v_readlane_b32 s8, v242, 44
	v_readlane_b32 s9, v243, 44
	v_readlane_b32 s18, v242, 45
	v_readlane_b32 s19, v243, 45
	v_readlane_b32 s20, v242, 46
	v_readlane_b32 s21, v243, 46
	v_readlane_b32 s22, v242, 47
	v_readlane_b32 s23, v243, 47
	s_waitcnt lgkmcnt(10)
	v_cvt_f32_f16_e32 v152, v152
	v_cvt_f32_f16_e32 v153, v153
	s_waitcnt lgkmcnt(8)
	v_cvt_f32_f16_e32 v154, v154
	v_cvt_f32_f16_e32 v155, v155
	s_waitcnt lgkmcnt(6)
	v_cvt_f32_f16_e32 v156, v156
	v_cvt_f32_f16_e32 v157, v157
	s_waitcnt lgkmcnt(4)
	v_cvt_f32_f16_e32 v158, v158
	v_cvt_f32_f16_e32 v159, v159
	v_pk_mul_f32 v[152:153], v[152:153], s[8:9] op_sel_hi:[1,0]
	v_mul_f32_e32 v153, s9, v153
	v_pk_mul_f32 v[154:155], v[154:155], s[18:19] op_sel_hi:[1,0]
	v_mul_f32_e32 v155, s19, v155
	v_pk_mul_f32 v[156:157], v[156:157], s[20:21] op_sel_hi:[1,0]
	v_mul_f32_e32 v157, s21, v157
	v_pk_mul_f32 v[158:159], v[158:159], s[22:23] op_sel_hi:[1,0]
	v_mul_f32_e32 v159, s23, v159
	ds_read_u16 v164, v253 offset:29984
	ds_read_u16 v165, v253 offset:30112
	ds_read_u16 v166, v253 offset:30256
	ds_read_u16 v167, v253 offset:30384
	ds_read_u16 v168, v253 offset:30528
	ds_read_u16 v169, v253 offset:30656
	ds_read_u16 v170, v253 offset:30800
	ds_read_u16 v171, v253 offset:30928
	v_readlane_b32 s8, v242, 48
	v_readlane_b32 s9, v243, 48
	v_readlane_b32 s18, v242, 49
	v_readlane_b32 s19, v243, 49
	v_readlane_b32 s20, v242, 50
	v_readlane_b32 s21, v243, 50
	v_readlane_b32 s22, v242, 51
	v_readlane_b32 s23, v243, 51
	s_waitcnt lgkmcnt(10)
	v_cvt_f32_f16_e32 v160, v160
	v_cvt_f32_f16_e32 v161, v161
	s_waitcnt lgkmcnt(8)
	v_cvt_f32_f16_e32 v162, v162
	v_cvt_f32_f16_e32 v163, v163
	s_waitcnt lgkmcnt(6)
	v_cvt_f32_f16_e32 v164, v164
	v_cvt_f32_f16_e32 v165, v165
	s_waitcnt lgkmcnt(4)
	v_cvt_f32_f16_e32 v166, v166
	v_cvt_f32_f16_e32 v167, v167
	v_pk_mul_f32 v[160:161], v[160:161], s[8:9] op_sel_hi:[1,0]
	v_mul_f32_e32 v161, s9, v161
	v_pk_mul_f32 v[162:163], v[162:163], s[18:19] op_sel_hi:[1,0]
	v_mul_f32_e32 v163, s19, v163
	v_pk_mul_f32 v[164:165], v[164:165], s[20:21] op_sel_hi:[1,0]
	v_mul_f32_e32 v165, s21, v165
	v_pk_mul_f32 v[166:167], v[166:167], s[22:23] op_sel_hi:[1,0]
	v_mul_f32_e32 v167, s23, v167
	ds_read_u16 v172, v253 offset:31072
	ds_read_u16 v173, v253 offset:31200
	ds_read_u16 v174, v253 offset:31344
	ds_read_u16 v175, v253 offset:31472
	ds_read_u16 v176, v253 offset:31616
	ds_read_u16 v177, v253 offset:31744
	ds_read_u16 v178, v253 offset:31888
	ds_read_u16 v179, v253 offset:32016
	v_readlane_b32 s8, v242, 52
	v_readlane_b32 s9, v243, 52
	v_readlane_b32 s18, v242, 53
	v_readlane_b32 s19, v243, 53
	v_readlane_b32 s20, v242, 54
	v_readlane_b32 s21, v243, 54
	v_readlane_b32 s22, v242, 55
	v_readlane_b32 s23, v243, 55
	s_waitcnt lgkmcnt(10)
; #define LAS __attribute__((address_space(3)))
; __device__ __forceinline__ void phase_gdb(const int wvs, const Params& p, LAS unsigned char* lds, int nwg) {
;     ...
;     { float x[64]; const bool isw = t >= 64;
; #pragma unroll
;       for (int i = 0; i < 64; ++i) { const float v = (float)R[i * RP + t]; x[i] = v * bs[i] * (isw ? __expf(gcs[i]) : 1.0f); asm volatile("" : "+v"(x[i])); if ((i & 7) == 7) __builtin_amdgcn_sched_barrier(0); }
; #pragma unroll
;       for (int i = 1; i < 64; ++i) {
; #pragma unroll
;         for (int j4 = 0; j4 < (i + 3) / 4; ++j4) { const f32x4 m4 = *(const LAS f32x4*)(M + i * 64 + j4 * 4);
; #pragma unroll
;           for (int jj = 0; jj < 4; ++jj) if (j4 * 4 + jj < i) x[i] -= m4[jj] * x[j4 * 4 + jj]; }
;         __builtin_amdgcn_sched_barrier(0); }
; #pragma unroll
;       for (int i = 0; i < 64; ++i) R[i * RP + t] = (hf)x[i]; }
	v_cvt_f32_f16_e32 v168, v168
	v_cvt_f32_f16_e32 v169, v169
	s_waitcnt lgkmcnt(8)
	v_cvt_f32_f16_e32 v170, v170
	v_cvt_f32_f16_e32 v171, v171
	s_waitcnt lgkmcnt(6)
	v_cvt_f32_f16_e32 v172, v172
	v_cvt_f32_f16_e32 v173, v173
	s_waitcnt lgkmcnt(4)
	v_cvt_f32_f16_e32 v174, v174
	v_cvt_f32_f16_e32 v175, v175
	v_pk_mul_f32 v[168:169], v[168:169], s[8:9] op_sel_hi:[1,0]
	v_mul_f32_e32 v169, s9, v169
	v_pk_mul_f32 v[170:171], v[170:171], s[18:19] op_sel_hi:[1,0]
	v_mul_f32_e32 v171, s19, v171
	v_pk_mul_f32 v[172:173], v[172:173], s[20:21] op_sel_hi:[1,0]
	v_mul_f32_e32 v173, s21, v173
	v_pk_mul_f32 v[174:175], v[174:175], s[22:23] op_sel_hi:[1,0]
	v_mul_f32_e32 v175, s23, v175
	ds_read_u16 v180, v253 offset:32160
	ds_read_u16 v181, v253 offset:32288
	ds_read_u16 v182, v253 offset:32432
	ds_read_u16 v183, v253 offset:32560
	ds_read_u16 v184, v253 offset:32704
	ds_read_u16 v185, v253 offset:32832
	ds_read_u16 v186, v253 offset:32976
	ds_read_u16 v187, v253 offset:33104
	ds_read_b128 v[4:7], v228 offset:256
	ds_read_b128 v[8:11], v228 offset:512
	ds_read_b128 v[12:15], v228 offset:768
	s_waitcnt lgkmcnt(14)
	ds_read_b128 v[16:19], v228 offset:1024
	s_waitcnt lgkmcnt(14)
	ds_read_b128 v[20:23], v228 offset:1280
	v_readlane_b32 s8, v242, 56
	v_readlane_b32 s9, v243, 56
	v_readlane_b32 s18, v242, 57
	v_readlane_b32 s19, v243, 57
	v_readlane_b32 s20, v242, 58
	v_readlane_b32 s21, v243, 58
	v_readlane_b32 s22, v242, 59
	v_readlane_b32 s23, v243, 59
	v_cvt_f32_f16_e32 v176, v176
	v_cvt_f32_f16_e32 v177, v177
	s_waitcnt lgkmcnt(13)
	v_cvt_f32_f16_e32 v178, v178
	v_cvt_f32_f16_e32 v179, v179
	s_waitcnt lgkmcnt(11)
	v_cvt_f32_f16_e32 v180, v180
	v_cvt_f32_f16_e32 v181, v181
	s_waitcnt lgkmcnt(9)
	v_cvt_f32_f16_e32 v182, v182
	v_cvt_f32_f16_e32 v183, v183
	v_pk_mul_f32 v[176:177], v[176:177], s[8:9] op_sel_hi:[1,0]
	v_mul_f32_e32 v177, s9, v177
	v_pk_mul_f32 v[178:179], v[178:179], s[18:19] op_sel_hi:[1,0]
	v_mul_f32_e32 v179, s19, v179
	v_pk_mul_f32 v[180:181], v[180:181], s[20:21] op_sel_hi:[1,0]
	v_mul_f32_e32 v181, s21, v181
	v_pk_mul_f32 v[182:183], v[182:183], s[22:23] op_sel_hi:[1,0]
	v_mul_f32_e32 v183, s23, v183
	ds_read_u16 v188, v253 offset:33248
	ds_read_u16 v189, v253 offset:33376
	ds_read_u16 v190, v253 offset:33520
	ds_read_u16 v191, v253 offset:33648
	v_readlane_b32 s8, v242, 60
	v_readlane_b32 s9, v243, 60
	v_readlane_b32 s18, v242, 61
	v_readlane_b32 s19, v243, 61
	v_readlane_b32 s20, v242, 62
	v_readlane_b32 s21, v243, 62
	v_readlane_b32 s22, v242, 63
	v_readlane_b32 s23, v243, 63
	s_waitcnt lgkmcnt(11)
	v_cvt_f32_f16_e32 v184, v184
	v_cvt_f32_f16_e32 v185, v185
	s_waitcnt lgkmcnt(9)
	v_cvt_f32_f16_e32 v186, v186
	v_cvt_f32_f16_e32 v187, v187
	s_waitcnt lgkmcnt(2)
	v_cvt_f32_f16_e32 v188, v188
	v_cvt_f32_f16_e32 v189, v189
	s_waitcnt lgkmcnt(0)
	v_cvt_f32_f16_e32 v190, v190
	v_cvt_f32_f16_e32 v191, v191
	v_pk_mul_f32 v[184:185], v[184:185], s[8:9] op_sel_hi:[1,0]
	v_mul_f32_e32 v185, s9, v185
	v_pk_mul_f32 v[186:187], v[186:187], s[18:19] op_sel_hi:[1,0]
	v_mul_f32_e32 v187, s19, v187
	v_pk_mul_f32 v[188:189], v[188:189], s[20:21] op_sel_hi:[1,0]
	v_mul_f32_e32 v189, s21, v189
	v_pk_mul_f32 v[190:191], v[190:191], s[22:23] op_sel_hi:[1,0]
	v_mul_f32_e32 v191, s23, v191
	v_cvt_f16_f32_e32 v0, v64
	v_cvt_f16_f32_e32 v2, v65
	ds_write_b16 v253, v0 offset:16384
	ds_write_b16 v253, v2 offset:16512
	ds_read_b128 v[24:27], v228 offset:1296
	ds_read_b128 v[28:31], v228 offset:1536
	ds_read_b128 v[32:35], v228 offset:1552
	ds_read_b128 v[36:39], v228 offset:1792
	ds_read_b128 v[40:43], v228 offset:1808
	ds_read_b128 v[44:47], v228 offset:2048
	ds_read_b128 v[48:51], v228 offset:2064
	ds_read_b128 v[52:55], v228 offset:2304
	v_fma_mixlo_f16 v3, -v64, v4, v66
	v_fma_mixlo_f16 v238, -v65, v4, v67
	v_pk_fma_f32 v[66:67], v[64:65], v[4:5], v[66:67] op_sel_hi:[1,0,1] neg_lo:[1,0,0] neg_hi:[1,0,0]
	ds_write_b16 v253, v3 offset:16656
	ds_write_b16 v253, v238 offset:16784
	ds_read_b128 v[56:59], v228 offset:2320
	v_pk_fma_f32 v[68:69], v[64:65], v[8:9], v[68:69] op_sel_hi:[1,0,1] neg_lo:[1,0,0] neg_hi:[1,0,0]
	v_fma_mixlo_f16 v239, -v66, v9, v68
	v_fma_mixlo_f16 v240, -v67, v9, v69
	v_pk_fma_f32 v[68:69], v[66:67], v[8:9], v[68:69] op_sel:[0,1,0] op_sel_hi:[1,1,1] neg_lo:[1,0,0] neg_hi:[1,0,0]
	ds_write_b16 v253, v239 offset:16928
	ds_write_b16 v253, v240 offset:17056
	s_waitcnt lgkmcnt(14)
	ds_read_b128 v[60:63], v228 offset:2336
	v_pk_fma_f32 v[70:71], v[64:65], v[12:13], v[70:71] op_sel_hi:[1,0,1] neg_lo:[1,0,0] neg_hi:[1,0,0]
	v_pk_fma_f32 v[70:71], v[66:67], v[12:13], v[70:71] op_sel:[0,1,0] op_sel_hi:[1,1,1] neg_lo:[1,0,0] neg_hi:[1,0,0]
	v_fma_mixlo_f16 v0, -v68, v14, v70
	v_fma_mixlo_f16 v2, -v69, v14, v71
	v_pk_fma_f32 v[70:71], v[68:69], v[14:15], v[70:71] op_sel_hi:[1,0,1] neg_lo:[1,0,0] neg_hi:[1,0,0]
	s_waitcnt lgkmcnt(14)
	ds_write_b16 v253, v0 offset:17200
	s_waitcnt lgkmcnt(14)
	ds_write_b16 v253, v2 offset:17328
	s_waitcnt lgkmcnt(14)
	ds_read_b128 v[244:247], v228 offset:2560
	v_pk_fma_f32 v[72:73], v[64:65], v[16:17], v[72:73] op_sel_hi:[1,0,1] neg_lo:[1,0,0] neg_hi:[1,0,0]
	v_pk_fma_f32 v[72:73], v[66:67], v[16:17], v[72:73] op_sel:[0,1,0] op_sel_hi:[1,1,1] neg_lo:[1,0,0] neg_hi:[1,0,0]
	v_pk_fma_f32 v[72:73], v[68:69], v[18:19], v[72:73] op_sel_hi:[1,0,1] neg_lo:[1,0,0] neg_hi:[1,0,0]
	v_fma_mixlo_f16 v3, -v70, v19, v72
	v_fma_mixlo_f16 v238, -v71, v19, v73
	v_pk_fma_f32 v[72:73], v[70:71], v[18:19], v[72:73] op_sel:[0,1,0] op_sel_hi:[1,1,1] neg_lo:[1,0,0] neg_hi:[1,0,0]
	s_waitcnt lgkmcnt(14)
	ds_write_b16 v253, v3 offset:17472
	s_waitcnt lgkmcnt(14)
	ds_write_b16 v253, v238 offset:17600
	s_waitcnt lgkmcnt(14)
; #define LAS __attribute__((address_space(3)))
; __device__ __forceinline__ void phase_gdb(const int wvs, const Params& p, LAS unsigned char* lds, int nwg) {
;     ...
;       for (int i = 1; i < 64; ++i) {
; #pragma unroll
;         for (int j4 = 0; j4 < (i + 3) / 4; ++j4) { const f32x4 m4 = *(const LAS f32x4*)(M + i * 64 + j4 * 4);
; #pragma unroll
;           for (int jj = 0; jj < 4; ++jj) if (j4 * 4 + jj < i) x[i] -= m4[jj] * x[j4 * 4 + jj]; }
;         __builtin_amdgcn_sched_barrier(0); }
; #pragma unroll
;       for (int i = 0; i < 64; ++i) R[i * RP + t] = (hf)x[i]; }
	ds_read_b128 v[248:251], v228 offset:2576
	v_pk_fma_f32 v[74:75], v[64:65], v[20:21], v[74:75] op_sel_hi:[1,0,1] neg_lo:[1,0,0] neg_hi:[1,0,0]
	v_pk_fma_f32 v[74:75], v[66:67], v[20:21], v[74:75] op_sel:[0,1,0] op_sel_hi:[1,1,1] neg_lo:[1,0,0] neg_hi:[1,0,0]
	v_pk_fma_f32 v[74:75], v[68:69], v[22:23], v[74:75] op_sel_hi:[1,0,1] neg_lo:[1,0,0] neg_hi:[1,0,0]
	v_pk_fma_f32 v[74:75], v[70:71], v[22:23], v[74:75] op_sel:[0,1,0] op_sel_hi:[1,1,1] neg_lo:[1,0,0] neg_hi:[1,0,0]
	s_waitcnt lgkmcnt(14)
	ds_read_b128 v[4:7], v228 offset:2592
	v_fma_mixlo_f16 v239, -v72, v24, v74
	v_fma_mixlo_f16 v240, -v73, v24, v75
	v_pk_fma_f32 v[74:75], v[72:73], v[24:25], v[74:75] op_sel_hi:[1,0,1] neg_lo:[1,0,0] neg_hi:[1,0,0]
	s_waitcnt lgkmcnt(14)
	ds_write_b16 v253, v239 offset:17744
	s_waitcnt lgkmcnt(14)
	ds_write_b16 v253, v240 offset:17872
	s_waitcnt lgkmcnt(14)
	ds_read_b128 v[8:11], v228 offset:2816
	v_pk_fma_f32 v[76:77], v[64:65], v[28:29], v[76:77] op_sel_hi:[1,0,1] neg_lo:[1,0,0] neg_hi:[1,0,0]
	v_pk_fma_f32 v[76:77], v[66:67], v[28:29], v[76:77] op_sel:[0,1,0] op_sel_hi:[1,1,1] neg_lo:[1,0,0] neg_hi:[1,0,0]
	v_pk_fma_f32 v[76:77], v[68:69], v[30:31], v[76:77] op_sel_hi:[1,0,1] neg_lo:[1,0,0] neg_hi:[1,0,0]
	v_pk_fma_f32 v[76:77], v[70:71], v[30:31], v[76:77] op_sel:[0,1,0] op_sel_hi:[1,1,1] neg_lo:[1,0,0] neg_hi:[1,0,0]
	s_waitcnt lgkmcnt(14)
	ds_read_b128 v[12:15], v228 offset:2832
	v_pk_fma_f32 v[76:77], v[72:73], v[32:33], v[76:77] op_sel_hi:[1,0,1] neg_lo:[1,0,0] neg_hi:[1,0,0]
	v_fma_mixlo_f16 v0, -v74, v33, v76
	v_fma_mixlo_f16 v2, -v75, v33, v77
	v_pk_fma_f32 v[76:77], v[74:75], v[32:33], v[76:77] op_sel:[0,1,0] op_sel_hi:[1,1,1] neg_lo:[1,0,0] neg_hi:[1,0,0]
	s_waitcnt lgkmcnt(14)
	ds_write_b16 v253, v0 offset:18016
	s_waitcnt lgkmcnt(14)
	ds_write_b16 v253, v2 offset:18144
	s_waitcnt lgkmcnt(14)
	ds_read_b128 v[16:19], v228 offset:2848
	v_pk_fma_f32 v[78:79], v[64:65], v[36:37], v[78:79] op_sel_hi:[1,0,1] neg_lo:[1,0,0] neg_hi:[1,0,0]
	v_pk_fma_f32 v[78:79], v[66:67], v[36:37], v[78:79] op_sel:[0,1,0] op_sel_hi:[1,1,1] neg_lo:[1,0,0] neg_hi:[1,0,0]
	v_pk_fma_f32 v[78:79], v[68:69], v[38:39], v[78:79] op_sel_hi:[1,0,1] neg_lo:[1,0,0] neg_hi:[1,0,0]
	v_pk_fma_f32 v[78:79], v[70:71], v[38:39], v[78:79] op_sel:[0,1,0] op_sel_hi:[1,1,1] neg_lo:[1,0,0] neg_hi:[1,0,0]
	s_waitcnt lgkmcnt(14)
	ds_read_b128 v[20:23], v228 offset:3072
	v_pk_fma_f32 v[78:79], v[72:73], v[40:41], v[78:79] op_sel_hi:[1,0,1] neg_lo:[1,0,0] neg_hi:[1,0,0]
	v_pk_fma_f32 v[78:79], v[74:75], v[40:41], v[78:79] op_sel:[0,1,0] op_sel_hi:[1,1,1] neg_lo:[1,0,0] neg_hi:[1,0,0]
	v_fma_mixlo_f16 v3, -v76, v42, v78
	v_fma_mixlo_f16 v238, -v77, v42, v79
	v_pk_fma_f32 v[78:79], v[76:77], v[42:43], v[78:79] op_sel_hi:[1,0,1] neg_lo:[1,0,0] neg_hi:[1,0,0]
	s_waitcnt lgkmcnt(14)
	ds_write_b16 v253, v3 offset:18288
	s_waitcnt lgkmcnt(14)
	ds_write_b16 v253, v238 offset:18416
	s_waitcnt lgkmcnt(14)
	ds_read_b128 v[24:27], v228 offset:3088
	v_pk_fma_f32 v[80:81], v[64:65], v[44:45], v[80:81] op_sel_hi:[1,0,1] neg_lo:[1,0,0] neg_hi:[1,0,0]
	v_pk_fma_f32 v[80:81], v[66:67], v[44:45], v[80:81] op_sel:[0,1,0] op_sel_hi:[1,1,1] neg_lo:[1,0,0] neg_hi:[1,0,0]
	v_pk_fma_f32 v[80:81], v[68:69], v[46:47], v[80:81] op_sel_hi:[1,0,1] neg_lo:[1,0,0] neg_hi:[1,0,0]
	v_pk_fma_f32 v[80:81], v[70:71], v[46:47], v[80:81] op_sel:[0,1,0] op_sel_hi:[1,1,1] neg_lo:[1,0,0] neg_hi:[1,0,0]
	s_waitcnt lgkmcnt(14)
	ds_read_b128 v[28:31], v228 offset:3104
	v_pk_fma_f32 v[80:81], v[72:73], v[48:49], v[80:81] op_sel_hi:[1,0,1] neg_lo:[1,0,0] neg_hi:[1,0,0]
	v_pk_fma_f32 v[80:81], v[74:75], v[48:49], v[80:81] op_sel:[0,1,0] op_sel_hi:[1,1,1] neg_lo:[1,0,0] neg_hi:[1,0,0]
	v_pk_fma_f32 v[80:81], v[76:77], v[50:51], v[80:81] op_sel_hi:[1,0,1] neg_lo:[1,0,0] neg_hi:[1,0,0]
	v_fma_mixlo_f16 v239, -v78, v51, v80
	v_fma_mixlo_f16 v240, -v79, v51, v81
	v_pk_fma_f32 v[80:81], v[78:79], v[50:51], v[80:81] op_sel:[0,1,0] op_sel_hi:[1,1,1] neg_lo:[1,0,0] neg_hi:[1,0,0]
	s_waitcnt lgkmcnt(14)
	ds_write_b16 v253, v239 offset:18560
	s_waitcnt lgkmcnt(14)
	ds_write_b16 v253, v240 offset:18688
	s_waitcnt lgkmcnt(14)
	ds_read_b128 v[32:35], v228 offset:3328
	v_pk_fma_f32 v[82:83], v[64:65], v[52:53], v[82:83] op_sel_hi:[1,0,1] neg_lo:[1,0,0] neg_hi:[1,0,0]
	v_pk_fma_f32 v[82:83], v[66:67], v[52:53], v[82:83] op_sel:[0,1,0] op_sel_hi:[1,1,1] neg_lo:[1,0,0] neg_hi:[1,0,0]
	v_pk_fma_f32 v[82:83], v[68:69], v[54:55], v[82:83] op_sel_hi:[1,0,1] neg_lo:[1,0,0] neg_hi:[1,0,0]
	v_pk_fma_f32 v[82:83], v[70:71], v[54:55], v[82:83] op_sel:[0,1,0] op_sel_hi:[1,1,1] neg_lo:[1,0,0] neg_hi:[1,0,0]
	s_waitcnt lgkmcnt(14)
	ds_read_b128 v[36:39], v228 offset:3344
	v_pk_fma_f32 v[82:83], v[72:73], v[56:57], v[82:83] op_sel_hi:[1,0,1] neg_lo:[1,0,0] neg_hi:[1,0,0]
	v_pk_fma_f32 v[82:83], v[74:75], v[56:57], v[82:83] op_sel:[0,1,0] op_sel_hi:[1,1,1] neg_lo:[1,0,0] neg_hi:[1,0,0]
	v_pk_fma_f32 v[82:83], v[76:77], v[58:59], v[82:83] op_sel_hi:[1,0,1] neg_lo:[1,0,0] neg_hi:[1,0,0]
	v_pk_fma_f32 v[82:83], v[78:79], v[58:59], v[82:83] op_sel:[0,1,0] op_sel_hi:[1,1,1] neg_lo:[1,0,0] neg_hi:[1,0,0]
	s_waitcnt lgkmcnt(14)
	ds_read_b128 v[40:43], v228 offset:3360
	v_fma_mixlo_f16 v0, -v80, v60, v82
	v_fma_mixlo_f16 v2, -v81, v60, v83
	v_pk_fma_f32 v[82:83], v[80:81], v[60:61], v[82:83] op_sel_hi:[1,0,1] neg_lo:[1,0,0] neg_hi:[1,0,0]
	s_waitcnt lgkmcnt(14)
	ds_write_b16 v253, v0 offset:18832
	s_waitcnt lgkmcnt(14)
	ds_write_b16 v253, v2 offset:18960
	s_waitcnt lgkmcnt(14)
; #define LAS __attribute__((address_space(3)))
; __device__ __forceinline__ void phase_gdb(const int wvs, const Params& p, LAS unsigned char* lds, int nwg) {
;     ...
;       for (int i = 1; i < 64; ++i) {
; #pragma unroll
;         for (int j4 = 0; j4 < (i + 3) / 4; ++j4) { const f32x4 m4 = *(const LAS f32x4*)(M + i * 64 + j4 * 4);
; #pragma unroll
;           for (int jj = 0; jj < 4; ++jj) if (j4 * 4 + jj < i) x[i] -= m4[jj] * x[j4 * 4 + jj]; }
;         __builtin_amdgcn_sched_barrier(0); }
; #pragma unroll
;       for (int i = 0; i < 64; ++i) R[i * RP + t] = (hf)x[i]; }
	ds_read_b128 v[44:47], v228 offset:3376
	v_pk_fma_f32 v[84:85], v[64:65], v[244:245], v[84:85] op_sel_hi:[1,0,1] neg_lo:[1,0,0] neg_hi:[1,0,0]
	v_pk_fma_f32 v[84:85], v[66:67], v[244:245], v[84:85] op_sel:[0,1,0] op_sel_hi:[1,1,1] neg_lo:[1,0,0] neg_hi:[1,0,0]
	v_pk_fma_f32 v[84:85], v[68:69], v[246:247], v[84:85] op_sel_hi:[1,0,1] neg_lo:[1,0,0] neg_hi:[1,0,0]
	v_pk_fma_f32 v[84:85], v[70:71], v[246:247], v[84:85] op_sel:[0,1,0] op_sel_hi:[1,1,1] neg_lo:[1,0,0] neg_hi:[1,0,0]
	s_waitcnt lgkmcnt(14)
	ds_read_b128 v[48:51], v228 offset:3584
	v_pk_fma_f32 v[84:85], v[72:73], v[248:249], v[84:85] op_sel_hi:[1,0,1] neg_lo:[1,0,0] neg_hi:[1,0,0]
	v_pk_fma_f32 v[84:85], v[74:75], v[248:249], v[84:85] op_sel:[0,1,0] op_sel_hi:[1,1,1] neg_lo:[1,0,0] neg_hi:[1,0,0]
	v_pk_fma_f32 v[84:85], v[76:77], v[250:251], v[84:85] op_sel_hi:[1,0,1] neg_lo:[1,0,0] neg_hi:[1,0,0]
	v_pk_fma_f32 v[84:85], v[78:79], v[250:251], v[84:85] op_sel:[0,1,0] op_sel_hi:[1,1,1] neg_lo:[1,0,0] neg_hi:[1,0,0]
	s_waitcnt lgkmcnt(14)
	ds_read_b128 v[52:55], v228 offset:3600
	v_pk_fma_f32 v[84:85], v[80:81], v[4:5], v[84:85] op_sel_hi:[1,0,1] neg_lo:[1,0,0] neg_hi:[1,0,0]
	v_fma_mixlo_f16 v3, -v82, v5, v84
	v_fma_mixlo_f16 v238, -v83, v5, v85
	v_pk_fma_f32 v[84:85], v[82:83], v[4:5], v[84:85] op_sel:[0,1,0] op_sel_hi:[1,1,1] neg_lo:[1,0,0] neg_hi:[1,0,0]
	s_waitcnt lgkmcnt(14)
	ds_write_b16 v253, v3 offset:19104
	s_waitcnt lgkmcnt(14)
	ds_write_b16 v253, v238 offset:19232
	s_waitcnt lgkmcnt(14)
	ds_read_b128 v[56:59], v228 offset:3616
	v_pk_fma_f32 v[86:87], v[64:65], v[8:9], v[86:87] op_sel_hi:[1,0,1] neg_lo:[1,0,0] neg_hi:[1,0,0]
	v_pk_fma_f32 v[86:87], v[66:67], v[8:9], v[86:87] op_sel:[0,1,0] op_sel_hi:[1,1,1] neg_lo:[1,0,0] neg_hi:[1,0,0]
	v_pk_fma_f32 v[86:87], v[68:69], v[10:11], v[86:87] op_sel_hi:[1,0,1] neg_lo:[1,0,0] neg_hi:[1,0,0]
	v_pk_fma_f32 v[86:87], v[70:71], v[10:11], v[86:87] op_sel:[0,1,0] op_sel_hi:[1,1,1] neg_lo:[1,0,0] neg_hi:[1,0,0]
	s_waitcnt lgkmcnt(14)
	ds_read_b128 v[60:63], v228 offset:3632
	v_pk_fma_f32 v[86:87], v[72:73], v[12:13], v[86:87] op_sel_hi:[1,0,1] neg_lo:[1,0,0] neg_hi:[1,0,0]
	v_pk_fma_f32 v[86:87], v[74:75], v[12:13], v[86:87] op_sel:[0,1,0] op_sel_hi:[1,1,1] neg_lo:[1,0,0] neg_hi:[1,0,0]
	v_pk_fma_f32 v[86:87], v[76:77], v[14:15], v[86:87] op_sel_hi:[1,0,1] neg_lo:[1,0,0] neg_hi:[1,0,0]
	v_pk_fma_f32 v[86:87], v[78:79], v[14:15], v[86:87] op_sel:[0,1,0] op_sel_hi:[1,1,1] neg_lo:[1,0,0] neg_hi:[1,0,0]
	s_waitcnt lgkmcnt(14)
	ds_read_b128 v[244:247], v228 offset:3840
	v_pk_fma_f32 v[86:87], v[80:81], v[16:17], v[86:87] op_sel_hi:[1,0,1] neg_lo:[1,0,0] neg_hi:[1,0,0]
	v_pk_fma_f32 v[86:87], v[82:83], v[16:17], v[86:87] op_sel:[0,1,0] op_sel_hi:[1,1,1] neg_lo:[1,0,0] neg_hi:[1,0,0]
	v_fma_mixlo_f16 v239, -v84, v18, v86
	v_fma_mixlo_f16 v240, -v85, v18, v87
	v_pk_fma_f32 v[86:87], v[84:85], v[18:19], v[86:87] op_sel_hi:[1,0,1] neg_lo:[1,0,0] neg_hi:[1,0,0]
	s_waitcnt lgkmcnt(14)
	ds_write_b16 v253, v239 offset:19376
	s_waitcnt lgkmcnt(14)
	ds_write_b16 v253, v240 offset:19504
	s_waitcnt lgkmcnt(14)
	ds_read_b128 v[248:251], v228 offset:3856
	v_pk_fma_f32 v[88:89], v[64:65], v[20:21], v[88:89] op_sel_hi:[1,0,1] neg_lo:[1,0,0] neg_hi:[1,0,0]
	v_pk_fma_f32 v[88:89], v[66:67], v[20:21], v[88:89] op_sel:[0,1,0] op_sel_hi:[1,1,1] neg_lo:[1,0,0] neg_hi:[1,0,0]
	v_pk_fma_f32 v[88:89], v[68:69], v[22:23], v[88:89] op_sel_hi:[1,0,1] neg_lo:[1,0,0] neg_hi:[1,0,0]
	v_pk_fma_f32 v[88:89], v[70:71], v[22:23], v[88:89] op_sel:[0,1,0] op_sel_hi:[1,1,1] neg_lo:[1,0,0] neg_hi:[1,0,0]
	s_waitcnt lgkmcnt(14)
	ds_read_b128 v[4:7], v228 offset:3872
	v_pk_fma_f32 v[88:89], v[72:73], v[24:25], v[88:89] op_sel_hi:[1,0,1] neg_lo:[1,0,0] neg_hi:[1,0,0]
	v_pk_fma_f32 v[88:89], v[74:75], v[24:25], v[88:89] op_sel:[0,1,0] op_sel_hi:[1,1,1] neg_lo:[1,0,0] neg_hi:[1,0,0]
	v_pk_fma_f32 v[88:89], v[76:77], v[26:27], v[88:89] op_sel_hi:[1,0,1] neg_lo:[1,0,0] neg_hi:[1,0,0]
	v_pk_fma_f32 v[88:89], v[78:79], v[26:27], v[88:89] op_sel:[0,1,0] op_sel_hi:[1,1,1] neg_lo:[1,0,0] neg_hi:[1,0,0]
	s_waitcnt lgkmcnt(14)
	ds_read_b128 v[8:11], v228 offset:3888
	v_pk_fma_f32 v[88:89], v[80:81], v[28:29], v[88:89] op_sel_hi:[1,0,1] neg_lo:[1,0,0] neg_hi:[1,0,0]
	v_pk_fma_f32 v[88:89], v[82:83], v[28:29], v[88:89] op_sel:[0,1,0] op_sel_hi:[1,1,1] neg_lo:[1,0,0] neg_hi:[1,0,0]
	v_pk_fma_f32 v[88:89], v[84:85], v[30:31], v[88:89] op_sel_hi:[1,0,1] neg_lo:[1,0,0] neg_hi:[1,0,0]
	v_fma_mixlo_f16 v0, -v86, v31, v88
	v_fma_mixlo_f16 v2, -v87, v31, v89
	v_pk_fma_f32 v[88:89], v[86:87], v[30:31], v[88:89] op_sel:[0,1,0] op_sel_hi:[1,1,1] neg_lo:[1,0,0] neg_hi:[1,0,0]
	s_waitcnt lgkmcnt(14)
	ds_write_b16 v253, v0 offset:19648
	s_waitcnt lgkmcnt(14)
	ds_write_b16 v253, v2 offset:19776
	s_waitcnt lgkmcnt(14)
	ds_read_b128 v[12:15], v228 offset:4096
	v_pk_fma_f32 v[90:91], v[64:65], v[32:33], v[90:91] op_sel_hi:[1,0,1] neg_lo:[1,0,0] neg_hi:[1,0,0]
	v_pk_fma_f32 v[90:91], v[66:67], v[32:33], v[90:91] op_sel:[0,1,0] op_sel_hi:[1,1,1] neg_lo:[1,0,0] neg_hi:[1,0,0]
	v_pk_fma_f32 v[90:91], v[68:69], v[34:35], v[90:91] op_sel_hi:[1,0,1] neg_lo:[1,0,0] neg_hi:[1,0,0]
	v_pk_fma_f32 v[90:91], v[70:71], v[34:35], v[90:91] op_sel:[0,1,0] op_sel_hi:[1,1,1] neg_lo:[1,0,0] neg_hi:[1,0,0]
	s_waitcnt lgkmcnt(14)
	ds_read_b128 v[16:19], v228 offset:4112
	v_pk_fma_f32 v[90:91], v[72:73], v[36:37], v[90:91] op_sel_hi:[1,0,1] neg_lo:[1,0,0] neg_hi:[1,0,0]
	v_pk_fma_f32 v[90:91], v[74:75], v[36:37], v[90:91] op_sel:[0,1,0] op_sel_hi:[1,1,1] neg_lo:[1,0,0] neg_hi:[1,0,0]
	v_pk_fma_f32 v[90:91], v[76:77], v[38:39], v[90:91] op_sel_hi:[1,0,1] neg_lo:[1,0,0] neg_hi:[1,0,0]
	v_pk_fma_f32 v[90:91], v[78:79], v[38:39], v[90:91] op_sel:[0,1,0] op_sel_hi:[1,1,1] neg_lo:[1,0,0] neg_hi:[1,0,0]
	s_waitcnt lgkmcnt(14)
; #define LAS __attribute__((address_space(3)))
; __device__ __forceinline__ void phase_gdb(const int wvs, const Params& p, LAS unsigned char* lds, int nwg) {
;     ...
;       for (int i = 1; i < 64; ++i) {
; #pragma unroll
;         for (int j4 = 0; j4 < (i + 3) / 4; ++j4) { const f32x4 m4 = *(const LAS f32x4*)(M + i * 64 + j4 * 4);
; #pragma unroll
;           for (int jj = 0; jj < 4; ++jj) if (j4 * 4 + jj < i) x[i] -= m4[jj] * x[j4 * 4 + jj]; }
;         __builtin_amdgcn_sched_barrier(0); }
; #pragma unroll
;       for (int i = 0; i < 64; ++i) R[i * RP + t] = (hf)x[i]; }
	ds_read_b128 v[20:23], v228 offset:4128
	v_pk_fma_f32 v[90:91], v[80:81], v[40:41], v[90:91] op_sel_hi:[1,0,1] neg_lo:[1,0,0] neg_hi:[1,0,0]
	v_pk_fma_f32 v[90:91], v[82:83], v[40:41], v[90:91] op_sel:[0,1,0] op_sel_hi:[1,1,1] neg_lo:[1,0,0] neg_hi:[1,0,0]
	v_pk_fma_f32 v[90:91], v[84:85], v[42:43], v[90:91] op_sel_hi:[1,0,1] neg_lo:[1,0,0] neg_hi:[1,0,0]
	v_pk_fma_f32 v[90:91], v[86:87], v[42:43], v[90:91] op_sel:[0,1,0] op_sel_hi:[1,1,1] neg_lo:[1,0,0] neg_hi:[1,0,0]
	s_waitcnt lgkmcnt(14)
	ds_read_b128 v[24:27], v228 offset:4144
	v_fma_mixlo_f16 v3, -v88, v44, v90
	v_fma_mixlo_f16 v238, -v89, v44, v91
	v_pk_fma_f32 v[90:91], v[88:89], v[44:45], v[90:91] op_sel_hi:[1,0,1] neg_lo:[1,0,0] neg_hi:[1,0,0]
	s_waitcnt lgkmcnt(14)
	ds_write_b16 v253, v3 offset:19920
	s_waitcnt lgkmcnt(14)
	ds_write_b16 v253, v238 offset:20048
	s_waitcnt lgkmcnt(14)
	ds_read_b128 v[28:31], v228 offset:4352
	v_pk_fma_f32 v[92:93], v[64:65], v[48:49], v[92:93] op_sel_hi:[1,0,1] neg_lo:[1,0,0] neg_hi:[1,0,0]
	v_pk_fma_f32 v[92:93], v[66:67], v[48:49], v[92:93] op_sel:[0,1,0] op_sel_hi:[1,1,1] neg_lo:[1,0,0] neg_hi:[1,0,0]
	v_pk_fma_f32 v[92:93], v[68:69], v[50:51], v[92:93] op_sel_hi:[1,0,1] neg_lo:[1,0,0] neg_hi:[1,0,0]
	v_pk_fma_f32 v[92:93], v[70:71], v[50:51], v[92:93] op_sel:[0,1,0] op_sel_hi:[1,1,1] neg_lo:[1,0,0] neg_hi:[1,0,0]
	s_waitcnt lgkmcnt(14)
	ds_read_b128 v[32:35], v228 offset:4368
	v_pk_fma_f32 v[92:93], v[72:73], v[52:53], v[92:93] op_sel_hi:[1,0,1] neg_lo:[1,0,0] neg_hi:[1,0,0]
	v_pk_fma_f32 v[92:93], v[74:75], v[52:53], v[92:93] op_sel:[0,1,0] op_sel_hi:[1,1,1] neg_lo:[1,0,0] neg_hi:[1,0,0]
	v_pk_fma_f32 v[92:93], v[76:77], v[54:55], v[92:93] op_sel_hi:[1,0,1] neg_lo:[1,0,0] neg_hi:[1,0,0]
	v_pk_fma_f32 v[92:93], v[78:79], v[54:55], v[92:93] op_sel:[0,1,0] op_sel_hi:[1,1,1] neg_lo:[1,0,0] neg_hi:[1,0,0]
	s_waitcnt lgkmcnt(14)
	ds_read_b128 v[36:39], v228 offset:4384
	v_pk_fma_f32 v[92:93], v[80:81], v[56:57], v[92:93] op_sel_hi:[1,0,1] neg_lo:[1,0,0] neg_hi:[1,0,0]
	v_pk_fma_f32 v[92:93], v[82:83], v[56:57], v[92:93] op_sel:[0,1,0] op_sel_hi:[1,1,1] neg_lo:[1,0,0] neg_hi:[1,0,0]
	v_pk_fma_f32 v[92:93], v[84:85], v[58:59], v[92:93] op_sel_hi:[1,0,1] neg_lo:[1,0,0] neg_hi:[1,0,0]
	v_pk_fma_f32 v[92:93], v[86:87], v[58:59], v[92:93] op_sel:[0,1,0] op_sel_hi:[1,1,1] neg_lo:[1,0,0] neg_hi:[1,0,0]
	s_waitcnt lgkmcnt(14)
	ds_read_b128 v[40:43], v228 offset:4400
	v_pk_fma_f32 v[92:93], v[88:89], v[60:61], v[92:93] op_sel_hi:[1,0,1] neg_lo:[1,0,0] neg_hi:[1,0,0]
	v_fma_mixlo_f16 v239, -v90, v61, v92
	v_fma_mixlo_f16 v240, -v91, v61, v93
	v_pk_fma_f32 v[92:93], v[90:91], v[60:61], v[92:93] op_sel:[0,1,0] op_sel_hi:[1,1,1] neg_lo:[1,0,0] neg_hi:[1,0,0]
	s_waitcnt lgkmcnt(14)
	ds_write_b16 v253, v239 offset:20192
	s_waitcnt lgkmcnt(14)
	ds_write_b16 v253, v240 offset:20320
	s_waitcnt lgkmcnt(14)
	ds_read_b128 v[44:47], v228 offset:4416
	v_pk_fma_f32 v[94:95], v[64:65], v[244:245], v[94:95] op_sel_hi:[1,0,1] neg_lo:[1,0,0] neg_hi:[1,0,0]
	v_pk_fma_f32 v[94:95], v[66:67], v[244:245], v[94:95] op_sel:[0,1,0] op_sel_hi:[1,1,1] neg_lo:[1,0,0] neg_hi:[1,0,0]
	v_pk_fma_f32 v[94:95], v[68:69], v[246:247], v[94:95] op_sel_hi:[1,0,1] neg_lo:[1,0,0] neg_hi:[1,0,0]
	v_pk_fma_f32 v[94:95], v[70:71], v[246:247], v[94:95] op_sel:[0,1,0] op_sel_hi:[1,1,1] neg_lo:[1,0,0] neg_hi:[1,0,0]
	s_waitcnt lgkmcnt(14)
	ds_read_b128 v[48:51], v228 offset:4608
	v_pk_fma_f32 v[94:95], v[72:73], v[248:249], v[94:95] op_sel_hi:[1,0,1] neg_lo:[1,0,0] neg_hi:[1,0,0]
	v_pk_fma_f32 v[94:95], v[74:75], v[248:249], v[94:95] op_sel:[0,1,0] op_sel_hi:[1,1,1] neg_lo:[1,0,0] neg_hi:[1,0,0]
	v_pk_fma_f32 v[94:95], v[76:77], v[250:251], v[94:95] op_sel_hi:[1,0,1] neg_lo:[1,0,0] neg_hi:[1,0,0]
	v_pk_fma_f32 v[94:95], v[78:79], v[250:251], v[94:95] op_sel:[0,1,0] op_sel_hi:[1,1,1] neg_lo:[1,0,0] neg_hi:[1,0,0]
	s_waitcnt lgkmcnt(14)
	ds_read_b128 v[52:55], v228 offset:4624
	v_pk_fma_f32 v[94:95], v[80:81], v[4:5], v[94:95] op_sel_hi:[1,0,1] neg_lo:[1,0,0] neg_hi:[1,0,0]
	v_pk_fma_f32 v[94:95], v[82:83], v[4:5], v[94:95] op_sel:[0,1,0] op_sel_hi:[1,1,1] neg_lo:[1,0,0] neg_hi:[1,0,0]
	v_pk_fma_f32 v[94:95], v[84:85], v[6:7], v[94:95] op_sel_hi:[1,0,1] neg_lo:[1,0,0] neg_hi:[1,0,0]
	v_pk_fma_f32 v[94:95], v[86:87], v[6:7], v[94:95] op_sel:[0,1,0] op_sel_hi:[1,1,1] neg_lo:[1,0,0] neg_hi:[1,0,0]
	s_waitcnt lgkmcnt(14)
	ds_read_b128 v[56:59], v228 offset:4640
	v_pk_fma_f32 v[94:95], v[88:89], v[8:9], v[94:95] op_sel_hi:[1,0,1] neg_lo:[1,0,0] neg_hi:[1,0,0]
	v_pk_fma_f32 v[94:95], v[90:91], v[8:9], v[94:95] op_sel:[0,1,0] op_sel_hi:[1,1,1] neg_lo:[1,0,0] neg_hi:[1,0,0]
	v_fma_mixlo_f16 v0, -v92, v10, v94
	v_fma_mixlo_f16 v2, -v93, v10, v95
	v_pk_fma_f32 v[94:95], v[92:93], v[10:11], v[94:95] op_sel_hi:[1,0,1] neg_lo:[1,0,0] neg_hi:[1,0,0]
	s_waitcnt lgkmcnt(14)
	ds_write_b16 v253, v0 offset:20464
	s_waitcnt lgkmcnt(14)
	ds_write_b16 v253, v2 offset:20592
	s_waitcnt lgkmcnt(14)
	ds_read_b128 v[60:63], v228 offset:4656
	v_pk_fma_f32 v[96:97], v[64:65], v[12:13], v[96:97] op_sel_hi:[1,0,1] neg_lo:[1,0,0] neg_hi:[1,0,0]
	v_pk_fma_f32 v[96:97], v[66:67], v[12:13], v[96:97] op_sel:[0,1,0] op_sel_hi:[1,1,1] neg_lo:[1,0,0] neg_hi:[1,0,0]
	v_pk_fma_f32 v[96:97], v[68:69], v[14:15], v[96:97] op_sel_hi:[1,0,1] neg_lo:[1,0,0] neg_hi:[1,0,0]
	v_pk_fma_f32 v[96:97], v[70:71], v[14:15], v[96:97] op_sel:[0,1,0] op_sel_hi:[1,1,1] neg_lo:[1,0,0] neg_hi:[1,0,0]
	s_waitcnt lgkmcnt(14)
; #define LAS __attribute__((address_space(3)))
; __device__ __forceinline__ void phase_gdb(const int wvs, const Params& p, LAS unsigned char* lds, int nwg) {
;     ...
;       for (int i = 1; i < 64; ++i) {
; #pragma unroll
;         for (int j4 = 0; j4 < (i + 3) / 4; ++j4) { const f32x4 m4 = *(const LAS f32x4*)(M + i * 64 + j4 * 4);
; #pragma unroll
;           for (int jj = 0; jj < 4; ++jj) if (j4 * 4 + jj < i) x[i] -= m4[jj] * x[j4 * 4 + jj]; }
;         __builtin_amdgcn_sched_barrier(0); }
; #pragma unroll
;       for (int i = 0; i < 64; ++i) R[i * RP + t] = (hf)x[i]; }
	ds_read_b128 v[244:247], v228 offset:4672
	v_pk_fma_f32 v[96:97], v[72:73], v[16:17], v[96:97] op_sel_hi:[1,0,1] neg_lo:[1,0,0] neg_hi:[1,0,0]
	v_pk_fma_f32 v[96:97], v[74:75], v[16:17], v[96:97] op_sel:[0,1,0] op_sel_hi:[1,1,1] neg_lo:[1,0,0] neg_hi:[1,0,0]
	v_pk_fma_f32 v[96:97], v[76:77], v[18:19], v[96:97] op_sel_hi:[1,0,1] neg_lo:[1,0,0] neg_hi:[1,0,0]
	v_pk_fma_f32 v[96:97], v[78:79], v[18:19], v[96:97] op_sel:[0,1,0] op_sel_hi:[1,1,1] neg_lo:[1,0,0] neg_hi:[1,0,0]
	s_waitcnt lgkmcnt(14)
	ds_read_b128 v[248:251], v228 offset:4864
	v_pk_fma_f32 v[96:97], v[80:81], v[20:21], v[96:97] op_sel_hi:[1,0,1] neg_lo:[1,0,0] neg_hi:[1,0,0]
	v_pk_fma_f32 v[96:97], v[82:83], v[20:21], v[96:97] op_sel:[0,1,0] op_sel_hi:[1,1,1] neg_lo:[1,0,0] neg_hi:[1,0,0]
	v_pk_fma_f32 v[96:97], v[84:85], v[22:23], v[96:97] op_sel_hi:[1,0,1] neg_lo:[1,0,0] neg_hi:[1,0,0]
	v_pk_fma_f32 v[96:97], v[86:87], v[22:23], v[96:97] op_sel:[0,1,0] op_sel_hi:[1,1,1] neg_lo:[1,0,0] neg_hi:[1,0,0]
	s_waitcnt lgkmcnt(14)
	ds_read_b128 v[4:7], v228 offset:4880
	v_pk_fma_f32 v[96:97], v[88:89], v[24:25], v[96:97] op_sel_hi:[1,0,1] neg_lo:[1,0,0] neg_hi:[1,0,0]
	v_pk_fma_f32 v[96:97], v[90:91], v[24:25], v[96:97] op_sel:[0,1,0] op_sel_hi:[1,1,1] neg_lo:[1,0,0] neg_hi:[1,0,0]
	v_pk_fma_f32 v[96:97], v[92:93], v[26:27], v[96:97] op_sel_hi:[1,0,1] neg_lo:[1,0,0] neg_hi:[1,0,0]
	v_fma_mixlo_f16 v3, -v94, v27, v96
	v_fma_mixlo_f16 v238, -v95, v27, v97
	v_pk_fma_f32 v[96:97], v[94:95], v[26:27], v[96:97] op_sel:[0,1,0] op_sel_hi:[1,1,1] neg_lo:[1,0,0] neg_hi:[1,0,0]
	s_waitcnt lgkmcnt(14)
	ds_write_b16 v253, v3 offset:20736
	s_waitcnt lgkmcnt(14)
	ds_write_b16 v253, v238 offset:20864
	s_waitcnt lgkmcnt(14)
	ds_read_b128 v[8:11], v228 offset:4896
	v_pk_fma_f32 v[98:99], v[64:65], v[28:29], v[98:99] op_sel_hi:[1,0,1] neg_lo:[1,0,0] neg_hi:[1,0,0]
	v_pk_fma_f32 v[98:99], v[66:67], v[28:29], v[98:99] op_sel:[0,1,0] op_sel_hi:[1,1,1] neg_lo:[1,0,0] neg_hi:[1,0,0]
	v_pk_fma_f32 v[98:99], v[68:69], v[30:31], v[98:99] op_sel_hi:[1,0,1] neg_lo:[1,0,0] neg_hi:[1,0,0]
	v_pk_fma_f32 v[98:99], v[70:71], v[30:31], v[98:99] op_sel:[0,1,0] op_sel_hi:[1,1,1] neg_lo:[1,0,0] neg_hi:[1,0,0]
	s_waitcnt lgkmcnt(14)
	ds_read_b128 v[12:15], v228 offset:4912
	v_pk_fma_f32 v[98:99], v[72:73], v[32:33], v[98:99] op_sel_hi:[1,0,1] neg_lo:[1,0,0] neg_hi:[1,0,0]
	v_pk_fma_f32 v[98:99], v[74:75], v[32:33], v[98:99] op_sel:[0,1,0] op_sel_hi:[1,1,1] neg_lo:[1,0,0] neg_hi:[1,0,0]
	v_pk_fma_f32 v[98:99], v[76:77], v[34:35], v[98:99] op_sel_hi:[1,0,1] neg_lo:[1,0,0] neg_hi:[1,0,0]
	v_pk_fma_f32 v[98:99], v[78:79], v[34:35], v[98:99] op_sel:[0,1,0] op_sel_hi:[1,1,1] neg_lo:[1,0,0] neg_hi:[1,0,0]
	s_waitcnt lgkmcnt(14)
	ds_read_b128 v[16:19], v228 offset:4928
	v_pk_fma_f32 v[98:99], v[80:81], v[36:37], v[98:99] op_sel_hi:[1,0,1] neg_lo:[1,0,0] neg_hi:[1,0,0]
	v_pk_fma_f32 v[98:99], v[82:83], v[36:37], v[98:99] op_sel:[0,1,0] op_sel_hi:[1,1,1] neg_lo:[1,0,0] neg_hi:[1,0,0]
	v_pk_fma_f32 v[98:99], v[84:85], v[38:39], v[98:99] op_sel_hi:[1,0,1] neg_lo:[1,0,0] neg_hi:[1,0,0]
	v_pk_fma_f32 v[98:99], v[86:87], v[38:39], v[98:99] op_sel:[0,1,0] op_sel_hi:[1,1,1] neg_lo:[1,0,0] neg_hi:[1,0,0]
	s_waitcnt lgkmcnt(14)
	ds_read_b128 v[20:23], v228 offset:5120
	v_pk_fma_f32 v[98:99], v[88:89], v[40:41], v[98:99] op_sel_hi:[1,0,1] neg_lo:[1,0,0] neg_hi:[1,0,0]
	v_pk_fma_f32 v[98:99], v[90:91], v[40:41], v[98:99] op_sel:[0,1,0] op_sel_hi:[1,1,1] neg_lo:[1,0,0] neg_hi:[1,0,0]
	v_pk_fma_f32 v[98:99], v[92:93], v[42:43], v[98:99] op_sel_hi:[1,0,1] neg_lo:[1,0,0] neg_hi:[1,0,0]
	v_pk_fma_f32 v[98:99], v[94:95], v[42:43], v[98:99] op_sel:[0,1,0] op_sel_hi:[1,1,1] neg_lo:[1,0,0] neg_hi:[1,0,0]
	s_waitcnt lgkmcnt(14)
	ds_read_b128 v[24:27], v228 offset:5136
	v_fma_mixlo_f16 v239, -v96, v44, v98
	v_fma_mixlo_f16 v240, -v97, v44, v99
	v_pk_fma_f32 v[98:99], v[96:97], v[44:45], v[98:99] op_sel_hi:[1,0,1] neg_lo:[1,0,0] neg_hi:[1,0,0]
	s_waitcnt lgkmcnt(14)
	ds_write_b16 v253, v239 offset:21008
	s_waitcnt lgkmcnt(14)
	ds_write_b16 v253, v240 offset:21136
	s_waitcnt lgkmcnt(14)
	ds_read_b128 v[28:31], v228 offset:5152
	v_pk_fma_f32 v[100:101], v[64:65], v[48:49], v[100:101] op_sel_hi:[1,0,1] neg_lo:[1,0,0] neg_hi:[1,0,0]
	v_pk_fma_f32 v[100:101], v[66:67], v[48:49], v[100:101] op_sel:[0,1,0] op_sel_hi:[1,1,1] neg_lo:[1,0,0] neg_hi:[1,0,0]
	v_pk_fma_f32 v[100:101], v[68:69], v[50:51], v[100:101] op_sel_hi:[1,0,1] neg_lo:[1,0,0] neg_hi:[1,0,0]
	v_pk_fma_f32 v[100:101], v[70:71], v[50:51], v[100:101] op_sel:[0,1,0] op_sel_hi:[1,1,1] neg_lo:[1,0,0] neg_hi:[1,0,0]
	s_waitcnt lgkmcnt(14)
	ds_read_b128 v[32:35], v228 offset:5168
	v_pk_fma_f32 v[100:101], v[72:73], v[52:53], v[100:101] op_sel_hi:[1,0,1] neg_lo:[1,0,0] neg_hi:[1,0,0]
	v_pk_fma_f32 v[100:101], v[74:75], v[52:53], v[100:101] op_sel:[0,1,0] op_sel_hi:[1,1,1] neg_lo:[1,0,0] neg_hi:[1,0,0]
	v_pk_fma_f32 v[100:101], v[76:77], v[54:55], v[100:101] op_sel_hi:[1,0,1] neg_lo:[1,0,0] neg_hi:[1,0,0]
	v_pk_fma_f32 v[100:101], v[78:79], v[54:55], v[100:101] op_sel:[0,1,0] op_sel_hi:[1,1,1] neg_lo:[1,0,0] neg_hi:[1,0,0]
	s_waitcnt lgkmcnt(14)
	ds_read_b128 v[36:39], v228 offset:5184
	v_pk_fma_f32 v[100:101], v[80:81], v[56:57], v[100:101] op_sel_hi:[1,0,1] neg_lo:[1,0,0] neg_hi:[1,0,0]
	v_pk_fma_f32 v[100:101], v[82:83], v[56:57], v[100:101] op_sel:[0,1,0] op_sel_hi:[1,1,1] neg_lo:[1,0,0] neg_hi:[1,0,0]
	v_pk_fma_f32 v[100:101], v[84:85], v[58:59], v[100:101] op_sel_hi:[1,0,1] neg_lo:[1,0,0] neg_hi:[1,0,0]
	v_pk_fma_f32 v[100:101], v[86:87], v[58:59], v[100:101] op_sel:[0,1,0] op_sel_hi:[1,1,1] neg_lo:[1,0,0] neg_hi:[1,0,0]
	s_waitcnt lgkmcnt(14)
; #define LAS __attribute__((address_space(3)))
; __device__ __forceinline__ void phase_gdb(const int wvs, const Params& p, LAS unsigned char* lds, int nwg) {
;     ...
;       for (int i = 1; i < 64; ++i) {
; #pragma unroll
;         for (int j4 = 0; j4 < (i + 3) / 4; ++j4) { const f32x4 m4 = *(const LAS f32x4*)(M + i * 64 + j4 * 4);
; #pragma unroll
;           for (int jj = 0; jj < 4; ++jj) if (j4 * 4 + jj < i) x[i] -= m4[jj] * x[j4 * 4 + jj]; }
;         __builtin_amdgcn_sched_barrier(0); }
; #pragma unroll
;       for (int i = 0; i < 64; ++i) R[i * RP + t] = (hf)x[i]; }
	ds_read_b128 v[40:43], v228 offset:5376
	v_pk_fma_f32 v[100:101], v[88:89], v[60:61], v[100:101] op_sel_hi:[1,0,1] neg_lo:[1,0,0] neg_hi:[1,0,0]
	v_pk_fma_f32 v[100:101], v[90:91], v[60:61], v[100:101] op_sel:[0,1,0] op_sel_hi:[1,1,1] neg_lo:[1,0,0] neg_hi:[1,0,0]
	v_pk_fma_f32 v[100:101], v[92:93], v[62:63], v[100:101] op_sel_hi:[1,0,1] neg_lo:[1,0,0] neg_hi:[1,0,0]
	v_pk_fma_f32 v[100:101], v[94:95], v[62:63], v[100:101] op_sel:[0,1,0] op_sel_hi:[1,1,1] neg_lo:[1,0,0] neg_hi:[1,0,0]
	s_waitcnt lgkmcnt(14)
	ds_read_b128 v[44:47], v228 offset:5392
	v_pk_fma_f32 v[100:101], v[96:97], v[244:245], v[100:101] op_sel_hi:[1,0,1] neg_lo:[1,0,0] neg_hi:[1,0,0]
	v_fma_mixlo_f16 v0, -v98, v245, v100
	v_fma_mixlo_f16 v2, -v99, v245, v101
	v_pk_fma_f32 v[100:101], v[98:99], v[244:245], v[100:101] op_sel:[0,1,0] op_sel_hi:[1,1,1] neg_lo:[1,0,0] neg_hi:[1,0,0]
	s_waitcnt lgkmcnt(14)
	ds_write_b16 v253, v0 offset:21280
	s_waitcnt lgkmcnt(14)
	ds_write_b16 v253, v2 offset:21408
	s_waitcnt lgkmcnt(14)
	ds_read_b128 v[48:51], v228 offset:5408
	v_pk_fma_f32 v[102:103], v[64:65], v[248:249], v[102:103] op_sel_hi:[1,0,1] neg_lo:[1,0,0] neg_hi:[1,0,0]
	v_pk_fma_f32 v[102:103], v[66:67], v[248:249], v[102:103] op_sel:[0,1,0] op_sel_hi:[1,1,1] neg_lo:[1,0,0] neg_hi:[1,0,0]
	v_pk_fma_f32 v[102:103], v[68:69], v[250:251], v[102:103] op_sel_hi:[1,0,1] neg_lo:[1,0,0] neg_hi:[1,0,0]
	v_pk_fma_f32 v[102:103], v[70:71], v[250:251], v[102:103] op_sel:[0,1,0] op_sel_hi:[1,1,1] neg_lo:[1,0,0] neg_hi:[1,0,0]
	s_waitcnt lgkmcnt(14)
	ds_read_b128 v[52:55], v228 offset:5424
	v_pk_fma_f32 v[102:103], v[72:73], v[4:5], v[102:103] op_sel_hi:[1,0,1] neg_lo:[1,0,0] neg_hi:[1,0,0]
	v_pk_fma_f32 v[102:103], v[74:75], v[4:5], v[102:103] op_sel:[0,1,0] op_sel_hi:[1,1,1] neg_lo:[1,0,0] neg_hi:[1,0,0]
	v_pk_fma_f32 v[102:103], v[76:77], v[6:7], v[102:103] op_sel_hi:[1,0,1] neg_lo:[1,0,0] neg_hi:[1,0,0]
	v_pk_fma_f32 v[102:103], v[78:79], v[6:7], v[102:103] op_sel:[0,1,0] op_sel_hi:[1,1,1] neg_lo:[1,0,0] neg_hi:[1,0,0]
	s_waitcnt lgkmcnt(14)
	ds_read_b128 v[56:59], v228 offset:5440
	v_pk_fma_f32 v[102:103], v[80:81], v[8:9], v[102:103] op_sel_hi:[1,0,1] neg_lo:[1,0,0] neg_hi:[1,0,0]
	v_pk_fma_f32 v[102:103], v[82:83], v[8:9], v[102:103] op_sel:[0,1,0] op_sel_hi:[1,1,1] neg_lo:[1,0,0] neg_hi:[1,0,0]
	v_pk_fma_f32 v[102:103], v[84:85], v[10:11], v[102:103] op_sel_hi:[1,0,1] neg_lo:[1,0,0] neg_hi:[1,0,0]
	v_pk_fma_f32 v[102:103], v[86:87], v[10:11], v[102:103] op_sel:[0,1,0] op_sel_hi:[1,1,1] neg_lo:[1,0,0] neg_hi:[1,0,0]
	s_waitcnt lgkmcnt(14)
	ds_read_b128 v[60:63], v228 offset:5456
	v_pk_fma_f32 v[102:103], v[88:89], v[12:13], v[102:103] op_sel_hi:[1,0,1] neg_lo:[1,0,0] neg_hi:[1,0,0]
	v_pk_fma_f32 v[102:103], v[90:91], v[12:13], v[102:103] op_sel:[0,1,0] op_sel_hi:[1,1,1] neg_lo:[1,0,0] neg_hi:[1,0,0]
	v_pk_fma_f32 v[102:103], v[92:93], v[14:15], v[102:103] op_sel_hi:[1,0,1] neg_lo:[1,0,0] neg_hi:[1,0,0]
	v_pk_fma_f32 v[102:103], v[94:95], v[14:15], v[102:103] op_sel:[0,1,0] op_sel_hi:[1,1,1] neg_lo:[1,0,0] neg_hi:[1,0,0]
	s_waitcnt lgkmcnt(14)
	ds_read_b128 v[244:247], v228 offset:5632
	v_pk_fma_f32 v[102:103], v[96:97], v[16:17], v[102:103] op_sel_hi:[1,0,1] neg_lo:[1,0,0] neg_hi:[1,0,0]
	v_pk_fma_f32 v[102:103], v[98:99], v[16:17], v[102:103] op_sel:[0,1,0] op_sel_hi:[1,1,1] neg_lo:[1,0,0] neg_hi:[1,0,0]
	v_fma_mixlo_f16 v3, -v100, v18, v102
	v_fma_mixlo_f16 v238, -v101, v18, v103
	v_pk_fma_f32 v[102:103], v[100:101], v[18:19], v[102:103] op_sel_hi:[1,0,1] neg_lo:[1,0,0] neg_hi:[1,0,0]
	s_waitcnt lgkmcnt(14)
	ds_write_b16 v253, v3 offset:21552
	s_waitcnt lgkmcnt(14)
	ds_write_b16 v253, v238 offset:21680
	s_waitcnt lgkmcnt(14)
	ds_read_b128 v[248:251], v228 offset:5648
	v_pk_fma_f32 v[104:105], v[64:65], v[20:21], v[104:105] op_sel_hi:[1,0,1] neg_lo:[1,0,0] neg_hi:[1,0,0]
	v_pk_fma_f32 v[104:105], v[66:67], v[20:21], v[104:105] op_sel:[0,1,0] op_sel_hi:[1,1,1] neg_lo:[1,0,0] neg_hi:[1,0,0]
	v_pk_fma_f32 v[104:105], v[68:69], v[22:23], v[104:105] op_sel_hi:[1,0,1] neg_lo:[1,0,0] neg_hi:[1,0,0]
	v_pk_fma_f32 v[104:105], v[70:71], v[22:23], v[104:105] op_sel:[0,1,0] op_sel_hi:[1,1,1] neg_lo:[1,0,0] neg_hi:[1,0,0]
	s_waitcnt lgkmcnt(14)
	ds_read_b128 v[4:7], v228 offset:5664
	v_pk_fma_f32 v[104:105], v[72:73], v[24:25], v[104:105] op_sel_hi:[1,0,1] neg_lo:[1,0,0] neg_hi:[1,0,0]
	v_pk_fma_f32 v[104:105], v[74:75], v[24:25], v[104:105] op_sel:[0,1,0] op_sel_hi:[1,1,1] neg_lo:[1,0,0] neg_hi:[1,0,0]
	v_pk_fma_f32 v[104:105], v[76:77], v[26:27], v[104:105] op_sel_hi:[1,0,1] neg_lo:[1,0,0] neg_hi:[1,0,0]
	v_pk_fma_f32 v[104:105], v[78:79], v[26:27], v[104:105] op_sel:[0,1,0] op_sel_hi:[1,1,1] neg_lo:[1,0,0] neg_hi:[1,0,0]
	s_waitcnt lgkmcnt(14)
	ds_read_b128 v[8:11], v228 offset:5680
	v_pk_fma_f32 v[104:105], v[80:81], v[28:29], v[104:105] op_sel_hi:[1,0,1] neg_lo:[1,0,0] neg_hi:[1,0,0]
	v_pk_fma_f32 v[104:105], v[82:83], v[28:29], v[104:105] op_sel:[0,1,0] op_sel_hi:[1,1,1] neg_lo:[1,0,0] neg_hi:[1,0,0]
	v_pk_fma_f32 v[104:105], v[84:85], v[30:31], v[104:105] op_sel_hi:[1,0,1] neg_lo:[1,0,0] neg_hi:[1,0,0]
	v_pk_fma_f32 v[104:105], v[86:87], v[30:31], v[104:105] op_sel:[0,1,0] op_sel_hi:[1,1,1] neg_lo:[1,0,0] neg_hi:[1,0,0]
	s_waitcnt lgkmcnt(14)
	ds_read_b128 v[12:15], v228 offset:5696
	v_pk_fma_f32 v[104:105], v[88:89], v[32:33], v[104:105] op_sel_hi:[1,0,1] neg_lo:[1,0,0] neg_hi:[1,0,0]
	v_pk_fma_f32 v[104:105], v[90:91], v[32:33], v[104:105] op_sel:[0,1,0] op_sel_hi:[1,1,1] neg_lo:[1,0,0] neg_hi:[1,0,0]
	v_pk_fma_f32 v[104:105], v[92:93], v[34:35], v[104:105] op_sel_hi:[1,0,1] neg_lo:[1,0,0] neg_hi:[1,0,0]
	v_pk_fma_f32 v[104:105], v[94:95], v[34:35], v[104:105] op_sel:[0,1,0] op_sel_hi:[1,1,1] neg_lo:[1,0,0] neg_hi:[1,0,0]
	s_waitcnt lgkmcnt(14)
; #define LAS __attribute__((address_space(3)))
; __device__ __forceinline__ void phase_gdb(const int wvs, const Params& p, LAS unsigned char* lds, int nwg) {
;     ...
;       for (int i = 1; i < 64; ++i) {
; #pragma unroll
;         for (int j4 = 0; j4 < (i + 3) / 4; ++j4) { const f32x4 m4 = *(const LAS f32x4*)(M + i * 64 + j4 * 4);
; #pragma unroll
;           for (int jj = 0; jj < 4; ++jj) if (j4 * 4 + jj < i) x[i] -= m4[jj] * x[j4 * 4 + jj]; }
;         __builtin_amdgcn_sched_barrier(0); }
; #pragma unroll
;       for (int i = 0; i < 64; ++i) R[i * RP + t] = (hf)x[i]; }
	ds_read_b128 v[16:19], v228 offset:5712
	v_pk_fma_f32 v[104:105], v[96:97], v[36:37], v[104:105] op_sel_hi:[1,0,1] neg_lo:[1,0,0] neg_hi:[1,0,0]
	v_pk_fma_f32 v[104:105], v[98:99], v[36:37], v[104:105] op_sel:[0,1,0] op_sel_hi:[1,1,1] neg_lo:[1,0,0] neg_hi:[1,0,0]
	v_pk_fma_f32 v[104:105], v[100:101], v[38:39], v[104:105] op_sel_hi:[1,0,1] neg_lo:[1,0,0] neg_hi:[1,0,0]
	v_fma_mixlo_f16 v239, -v102, v39, v104
	v_fma_mixlo_f16 v240, -v103, v39, v105
	v_pk_fma_f32 v[104:105], v[102:103], v[38:39], v[104:105] op_sel:[0,1,0] op_sel_hi:[1,1,1] neg_lo:[1,0,0] neg_hi:[1,0,0]
	s_waitcnt lgkmcnt(14)
	ds_write_b16 v253, v239 offset:21824
	s_waitcnt lgkmcnt(14)
	ds_write_b16 v253, v240 offset:21952
	s_waitcnt lgkmcnt(14)
	ds_read_b128 v[20:23], v228 offset:5888
	v_pk_fma_f32 v[106:107], v[64:65], v[40:41], v[106:107] op_sel_hi:[1,0,1] neg_lo:[1,0,0] neg_hi:[1,0,0]
	v_pk_fma_f32 v[106:107], v[66:67], v[40:41], v[106:107] op_sel:[0,1,0] op_sel_hi:[1,1,1] neg_lo:[1,0,0] neg_hi:[1,0,0]
	v_pk_fma_f32 v[106:107], v[68:69], v[42:43], v[106:107] op_sel_hi:[1,0,1] neg_lo:[1,0,0] neg_hi:[1,0,0]
	v_pk_fma_f32 v[106:107], v[70:71], v[42:43], v[106:107] op_sel:[0,1,0] op_sel_hi:[1,1,1] neg_lo:[1,0,0] neg_hi:[1,0,0]
	s_waitcnt lgkmcnt(14)
	ds_read_b128 v[24:27], v228 offset:5904
	v_pk_fma_f32 v[106:107], v[72:73], v[44:45], v[106:107] op_sel_hi:[1,0,1] neg_lo:[1,0,0] neg_hi:[1,0,0]
	v_pk_fma_f32 v[106:107], v[74:75], v[44:45], v[106:107] op_sel:[0,1,0] op_sel_hi:[1,1,1] neg_lo:[1,0,0] neg_hi:[1,0,0]
	v_pk_fma_f32 v[106:107], v[76:77], v[46:47], v[106:107] op_sel_hi:[1,0,1] neg_lo:[1,0,0] neg_hi:[1,0,0]
	v_pk_fma_f32 v[106:107], v[78:79], v[46:47], v[106:107] op_sel:[0,1,0] op_sel_hi:[1,1,1] neg_lo:[1,0,0] neg_hi:[1,0,0]
	s_waitcnt lgkmcnt(14)
	ds_read_b128 v[28:31], v228 offset:5920
	v_pk_fma_f32 v[106:107], v[80:81], v[48:49], v[106:107] op_sel_hi:[1,0,1] neg_lo:[1,0,0] neg_hi:[1,0,0]
	v_pk_fma_f32 v[106:107], v[82:83], v[48:49], v[106:107] op_sel:[0,1,0] op_sel_hi:[1,1,1] neg_lo:[1,0,0] neg_hi:[1,0,0]
	v_pk_fma_f32 v[106:107], v[84:85], v[50:51], v[106:107] op_sel_hi:[1,0,1] neg_lo:[1,0,0] neg_hi:[1,0,0]
	v_pk_fma_f32 v[106:107], v[86:87], v[50:51], v[106:107] op_sel:[0,1,0] op_sel_hi:[1,1,1] neg_lo:[1,0,0] neg_hi:[1,0,0]
	s_waitcnt lgkmcnt(14)
	ds_read_b128 v[32:35], v228 offset:5936
	v_pk_fma_f32 v[106:107], v[88:89], v[52:53], v[106:107] op_sel_hi:[1,0,1] neg_lo:[1,0,0] neg_hi:[1,0,0]
	v_pk_fma_f32 v[106:107], v[90:91], v[52:53], v[106:107] op_sel:[0,1,0] op_sel_hi:[1,1,1] neg_lo:[1,0,0] neg_hi:[1,0,0]
	v_pk_fma_f32 v[106:107], v[92:93], v[54:55], v[106:107] op_sel_hi:[1,0,1] neg_lo:[1,0,0] neg_hi:[1,0,0]
	v_pk_fma_f32 v[106:107], v[94:95], v[54:55], v[106:107] op_sel:[0,1,0] op_sel_hi:[1,1,1] neg_lo:[1,0,0] neg_hi:[1,0,0]
	s_waitcnt lgkmcnt(14)
	ds_read_b128 v[36:39], v228 offset:5952
	v_pk_fma_f32 v[106:107], v[96:97], v[56:57], v[106:107] op_sel_hi:[1,0,1] neg_lo:[1,0,0] neg_hi:[1,0,0]
	v_pk_fma_f32 v[106:107], v[98:99], v[56:57], v[106:107] op_sel:[0,1,0] op_sel_hi:[1,1,1] neg_lo:[1,0,0] neg_hi:[1,0,0]
	v_pk_fma_f32 v[106:107], v[100:101], v[58:59], v[106:107] op_sel_hi:[1,0,1] neg_lo:[1,0,0] neg_hi:[1,0,0]
	v_pk_fma_f32 v[106:107], v[102:103], v[58:59], v[106:107] op_sel:[0,1,0] op_sel_hi:[1,1,1] neg_lo:[1,0,0] neg_hi:[1,0,0]
	s_waitcnt lgkmcnt(14)
	ds_read_b128 v[40:43], v228 offset:5968
	v_fma_mixlo_f16 v0, -v104, v60, v106
	v_fma_mixlo_f16 v2, -v105, v60, v107
	v_pk_fma_f32 v[106:107], v[104:105], v[60:61], v[106:107] op_sel_hi:[1,0,1] neg_lo:[1,0,0] neg_hi:[1,0,0]
	s_waitcnt lgkmcnt(14)
	ds_write_b16 v253, v0 offset:22096
	s_waitcnt lgkmcnt(14)
	ds_write_b16 v253, v2 offset:22224
	s_waitcnt lgkmcnt(14)
	ds_read_b128 v[44:47], v228 offset:6144
	v_pk_fma_f32 v[108:109], v[64:65], v[244:245], v[108:109] op_sel_hi:[1,0,1] neg_lo:[1,0,0] neg_hi:[1,0,0]
	v_pk_fma_f32 v[108:109], v[66:67], v[244:245], v[108:109] op_sel:[0,1,0] op_sel_hi:[1,1,1] neg_lo:[1,0,0] neg_hi:[1,0,0]
	v_pk_fma_f32 v[108:109], v[68:69], v[246:247], v[108:109] op_sel_hi:[1,0,1] neg_lo:[1,0,0] neg_hi:[1,0,0]
	v_pk_fma_f32 v[108:109], v[70:71], v[246:247], v[108:109] op_sel:[0,1,0] op_sel_hi:[1,1,1] neg_lo:[1,0,0] neg_hi:[1,0,0]
	s_waitcnt lgkmcnt(14)
	ds_read_b128 v[48:51], v228 offset:6160
	v_pk_fma_f32 v[108:109], v[72:73], v[248:249], v[108:109] op_sel_hi:[1,0,1] neg_lo:[1,0,0] neg_hi:[1,0,0]
	v_pk_fma_f32 v[108:109], v[74:75], v[248:249], v[108:109] op_sel:[0,1,0] op_sel_hi:[1,1,1] neg_lo:[1,0,0] neg_hi:[1,0,0]
	v_pk_fma_f32 v[108:109], v[76:77], v[250:251], v[108:109] op_sel_hi:[1,0,1] neg_lo:[1,0,0] neg_hi:[1,0,0]
	v_pk_fma_f32 v[108:109], v[78:79], v[250:251], v[108:109] op_sel:[0,1,0] op_sel_hi:[1,1,1] neg_lo:[1,0,0] neg_hi:[1,0,0]
	s_waitcnt lgkmcnt(14)
	ds_read_b128 v[52:55], v228 offset:6176
	v_pk_fma_f32 v[108:109], v[80:81], v[4:5], v[108:109] op_sel_hi:[1,0,1] neg_lo:[1,0,0] neg_hi:[1,0,0]
	v_pk_fma_f32 v[108:109], v[82:83], v[4:5], v[108:109] op_sel:[0,1,0] op_sel_hi:[1,1,1] neg_lo:[1,0,0] neg_hi:[1,0,0]
	v_pk_fma_f32 v[108:109], v[84:85], v[6:7], v[108:109] op_sel_hi:[1,0,1] neg_lo:[1,0,0] neg_hi:[1,0,0]
	v_pk_fma_f32 v[108:109], v[86:87], v[6:7], v[108:109] op_sel:[0,1,0] op_sel_hi:[1,1,1] neg_lo:[1,0,0] neg_hi:[1,0,0]
	s_waitcnt lgkmcnt(14)
	ds_read_b128 v[56:59], v228 offset:6192
	v_pk_fma_f32 v[108:109], v[88:89], v[8:9], v[108:109] op_sel_hi:[1,0,1] neg_lo:[1,0,0] neg_hi:[1,0,0]
	v_pk_fma_f32 v[108:109], v[90:91], v[8:9], v[108:109] op_sel:[0,1,0] op_sel_hi:[1,1,1] neg_lo:[1,0,0] neg_hi:[1,0,0]
	v_pk_fma_f32 v[108:109], v[92:93], v[10:11], v[108:109] op_sel_hi:[1,0,1] neg_lo:[1,0,0] neg_hi:[1,0,0]
	v_pk_fma_f32 v[108:109], v[94:95], v[10:11], v[108:109] op_sel:[0,1,0] op_sel_hi:[1,1,1] neg_lo:[1,0,0] neg_hi:[1,0,0]
	s_waitcnt lgkmcnt(14)
; #define LAS __attribute__((address_space(3)))
; __device__ __forceinline__ void phase_gdb(const int wvs, const Params& p, LAS unsigned char* lds, int nwg) {
;     ...
;       for (int i = 1; i < 64; ++i) {
; #pragma unroll
;         for (int j4 = 0; j4 < (i + 3) / 4; ++j4) { const f32x4 m4 = *(const LAS f32x4*)(M + i * 64 + j4 * 4);
; #pragma unroll
;           for (int jj = 0; jj < 4; ++jj) if (j4 * 4 + jj < i) x[i] -= m4[jj] * x[j4 * 4 + jj]; }
;         __builtin_amdgcn_sched_barrier(0); }
; #pragma unroll
;       for (int i = 0; i < 64; ++i) R[i * RP + t] = (hf)x[i]; }
	ds_read_b128 v[60:63], v228 offset:6208
	v_pk_fma_f32 v[108:109], v[96:97], v[12:13], v[108:109] op_sel_hi:[1,0,1] neg_lo:[1,0,0] neg_hi:[1,0,0]
	v_pk_fma_f32 v[108:109], v[98:99], v[12:13], v[108:109] op_sel:[0,1,0] op_sel_hi:[1,1,1] neg_lo:[1,0,0] neg_hi:[1,0,0]
	v_pk_fma_f32 v[108:109], v[100:101], v[14:15], v[108:109] op_sel_hi:[1,0,1] neg_lo:[1,0,0] neg_hi:[1,0,0]
	v_pk_fma_f32 v[108:109], v[102:103], v[14:15], v[108:109] op_sel:[0,1,0] op_sel_hi:[1,1,1] neg_lo:[1,0,0] neg_hi:[1,0,0]
	s_waitcnt lgkmcnt(14)
	ds_read_b128 v[244:247], v228 offset:6224
	v_pk_fma_f32 v[108:109], v[104:105], v[16:17], v[108:109] op_sel_hi:[1,0,1] neg_lo:[1,0,0] neg_hi:[1,0,0]
	v_fma_mixlo_f16 v3, -v106, v17, v108
	v_fma_mixlo_f16 v238, -v107, v17, v109
	v_pk_fma_f32 v[108:109], v[106:107], v[16:17], v[108:109] op_sel:[0,1,0] op_sel_hi:[1,1,1] neg_lo:[1,0,0] neg_hi:[1,0,0]
	s_waitcnt lgkmcnt(14)
	ds_write_b16 v253, v3 offset:22368
	s_waitcnt lgkmcnt(14)
	ds_write_b16 v253, v238 offset:22496
	s_waitcnt lgkmcnt(14)
	ds_read_b128 v[248:251], v228 offset:6400
	v_pk_fma_f32 v[110:111], v[64:65], v[20:21], v[110:111] op_sel_hi:[1,0,1] neg_lo:[1,0,0] neg_hi:[1,0,0]
	v_pk_fma_f32 v[110:111], v[66:67], v[20:21], v[110:111] op_sel:[0,1,0] op_sel_hi:[1,1,1] neg_lo:[1,0,0] neg_hi:[1,0,0]
	v_pk_fma_f32 v[110:111], v[68:69], v[22:23], v[110:111] op_sel_hi:[1,0,1] neg_lo:[1,0,0] neg_hi:[1,0,0]
	v_pk_fma_f32 v[110:111], v[70:71], v[22:23], v[110:111] op_sel:[0,1,0] op_sel_hi:[1,1,1] neg_lo:[1,0,0] neg_hi:[1,0,0]
	s_waitcnt lgkmcnt(14)
	ds_read_b128 v[4:7], v228 offset:6416
	v_pk_fma_f32 v[110:111], v[72:73], v[24:25], v[110:111] op_sel_hi:[1,0,1] neg_lo:[1,0,0] neg_hi:[1,0,0]
	v_pk_fma_f32 v[110:111], v[74:75], v[24:25], v[110:111] op_sel:[0,1,0] op_sel_hi:[1,1,1] neg_lo:[1,0,0] neg_hi:[1,0,0]
	v_pk_fma_f32 v[110:111], v[76:77], v[26:27], v[110:111] op_sel_hi:[1,0,1] neg_lo:[1,0,0] neg_hi:[1,0,0]
	v_pk_fma_f32 v[110:111], v[78:79], v[26:27], v[110:111] op_sel:[0,1,0] op_sel_hi:[1,1,1] neg_lo:[1,0,0] neg_hi:[1,0,0]
	s_waitcnt lgkmcnt(14)
	ds_read_b128 v[8:11], v228 offset:6432
	v_pk_fma_f32 v[110:111], v[80:81], v[28:29], v[110:111] op_sel_hi:[1,0,1] neg_lo:[1,0,0] neg_hi:[1,0,0]
	v_pk_fma_f32 v[110:111], v[82:83], v[28:29], v[110:111] op_sel:[0,1,0] op_sel_hi:[1,1,1] neg_lo:[1,0,0] neg_hi:[1,0,0]
	v_pk_fma_f32 v[110:111], v[84:85], v[30:31], v[110:111] op_sel_hi:[1,0,1] neg_lo:[1,0,0] neg_hi:[1,0,0]
	v_pk_fma_f32 v[110:111], v[86:87], v[30:31], v[110:111] op_sel:[0,1,0] op_sel_hi:[1,1,1] neg_lo:[1,0,0] neg_hi:[1,0,0]
	s_waitcnt lgkmcnt(14)
	ds_read_b128 v[12:15], v228 offset:6448
	v_pk_fma_f32 v[110:111], v[88:89], v[32:33], v[110:111] op_sel_hi:[1,0,1] neg_lo:[1,0,0] neg_hi:[1,0,0]
	v_pk_fma_f32 v[110:111], v[90:91], v[32:33], v[110:111] op_sel:[0,1,0] op_sel_hi:[1,1,1] neg_lo:[1,0,0] neg_hi:[1,0,0]
	v_pk_fma_f32 v[110:111], v[92:93], v[34:35], v[110:111] op_sel_hi:[1,0,1] neg_lo:[1,0,0] neg_hi:[1,0,0]
	v_pk_fma_f32 v[110:111], v[94:95], v[34:35], v[110:111] op_sel:[0,1,0] op_sel_hi:[1,1,1] neg_lo:[1,0,0] neg_hi:[1,0,0]
	s_waitcnt lgkmcnt(14)
	ds_read_b128 v[16:19], v228 offset:6464
	v_pk_fma_f32 v[110:111], v[96:97], v[36:37], v[110:111] op_sel_hi:[1,0,1] neg_lo:[1,0,0] neg_hi:[1,0,0]
	v_pk_fma_f32 v[110:111], v[98:99], v[36:37], v[110:111] op_sel:[0,1,0] op_sel_hi:[1,1,1] neg_lo:[1,0,0] neg_hi:[1,0,0]
	v_pk_fma_f32 v[110:111], v[100:101], v[38:39], v[110:111] op_sel_hi:[1,0,1] neg_lo:[1,0,0] neg_hi:[1,0,0]
	v_pk_fma_f32 v[110:111], v[102:103], v[38:39], v[110:111] op_sel:[0,1,0] op_sel_hi:[1,1,1] neg_lo:[1,0,0] neg_hi:[1,0,0]
	s_waitcnt lgkmcnt(14)
	ds_read_b128 v[20:23], v228 offset:6480
	v_pk_fma_f32 v[110:111], v[104:105], v[40:41], v[110:111] op_sel_hi:[1,0,1] neg_lo:[1,0,0] neg_hi:[1,0,0]
	v_pk_fma_f32 v[110:111], v[106:107], v[40:41], v[110:111] op_sel:[0,1,0] op_sel_hi:[1,1,1] neg_lo:[1,0,0] neg_hi:[1,0,0]
	v_fma_mixlo_f16 v239, -v108, v42, v110
	v_fma_mixlo_f16 v240, -v109, v42, v111
	v_pk_fma_f32 v[110:111], v[108:109], v[42:43], v[110:111] op_sel_hi:[1,0,1] neg_lo:[1,0,0] neg_hi:[1,0,0]
	s_waitcnt lgkmcnt(14)
	ds_write_b16 v253, v239 offset:22640
	s_waitcnt lgkmcnt(14)
	ds_write_b16 v253, v240 offset:22768
	s_waitcnt lgkmcnt(14)
	ds_read_b128 v[24:27], v228 offset:6496
	v_pk_fma_f32 v[112:113], v[64:65], v[44:45], v[112:113] op_sel_hi:[1,0,1] neg_lo:[1,0,0] neg_hi:[1,0,0]
	v_pk_fma_f32 v[112:113], v[66:67], v[44:45], v[112:113] op_sel:[0,1,0] op_sel_hi:[1,1,1] neg_lo:[1,0,0] neg_hi:[1,0,0]
	v_pk_fma_f32 v[112:113], v[68:69], v[46:47], v[112:113] op_sel_hi:[1,0,1] neg_lo:[1,0,0] neg_hi:[1,0,0]
	v_pk_fma_f32 v[112:113], v[70:71], v[46:47], v[112:113] op_sel:[0,1,0] op_sel_hi:[1,1,1] neg_lo:[1,0,0] neg_hi:[1,0,0]
	s_waitcnt lgkmcnt(14)
	ds_read_b128 v[28:31], v228 offset:6656
	v_pk_fma_f32 v[112:113], v[72:73], v[48:49], v[112:113] op_sel_hi:[1,0,1] neg_lo:[1,0,0] neg_hi:[1,0,0]
	v_pk_fma_f32 v[112:113], v[74:75], v[48:49], v[112:113] op_sel:[0,1,0] op_sel_hi:[1,1,1] neg_lo:[1,0,0] neg_hi:[1,0,0]
	v_pk_fma_f32 v[112:113], v[76:77], v[50:51], v[112:113] op_sel_hi:[1,0,1] neg_lo:[1,0,0] neg_hi:[1,0,0]
	v_pk_fma_f32 v[112:113], v[78:79], v[50:51], v[112:113] op_sel:[0,1,0] op_sel_hi:[1,1,1] neg_lo:[1,0,0] neg_hi:[1,0,0]
	s_waitcnt lgkmcnt(14)
	ds_read_b128 v[32:35], v228 offset:6672
	v_pk_fma_f32 v[112:113], v[80:81], v[52:53], v[112:113] op_sel_hi:[1,0,1] neg_lo:[1,0,0] neg_hi:[1,0,0]
	v_pk_fma_f32 v[112:113], v[82:83], v[52:53], v[112:113] op_sel:[0,1,0] op_sel_hi:[1,1,1] neg_lo:[1,0,0] neg_hi:[1,0,0]
	v_pk_fma_f32 v[112:113], v[84:85], v[54:55], v[112:113] op_sel_hi:[1,0,1] neg_lo:[1,0,0] neg_hi:[1,0,0]
	v_pk_fma_f32 v[112:113], v[86:87], v[54:55], v[112:113] op_sel:[0,1,0] op_sel_hi:[1,1,1] neg_lo:[1,0,0] neg_hi:[1,0,0]
	s_waitcnt lgkmcnt(14)
; #define LAS __attribute__((address_space(3)))
; __device__ __forceinline__ void phase_gdb(const int wvs, const Params& p, LAS unsigned char* lds, int nwg) {
;     ...
;       for (int i = 1; i < 64; ++i) {
; #pragma unroll
;         for (int j4 = 0; j4 < (i + 3) / 4; ++j4) { const f32x4 m4 = *(const LAS f32x4*)(M + i * 64 + j4 * 4);
; #pragma unroll
;           for (int jj = 0; jj < 4; ++jj) if (j4 * 4 + jj < i) x[i] -= m4[jj] * x[j4 * 4 + jj]; }
;         __builtin_amdgcn_sched_barrier(0); }
; #pragma unroll
;       for (int i = 0; i < 64; ++i) R[i * RP + t] = (hf)x[i]; }
	ds_read_b128 v[36:39], v228 offset:6688
	v_pk_fma_f32 v[112:113], v[88:89], v[56:57], v[112:113] op_sel_hi:[1,0,1] neg_lo:[1,0,0] neg_hi:[1,0,0]
	v_pk_fma_f32 v[112:113], v[90:91], v[56:57], v[112:113] op_sel:[0,1,0] op_sel_hi:[1,1,1] neg_lo:[1,0,0] neg_hi:[1,0,0]
	v_pk_fma_f32 v[112:113], v[92:93], v[58:59], v[112:113] op_sel_hi:[1,0,1] neg_lo:[1,0,0] neg_hi:[1,0,0]
	v_pk_fma_f32 v[112:113], v[94:95], v[58:59], v[112:113] op_sel:[0,1,0] op_sel_hi:[1,1,1] neg_lo:[1,0,0] neg_hi:[1,0,0]
	s_waitcnt lgkmcnt(14)
	ds_read_b128 v[40:43], v228 offset:6704
	v_pk_fma_f32 v[112:113], v[96:97], v[60:61], v[112:113] op_sel_hi:[1,0,1] neg_lo:[1,0,0] neg_hi:[1,0,0]
	v_pk_fma_f32 v[112:113], v[98:99], v[60:61], v[112:113] op_sel:[0,1,0] op_sel_hi:[1,1,1] neg_lo:[1,0,0] neg_hi:[1,0,0]
	v_pk_fma_f32 v[112:113], v[100:101], v[62:63], v[112:113] op_sel_hi:[1,0,1] neg_lo:[1,0,0] neg_hi:[1,0,0]
	v_pk_fma_f32 v[112:113], v[102:103], v[62:63], v[112:113] op_sel:[0,1,0] op_sel_hi:[1,1,1] neg_lo:[1,0,0] neg_hi:[1,0,0]
	s_waitcnt lgkmcnt(14)
	ds_read_b128 v[44:47], v228 offset:6720
	v_pk_fma_f32 v[112:113], v[104:105], v[244:245], v[112:113] op_sel_hi:[1,0,1] neg_lo:[1,0,0] neg_hi:[1,0,0]
	v_pk_fma_f32 v[112:113], v[106:107], v[244:245], v[112:113] op_sel:[0,1,0] op_sel_hi:[1,1,1] neg_lo:[1,0,0] neg_hi:[1,0,0]
	v_pk_fma_f32 v[112:113], v[108:109], v[246:247], v[112:113] op_sel_hi:[1,0,1] neg_lo:[1,0,0] neg_hi:[1,0,0]
	v_fma_mixlo_f16 v0, -v110, v247, v112
	v_fma_mixlo_f16 v2, -v111, v247, v113
	v_pk_fma_f32 v[112:113], v[110:111], v[246:247], v[112:113] op_sel:[0,1,0] op_sel_hi:[1,1,1] neg_lo:[1,0,0] neg_hi:[1,0,0]
	s_waitcnt lgkmcnt(14)
	ds_write_b16 v253, v0 offset:22912
	s_waitcnt lgkmcnt(14)
	ds_write_b16 v253, v2 offset:23040
	s_waitcnt lgkmcnt(14)
	ds_read_b128 v[48:51], v228 offset:6736
	v_pk_fma_f32 v[114:115], v[64:65], v[248:249], v[114:115] op_sel_hi:[1,0,1] neg_lo:[1,0,0] neg_hi:[1,0,0]
	v_pk_fma_f32 v[114:115], v[66:67], v[248:249], v[114:115] op_sel:[0,1,0] op_sel_hi:[1,1,1] neg_lo:[1,0,0] neg_hi:[1,0,0]
	v_pk_fma_f32 v[114:115], v[68:69], v[250:251], v[114:115] op_sel_hi:[1,0,1] neg_lo:[1,0,0] neg_hi:[1,0,0]
	v_pk_fma_f32 v[114:115], v[70:71], v[250:251], v[114:115] op_sel:[0,1,0] op_sel_hi:[1,1,1] neg_lo:[1,0,0] neg_hi:[1,0,0]
	s_waitcnt lgkmcnt(14)
	ds_read_b128 v[52:55], v228 offset:6752
	v_pk_fma_f32 v[114:115], v[72:73], v[4:5], v[114:115] op_sel_hi:[1,0,1] neg_lo:[1,0,0] neg_hi:[1,0,0]
	v_pk_fma_f32 v[114:115], v[74:75], v[4:5], v[114:115] op_sel:[0,1,0] op_sel_hi:[1,1,1] neg_lo:[1,0,0] neg_hi:[1,0,0]
	v_pk_fma_f32 v[114:115], v[76:77], v[6:7], v[114:115] op_sel_hi:[1,0,1] neg_lo:[1,0,0] neg_hi:[1,0,0]
	v_pk_fma_f32 v[114:115], v[78:79], v[6:7], v[114:115] op_sel:[0,1,0] op_sel_hi:[1,1,1] neg_lo:[1,0,0] neg_hi:[1,0,0]
	s_waitcnt lgkmcnt(14)
	ds_read_b128 v[56:59], v228 offset:6912
	v_pk_fma_f32 v[114:115], v[80:81], v[8:9], v[114:115] op_sel_hi:[1,0,1] neg_lo:[1,0,0] neg_hi:[1,0,0]
	v_pk_fma_f32 v[114:115], v[82:83], v[8:9], v[114:115] op_sel:[0,1,0] op_sel_hi:[1,1,1] neg_lo:[1,0,0] neg_hi:[1,0,0]
	v_pk_fma_f32 v[114:115], v[84:85], v[10:11], v[114:115] op_sel_hi:[1,0,1] neg_lo:[1,0,0] neg_hi:[1,0,0]
	v_pk_fma_f32 v[114:115], v[86:87], v[10:11], v[114:115] op_sel:[0,1,0] op_sel_hi:[1,1,1] neg_lo:[1,0,0] neg_hi:[1,0,0]
	s_waitcnt lgkmcnt(14)
	ds_read_b128 v[60:63], v228 offset:6928
	v_pk_fma_f32 v[114:115], v[88:89], v[12:13], v[114:115] op_sel_hi:[1,0,1] neg_lo:[1,0,0] neg_hi:[1,0,0]
	v_pk_fma_f32 v[114:115], v[90:91], v[12:13], v[114:115] op_sel:[0,1,0] op_sel_hi:[1,1,1] neg_lo:[1,0,0] neg_hi:[1,0,0]
	v_pk_fma_f32 v[114:115], v[92:93], v[14:15], v[114:115] op_sel_hi:[1,0,1] neg_lo:[1,0,0] neg_hi:[1,0,0]
	v_pk_fma_f32 v[114:115], v[94:95], v[14:15], v[114:115] op_sel:[0,1,0] op_sel_hi:[1,1,1] neg_lo:[1,0,0] neg_hi:[1,0,0]
	s_waitcnt lgkmcnt(14)
	ds_read_b128 v[244:247], v228 offset:6944
	v_pk_fma_f32 v[114:115], v[96:97], v[16:17], v[114:115] op_sel_hi:[1,0,1] neg_lo:[1,0,0] neg_hi:[1,0,0]
	v_pk_fma_f32 v[114:115], v[98:99], v[16:17], v[114:115] op_sel:[0,1,0] op_sel_hi:[1,1,1] neg_lo:[1,0,0] neg_hi:[1,0,0]
	v_pk_fma_f32 v[114:115], v[100:101], v[18:19], v[114:115] op_sel_hi:[1,0,1] neg_lo:[1,0,0] neg_hi:[1,0,0]
	v_pk_fma_f32 v[114:115], v[102:103], v[18:19], v[114:115] op_sel:[0,1,0] op_sel_hi:[1,1,1] neg_lo:[1,0,0] neg_hi:[1,0,0]
	s_waitcnt lgkmcnt(14)
	ds_read_b128 v[248:251], v228 offset:6960
	v_pk_fma_f32 v[114:115], v[104:105], v[20:21], v[114:115] op_sel_hi:[1,0,1] neg_lo:[1,0,0] neg_hi:[1,0,0]
	v_pk_fma_f32 v[114:115], v[106:107], v[20:21], v[114:115] op_sel:[0,1,0] op_sel_hi:[1,1,1] neg_lo:[1,0,0] neg_hi:[1,0,0]
	v_pk_fma_f32 v[114:115], v[108:109], v[22:23], v[114:115] op_sel_hi:[1,0,1] neg_lo:[1,0,0] neg_hi:[1,0,0]
	v_pk_fma_f32 v[114:115], v[110:111], v[22:23], v[114:115] op_sel:[0,1,0] op_sel_hi:[1,1,1] neg_lo:[1,0,0] neg_hi:[1,0,0]
	s_waitcnt lgkmcnt(14)
	ds_read_b128 v[4:7], v228 offset:6976
	s_waitcnt lgkmcnt(11)
	v_fma_mixlo_f16 v3, -v112, v24, v114
	v_fma_mixlo_f16 v238, -v113, v24, v115
	v_pk_fma_f32 v[114:115], v[112:113], v[24:25], v[114:115] op_sel_hi:[1,0,1] neg_lo:[1,0,0] neg_hi:[1,0,0]
	ds_write_b16 v253, v3 offset:23184
	ds_write_b16 v253, v238 offset:23312
	ds_read_b128 v[8:11], v228 offset:6992
	v_pk_fma_f32 v[116:117], v[64:65], v[28:29], v[116:117] op_sel_hi:[1,0,1] neg_lo:[1,0,0] neg_hi:[1,0,0]
	v_pk_fma_f32 v[116:117], v[66:67], v[28:29], v[116:117] op_sel:[0,1,0] op_sel_hi:[1,1,1] neg_lo:[1,0,0] neg_hi:[1,0,0]
	v_pk_fma_f32 v[116:117], v[68:69], v[30:31], v[116:117] op_sel_hi:[1,0,1] neg_lo:[1,0,0] neg_hi:[1,0,0]
	v_pk_fma_f32 v[116:117], v[70:71], v[30:31], v[116:117] op_sel:[0,1,0] op_sel_hi:[1,1,1] neg_lo:[1,0,0] neg_hi:[1,0,0]
	ds_read_b128 v[12:15], v228 offset:7008
	v_pk_fma_f32 v[116:117], v[72:73], v[32:33], v[116:117] op_sel_hi:[1,0,1] neg_lo:[1,0,0] neg_hi:[1,0,0]
	v_pk_fma_f32 v[116:117], v[74:75], v[32:33], v[116:117] op_sel:[0,1,0] op_sel_hi:[1,1,1] neg_lo:[1,0,0] neg_hi:[1,0,0]
	v_pk_fma_f32 v[116:117], v[76:77], v[34:35], v[116:117] op_sel_hi:[1,0,1] neg_lo:[1,0,0] neg_hi:[1,0,0]
	v_pk_fma_f32 v[116:117], v[78:79], v[34:35], v[116:117] op_sel:[0,1,0] op_sel_hi:[1,1,1] neg_lo:[1,0,0] neg_hi:[1,0,0]
	s_waitcnt lgkmcnt(14)
; #define LAS __attribute__((address_space(3)))
; __device__ __forceinline__ void phase_gdb(const int wvs, const Params& p, LAS unsigned char* lds, int nwg) {
;     ...
;       for (int i = 1; i < 64; ++i) {
; #pragma unroll
;         for (int j4 = 0; j4 < (i + 3) / 4; ++j4) { const f32x4 m4 = *(const LAS f32x4*)(M + i * 64 + j4 * 4);
; #pragma unroll
;           for (int jj = 0; jj < 4; ++jj) if (j4 * 4 + jj < i) x[i] -= m4[jj] * x[j4 * 4 + jj]; }
;         __builtin_amdgcn_sched_barrier(0); }
; #pragma unroll
;       for (int i = 0; i < 64; ++i) R[i * RP + t] = (hf)x[i]; }
	ds_read_b128 v[16:19], v228 offset:7168
	v_pk_fma_f32 v[116:117], v[80:81], v[36:37], v[116:117] op_sel_hi:[1,0,1] neg_lo:[1,0,0] neg_hi:[1,0,0]
	v_pk_fma_f32 v[116:117], v[82:83], v[36:37], v[116:117] op_sel:[0,1,0] op_sel_hi:[1,1,1] neg_lo:[1,0,0] neg_hi:[1,0,0]
	v_pk_fma_f32 v[116:117], v[84:85], v[38:39], v[116:117] op_sel_hi:[1,0,1] neg_lo:[1,0,0] neg_hi:[1,0,0]
	v_pk_fma_f32 v[116:117], v[86:87], v[38:39], v[116:117] op_sel:[0,1,0] op_sel_hi:[1,1,1] neg_lo:[1,0,0] neg_hi:[1,0,0]
	s_waitcnt lgkmcnt(14)
	ds_read_b128 v[20:23], v228 offset:7184
	v_pk_fma_f32 v[116:117], v[88:89], v[40:41], v[116:117] op_sel_hi:[1,0,1] neg_lo:[1,0,0] neg_hi:[1,0,0]
	v_pk_fma_f32 v[116:117], v[90:91], v[40:41], v[116:117] op_sel:[0,1,0] op_sel_hi:[1,1,1] neg_lo:[1,0,0] neg_hi:[1,0,0]
	v_pk_fma_f32 v[116:117], v[92:93], v[42:43], v[116:117] op_sel_hi:[1,0,1] neg_lo:[1,0,0] neg_hi:[1,0,0]
	v_pk_fma_f32 v[116:117], v[94:95], v[42:43], v[116:117] op_sel:[0,1,0] op_sel_hi:[1,1,1] neg_lo:[1,0,0] neg_hi:[1,0,0]
	s_waitcnt lgkmcnt(14)
	ds_read_b128 v[24:27], v228 offset:7200
	v_pk_fma_f32 v[116:117], v[96:97], v[44:45], v[116:117] op_sel_hi:[1,0,1] neg_lo:[1,0,0] neg_hi:[1,0,0]
	v_pk_fma_f32 v[116:117], v[98:99], v[44:45], v[116:117] op_sel:[0,1,0] op_sel_hi:[1,1,1] neg_lo:[1,0,0] neg_hi:[1,0,0]
	v_pk_fma_f32 v[116:117], v[100:101], v[46:47], v[116:117] op_sel_hi:[1,0,1] neg_lo:[1,0,0] neg_hi:[1,0,0]
	v_pk_fma_f32 v[116:117], v[102:103], v[46:47], v[116:117] op_sel:[0,1,0] op_sel_hi:[1,1,1] neg_lo:[1,0,0] neg_hi:[1,0,0]
	s_waitcnt lgkmcnt(14)
	ds_read_b128 v[28:31], v228 offset:7216
	s_waitcnt lgkmcnt(11)
	v_pk_fma_f32 v[116:117], v[104:105], v[48:49], v[116:117] op_sel_hi:[1,0,1] neg_lo:[1,0,0] neg_hi:[1,0,0]
	v_pk_fma_f32 v[116:117], v[106:107], v[48:49], v[116:117] op_sel:[0,1,0] op_sel_hi:[1,1,1] neg_lo:[1,0,0] neg_hi:[1,0,0]
	v_pk_fma_f32 v[116:117], v[108:109], v[50:51], v[116:117] op_sel_hi:[1,0,1] neg_lo:[1,0,0] neg_hi:[1,0,0]
	v_pk_fma_f32 v[116:117], v[110:111], v[50:51], v[116:117] op_sel:[0,1,0] op_sel_hi:[1,1,1] neg_lo:[1,0,0] neg_hi:[1,0,0]
	ds_read_b128 v[32:35], v228 offset:7232
	v_pk_fma_f32 v[116:117], v[112:113], v[52:53], v[116:117] op_sel_hi:[1,0,1] neg_lo:[1,0,0] neg_hi:[1,0,0]
	v_fma_mixlo_f16 v239, -v114, v53, v116
	v_fma_mixlo_f16 v240, -v115, v53, v117
	v_pk_fma_f32 v[116:117], v[114:115], v[52:53], v[116:117] op_sel:[0,1,0] op_sel_hi:[1,1,1] neg_lo:[1,0,0] neg_hi:[1,0,0]
	ds_write_b16 v253, v239 offset:23456
	ds_write_b16 v253, v240 offset:23584
	ds_read_b128 v[36:39], v228 offset:7248
	v_pk_fma_f32 v[118:119], v[64:65], v[56:57], v[118:119] op_sel_hi:[1,0,1] neg_lo:[1,0,0] neg_hi:[1,0,0]
	v_pk_fma_f32 v[118:119], v[66:67], v[56:57], v[118:119] op_sel:[0,1,0] op_sel_hi:[1,1,1] neg_lo:[1,0,0] neg_hi:[1,0,0]
	v_pk_fma_f32 v[118:119], v[68:69], v[58:59], v[118:119] op_sel_hi:[1,0,1] neg_lo:[1,0,0] neg_hi:[1,0,0]
	v_pk_fma_f32 v[118:119], v[70:71], v[58:59], v[118:119] op_sel:[0,1,0] op_sel_hi:[1,1,1] neg_lo:[1,0,0] neg_hi:[1,0,0]
	s_waitcnt lgkmcnt(14)
	ds_read_b128 v[40:43], v228 offset:7264
	v_pk_fma_f32 v[118:119], v[72:73], v[60:61], v[118:119] op_sel_hi:[1,0,1] neg_lo:[1,0,0] neg_hi:[1,0,0]
	v_pk_fma_f32 v[118:119], v[74:75], v[60:61], v[118:119] op_sel:[0,1,0] op_sel_hi:[1,1,1] neg_lo:[1,0,0] neg_hi:[1,0,0]
	v_pk_fma_f32 v[118:119], v[76:77], v[62:63], v[118:119] op_sel_hi:[1,0,1] neg_lo:[1,0,0] neg_hi:[1,0,0]
	v_pk_fma_f32 v[118:119], v[78:79], v[62:63], v[118:119] op_sel:[0,1,0] op_sel_hi:[1,1,1] neg_lo:[1,0,0] neg_hi:[1,0,0]
	s_waitcnt lgkmcnt(14)
	ds_read_b128 v[44:47], v228 offset:7424
	v_pk_fma_f32 v[118:119], v[80:81], v[244:245], v[118:119] op_sel_hi:[1,0,1] neg_lo:[1,0,0] neg_hi:[1,0,0]
	v_pk_fma_f32 v[118:119], v[82:83], v[244:245], v[118:119] op_sel:[0,1,0] op_sel_hi:[1,1,1] neg_lo:[1,0,0] neg_hi:[1,0,0]
	v_pk_fma_f32 v[118:119], v[84:85], v[246:247], v[118:119] op_sel_hi:[1,0,1] neg_lo:[1,0,0] neg_hi:[1,0,0]
	v_pk_fma_f32 v[118:119], v[86:87], v[246:247], v[118:119] op_sel:[0,1,0] op_sel_hi:[1,1,1] neg_lo:[1,0,0] neg_hi:[1,0,0]
	s_waitcnt lgkmcnt(14)
	ds_read_b128 v[48:51], v228 offset:7440
	v_pk_fma_f32 v[118:119], v[88:89], v[248:249], v[118:119] op_sel_hi:[1,0,1] neg_lo:[1,0,0] neg_hi:[1,0,0]
	v_pk_fma_f32 v[118:119], v[90:91], v[248:249], v[118:119] op_sel:[0,1,0] op_sel_hi:[1,1,1] neg_lo:[1,0,0] neg_hi:[1,0,0]
	v_pk_fma_f32 v[118:119], v[92:93], v[250:251], v[118:119] op_sel_hi:[1,0,1] neg_lo:[1,0,0] neg_hi:[1,0,0]
	v_pk_fma_f32 v[118:119], v[94:95], v[250:251], v[118:119] op_sel:[0,1,0] op_sel_hi:[1,1,1] neg_lo:[1,0,0] neg_hi:[1,0,0]
	s_waitcnt lgkmcnt(14)
	ds_read_b128 v[52:55], v228 offset:7456
	v_pk_fma_f32 v[118:119], v[96:97], v[4:5], v[118:119] op_sel_hi:[1,0,1] neg_lo:[1,0,0] neg_hi:[1,0,0]
	v_pk_fma_f32 v[118:119], v[98:99], v[4:5], v[118:119] op_sel:[0,1,0] op_sel_hi:[1,1,1] neg_lo:[1,0,0] neg_hi:[1,0,0]
	v_pk_fma_f32 v[118:119], v[100:101], v[6:7], v[118:119] op_sel_hi:[1,0,1] neg_lo:[1,0,0] neg_hi:[1,0,0]
	v_pk_fma_f32 v[118:119], v[102:103], v[6:7], v[118:119] op_sel:[0,1,0] op_sel_hi:[1,1,1] neg_lo:[1,0,0] neg_hi:[1,0,0]
	s_waitcnt lgkmcnt(14)
	ds_read_b128 v[56:59], v228 offset:7472
	s_waitcnt lgkmcnt(11)
; #define LAS __attribute__((address_space(3)))
; __device__ __forceinline__ void phase_gdb(const int wvs, const Params& p, LAS unsigned char* lds, int nwg) {
;     ...
;       for (int i = 1; i < 64; ++i) {
; #pragma unroll
;         for (int j4 = 0; j4 < (i + 3) / 4; ++j4) { const f32x4 m4 = *(const LAS f32x4*)(M + i * 64 + j4 * 4);
; #pragma unroll
;           for (int jj = 0; jj < 4; ++jj) if (j4 * 4 + jj < i) x[i] -= m4[jj] * x[j4 * 4 + jj]; }
;         __builtin_amdgcn_sched_barrier(0); }
; #pragma unroll
;       for (int i = 0; i < 64; ++i) R[i * RP + t] = (hf)x[i]; }
	v_pk_fma_f32 v[118:119], v[104:105], v[8:9], v[118:119] op_sel_hi:[1,0,1] neg_lo:[1,0,0] neg_hi:[1,0,0]
	v_pk_fma_f32 v[118:119], v[106:107], v[8:9], v[118:119] op_sel:[0,1,0] op_sel_hi:[1,1,1] neg_lo:[1,0,0] neg_hi:[1,0,0]
	v_pk_fma_f32 v[118:119], v[108:109], v[10:11], v[118:119] op_sel_hi:[1,0,1] neg_lo:[1,0,0] neg_hi:[1,0,0]
	v_pk_fma_f32 v[118:119], v[110:111], v[10:11], v[118:119] op_sel:[0,1,0] op_sel_hi:[1,1,1] neg_lo:[1,0,0] neg_hi:[1,0,0]
	ds_read_b128 v[60:63], v228 offset:7488
	v_pk_fma_f32 v[118:119], v[112:113], v[12:13], v[118:119] op_sel_hi:[1,0,1] neg_lo:[1,0,0] neg_hi:[1,0,0]
	v_pk_fma_f32 v[118:119], v[114:115], v[12:13], v[118:119] op_sel:[0,1,0] op_sel_hi:[1,1,1] neg_lo:[1,0,0] neg_hi:[1,0,0]
	v_fma_mixlo_f16 v0, -v116, v14, v118
	v_fma_mixlo_f16 v2, -v117, v14, v119
	v_pk_fma_f32 v[118:119], v[116:117], v[14:15], v[118:119] op_sel_hi:[1,0,1] neg_lo:[1,0,0] neg_hi:[1,0,0]
	ds_write_b16 v253, v0 offset:23728
	ds_write_b16 v253, v2 offset:23856
	ds_read_b128 v[244:247], v228 offset:7504
	v_pk_fma_f32 v[120:121], v[64:65], v[16:17], v[120:121] op_sel_hi:[1,0,1] neg_lo:[1,0,0] neg_hi:[1,0,0]
	v_pk_fma_f32 v[120:121], v[66:67], v[16:17], v[120:121] op_sel:[0,1,0] op_sel_hi:[1,1,1] neg_lo:[1,0,0] neg_hi:[1,0,0]
	v_pk_fma_f32 v[120:121], v[68:69], v[18:19], v[120:121] op_sel_hi:[1,0,1] neg_lo:[1,0,0] neg_hi:[1,0,0]
	v_pk_fma_f32 v[120:121], v[70:71], v[18:19], v[120:121] op_sel:[0,1,0] op_sel_hi:[1,1,1] neg_lo:[1,0,0] neg_hi:[1,0,0]
	s_waitcnt lgkmcnt(14)
	ds_read_b128 v[248:251], v228 offset:7520
	v_pk_fma_f32 v[120:121], v[72:73], v[20:21], v[120:121] op_sel_hi:[1,0,1] neg_lo:[1,0,0] neg_hi:[1,0,0]
	v_pk_fma_f32 v[120:121], v[74:75], v[20:21], v[120:121] op_sel:[0,1,0] op_sel_hi:[1,1,1] neg_lo:[1,0,0] neg_hi:[1,0,0]
	v_pk_fma_f32 v[120:121], v[76:77], v[22:23], v[120:121] op_sel_hi:[1,0,1] neg_lo:[1,0,0] neg_hi:[1,0,0]
	v_pk_fma_f32 v[120:121], v[78:79], v[22:23], v[120:121] op_sel:[0,1,0] op_sel_hi:[1,1,1] neg_lo:[1,0,0] neg_hi:[1,0,0]
	s_waitcnt lgkmcnt(14)
	ds_read_b128 v[4:7], v228 offset:7536
	v_pk_fma_f32 v[120:121], v[80:81], v[24:25], v[120:121] op_sel_hi:[1,0,1] neg_lo:[1,0,0] neg_hi:[1,0,0]
	v_pk_fma_f32 v[120:121], v[82:83], v[24:25], v[120:121] op_sel:[0,1,0] op_sel_hi:[1,1,1] neg_lo:[1,0,0] neg_hi:[1,0,0]
	v_pk_fma_f32 v[120:121], v[84:85], v[26:27], v[120:121] op_sel_hi:[1,0,1] neg_lo:[1,0,0] neg_hi:[1,0,0]
	v_pk_fma_f32 v[120:121], v[86:87], v[26:27], v[120:121] op_sel:[0,1,0] op_sel_hi:[1,1,1] neg_lo:[1,0,0] neg_hi:[1,0,0]
	s_waitcnt lgkmcnt(14)
	ds_read_b128 v[8:11], v228 offset:7680
	v_pk_fma_f32 v[120:121], v[88:89], v[28:29], v[120:121] op_sel_hi:[1,0,1] neg_lo:[1,0,0] neg_hi:[1,0,0]
	v_pk_fma_f32 v[120:121], v[90:91], v[28:29], v[120:121] op_sel:[0,1,0] op_sel_hi:[1,1,1] neg_lo:[1,0,0] neg_hi:[1,0,0]
	v_pk_fma_f32 v[120:121], v[92:93], v[30:31], v[120:121] op_sel_hi:[1,0,1] neg_lo:[1,0,0] neg_hi:[1,0,0]
	v_pk_fma_f32 v[120:121], v[94:95], v[30:31], v[120:121] op_sel:[0,1,0] op_sel_hi:[1,1,1] neg_lo:[1,0,0] neg_hi:[1,0,0]
	s_waitcnt lgkmcnt(14)
	ds_read_b128 v[12:15], v228 offset:7696
	v_pk_fma_f32 v[120:121], v[96:97], v[32:33], v[120:121] op_sel_hi:[1,0,1] neg_lo:[1,0,0] neg_hi:[1,0,0]
	v_pk_fma_f32 v[120:121], v[98:99], v[32:33], v[120:121] op_sel:[0,1,0] op_sel_hi:[1,1,1] neg_lo:[1,0,0] neg_hi:[1,0,0]
	v_pk_fma_f32 v[120:121], v[100:101], v[34:35], v[120:121] op_sel_hi:[1,0,1] neg_lo:[1,0,0] neg_hi:[1,0,0]
	v_pk_fma_f32 v[120:121], v[102:103], v[34:35], v[120:121] op_sel:[0,1,0] op_sel_hi:[1,1,1] neg_lo:[1,0,0] neg_hi:[1,0,0]
	s_waitcnt lgkmcnt(14)
	ds_read_b128 v[16:19], v228 offset:7712
	s_waitcnt lgkmcnt(11)
	v_pk_fma_f32 v[120:121], v[104:105], v[36:37], v[120:121] op_sel_hi:[1,0,1] neg_lo:[1,0,0] neg_hi:[1,0,0]
	v_pk_fma_f32 v[120:121], v[106:107], v[36:37], v[120:121] op_sel:[0,1,0] op_sel_hi:[1,1,1] neg_lo:[1,0,0] neg_hi:[1,0,0]
	v_pk_fma_f32 v[120:121], v[108:109], v[38:39], v[120:121] op_sel_hi:[1,0,1] neg_lo:[1,0,0] neg_hi:[1,0,0]
	v_pk_fma_f32 v[120:121], v[110:111], v[38:39], v[120:121] op_sel:[0,1,0] op_sel_hi:[1,1,1] neg_lo:[1,0,0] neg_hi:[1,0,0]
	ds_read_b128 v[20:23], v228 offset:7728
	v_pk_fma_f32 v[120:121], v[112:113], v[40:41], v[120:121] op_sel_hi:[1,0,1] neg_lo:[1,0,0] neg_hi:[1,0,0]
	v_pk_fma_f32 v[120:121], v[114:115], v[40:41], v[120:121] op_sel:[0,1,0] op_sel_hi:[1,1,1] neg_lo:[1,0,0] neg_hi:[1,0,0]
	v_pk_fma_f32 v[120:121], v[116:117], v[42:43], v[120:121] op_sel_hi:[1,0,1] neg_lo:[1,0,0] neg_hi:[1,0,0]
	v_fma_mixlo_f16 v3, -v118, v43, v120
	v_fma_mixlo_f16 v238, -v119, v43, v121
	v_pk_fma_f32 v[120:121], v[118:119], v[42:43], v[120:121] op_sel:[0,1,0] op_sel_hi:[1,1,1] neg_lo:[1,0,0] neg_hi:[1,0,0]
	ds_write_b16 v253, v3 offset:24000
	ds_write_b16 v253, v238 offset:24128
	ds_read_b128 v[24:27], v228 offset:7744
	v_pk_fma_f32 v[122:123], v[64:65], v[44:45], v[122:123] op_sel_hi:[1,0,1] neg_lo:[1,0,0] neg_hi:[1,0,0]
	v_pk_fma_f32 v[122:123], v[66:67], v[44:45], v[122:123] op_sel:[0,1,0] op_sel_hi:[1,1,1] neg_lo:[1,0,0] neg_hi:[1,0,0]
	v_pk_fma_f32 v[122:123], v[68:69], v[46:47], v[122:123] op_sel_hi:[1,0,1] neg_lo:[1,0,0] neg_hi:[1,0,0]
	v_pk_fma_f32 v[122:123], v[70:71], v[46:47], v[122:123] op_sel:[0,1,0] op_sel_hi:[1,1,1] neg_lo:[1,0,0] neg_hi:[1,0,0]
	s_waitcnt lgkmcnt(14)
	ds_read_b128 v[28:31], v228 offset:7760
	v_pk_fma_f32 v[122:123], v[72:73], v[48:49], v[122:123] op_sel_hi:[1,0,1] neg_lo:[1,0,0] neg_hi:[1,0,0]
	v_pk_fma_f32 v[122:123], v[74:75], v[48:49], v[122:123] op_sel:[0,1,0] op_sel_hi:[1,1,1] neg_lo:[1,0,0] neg_hi:[1,0,0]
	v_pk_fma_f32 v[122:123], v[76:77], v[50:51], v[122:123] op_sel_hi:[1,0,1] neg_lo:[1,0,0] neg_hi:[1,0,0]
	v_pk_fma_f32 v[122:123], v[78:79], v[50:51], v[122:123] op_sel:[0,1,0] op_sel_hi:[1,1,1] neg_lo:[1,0,0] neg_hi:[1,0,0]
	s_waitcnt lgkmcnt(14)
; #define LAS __attribute__((address_space(3)))
; __device__ __forceinline__ void phase_gdb(const int wvs, const Params& p, LAS unsigned char* lds, int nwg) {
;     ...
;       for (int i = 1; i < 64; ++i) {
; #pragma unroll
;         for (int j4 = 0; j4 < (i + 3) / 4; ++j4) { const f32x4 m4 = *(const LAS f32x4*)(M + i * 64 + j4 * 4);
; #pragma unroll
;           for (int jj = 0; jj < 4; ++jj) if (j4 * 4 + jj < i) x[i] -= m4[jj] * x[j4 * 4 + jj]; }
;         __builtin_amdgcn_sched_barrier(0); }
; #pragma unroll
;       for (int i = 0; i < 64; ++i) R[i * RP + t] = (hf)x[i]; }
	ds_read_b128 v[32:35], v228 offset:7776
	v_pk_fma_f32 v[122:123], v[80:81], v[52:53], v[122:123] op_sel_hi:[1,0,1] neg_lo:[1,0,0] neg_hi:[1,0,0]
	v_pk_fma_f32 v[122:123], v[82:83], v[52:53], v[122:123] op_sel:[0,1,0] op_sel_hi:[1,1,1] neg_lo:[1,0,0] neg_hi:[1,0,0]
	v_pk_fma_f32 v[122:123], v[84:85], v[54:55], v[122:123] op_sel_hi:[1,0,1] neg_lo:[1,0,0] neg_hi:[1,0,0]
	v_pk_fma_f32 v[122:123], v[86:87], v[54:55], v[122:123] op_sel:[0,1,0] op_sel_hi:[1,1,1] neg_lo:[1,0,0] neg_hi:[1,0,0]
	s_waitcnt lgkmcnt(14)
	ds_read_b128 v[36:39], v228 offset:7792
	v_pk_fma_f32 v[122:123], v[88:89], v[56:57], v[122:123] op_sel_hi:[1,0,1] neg_lo:[1,0,0] neg_hi:[1,0,0]
	v_pk_fma_f32 v[122:123], v[90:91], v[56:57], v[122:123] op_sel:[0,1,0] op_sel_hi:[1,1,1] neg_lo:[1,0,0] neg_hi:[1,0,0]
	v_pk_fma_f32 v[122:123], v[92:93], v[58:59], v[122:123] op_sel_hi:[1,0,1] neg_lo:[1,0,0] neg_hi:[1,0,0]
	v_pk_fma_f32 v[122:123], v[94:95], v[58:59], v[122:123] op_sel:[0,1,0] op_sel_hi:[1,1,1] neg_lo:[1,0,0] neg_hi:[1,0,0]
	s_waitcnt lgkmcnt(14)
	ds_read_b128 v[40:43], v228 offset:7936
	v_pk_fma_f32 v[122:123], v[96:97], v[60:61], v[122:123] op_sel_hi:[1,0,1] neg_lo:[1,0,0] neg_hi:[1,0,0]
	v_pk_fma_f32 v[122:123], v[98:99], v[60:61], v[122:123] op_sel:[0,1,0] op_sel_hi:[1,1,1] neg_lo:[1,0,0] neg_hi:[1,0,0]
	v_pk_fma_f32 v[122:123], v[100:101], v[62:63], v[122:123] op_sel_hi:[1,0,1] neg_lo:[1,0,0] neg_hi:[1,0,0]
	v_pk_fma_f32 v[122:123], v[102:103], v[62:63], v[122:123] op_sel:[0,1,0] op_sel_hi:[1,1,1] neg_lo:[1,0,0] neg_hi:[1,0,0]
	s_waitcnt lgkmcnt(14)
	ds_read_b128 v[44:47], v228 offset:7952
	s_waitcnt lgkmcnt(11)
	v_pk_fma_f32 v[122:123], v[104:105], v[244:245], v[122:123] op_sel_hi:[1,0,1] neg_lo:[1,0,0] neg_hi:[1,0,0]
	v_pk_fma_f32 v[122:123], v[106:107], v[244:245], v[122:123] op_sel:[0,1,0] op_sel_hi:[1,1,1] neg_lo:[1,0,0] neg_hi:[1,0,0]
	v_pk_fma_f32 v[122:123], v[108:109], v[246:247], v[122:123] op_sel_hi:[1,0,1] neg_lo:[1,0,0] neg_hi:[1,0,0]
	v_pk_fma_f32 v[122:123], v[110:111], v[246:247], v[122:123] op_sel:[0,1,0] op_sel_hi:[1,1,1] neg_lo:[1,0,0] neg_hi:[1,0,0]
	ds_read_b128 v[48:51], v228 offset:7968
	v_pk_fma_f32 v[122:123], v[112:113], v[248:249], v[122:123] op_sel_hi:[1,0,1] neg_lo:[1,0,0] neg_hi:[1,0,0]
	v_pk_fma_f32 v[122:123], v[114:115], v[248:249], v[122:123] op_sel:[0,1,0] op_sel_hi:[1,1,1] neg_lo:[1,0,0] neg_hi:[1,0,0]
	v_pk_fma_f32 v[122:123], v[116:117], v[250:251], v[122:123] op_sel_hi:[1,0,1] neg_lo:[1,0,0] neg_hi:[1,0,0]
	v_pk_fma_f32 v[122:123], v[118:119], v[250:251], v[122:123] op_sel:[0,1,0] op_sel_hi:[1,1,1] neg_lo:[1,0,0] neg_hi:[1,0,0]
	ds_read_b128 v[52:55], v228 offset:7984
	v_fma_mixlo_f16 v239, -v120, v4, v122
	v_fma_mixlo_f16 v240, -v121, v4, v123
	v_pk_fma_f32 v[122:123], v[120:121], v[4:5], v[122:123] op_sel_hi:[1,0,1] neg_lo:[1,0,0] neg_hi:[1,0,0]
	ds_write_b16 v253, v239 offset:24272
	ds_write_b16 v253, v240 offset:24400
	s_waitcnt lgkmcnt(14)
	ds_read_b128 v[56:59], v228 offset:8000
	v_pk_fma_f32 v[124:125], v[64:65], v[8:9], v[124:125] op_sel_hi:[1,0,1] neg_lo:[1,0,0] neg_hi:[1,0,0]
	v_pk_fma_f32 v[124:125], v[66:67], v[8:9], v[124:125] op_sel:[0,1,0] op_sel_hi:[1,1,1] neg_lo:[1,0,0] neg_hi:[1,0,0]
	v_pk_fma_f32 v[124:125], v[68:69], v[10:11], v[124:125] op_sel_hi:[1,0,1] neg_lo:[1,0,0] neg_hi:[1,0,0]
	v_pk_fma_f32 v[124:125], v[70:71], v[10:11], v[124:125] op_sel:[0,1,0] op_sel_hi:[1,1,1] neg_lo:[1,0,0] neg_hi:[1,0,0]
	s_waitcnt lgkmcnt(14)
	ds_read_b128 v[60:63], v228 offset:8016
	v_pk_fma_f32 v[124:125], v[72:73], v[12:13], v[124:125] op_sel_hi:[1,0,1] neg_lo:[1,0,0] neg_hi:[1,0,0]
	v_pk_fma_f32 v[124:125], v[74:75], v[12:13], v[124:125] op_sel:[0,1,0] op_sel_hi:[1,1,1] neg_lo:[1,0,0] neg_hi:[1,0,0]
	v_pk_fma_f32 v[124:125], v[76:77], v[14:15], v[124:125] op_sel_hi:[1,0,1] neg_lo:[1,0,0] neg_hi:[1,0,0]
	v_pk_fma_f32 v[124:125], v[78:79], v[14:15], v[124:125] op_sel:[0,1,0] op_sel_hi:[1,1,1] neg_lo:[1,0,0] neg_hi:[1,0,0]
	s_waitcnt lgkmcnt(14)
	ds_read_b128 v[244:247], v228 offset:8032
	v_pk_fma_f32 v[124:125], v[80:81], v[16:17], v[124:125] op_sel_hi:[1,0,1] neg_lo:[1,0,0] neg_hi:[1,0,0]
	v_pk_fma_f32 v[124:125], v[82:83], v[16:17], v[124:125] op_sel:[0,1,0] op_sel_hi:[1,1,1] neg_lo:[1,0,0] neg_hi:[1,0,0]
	v_pk_fma_f32 v[124:125], v[84:85], v[18:19], v[124:125] op_sel_hi:[1,0,1] neg_lo:[1,0,0] neg_hi:[1,0,0]
	v_pk_fma_f32 v[124:125], v[86:87], v[18:19], v[124:125] op_sel:[0,1,0] op_sel_hi:[1,1,1] neg_lo:[1,0,0] neg_hi:[1,0,0]
	s_waitcnt lgkmcnt(14)
	ds_read_b128 v[248:251], v228 offset:8048
	v_pk_fma_f32 v[124:125], v[88:89], v[20:21], v[124:125] op_sel_hi:[1,0,1] neg_lo:[1,0,0] neg_hi:[1,0,0]
	v_pk_fma_f32 v[124:125], v[90:91], v[20:21], v[124:125] op_sel:[0,1,0] op_sel_hi:[1,1,1] neg_lo:[1,0,0] neg_hi:[1,0,0]
	v_pk_fma_f32 v[124:125], v[92:93], v[22:23], v[124:125] op_sel_hi:[1,0,1] neg_lo:[1,0,0] neg_hi:[1,0,0]
	v_pk_fma_f32 v[124:125], v[94:95], v[22:23], v[124:125] op_sel:[0,1,0] op_sel_hi:[1,1,1] neg_lo:[1,0,0] neg_hi:[1,0,0]
	s_waitcnt lgkmcnt(14)
	ds_read_b128 v[4:7], v228 offset:8192
	s_waitcnt lgkmcnt(11)
; #define LAS __attribute__((address_space(3)))
; __device__ __forceinline__ void phase_gdb(const int wvs, const Params& p, LAS unsigned char* lds, int nwg) {
;     ...
;       for (int i = 1; i < 64; ++i) {
; #pragma unroll
;         for (int j4 = 0; j4 < (i + 3) / 4; ++j4) { const f32x4 m4 = *(const LAS f32x4*)(M + i * 64 + j4 * 4);
; #pragma unroll
;           for (int jj = 0; jj < 4; ++jj) if (j4 * 4 + jj < i) x[i] -= m4[jj] * x[j4 * 4 + jj]; }
;         __builtin_amdgcn_sched_barrier(0); }
; #pragma unroll
;       for (int i = 0; i < 64; ++i) R[i * RP + t] = (hf)x[i]; }
	v_pk_fma_f32 v[124:125], v[96:97], v[24:25], v[124:125] op_sel_hi:[1,0,1] neg_lo:[1,0,0] neg_hi:[1,0,0]
	v_pk_fma_f32 v[124:125], v[98:99], v[24:25], v[124:125] op_sel:[0,1,0] op_sel_hi:[1,1,1] neg_lo:[1,0,0] neg_hi:[1,0,0]
	v_pk_fma_f32 v[124:125], v[100:101], v[26:27], v[124:125] op_sel_hi:[1,0,1] neg_lo:[1,0,0] neg_hi:[1,0,0]
	v_pk_fma_f32 v[124:125], v[102:103], v[26:27], v[124:125] op_sel:[0,1,0] op_sel_hi:[1,1,1] neg_lo:[1,0,0] neg_hi:[1,0,0]
	ds_read_b128 v[8:11], v228 offset:8208
	v_pk_fma_f32 v[124:125], v[104:105], v[28:29], v[124:125] op_sel_hi:[1,0,1] neg_lo:[1,0,0] neg_hi:[1,0,0]
	v_pk_fma_f32 v[124:125], v[106:107], v[28:29], v[124:125] op_sel:[0,1,0] op_sel_hi:[1,1,1] neg_lo:[1,0,0] neg_hi:[1,0,0]
	v_pk_fma_f32 v[124:125], v[108:109], v[30:31], v[124:125] op_sel_hi:[1,0,1] neg_lo:[1,0,0] neg_hi:[1,0,0]
	v_pk_fma_f32 v[124:125], v[110:111], v[30:31], v[124:125] op_sel:[0,1,0] op_sel_hi:[1,1,1] neg_lo:[1,0,0] neg_hi:[1,0,0]
	ds_read_b128 v[12:15], v228 offset:8224
	v_pk_fma_f32 v[124:125], v[112:113], v[32:33], v[124:125] op_sel_hi:[1,0,1] neg_lo:[1,0,0] neg_hi:[1,0,0]
	v_pk_fma_f32 v[124:125], v[114:115], v[32:33], v[124:125] op_sel:[0,1,0] op_sel_hi:[1,1,1] neg_lo:[1,0,0] neg_hi:[1,0,0]
	v_pk_fma_f32 v[124:125], v[116:117], v[34:35], v[124:125] op_sel_hi:[1,0,1] neg_lo:[1,0,0] neg_hi:[1,0,0]
	v_pk_fma_f32 v[124:125], v[118:119], v[34:35], v[124:125] op_sel:[0,1,0] op_sel_hi:[1,1,1] neg_lo:[1,0,0] neg_hi:[1,0,0]
	ds_read_b128 v[16:19], v228 offset:8240
	v_pk_fma_f32 v[124:125], v[120:121], v[36:37], v[124:125] op_sel_hi:[1,0,1] neg_lo:[1,0,0] neg_hi:[1,0,0]
	v_fma_mixlo_f16 v0, -v122, v37, v124
	v_fma_mixlo_f16 v2, -v123, v37, v125
	v_pk_fma_f32 v[124:125], v[122:123], v[36:37], v[124:125] op_sel:[0,1,0] op_sel_hi:[1,1,1] neg_lo:[1,0,0] neg_hi:[1,0,0]
	ds_write_b16 v253, v0 offset:24544
	s_waitcnt lgkmcnt(14)
	ds_write_b16 v253, v2 offset:24672
	s_waitcnt lgkmcnt(14)
	ds_read_b128 v[20:23], v228 offset:8256
	v_pk_fma_f32 v[126:127], v[64:65], v[40:41], v[126:127] op_sel_hi:[1,0,1] neg_lo:[1,0,0] neg_hi:[1,0,0]
	v_pk_fma_f32 v[126:127], v[66:67], v[40:41], v[126:127] op_sel:[0,1,0] op_sel_hi:[1,1,1] neg_lo:[1,0,0] neg_hi:[1,0,0]
	v_pk_fma_f32 v[126:127], v[68:69], v[42:43], v[126:127] op_sel_hi:[1,0,1] neg_lo:[1,0,0] neg_hi:[1,0,0]
	v_pk_fma_f32 v[126:127], v[70:71], v[42:43], v[126:127] op_sel:[0,1,0] op_sel_hi:[1,1,1] neg_lo:[1,0,0] neg_hi:[1,0,0]
	s_waitcnt lgkmcnt(14)
	ds_read_b128 v[24:27], v228 offset:8272
	v_pk_fma_f32 v[126:127], v[72:73], v[44:45], v[126:127] op_sel_hi:[1,0,1] neg_lo:[1,0,0] neg_hi:[1,0,0]
	v_pk_fma_f32 v[126:127], v[74:75], v[44:45], v[126:127] op_sel:[0,1,0] op_sel_hi:[1,1,1] neg_lo:[1,0,0] neg_hi:[1,0,0]
	v_pk_fma_f32 v[126:127], v[76:77], v[46:47], v[126:127] op_sel_hi:[1,0,1] neg_lo:[1,0,0] neg_hi:[1,0,0]
	v_pk_fma_f32 v[126:127], v[78:79], v[46:47], v[126:127] op_sel:[0,1,0] op_sel_hi:[1,1,1] neg_lo:[1,0,0] neg_hi:[1,0,0]
	s_waitcnt lgkmcnt(14)
	ds_read_b128 v[28:31], v228 offset:8288
	v_pk_fma_f32 v[126:127], v[80:81], v[48:49], v[126:127] op_sel_hi:[1,0,1] neg_lo:[1,0,0] neg_hi:[1,0,0]
	v_pk_fma_f32 v[126:127], v[82:83], v[48:49], v[126:127] op_sel:[0,1,0] op_sel_hi:[1,1,1] neg_lo:[1,0,0] neg_hi:[1,0,0]
	v_pk_fma_f32 v[126:127], v[84:85], v[50:51], v[126:127] op_sel_hi:[1,0,1] neg_lo:[1,0,0] neg_hi:[1,0,0]
	v_pk_fma_f32 v[126:127], v[86:87], v[50:51], v[126:127] op_sel:[0,1,0] op_sel_hi:[1,1,1] neg_lo:[1,0,0] neg_hi:[1,0,0]
	s_waitcnt lgkmcnt(14)
	ds_read_b128 v[32:35], v228 offset:8304
	v_pk_fma_f32 v[126:127], v[88:89], v[52:53], v[126:127] op_sel_hi:[1,0,1] neg_lo:[1,0,0] neg_hi:[1,0,0]
	v_pk_fma_f32 v[126:127], v[90:91], v[52:53], v[126:127] op_sel:[0,1,0] op_sel_hi:[1,1,1] neg_lo:[1,0,0] neg_hi:[1,0,0]
	v_pk_fma_f32 v[126:127], v[92:93], v[54:55], v[126:127] op_sel_hi:[1,0,1] neg_lo:[1,0,0] neg_hi:[1,0,0]
	v_pk_fma_f32 v[126:127], v[94:95], v[54:55], v[126:127] op_sel:[0,1,0] op_sel_hi:[1,1,1] neg_lo:[1,0,0] neg_hi:[1,0,0]
	s_waitcnt lgkmcnt(14)
	ds_read_b128 v[36:39], v228 offset:8448
	s_waitcnt lgkmcnt(11)
	v_pk_fma_f32 v[126:127], v[96:97], v[56:57], v[126:127] op_sel_hi:[1,0,1] neg_lo:[1,0,0] neg_hi:[1,0,0]
	v_pk_fma_f32 v[126:127], v[98:99], v[56:57], v[126:127] op_sel:[0,1,0] op_sel_hi:[1,1,1] neg_lo:[1,0,0] neg_hi:[1,0,0]
	v_pk_fma_f32 v[126:127], v[100:101], v[58:59], v[126:127] op_sel_hi:[1,0,1] neg_lo:[1,0,0] neg_hi:[1,0,0]
	v_pk_fma_f32 v[126:127], v[102:103], v[58:59], v[126:127] op_sel:[0,1,0] op_sel_hi:[1,1,1] neg_lo:[1,0,0] neg_hi:[1,0,0]
	ds_read_b128 v[40:43], v228 offset:8464
	v_pk_fma_f32 v[126:127], v[104:105], v[60:61], v[126:127] op_sel_hi:[1,0,1] neg_lo:[1,0,0] neg_hi:[1,0,0]
	v_pk_fma_f32 v[126:127], v[106:107], v[60:61], v[126:127] op_sel:[0,1,0] op_sel_hi:[1,1,1] neg_lo:[1,0,0] neg_hi:[1,0,0]
	v_pk_fma_f32 v[126:127], v[108:109], v[62:63], v[126:127] op_sel_hi:[1,0,1] neg_lo:[1,0,0] neg_hi:[1,0,0]
	v_pk_fma_f32 v[126:127], v[110:111], v[62:63], v[126:127] op_sel:[0,1,0] op_sel_hi:[1,1,1] neg_lo:[1,0,0] neg_hi:[1,0,0]
	ds_read_b128 v[44:47], v228 offset:8480
	v_pk_fma_f32 v[126:127], v[112:113], v[244:245], v[126:127] op_sel_hi:[1,0,1] neg_lo:[1,0,0] neg_hi:[1,0,0]
	v_pk_fma_f32 v[126:127], v[114:115], v[244:245], v[126:127] op_sel:[0,1,0] op_sel_hi:[1,1,1] neg_lo:[1,0,0] neg_hi:[1,0,0]
	v_pk_fma_f32 v[126:127], v[116:117], v[246:247], v[126:127] op_sel_hi:[1,0,1] neg_lo:[1,0,0] neg_hi:[1,0,0]
	v_pk_fma_f32 v[126:127], v[118:119], v[246:247], v[126:127] op_sel:[0,1,0] op_sel_hi:[1,1,1] neg_lo:[1,0,0] neg_hi:[1,0,0]
	ds_read_b128 v[48:51], v228 offset:8496
	v_pk_fma_f32 v[126:127], v[120:121], v[248:249], v[126:127] op_sel_hi:[1,0,1] neg_lo:[1,0,0] neg_hi:[1,0,0]
	v_pk_fma_f32 v[126:127], v[122:123], v[248:249], v[126:127] op_sel:[0,1,0] op_sel_hi:[1,1,1] neg_lo:[1,0,0] neg_hi:[1,0,0]
	v_fma_mixlo_f16 v3, -v124, v250, v126
	v_fma_mixlo_f16 v238, -v125, v250, v127
	v_pk_fma_f32 v[126:127], v[124:125], v[250:251], v[126:127] op_sel_hi:[1,0,1] neg_lo:[1,0,0] neg_hi:[1,0,0]
	ds_write_b16 v253, v3 offset:24816
	s_waitcnt lgkmcnt(14)
; #define LAS __attribute__((address_space(3)))
; __device__ __forceinline__ void phase_gdb(const int wvs, const Params& p, LAS unsigned char* lds, int nwg) {
;     ...
;       for (int i = 1; i < 64; ++i) {
; #pragma unroll
;         for (int j4 = 0; j4 < (i + 3) / 4; ++j4) { const f32x4 m4 = *(const LAS f32x4*)(M + i * 64 + j4 * 4);
; #pragma unroll
;           for (int jj = 0; jj < 4; ++jj) if (j4 * 4 + jj < i) x[i] -= m4[jj] * x[j4 * 4 + jj]; }
;         __builtin_amdgcn_sched_barrier(0); }
; #pragma unroll
;       for (int i = 0; i < 64; ++i) R[i * RP + t] = (hf)x[i]; }
	ds_write_b16 v253, v238 offset:24944
	s_waitcnt lgkmcnt(14)
	ds_read_b128 v[52:55], v228 offset:8512
	v_pk_fma_f32 v[128:129], v[64:65], v[4:5], v[128:129] op_sel_hi:[1,0,1] neg_lo:[1,0,0] neg_hi:[1,0,0]
	v_pk_fma_f32 v[128:129], v[66:67], v[4:5], v[128:129] op_sel:[0,1,0] op_sel_hi:[1,1,1] neg_lo:[1,0,0] neg_hi:[1,0,0]
	v_pk_fma_f32 v[128:129], v[68:69], v[6:7], v[128:129] op_sel_hi:[1,0,1] neg_lo:[1,0,0] neg_hi:[1,0,0]
	v_pk_fma_f32 v[128:129], v[70:71], v[6:7], v[128:129] op_sel:[0,1,0] op_sel_hi:[1,1,1] neg_lo:[1,0,0] neg_hi:[1,0,0]
	s_waitcnt lgkmcnt(14)
	ds_read_b128 v[56:59], v228 offset:8528
	v_pk_fma_f32 v[128:129], v[72:73], v[8:9], v[128:129] op_sel_hi:[1,0,1] neg_lo:[1,0,0] neg_hi:[1,0,0]
	v_pk_fma_f32 v[128:129], v[74:75], v[8:9], v[128:129] op_sel:[0,1,0] op_sel_hi:[1,1,1] neg_lo:[1,0,0] neg_hi:[1,0,0]
	v_pk_fma_f32 v[128:129], v[76:77], v[10:11], v[128:129] op_sel_hi:[1,0,1] neg_lo:[1,0,0] neg_hi:[1,0,0]
	v_pk_fma_f32 v[128:129], v[78:79], v[10:11], v[128:129] op_sel:[0,1,0] op_sel_hi:[1,1,1] neg_lo:[1,0,0] neg_hi:[1,0,0]
	s_waitcnt lgkmcnt(14)
	ds_read_b128 v[60:63], v228 offset:8544
	v_pk_fma_f32 v[128:129], v[80:81], v[12:13], v[128:129] op_sel_hi:[1,0,1] neg_lo:[1,0,0] neg_hi:[1,0,0]
	v_pk_fma_f32 v[128:129], v[82:83], v[12:13], v[128:129] op_sel:[0,1,0] op_sel_hi:[1,1,1] neg_lo:[1,0,0] neg_hi:[1,0,0]
	v_pk_fma_f32 v[128:129], v[84:85], v[14:15], v[128:129] op_sel_hi:[1,0,1] neg_lo:[1,0,0] neg_hi:[1,0,0]
	v_pk_fma_f32 v[128:129], v[86:87], v[14:15], v[128:129] op_sel:[0,1,0] op_sel_hi:[1,1,1] neg_lo:[1,0,0] neg_hi:[1,0,0]
	s_waitcnt lgkmcnt(14)
	ds_read_b128 v[244:247], v228 offset:8560
	v_pk_fma_f32 v[128:129], v[88:89], v[16:17], v[128:129] op_sel_hi:[1,0,1] neg_lo:[1,0,0] neg_hi:[1,0,0]
	v_pk_fma_f32 v[128:129], v[90:91], v[16:17], v[128:129] op_sel:[0,1,0] op_sel_hi:[1,1,1] neg_lo:[1,0,0] neg_hi:[1,0,0]
	v_pk_fma_f32 v[128:129], v[92:93], v[18:19], v[128:129] op_sel_hi:[1,0,1] neg_lo:[1,0,0] neg_hi:[1,0,0]
	v_pk_fma_f32 v[128:129], v[94:95], v[18:19], v[128:129] op_sel:[0,1,0] op_sel_hi:[1,1,1] neg_lo:[1,0,0] neg_hi:[1,0,0]
	s_waitcnt lgkmcnt(14)
	ds_read_b128 v[248:251], v228 offset:8576
	s_waitcnt lgkmcnt(11)
	v_pk_fma_f32 v[128:129], v[96:97], v[20:21], v[128:129] op_sel_hi:[1,0,1] neg_lo:[1,0,0] neg_hi:[1,0,0]
	v_pk_fma_f32 v[128:129], v[98:99], v[20:21], v[128:129] op_sel:[0,1,0] op_sel_hi:[1,1,1] neg_lo:[1,0,0] neg_hi:[1,0,0]
	v_pk_fma_f32 v[128:129], v[100:101], v[22:23], v[128:129] op_sel_hi:[1,0,1] neg_lo:[1,0,0] neg_hi:[1,0,0]
	v_pk_fma_f32 v[128:129], v[102:103], v[22:23], v[128:129] op_sel:[0,1,0] op_sel_hi:[1,1,1] neg_lo:[1,0,0] neg_hi:[1,0,0]
	ds_read_b128 v[4:7], v228 offset:8704
	v_pk_fma_f32 v[128:129], v[104:105], v[24:25], v[128:129] op_sel_hi:[1,0,1] neg_lo:[1,0,0] neg_hi:[1,0,0]
	v_pk_fma_f32 v[128:129], v[106:107], v[24:25], v[128:129] op_sel:[0,1,0] op_sel_hi:[1,1,1] neg_lo:[1,0,0] neg_hi:[1,0,0]
	v_pk_fma_f32 v[128:129], v[108:109], v[26:27], v[128:129] op_sel_hi:[1,0,1] neg_lo:[1,0,0] neg_hi:[1,0,0]
	v_pk_fma_f32 v[128:129], v[110:111], v[26:27], v[128:129] op_sel:[0,1,0] op_sel_hi:[1,1,1] neg_lo:[1,0,0] neg_hi:[1,0,0]
	ds_read_b128 v[8:11], v228 offset:8720
	v_pk_fma_f32 v[128:129], v[112:113], v[28:29], v[128:129] op_sel_hi:[1,0,1] neg_lo:[1,0,0] neg_hi:[1,0,0]
	v_pk_fma_f32 v[128:129], v[114:115], v[28:29], v[128:129] op_sel:[0,1,0] op_sel_hi:[1,1,1] neg_lo:[1,0,0] neg_hi:[1,0,0]
	v_pk_fma_f32 v[128:129], v[116:117], v[30:31], v[128:129] op_sel_hi:[1,0,1] neg_lo:[1,0,0] neg_hi:[1,0,0]
	v_pk_fma_f32 v[128:129], v[118:119], v[30:31], v[128:129] op_sel:[0,1,0] op_sel_hi:[1,1,1] neg_lo:[1,0,0] neg_hi:[1,0,0]
	ds_read_b128 v[12:15], v228 offset:8736
	v_pk_fma_f32 v[128:129], v[120:121], v[32:33], v[128:129] op_sel_hi:[1,0,1] neg_lo:[1,0,0] neg_hi:[1,0,0]
	v_pk_fma_f32 v[128:129], v[122:123], v[32:33], v[128:129] op_sel:[0,1,0] op_sel_hi:[1,1,1] neg_lo:[1,0,0] neg_hi:[1,0,0]
	v_pk_fma_f32 v[128:129], v[124:125], v[34:35], v[128:129] op_sel_hi:[1,0,1] neg_lo:[1,0,0] neg_hi:[1,0,0]
	v_fma_mixlo_f16 v239, -v126, v35, v128
	v_fma_mixlo_f16 v240, -v127, v35, v129
	v_pk_fma_f32 v[128:129], v[126:127], v[34:35], v[128:129] op_sel:[0,1,0] op_sel_hi:[1,1,1] neg_lo:[1,0,0] neg_hi:[1,0,0]
	ds_write_b16 v253, v239 offset:25088
	s_waitcnt lgkmcnt(14)
	ds_write_b16 v253, v240 offset:25216
	s_waitcnt lgkmcnt(14)
	ds_read_b128 v[16:19], v228 offset:8752
	v_pk_fma_f32 v[130:131], v[64:65], v[36:37], v[130:131] op_sel_hi:[1,0,1] neg_lo:[1,0,0] neg_hi:[1,0,0]
	v_pk_fma_f32 v[130:131], v[66:67], v[36:37], v[130:131] op_sel:[0,1,0] op_sel_hi:[1,1,1] neg_lo:[1,0,0] neg_hi:[1,0,0]
	v_pk_fma_f32 v[130:131], v[68:69], v[38:39], v[130:131] op_sel_hi:[1,0,1] neg_lo:[1,0,0] neg_hi:[1,0,0]
	v_pk_fma_f32 v[130:131], v[70:71], v[38:39], v[130:131] op_sel:[0,1,0] op_sel_hi:[1,1,1] neg_lo:[1,0,0] neg_hi:[1,0,0]
	s_waitcnt lgkmcnt(14)
	ds_read_b128 v[20:23], v228 offset:8768
	v_pk_fma_f32 v[130:131], v[72:73], v[40:41], v[130:131] op_sel_hi:[1,0,1] neg_lo:[1,0,0] neg_hi:[1,0,0]
	v_pk_fma_f32 v[130:131], v[74:75], v[40:41], v[130:131] op_sel:[0,1,0] op_sel_hi:[1,1,1] neg_lo:[1,0,0] neg_hi:[1,0,0]
	v_pk_fma_f32 v[130:131], v[76:77], v[42:43], v[130:131] op_sel_hi:[1,0,1] neg_lo:[1,0,0] neg_hi:[1,0,0]
	v_pk_fma_f32 v[130:131], v[78:79], v[42:43], v[130:131] op_sel:[0,1,0] op_sel_hi:[1,1,1] neg_lo:[1,0,0] neg_hi:[1,0,0]
	s_waitcnt lgkmcnt(14)
	ds_read_b128 v[24:27], v228 offset:8784
	v_pk_fma_f32 v[130:131], v[80:81], v[44:45], v[130:131] op_sel_hi:[1,0,1] neg_lo:[1,0,0] neg_hi:[1,0,0]
	v_pk_fma_f32 v[130:131], v[82:83], v[44:45], v[130:131] op_sel:[0,1,0] op_sel_hi:[1,1,1] neg_lo:[1,0,0] neg_hi:[1,0,0]
	v_pk_fma_f32 v[130:131], v[84:85], v[46:47], v[130:131] op_sel_hi:[1,0,1] neg_lo:[1,0,0] neg_hi:[1,0,0]
	v_pk_fma_f32 v[130:131], v[86:87], v[46:47], v[130:131] op_sel:[0,1,0] op_sel_hi:[1,1,1] neg_lo:[1,0,0] neg_hi:[1,0,0]
	s_waitcnt lgkmcnt(14)
; #define LAS __attribute__((address_space(3)))
; __device__ __forceinline__ void phase_gdb(const int wvs, const Params& p, LAS unsigned char* lds, int nwg) {
;     ...
;       for (int i = 1; i < 64; ++i) {
; #pragma unroll
;         for (int j4 = 0; j4 < (i + 3) / 4; ++j4) { const f32x4 m4 = *(const LAS f32x4*)(M + i * 64 + j4 * 4);
; #pragma unroll
;           for (int jj = 0; jj < 4; ++jj) if (j4 * 4 + jj < i) x[i] -= m4[jj] * x[j4 * 4 + jj]; }
;         __builtin_amdgcn_sched_barrier(0); }
; #pragma unroll
;       for (int i = 0; i < 64; ++i) R[i * RP + t] = (hf)x[i]; }
	ds_read_b128 v[28:31], v228 offset:8800
	v_pk_fma_f32 v[130:131], v[88:89], v[48:49], v[130:131] op_sel_hi:[1,0,1] neg_lo:[1,0,0] neg_hi:[1,0,0]
	v_pk_fma_f32 v[130:131], v[90:91], v[48:49], v[130:131] op_sel:[0,1,0] op_sel_hi:[1,1,1] neg_lo:[1,0,0] neg_hi:[1,0,0]
	v_pk_fma_f32 v[130:131], v[92:93], v[50:51], v[130:131] op_sel_hi:[1,0,1] neg_lo:[1,0,0] neg_hi:[1,0,0]
	v_pk_fma_f32 v[130:131], v[94:95], v[50:51], v[130:131] op_sel:[0,1,0] op_sel_hi:[1,1,1] neg_lo:[1,0,0] neg_hi:[1,0,0]
	s_waitcnt lgkmcnt(14)
	ds_read_b128 v[32:35], v228 offset:8816
	s_waitcnt lgkmcnt(11)
	v_pk_fma_f32 v[130:131], v[96:97], v[52:53], v[130:131] op_sel_hi:[1,0,1] neg_lo:[1,0,0] neg_hi:[1,0,0]
	v_pk_fma_f32 v[130:131], v[98:99], v[52:53], v[130:131] op_sel:[0,1,0] op_sel_hi:[1,1,1] neg_lo:[1,0,0] neg_hi:[1,0,0]
	v_pk_fma_f32 v[130:131], v[100:101], v[54:55], v[130:131] op_sel_hi:[1,0,1] neg_lo:[1,0,0] neg_hi:[1,0,0]
	v_pk_fma_f32 v[130:131], v[102:103], v[54:55], v[130:131] op_sel:[0,1,0] op_sel_hi:[1,1,1] neg_lo:[1,0,0] neg_hi:[1,0,0]
	ds_read_b128 v[36:39], v228 offset:8832
	v_pk_fma_f32 v[130:131], v[104:105], v[56:57], v[130:131] op_sel_hi:[1,0,1] neg_lo:[1,0,0] neg_hi:[1,0,0]
	v_pk_fma_f32 v[130:131], v[106:107], v[56:57], v[130:131] op_sel:[0,1,0] op_sel_hi:[1,1,1] neg_lo:[1,0,0] neg_hi:[1,0,0]
	v_pk_fma_f32 v[130:131], v[108:109], v[58:59], v[130:131] op_sel_hi:[1,0,1] neg_lo:[1,0,0] neg_hi:[1,0,0]
	v_pk_fma_f32 v[130:131], v[110:111], v[58:59], v[130:131] op_sel:[0,1,0] op_sel_hi:[1,1,1] neg_lo:[1,0,0] neg_hi:[1,0,0]
	ds_read_b128 v[40:43], v228 offset:8960
	v_pk_fma_f32 v[130:131], v[112:113], v[60:61], v[130:131] op_sel_hi:[1,0,1] neg_lo:[1,0,0] neg_hi:[1,0,0]
	v_pk_fma_f32 v[130:131], v[114:115], v[60:61], v[130:131] op_sel:[0,1,0] op_sel_hi:[1,1,1] neg_lo:[1,0,0] neg_hi:[1,0,0]
	v_pk_fma_f32 v[130:131], v[116:117], v[62:63], v[130:131] op_sel_hi:[1,0,1] neg_lo:[1,0,0] neg_hi:[1,0,0]
	v_pk_fma_f32 v[130:131], v[118:119], v[62:63], v[130:131] op_sel:[0,1,0] op_sel_hi:[1,1,1] neg_lo:[1,0,0] neg_hi:[1,0,0]
	ds_read_b128 v[44:47], v228 offset:8976
	v_pk_fma_f32 v[130:131], v[120:121], v[244:245], v[130:131] op_sel_hi:[1,0,1] neg_lo:[1,0,0] neg_hi:[1,0,0]
	v_pk_fma_f32 v[130:131], v[122:123], v[244:245], v[130:131] op_sel:[0,1,0] op_sel_hi:[1,1,1] neg_lo:[1,0,0] neg_hi:[1,0,0]
	v_pk_fma_f32 v[130:131], v[124:125], v[246:247], v[130:131] op_sel_hi:[1,0,1] neg_lo:[1,0,0] neg_hi:[1,0,0]
	v_pk_fma_f32 v[130:131], v[126:127], v[246:247], v[130:131] op_sel:[0,1,0] op_sel_hi:[1,1,1] neg_lo:[1,0,0] neg_hi:[1,0,0]
	ds_read_b128 v[48:51], v228 offset:8992
	s_waitcnt lgkmcnt(11)
	v_fma_mixlo_f16 v0, -v128, v248, v130
	v_fma_mixlo_f16 v2, -v129, v248, v131
	v_pk_fma_f32 v[130:131], v[128:129], v[248:249], v[130:131] op_sel_hi:[1,0,1] neg_lo:[1,0,0] neg_hi:[1,0,0]
	ds_write_b16 v253, v0 offset:25360
	ds_write_b16 v253, v2 offset:25488
	ds_read_b128 v[52:55], v228 offset:9008
	v_pk_fma_f32 v[132:133], v[64:65], v[4:5], v[132:133] op_sel_hi:[1,0,1] neg_lo:[1,0,0] neg_hi:[1,0,0]
	v_pk_fma_f32 v[132:133], v[66:67], v[4:5], v[132:133] op_sel:[0,1,0] op_sel_hi:[1,1,1] neg_lo:[1,0,0] neg_hi:[1,0,0]
	v_pk_fma_f32 v[132:133], v[68:69], v[6:7], v[132:133] op_sel_hi:[1,0,1] neg_lo:[1,0,0] neg_hi:[1,0,0]
	v_pk_fma_f32 v[132:133], v[70:71], v[6:7], v[132:133] op_sel:[0,1,0] op_sel_hi:[1,1,1] neg_lo:[1,0,0] neg_hi:[1,0,0]
	ds_read_b128 v[56:59], v228 offset:9024
	v_pk_fma_f32 v[132:133], v[72:73], v[8:9], v[132:133] op_sel_hi:[1,0,1] neg_lo:[1,0,0] neg_hi:[1,0,0]
	v_pk_fma_f32 v[132:133], v[74:75], v[8:9], v[132:133] op_sel:[0,1,0] op_sel_hi:[1,1,1] neg_lo:[1,0,0] neg_hi:[1,0,0]
	v_pk_fma_f32 v[132:133], v[76:77], v[10:11], v[132:133] op_sel_hi:[1,0,1] neg_lo:[1,0,0] neg_hi:[1,0,0]
	v_pk_fma_f32 v[132:133], v[78:79], v[10:11], v[132:133] op_sel:[0,1,0] op_sel_hi:[1,1,1] neg_lo:[1,0,0] neg_hi:[1,0,0]
	s_waitcnt lgkmcnt(14)
	ds_read_b128 v[60:63], v228 offset:9040
	v_pk_fma_f32 v[132:133], v[80:81], v[12:13], v[132:133] op_sel_hi:[1,0,1] neg_lo:[1,0,0] neg_hi:[1,0,0]
	v_pk_fma_f32 v[132:133], v[82:83], v[12:13], v[132:133] op_sel:[0,1,0] op_sel_hi:[1,1,1] neg_lo:[1,0,0] neg_hi:[1,0,0]
	v_pk_fma_f32 v[132:133], v[84:85], v[14:15], v[132:133] op_sel_hi:[1,0,1] neg_lo:[1,0,0] neg_hi:[1,0,0]
	v_pk_fma_f32 v[132:133], v[86:87], v[14:15], v[132:133] op_sel:[0,1,0] op_sel_hi:[1,1,1] neg_lo:[1,0,0] neg_hi:[1,0,0]
	s_waitcnt lgkmcnt(14)
	ds_read_b128 v[244:247], v228 offset:9056
	s_waitcnt lgkmcnt(11)
	v_pk_fma_f32 v[132:133], v[88:89], v[16:17], v[132:133] op_sel_hi:[1,0,1] neg_lo:[1,0,0] neg_hi:[1,0,0]
	v_pk_fma_f32 v[132:133], v[90:91], v[16:17], v[132:133] op_sel:[0,1,0] op_sel_hi:[1,1,1] neg_lo:[1,0,0] neg_hi:[1,0,0]
	v_pk_fma_f32 v[132:133], v[92:93], v[18:19], v[132:133] op_sel_hi:[1,0,1] neg_lo:[1,0,0] neg_hi:[1,0,0]
	v_pk_fma_f32 v[132:133], v[94:95], v[18:19], v[132:133] op_sel:[0,1,0] op_sel_hi:[1,1,1] neg_lo:[1,0,0] neg_hi:[1,0,0]
	ds_read_b128 v[248:251], v228 offset:9072
	v_pk_fma_f32 v[132:133], v[96:97], v[20:21], v[132:133] op_sel_hi:[1,0,1] neg_lo:[1,0,0] neg_hi:[1,0,0]
	v_pk_fma_f32 v[132:133], v[98:99], v[20:21], v[132:133] op_sel:[0,1,0] op_sel_hi:[1,1,1] neg_lo:[1,0,0] neg_hi:[1,0,0]
	v_pk_fma_f32 v[132:133], v[100:101], v[22:23], v[132:133] op_sel_hi:[1,0,1] neg_lo:[1,0,0] neg_hi:[1,0,0]
	v_pk_fma_f32 v[132:133], v[102:103], v[22:23], v[132:133] op_sel:[0,1,0] op_sel_hi:[1,1,1] neg_lo:[1,0,0] neg_hi:[1,0,0]
	ds_read_b128 v[4:7], v228 offset:9088
	v_pk_fma_f32 v[132:133], v[104:105], v[24:25], v[132:133] op_sel_hi:[1,0,1] neg_lo:[1,0,0] neg_hi:[1,0,0]
	v_pk_fma_f32 v[132:133], v[106:107], v[24:25], v[132:133] op_sel:[0,1,0] op_sel_hi:[1,1,1] neg_lo:[1,0,0] neg_hi:[1,0,0]
	v_pk_fma_f32 v[132:133], v[108:109], v[26:27], v[132:133] op_sel_hi:[1,0,1] neg_lo:[1,0,0] neg_hi:[1,0,0]
	v_pk_fma_f32 v[132:133], v[110:111], v[26:27], v[132:133] op_sel:[0,1,0] op_sel_hi:[1,1,1] neg_lo:[1,0,0] neg_hi:[1,0,0]
	ds_read_b128 v[8:11], v228 offset:9216
	v_pk_fma_f32 v[132:133], v[112:113], v[28:29], v[132:133] op_sel_hi:[1,0,1] neg_lo:[1,0,0] neg_hi:[1,0,0]
	v_pk_fma_f32 v[132:133], v[114:115], v[28:29], v[132:133] op_sel:[0,1,0] op_sel_hi:[1,1,1] neg_lo:[1,0,0] neg_hi:[1,0,0]
	v_pk_fma_f32 v[132:133], v[116:117], v[30:31], v[132:133] op_sel_hi:[1,0,1] neg_lo:[1,0,0] neg_hi:[1,0,0]
	v_pk_fma_f32 v[132:133], v[118:119], v[30:31], v[132:133] op_sel:[0,1,0] op_sel_hi:[1,1,1] neg_lo:[1,0,0] neg_hi:[1,0,0]
	ds_read_b128 v[12:15], v228 offset:9232
	s_waitcnt lgkmcnt(11)
; #define LAS __attribute__((address_space(3)))
; __device__ __forceinline__ void phase_gdb(const int wvs, const Params& p, LAS unsigned char* lds, int nwg) {
;     ...
;       for (int i = 1; i < 64; ++i) {
; #pragma unroll
;         for (int j4 = 0; j4 < (i + 3) / 4; ++j4) { const f32x4 m4 = *(const LAS f32x4*)(M + i * 64 + j4 * 4);
; #pragma unroll
;           for (int jj = 0; jj < 4; ++jj) if (j4 * 4 + jj < i) x[i] -= m4[jj] * x[j4 * 4 + jj]; }
;         __builtin_amdgcn_sched_barrier(0); }
; #pragma unroll
;       for (int i = 0; i < 64; ++i) R[i * RP + t] = (hf)x[i]; }
	v_pk_fma_f32 v[132:133], v[120:121], v[32:33], v[132:133] op_sel_hi:[1,0,1] neg_lo:[1,0,0] neg_hi:[1,0,0]
	v_pk_fma_f32 v[132:133], v[122:123], v[32:33], v[132:133] op_sel:[0,1,0] op_sel_hi:[1,1,1] neg_lo:[1,0,0] neg_hi:[1,0,0]
	v_pk_fma_f32 v[132:133], v[124:125], v[34:35], v[132:133] op_sel_hi:[1,0,1] neg_lo:[1,0,0] neg_hi:[1,0,0]
	v_pk_fma_f32 v[132:133], v[126:127], v[34:35], v[132:133] op_sel:[0,1,0] op_sel_hi:[1,1,1] neg_lo:[1,0,0] neg_hi:[1,0,0]
	ds_read_b128 v[16:19], v228 offset:9248
	v_pk_fma_f32 v[132:133], v[128:129], v[36:37], v[132:133] op_sel_hi:[1,0,1] neg_lo:[1,0,0] neg_hi:[1,0,0]
	v_fma_mixlo_f16 v3, -v130, v37, v132
	v_fma_mixlo_f16 v238, -v131, v37, v133
	v_pk_fma_f32 v[132:133], v[130:131], v[36:37], v[132:133] op_sel:[0,1,0] op_sel_hi:[1,1,1] neg_lo:[1,0,0] neg_hi:[1,0,0]
	ds_write_b16 v253, v3 offset:25632
	ds_write_b16 v253, v238 offset:25760
	ds_read_b128 v[20:23], v228 offset:9264
	v_pk_fma_f32 v[134:135], v[64:65], v[40:41], v[134:135] op_sel_hi:[1,0,1] neg_lo:[1,0,0] neg_hi:[1,0,0]
	v_pk_fma_f32 v[134:135], v[66:67], v[40:41], v[134:135] op_sel:[0,1,0] op_sel_hi:[1,1,1] neg_lo:[1,0,0] neg_hi:[1,0,0]
	v_pk_fma_f32 v[134:135], v[68:69], v[42:43], v[134:135] op_sel_hi:[1,0,1] neg_lo:[1,0,0] neg_hi:[1,0,0]
	v_pk_fma_f32 v[134:135], v[70:71], v[42:43], v[134:135] op_sel:[0,1,0] op_sel_hi:[1,1,1] neg_lo:[1,0,0] neg_hi:[1,0,0]
	s_waitcnt lgkmcnt(14)
	ds_read_b128 v[24:27], v228 offset:9280
	v_pk_fma_f32 v[134:135], v[72:73], v[44:45], v[134:135] op_sel_hi:[1,0,1] neg_lo:[1,0,0] neg_hi:[1,0,0]
	v_pk_fma_f32 v[134:135], v[74:75], v[44:45], v[134:135] op_sel:[0,1,0] op_sel_hi:[1,1,1] neg_lo:[1,0,0] neg_hi:[1,0,0]
	v_pk_fma_f32 v[134:135], v[76:77], v[46:47], v[134:135] op_sel_hi:[1,0,1] neg_lo:[1,0,0] neg_hi:[1,0,0]
	v_pk_fma_f32 v[134:135], v[78:79], v[46:47], v[134:135] op_sel:[0,1,0] op_sel_hi:[1,1,1] neg_lo:[1,0,0] neg_hi:[1,0,0]
	s_waitcnt lgkmcnt(14)
	ds_read_b128 v[28:31], v228 offset:9296
	v_pk_fma_f32 v[134:135], v[80:81], v[48:49], v[134:135] op_sel_hi:[1,0,1] neg_lo:[1,0,0] neg_hi:[1,0,0]
	v_pk_fma_f32 v[134:135], v[82:83], v[48:49], v[134:135] op_sel:[0,1,0] op_sel_hi:[1,1,1] neg_lo:[1,0,0] neg_hi:[1,0,0]
	v_pk_fma_f32 v[134:135], v[84:85], v[50:51], v[134:135] op_sel_hi:[1,0,1] neg_lo:[1,0,0] neg_hi:[1,0,0]
	v_pk_fma_f32 v[134:135], v[86:87], v[50:51], v[134:135] op_sel:[0,1,0] op_sel_hi:[1,1,1] neg_lo:[1,0,0] neg_hi:[1,0,0]
	s_waitcnt lgkmcnt(14)
	ds_read_b128 v[32:35], v228 offset:9312
	s_waitcnt lgkmcnt(11)
	v_pk_fma_f32 v[134:135], v[88:89], v[52:53], v[134:135] op_sel_hi:[1,0,1] neg_lo:[1,0,0] neg_hi:[1,0,0]
	v_pk_fma_f32 v[134:135], v[90:91], v[52:53], v[134:135] op_sel:[0,1,0] op_sel_hi:[1,1,1] neg_lo:[1,0,0] neg_hi:[1,0,0]
	v_pk_fma_f32 v[134:135], v[92:93], v[54:55], v[134:135] op_sel_hi:[1,0,1] neg_lo:[1,0,0] neg_hi:[1,0,0]
	v_pk_fma_f32 v[134:135], v[94:95], v[54:55], v[134:135] op_sel:[0,1,0] op_sel_hi:[1,1,1] neg_lo:[1,0,0] neg_hi:[1,0,0]
	ds_read_b128 v[36:39], v228 offset:9328
	v_pk_fma_f32 v[134:135], v[96:97], v[56:57], v[134:135] op_sel_hi:[1,0,1] neg_lo:[1,0,0] neg_hi:[1,0,0]
	v_pk_fma_f32 v[134:135], v[98:99], v[56:57], v[134:135] op_sel:[0,1,0] op_sel_hi:[1,1,1] neg_lo:[1,0,0] neg_hi:[1,0,0]
	v_pk_fma_f32 v[134:135], v[100:101], v[58:59], v[134:135] op_sel_hi:[1,0,1] neg_lo:[1,0,0] neg_hi:[1,0,0]
	v_pk_fma_f32 v[134:135], v[102:103], v[58:59], v[134:135] op_sel:[0,1,0] op_sel_hi:[1,1,1] neg_lo:[1,0,0] neg_hi:[1,0,0]
	ds_read_b128 v[40:43], v228 offset:9344
	v_pk_fma_f32 v[134:135], v[104:105], v[60:61], v[134:135] op_sel_hi:[1,0,1] neg_lo:[1,0,0] neg_hi:[1,0,0]
	v_pk_fma_f32 v[134:135], v[106:107], v[60:61], v[134:135] op_sel:[0,1,0] op_sel_hi:[1,1,1] neg_lo:[1,0,0] neg_hi:[1,0,0]
	v_pk_fma_f32 v[134:135], v[108:109], v[62:63], v[134:135] op_sel_hi:[1,0,1] neg_lo:[1,0,0] neg_hi:[1,0,0]
	v_pk_fma_f32 v[134:135], v[110:111], v[62:63], v[134:135] op_sel:[0,1,0] op_sel_hi:[1,1,1] neg_lo:[1,0,0] neg_hi:[1,0,0]
	ds_read_b128 v[44:47], v228 offset:9472
	v_pk_fma_f32 v[134:135], v[112:113], v[244:245], v[134:135] op_sel_hi:[1,0,1] neg_lo:[1,0,0] neg_hi:[1,0,0]
	v_pk_fma_f32 v[134:135], v[114:115], v[244:245], v[134:135] op_sel:[0,1,0] op_sel_hi:[1,1,1] neg_lo:[1,0,0] neg_hi:[1,0,0]
	v_pk_fma_f32 v[134:135], v[116:117], v[246:247], v[134:135] op_sel_hi:[1,0,1] neg_lo:[1,0,0] neg_hi:[1,0,0]
	v_pk_fma_f32 v[134:135], v[118:119], v[246:247], v[134:135] op_sel:[0,1,0] op_sel_hi:[1,1,1] neg_lo:[1,0,0] neg_hi:[1,0,0]
	ds_read_b128 v[48:51], v228 offset:9488
	s_waitcnt lgkmcnt(11)
	v_pk_fma_f32 v[134:135], v[120:121], v[248:249], v[134:135] op_sel_hi:[1,0,1] neg_lo:[1,0,0] neg_hi:[1,0,0]
	v_pk_fma_f32 v[134:135], v[122:123], v[248:249], v[134:135] op_sel:[0,1,0] op_sel_hi:[1,1,1] neg_lo:[1,0,0] neg_hi:[1,0,0]
	v_pk_fma_f32 v[134:135], v[124:125], v[250:251], v[134:135] op_sel_hi:[1,0,1] neg_lo:[1,0,0] neg_hi:[1,0,0]
	v_pk_fma_f32 v[134:135], v[126:127], v[250:251], v[134:135] op_sel:[0,1,0] op_sel_hi:[1,1,1] neg_lo:[1,0,0] neg_hi:[1,0,0]
	ds_read_b128 v[52:55], v228 offset:9504
	v_pk_fma_f32 v[134:135], v[128:129], v[4:5], v[134:135] op_sel_hi:[1,0,1] neg_lo:[1,0,0] neg_hi:[1,0,0]
	v_pk_fma_f32 v[134:135], v[130:131], v[4:5], v[134:135] op_sel:[0,1,0] op_sel_hi:[1,1,1] neg_lo:[1,0,0] neg_hi:[1,0,0]
	v_fma_mixlo_f16 v239, -v132, v6, v134
	v_fma_mixlo_f16 v240, -v133, v6, v135
	v_pk_fma_f32 v[134:135], v[132:133], v[6:7], v[134:135] op_sel_hi:[1,0,1] neg_lo:[1,0,0] neg_hi:[1,0,0]
	ds_write_b16 v253, v239 offset:25904
	ds_write_b16 v253, v240 offset:26032
	ds_read_b128 v[56:59], v228 offset:9520
	v_pk_fma_f32 v[136:137], v[64:65], v[8:9], v[136:137] op_sel_hi:[1,0,1] neg_lo:[1,0,0] neg_hi:[1,0,0]
	v_pk_fma_f32 v[136:137], v[66:67], v[8:9], v[136:137] op_sel:[0,1,0] op_sel_hi:[1,1,1] neg_lo:[1,0,0] neg_hi:[1,0,0]
	v_pk_fma_f32 v[136:137], v[68:69], v[10:11], v[136:137] op_sel_hi:[1,0,1] neg_lo:[1,0,0] neg_hi:[1,0,0]
	v_pk_fma_f32 v[136:137], v[70:71], v[10:11], v[136:137] op_sel:[0,1,0] op_sel_hi:[1,1,1] neg_lo:[1,0,0] neg_hi:[1,0,0]
	s_waitcnt lgkmcnt(14)
; #define LAS __attribute__((address_space(3)))
; __device__ __forceinline__ void phase_gdb(const int wvs, const Params& p, LAS unsigned char* lds, int nwg) {
;     ...
;       for (int i = 1; i < 64; ++i) {
; #pragma unroll
;         for (int j4 = 0; j4 < (i + 3) / 4; ++j4) { const f32x4 m4 = *(const LAS f32x4*)(M + i * 64 + j4 * 4);
; #pragma unroll
;           for (int jj = 0; jj < 4; ++jj) if (j4 * 4 + jj < i) x[i] -= m4[jj] * x[j4 * 4 + jj]; }
;         __builtin_amdgcn_sched_barrier(0); }
; #pragma unroll
;       for (int i = 0; i < 64; ++i) R[i * RP + t] = (hf)x[i]; }
	ds_read_b128 v[60:63], v228 offset:9536
	v_pk_fma_f32 v[136:137], v[72:73], v[12:13], v[136:137] op_sel_hi:[1,0,1] neg_lo:[1,0,0] neg_hi:[1,0,0]
	v_pk_fma_f32 v[136:137], v[74:75], v[12:13], v[136:137] op_sel:[0,1,0] op_sel_hi:[1,1,1] neg_lo:[1,0,0] neg_hi:[1,0,0]
	v_pk_fma_f32 v[136:137], v[76:77], v[14:15], v[136:137] op_sel_hi:[1,0,1] neg_lo:[1,0,0] neg_hi:[1,0,0]
	v_pk_fma_f32 v[136:137], v[78:79], v[14:15], v[136:137] op_sel:[0,1,0] op_sel_hi:[1,1,1] neg_lo:[1,0,0] neg_hi:[1,0,0]
	s_waitcnt lgkmcnt(14)
	ds_read_b128 v[244:247], v228 offset:9552
	v_pk_fma_f32 v[136:137], v[80:81], v[16:17], v[136:137] op_sel_hi:[1,0,1] neg_lo:[1,0,0] neg_hi:[1,0,0]
	v_pk_fma_f32 v[136:137], v[82:83], v[16:17], v[136:137] op_sel:[0,1,0] op_sel_hi:[1,1,1] neg_lo:[1,0,0] neg_hi:[1,0,0]
	v_pk_fma_f32 v[136:137], v[84:85], v[18:19], v[136:137] op_sel_hi:[1,0,1] neg_lo:[1,0,0] neg_hi:[1,0,0]
	v_pk_fma_f32 v[136:137], v[86:87], v[18:19], v[136:137] op_sel:[0,1,0] op_sel_hi:[1,1,1] neg_lo:[1,0,0] neg_hi:[1,0,0]
	s_waitcnt lgkmcnt(14)
	ds_read_b128 v[248:251], v228 offset:9568
	s_waitcnt lgkmcnt(11)
	v_pk_fma_f32 v[136:137], v[88:89], v[20:21], v[136:137] op_sel_hi:[1,0,1] neg_lo:[1,0,0] neg_hi:[1,0,0]
	v_pk_fma_f32 v[136:137], v[90:91], v[20:21], v[136:137] op_sel:[0,1,0] op_sel_hi:[1,1,1] neg_lo:[1,0,0] neg_hi:[1,0,0]
	v_pk_fma_f32 v[136:137], v[92:93], v[22:23], v[136:137] op_sel_hi:[1,0,1] neg_lo:[1,0,0] neg_hi:[1,0,0]
	v_pk_fma_f32 v[136:137], v[94:95], v[22:23], v[136:137] op_sel:[0,1,0] op_sel_hi:[1,1,1] neg_lo:[1,0,0] neg_hi:[1,0,0]
	ds_read_b128 v[4:7], v228 offset:9584
	v_pk_fma_f32 v[136:137], v[96:97], v[24:25], v[136:137] op_sel_hi:[1,0,1] neg_lo:[1,0,0] neg_hi:[1,0,0]
	v_pk_fma_f32 v[136:137], v[98:99], v[24:25], v[136:137] op_sel:[0,1,0] op_sel_hi:[1,1,1] neg_lo:[1,0,0] neg_hi:[1,0,0]
	v_pk_fma_f32 v[136:137], v[100:101], v[26:27], v[136:137] op_sel_hi:[1,0,1] neg_lo:[1,0,0] neg_hi:[1,0,0]
	v_pk_fma_f32 v[136:137], v[102:103], v[26:27], v[136:137] op_sel:[0,1,0] op_sel_hi:[1,1,1] neg_lo:[1,0,0] neg_hi:[1,0,0]
	ds_read_b128 v[8:11], v228 offset:9600
	v_pk_fma_f32 v[136:137], v[104:105], v[28:29], v[136:137] op_sel_hi:[1,0,1] neg_lo:[1,0,0] neg_hi:[1,0,0]
	v_pk_fma_f32 v[136:137], v[106:107], v[28:29], v[136:137] op_sel:[0,1,0] op_sel_hi:[1,1,1] neg_lo:[1,0,0] neg_hi:[1,0,0]
	v_pk_fma_f32 v[136:137], v[108:109], v[30:31], v[136:137] op_sel_hi:[1,0,1] neg_lo:[1,0,0] neg_hi:[1,0,0]
	v_pk_fma_f32 v[136:137], v[110:111], v[30:31], v[136:137] op_sel:[0,1,0] op_sel_hi:[1,1,1] neg_lo:[1,0,0] neg_hi:[1,0,0]
	ds_read_b128 v[12:15], v228 offset:9616
	v_pk_fma_f32 v[136:137], v[112:113], v[32:33], v[136:137] op_sel_hi:[1,0,1] neg_lo:[1,0,0] neg_hi:[1,0,0]
	v_pk_fma_f32 v[136:137], v[114:115], v[32:33], v[136:137] op_sel:[0,1,0] op_sel_hi:[1,1,1] neg_lo:[1,0,0] neg_hi:[1,0,0]
	v_pk_fma_f32 v[136:137], v[116:117], v[34:35], v[136:137] op_sel_hi:[1,0,1] neg_lo:[1,0,0] neg_hi:[1,0,0]
	v_pk_fma_f32 v[136:137], v[118:119], v[34:35], v[136:137] op_sel:[0,1,0] op_sel_hi:[1,1,1] neg_lo:[1,0,0] neg_hi:[1,0,0]
	ds_read_b128 v[16:19], v228 offset:9728
	s_waitcnt lgkmcnt(11)
	v_pk_fma_f32 v[136:137], v[120:121], v[36:37], v[136:137] op_sel_hi:[1,0,1] neg_lo:[1,0,0] neg_hi:[1,0,0]
	v_pk_fma_f32 v[136:137], v[122:123], v[36:37], v[136:137] op_sel:[0,1,0] op_sel_hi:[1,1,1] neg_lo:[1,0,0] neg_hi:[1,0,0]
	v_pk_fma_f32 v[136:137], v[124:125], v[38:39], v[136:137] op_sel_hi:[1,0,1] neg_lo:[1,0,0] neg_hi:[1,0,0]
	v_pk_fma_f32 v[136:137], v[126:127], v[38:39], v[136:137] op_sel:[0,1,0] op_sel_hi:[1,1,1] neg_lo:[1,0,0] neg_hi:[1,0,0]
	ds_read_b128 v[20:23], v228 offset:9744
	v_pk_fma_f32 v[136:137], v[128:129], v[40:41], v[136:137] op_sel_hi:[1,0,1] neg_lo:[1,0,0] neg_hi:[1,0,0]
	v_pk_fma_f32 v[136:137], v[130:131], v[40:41], v[136:137] op_sel:[0,1,0] op_sel_hi:[1,1,1] neg_lo:[1,0,0] neg_hi:[1,0,0]
	v_pk_fma_f32 v[136:137], v[132:133], v[42:43], v[136:137] op_sel_hi:[1,0,1] neg_lo:[1,0,0] neg_hi:[1,0,0]
	v_fma_mixlo_f16 v0, -v134, v43, v136
	v_fma_mixlo_f16 v2, -v135, v43, v137
	v_pk_fma_f32 v[136:137], v[134:135], v[42:43], v[136:137] op_sel:[0,1,0] op_sel_hi:[1,1,1] neg_lo:[1,0,0] neg_hi:[1,0,0]
	ds_write_b16 v253, v0 offset:26176
	ds_write_b16 v253, v2 offset:26304
	ds_read_b128 v[24:27], v228 offset:9760
	v_pk_fma_f32 v[138:139], v[64:65], v[44:45], v[138:139] op_sel_hi:[1,0,1] neg_lo:[1,0,0] neg_hi:[1,0,0]
	v_pk_fma_f32 v[138:139], v[66:67], v[44:45], v[138:139] op_sel:[0,1,0] op_sel_hi:[1,1,1] neg_lo:[1,0,0] neg_hi:[1,0,0]
	v_pk_fma_f32 v[138:139], v[68:69], v[46:47], v[138:139] op_sel_hi:[1,0,1] neg_lo:[1,0,0] neg_hi:[1,0,0]
	v_pk_fma_f32 v[138:139], v[70:71], v[46:47], v[138:139] op_sel:[0,1,0] op_sel_hi:[1,1,1] neg_lo:[1,0,0] neg_hi:[1,0,0]
	s_waitcnt lgkmcnt(14)
	ds_read_b128 v[28:31], v228 offset:9776
	v_pk_fma_f32 v[138:139], v[72:73], v[48:49], v[138:139] op_sel_hi:[1,0,1] neg_lo:[1,0,0] neg_hi:[1,0,0]
	v_pk_fma_f32 v[138:139], v[74:75], v[48:49], v[138:139] op_sel:[0,1,0] op_sel_hi:[1,1,1] neg_lo:[1,0,0] neg_hi:[1,0,0]
	v_pk_fma_f32 v[138:139], v[76:77], v[50:51], v[138:139] op_sel_hi:[1,0,1] neg_lo:[1,0,0] neg_hi:[1,0,0]
	v_pk_fma_f32 v[138:139], v[78:79], v[50:51], v[138:139] op_sel:[0,1,0] op_sel_hi:[1,1,1] neg_lo:[1,0,0] neg_hi:[1,0,0]
	s_waitcnt lgkmcnt(14)
	ds_read_b128 v[32:35], v228 offset:9792
	v_pk_fma_f32 v[138:139], v[80:81], v[52:53], v[138:139] op_sel_hi:[1,0,1] neg_lo:[1,0,0] neg_hi:[1,0,0]
	v_pk_fma_f32 v[138:139], v[82:83], v[52:53], v[138:139] op_sel:[0,1,0] op_sel_hi:[1,1,1] neg_lo:[1,0,0] neg_hi:[1,0,0]
	v_pk_fma_f32 v[138:139], v[84:85], v[54:55], v[138:139] op_sel_hi:[1,0,1] neg_lo:[1,0,0] neg_hi:[1,0,0]
	v_pk_fma_f32 v[138:139], v[86:87], v[54:55], v[138:139] op_sel:[0,1,0] op_sel_hi:[1,1,1] neg_lo:[1,0,0] neg_hi:[1,0,0]
	s_waitcnt lgkmcnt(14)
; #define LAS __attribute__((address_space(3)))
; __device__ __forceinline__ void phase_gdb(const int wvs, const Params& p, LAS unsigned char* lds, int nwg) {
;     ...
;     { float x[64]; const bool isw = t >= 64;
; #pragma unroll
;       for (int i = 0; i < 64; ++i) { const float v = (float)R[i * RP + t]; x[i] = v * bs[i] * (isw ? __expf(gcs[i]) : 1.0f); asm volatile("" : "+v"(x[i])); if ((i & 7) == 7) __builtin_amdgcn_sched_barrier(0); }
; #pragma unroll
;       for (int i = 1; i < 64; ++i) {
; #pragma unroll
;         for (int j4 = 0; j4 < (i + 3) / 4; ++j4) { const f32x4 m4 = *(const LAS f32x4*)(M + i * 64 + j4 * 4);
; #pragma unroll
;           for (int jj = 0; jj < 4; ++jj) if (j4 * 4 + jj < i) x[i] -= m4[jj] * x[j4 * 4 + jj]; }
;         __builtin_amdgcn_sched_barrier(0); }
; #pragma unroll
;       for (int i = 0; i < 64; ++i) R[i * RP + t] = (hf)x[i]; }
	ds_read_b128 v[36:39], v228 offset:9808
	s_waitcnt lgkmcnt(11)
	v_pk_fma_f32 v[138:139], v[88:89], v[56:57], v[138:139] op_sel_hi:[1,0,1] neg_lo:[1,0,0] neg_hi:[1,0,0]
	v_pk_fma_f32 v[138:139], v[90:91], v[56:57], v[138:139] op_sel:[0,1,0] op_sel_hi:[1,1,1] neg_lo:[1,0,0] neg_hi:[1,0,0]
	v_pk_fma_f32 v[138:139], v[92:93], v[58:59], v[138:139] op_sel_hi:[1,0,1] neg_lo:[1,0,0] neg_hi:[1,0,0]
	v_pk_fma_f32 v[138:139], v[94:95], v[58:59], v[138:139] op_sel:[0,1,0] op_sel_hi:[1,1,1] neg_lo:[1,0,0] neg_hi:[1,0,0]
	ds_read_b128 v[40:43], v228 offset:9824
	v_pk_fma_f32 v[138:139], v[96:97], v[60:61], v[138:139] op_sel_hi:[1,0,1] neg_lo:[1,0,0] neg_hi:[1,0,0]
	v_pk_fma_f32 v[138:139], v[98:99], v[60:61], v[138:139] op_sel:[0,1,0] op_sel_hi:[1,1,1] neg_lo:[1,0,0] neg_hi:[1,0,0]
	v_pk_fma_f32 v[138:139], v[100:101], v[62:63], v[138:139] op_sel_hi:[1,0,1] neg_lo:[1,0,0] neg_hi:[1,0,0]
	v_pk_fma_f32 v[138:139], v[102:103], v[62:63], v[138:139] op_sel:[0,1,0] op_sel_hi:[1,1,1] neg_lo:[1,0,0] neg_hi:[1,0,0]
	ds_read_b128 v[44:47], v228 offset:9840
	v_pk_fma_f32 v[138:139], v[104:105], v[244:245], v[138:139] op_sel_hi:[1,0,1] neg_lo:[1,0,0] neg_hi:[1,0,0]
	v_pk_fma_f32 v[138:139], v[106:107], v[244:245], v[138:139] op_sel:[0,1,0] op_sel_hi:[1,1,1] neg_lo:[1,0,0] neg_hi:[1,0,0]
	v_pk_fma_f32 v[138:139], v[108:109], v[246:247], v[138:139] op_sel_hi:[1,0,1] neg_lo:[1,0,0] neg_hi:[1,0,0]
	v_pk_fma_f32 v[138:139], v[110:111], v[246:247], v[138:139] op_sel:[0,1,0] op_sel_hi:[1,1,1] neg_lo:[1,0,0] neg_hi:[1,0,0]
	ds_read_b128 v[48:51], v228 offset:9856
	v_pk_fma_f32 v[138:139], v[112:113], v[248:249], v[138:139] op_sel_hi:[1,0,1] neg_lo:[1,0,0] neg_hi:[1,0,0]
	v_pk_fma_f32 v[138:139], v[114:115], v[248:249], v[138:139] op_sel:[0,1,0] op_sel_hi:[1,1,1] neg_lo:[1,0,0] neg_hi:[1,0,0]
	v_pk_fma_f32 v[138:139], v[116:117], v[250:251], v[138:139] op_sel_hi:[1,0,1] neg_lo:[1,0,0] neg_hi:[1,0,0]
	v_pk_fma_f32 v[138:139], v[118:119], v[250:251], v[138:139] op_sel:[0,1,0] op_sel_hi:[1,1,1] neg_lo:[1,0,0] neg_hi:[1,0,0]
	ds_read_b128 v[52:55], v228 offset:9872
	s_waitcnt lgkmcnt(11)
	v_pk_fma_f32 v[138:139], v[120:121], v[4:5], v[138:139] op_sel_hi:[1,0,1] neg_lo:[1,0,0] neg_hi:[1,0,0]
	v_pk_fma_f32 v[138:139], v[122:123], v[4:5], v[138:139] op_sel:[0,1,0] op_sel_hi:[1,1,1] neg_lo:[1,0,0] neg_hi:[1,0,0]
	v_pk_fma_f32 v[138:139], v[124:125], v[6:7], v[138:139] op_sel_hi:[1,0,1] neg_lo:[1,0,0] neg_hi:[1,0,0]
	v_pk_fma_f32 v[138:139], v[126:127], v[6:7], v[138:139] op_sel:[0,1,0] op_sel_hi:[1,1,1] neg_lo:[1,0,0] neg_hi:[1,0,0]
	ds_read_b128 v[56:59], v228 offset:9984
	v_pk_fma_f32 v[138:139], v[128:129], v[8:9], v[138:139] op_sel_hi:[1,0,1] neg_lo:[1,0,0] neg_hi:[1,0,0]
	v_pk_fma_f32 v[138:139], v[130:131], v[8:9], v[138:139] op_sel:[0,1,0] op_sel_hi:[1,1,1] neg_lo:[1,0,0] neg_hi:[1,0,0]
	v_pk_fma_f32 v[138:139], v[132:133], v[10:11], v[138:139] op_sel_hi:[1,0,1] neg_lo:[1,0,0] neg_hi:[1,0,0]
	v_pk_fma_f32 v[138:139], v[134:135], v[10:11], v[138:139] op_sel:[0,1,0] op_sel_hi:[1,1,1] neg_lo:[1,0,0] neg_hi:[1,0,0]
	ds_read_b128 v[60:63], v228 offset:10000
	v_fma_mixlo_f16 v3, -v136, v12, v138
	v_fma_mixlo_f16 v238, -v137, v12, v139
	v_pk_fma_f32 v[138:139], v[136:137], v[12:13], v[138:139] op_sel_hi:[1,0,1] neg_lo:[1,0,0] neg_hi:[1,0,0]
	ds_write_b16 v253, v3 offset:26448
	ds_write_b16 v253, v238 offset:26576
	s_waitcnt lgkmcnt(14)
	ds_read_b128 v[244:247], v228 offset:10016
	v_pk_fma_f32 v[140:141], v[64:65], v[16:17], v[140:141] op_sel_hi:[1,0,1] neg_lo:[1,0,0] neg_hi:[1,0,0]
	v_pk_fma_f32 v[140:141], v[66:67], v[16:17], v[140:141] op_sel:[0,1,0] op_sel_hi:[1,1,1] neg_lo:[1,0,0] neg_hi:[1,0,0]
	v_pk_fma_f32 v[140:141], v[68:69], v[18:19], v[140:141] op_sel_hi:[1,0,1] neg_lo:[1,0,0] neg_hi:[1,0,0]
	v_pk_fma_f32 v[140:141], v[70:71], v[18:19], v[140:141] op_sel:[0,1,0] op_sel_hi:[1,1,1] neg_lo:[1,0,0] neg_hi:[1,0,0]
	s_waitcnt lgkmcnt(14)
	ds_read_b128 v[248:251], v228 offset:10032
	v_pk_fma_f32 v[140:141], v[72:73], v[20:21], v[140:141] op_sel_hi:[1,0,1] neg_lo:[1,0,0] neg_hi:[1,0,0]
	v_pk_fma_f32 v[140:141], v[74:75], v[20:21], v[140:141] op_sel:[0,1,0] op_sel_hi:[1,1,1] neg_lo:[1,0,0] neg_hi:[1,0,0]
	v_pk_fma_f32 v[140:141], v[76:77], v[22:23], v[140:141] op_sel_hi:[1,0,1] neg_lo:[1,0,0] neg_hi:[1,0,0]
	v_pk_fma_f32 v[140:141], v[78:79], v[22:23], v[140:141] op_sel:[0,1,0] op_sel_hi:[1,1,1] neg_lo:[1,0,0] neg_hi:[1,0,0]
	s_waitcnt lgkmcnt(14)
	ds_read_b128 v[4:7], v228 offset:10048
	s_waitcnt lgkmcnt(11)
	v_pk_fma_f32 v[140:141], v[80:81], v[24:25], v[140:141] op_sel_hi:[1,0,1] neg_lo:[1,0,0] neg_hi:[1,0,0]
	v_pk_fma_f32 v[140:141], v[82:83], v[24:25], v[140:141] op_sel:[0,1,0] op_sel_hi:[1,1,1] neg_lo:[1,0,0] neg_hi:[1,0,0]
	v_pk_fma_f32 v[140:141], v[84:85], v[26:27], v[140:141] op_sel_hi:[1,0,1] neg_lo:[1,0,0] neg_hi:[1,0,0]
	v_pk_fma_f32 v[140:141], v[86:87], v[26:27], v[140:141] op_sel:[0,1,0] op_sel_hi:[1,1,1] neg_lo:[1,0,0] neg_hi:[1,0,0]
	ds_read_b128 v[8:11], v228 offset:10064
	v_pk_fma_f32 v[140:141], v[88:89], v[28:29], v[140:141] op_sel_hi:[1,0,1] neg_lo:[1,0,0] neg_hi:[1,0,0]
	v_pk_fma_f32 v[140:141], v[90:91], v[28:29], v[140:141] op_sel:[0,1,0] op_sel_hi:[1,1,1] neg_lo:[1,0,0] neg_hi:[1,0,0]
	v_pk_fma_f32 v[140:141], v[92:93], v[30:31], v[140:141] op_sel_hi:[1,0,1] neg_lo:[1,0,0] neg_hi:[1,0,0]
	v_pk_fma_f32 v[140:141], v[94:95], v[30:31], v[140:141] op_sel:[0,1,0] op_sel_hi:[1,1,1] neg_lo:[1,0,0] neg_hi:[1,0,0]
	ds_read_b128 v[12:15], v228 offset:10080
	v_pk_fma_f32 v[140:141], v[96:97], v[32:33], v[140:141] op_sel_hi:[1,0,1] neg_lo:[1,0,0] neg_hi:[1,0,0]
	v_pk_fma_f32 v[140:141], v[98:99], v[32:33], v[140:141] op_sel:[0,1,0] op_sel_hi:[1,1,1] neg_lo:[1,0,0] neg_hi:[1,0,0]
	v_pk_fma_f32 v[140:141], v[100:101], v[34:35], v[140:141] op_sel_hi:[1,0,1] neg_lo:[1,0,0] neg_hi:[1,0,0]
	v_pk_fma_f32 v[140:141], v[102:103], v[34:35], v[140:141] op_sel:[0,1,0] op_sel_hi:[1,1,1] neg_lo:[1,0,0] neg_hi:[1,0,0]
	ds_read_b128 v[16:19], v228 offset:10096
	v_pk_fma_f32 v[140:141], v[104:105], v[36:37], v[140:141] op_sel_hi:[1,0,1] neg_lo:[1,0,0] neg_hi:[1,0,0]
	v_pk_fma_f32 v[140:141], v[106:107], v[36:37], v[140:141] op_sel:[0,1,0] op_sel_hi:[1,1,1] neg_lo:[1,0,0] neg_hi:[1,0,0]
	v_pk_fma_f32 v[140:141], v[108:109], v[38:39], v[140:141] op_sel_hi:[1,0,1] neg_lo:[1,0,0] neg_hi:[1,0,0]
	v_pk_fma_f32 v[140:141], v[110:111], v[38:39], v[140:141] op_sel:[0,1,0] op_sel_hi:[1,1,1] neg_lo:[1,0,0] neg_hi:[1,0,0]
	ds_read_b128 v[20:23], v228 offset:10112
	s_waitcnt lgkmcnt(11)
; #define LAS __attribute__((address_space(3)))
; __device__ __forceinline__ void phase_gdb(const int wvs, const Params& p, LAS unsigned char* lds, int nwg) {
;     ...
;     { float x[64]; const bool isw = t >= 64;
; #pragma unroll
;       for (int i = 0; i < 64; ++i) { const float v = (float)R[i * RP + t]; x[i] = v * bs[i] * (isw ? __expf(gcs[i]) : 1.0f); asm volatile("" : "+v"(x[i])); if ((i & 7) == 7) __builtin_amdgcn_sched_barrier(0); }
; #pragma unroll
;       for (int i = 1; i < 64; ++i) {
; #pragma unroll
;         for (int j4 = 0; j4 < (i + 3) / 4; ++j4) { const f32x4 m4 = *(const LAS f32x4*)(M + i * 64 + j4 * 4);
; #pragma unroll
;           for (int jj = 0; jj < 4; ++jj) if (j4 * 4 + jj < i) x[i] -= m4[jj] * x[j4 * 4 + jj]; }
;         __builtin_amdgcn_sched_barrier(0); }
; #pragma unroll
;       for (int i = 0; i < 64; ++i) R[i * RP + t] = (hf)x[i]; }
	v_pk_fma_f32 v[140:141], v[112:113], v[40:41], v[140:141] op_sel_hi:[1,0,1] neg_lo:[1,0,0] neg_hi:[1,0,0]
	v_pk_fma_f32 v[140:141], v[114:115], v[40:41], v[140:141] op_sel:[0,1,0] op_sel_hi:[1,1,1] neg_lo:[1,0,0] neg_hi:[1,0,0]
	v_pk_fma_f32 v[140:141], v[116:117], v[42:43], v[140:141] op_sel_hi:[1,0,1] neg_lo:[1,0,0] neg_hi:[1,0,0]
	v_pk_fma_f32 v[140:141], v[118:119], v[42:43], v[140:141] op_sel:[0,1,0] op_sel_hi:[1,1,1] neg_lo:[1,0,0] neg_hi:[1,0,0]
	ds_read_b128 v[24:27], v228 offset:10128
	v_pk_fma_f32 v[140:141], v[120:121], v[44:45], v[140:141] op_sel_hi:[1,0,1] neg_lo:[1,0,0] neg_hi:[1,0,0]
	v_pk_fma_f32 v[140:141], v[122:123], v[44:45], v[140:141] op_sel:[0,1,0] op_sel_hi:[1,1,1] neg_lo:[1,0,0] neg_hi:[1,0,0]
	v_pk_fma_f32 v[140:141], v[124:125], v[46:47], v[140:141] op_sel_hi:[1,0,1] neg_lo:[1,0,0] neg_hi:[1,0,0]
	v_pk_fma_f32 v[140:141], v[126:127], v[46:47], v[140:141] op_sel:[0,1,0] op_sel_hi:[1,1,1] neg_lo:[1,0,0] neg_hi:[1,0,0]
	ds_read_b128 v[28:31], v228 offset:10240
	v_pk_fma_f32 v[140:141], v[128:129], v[48:49], v[140:141] op_sel_hi:[1,0,1] neg_lo:[1,0,0] neg_hi:[1,0,0]
	v_pk_fma_f32 v[140:141], v[130:131], v[48:49], v[140:141] op_sel:[0,1,0] op_sel_hi:[1,1,1] neg_lo:[1,0,0] neg_hi:[1,0,0]
	v_pk_fma_f32 v[140:141], v[132:133], v[50:51], v[140:141] op_sel_hi:[1,0,1] neg_lo:[1,0,0] neg_hi:[1,0,0]
	v_pk_fma_f32 v[140:141], v[134:135], v[50:51], v[140:141] op_sel:[0,1,0] op_sel_hi:[1,1,1] neg_lo:[1,0,0] neg_hi:[1,0,0]
	ds_read_b128 v[32:35], v228 offset:10256
	v_pk_fma_f32 v[140:141], v[136:137], v[52:53], v[140:141] op_sel_hi:[1,0,1] neg_lo:[1,0,0] neg_hi:[1,0,0]
	v_fma_mixlo_f16 v239, -v138, v53, v140
	v_fma_mixlo_f16 v240, -v139, v53, v141
	v_pk_fma_f32 v[140:141], v[138:139], v[52:53], v[140:141] op_sel:[0,1,0] op_sel_hi:[1,1,1] neg_lo:[1,0,0] neg_hi:[1,0,0]
	ds_write_b16 v253, v239 offset:26720
	s_waitcnt lgkmcnt(14)
	ds_write_b16 v253, v240 offset:26848
	s_waitcnt lgkmcnt(14)
	ds_read_b128 v[36:39], v228 offset:10272
	v_pk_fma_f32 v[142:143], v[64:65], v[56:57], v[142:143] op_sel_hi:[1,0,1] neg_lo:[1,0,0] neg_hi:[1,0,0]
	v_pk_fma_f32 v[142:143], v[66:67], v[56:57], v[142:143] op_sel:[0,1,0] op_sel_hi:[1,1,1] neg_lo:[1,0,0] neg_hi:[1,0,0]
	v_pk_fma_f32 v[142:143], v[68:69], v[58:59], v[142:143] op_sel_hi:[1,0,1] neg_lo:[1,0,0] neg_hi:[1,0,0]
	v_pk_fma_f32 v[142:143], v[70:71], v[58:59], v[142:143] op_sel:[0,1,0] op_sel_hi:[1,1,1] neg_lo:[1,0,0] neg_hi:[1,0,0]
	s_waitcnt lgkmcnt(14)
	ds_read_b128 v[40:43], v228 offset:10288
	v_pk_fma_f32 v[142:143], v[72:73], v[60:61], v[142:143] op_sel_hi:[1,0,1] neg_lo:[1,0,0] neg_hi:[1,0,0]
	v_pk_fma_f32 v[142:143], v[74:75], v[60:61], v[142:143] op_sel:[0,1,0] op_sel_hi:[1,1,1] neg_lo:[1,0,0] neg_hi:[1,0,0]
	v_pk_fma_f32 v[142:143], v[76:77], v[62:63], v[142:143] op_sel_hi:[1,0,1] neg_lo:[1,0,0] neg_hi:[1,0,0]
	v_pk_fma_f32 v[142:143], v[78:79], v[62:63], v[142:143] op_sel:[0,1,0] op_sel_hi:[1,1,1] neg_lo:[1,0,0] neg_hi:[1,0,0]
	s_waitcnt lgkmcnt(14)
	ds_read_b128 v[44:47], v228 offset:10304
	s_waitcnt lgkmcnt(11)
	v_pk_fma_f32 v[142:143], v[80:81], v[244:245], v[142:143] op_sel_hi:[1,0,1] neg_lo:[1,0,0] neg_hi:[1,0,0]
	v_pk_fma_f32 v[142:143], v[82:83], v[244:245], v[142:143] op_sel:[0,1,0] op_sel_hi:[1,1,1] neg_lo:[1,0,0] neg_hi:[1,0,0]
	v_pk_fma_f32 v[142:143], v[84:85], v[246:247], v[142:143] op_sel_hi:[1,0,1] neg_lo:[1,0,0] neg_hi:[1,0,0]
	v_pk_fma_f32 v[142:143], v[86:87], v[246:247], v[142:143] op_sel:[0,1,0] op_sel_hi:[1,1,1] neg_lo:[1,0,0] neg_hi:[1,0,0]
	ds_read_b128 v[48:51], v228 offset:10320
	v_pk_fma_f32 v[142:143], v[88:89], v[248:249], v[142:143] op_sel_hi:[1,0,1] neg_lo:[1,0,0] neg_hi:[1,0,0]
	v_pk_fma_f32 v[142:143], v[90:91], v[248:249], v[142:143] op_sel:[0,1,0] op_sel_hi:[1,1,1] neg_lo:[1,0,0] neg_hi:[1,0,0]
	v_pk_fma_f32 v[142:143], v[92:93], v[250:251], v[142:143] op_sel_hi:[1,0,1] neg_lo:[1,0,0] neg_hi:[1,0,0]
	v_pk_fma_f32 v[142:143], v[94:95], v[250:251], v[142:143] op_sel:[0,1,0] op_sel_hi:[1,1,1] neg_lo:[1,0,0] neg_hi:[1,0,0]
	ds_read_b128 v[52:55], v228 offset:10336
	v_pk_fma_f32 v[142:143], v[96:97], v[4:5], v[142:143] op_sel_hi:[1,0,1] neg_lo:[1,0,0] neg_hi:[1,0,0]
	v_pk_fma_f32 v[142:143], v[98:99], v[4:5], v[142:143] op_sel:[0,1,0] op_sel_hi:[1,1,1] neg_lo:[1,0,0] neg_hi:[1,0,0]
	v_pk_fma_f32 v[142:143], v[100:101], v[6:7], v[142:143] op_sel_hi:[1,0,1] neg_lo:[1,0,0] neg_hi:[1,0,0]
	v_pk_fma_f32 v[142:143], v[102:103], v[6:7], v[142:143] op_sel:[0,1,0] op_sel_hi:[1,1,1] neg_lo:[1,0,0] neg_hi:[1,0,0]
	ds_read_b128 v[56:59], v228 offset:10352
	v_pk_fma_f32 v[142:143], v[104:105], v[8:9], v[142:143] op_sel_hi:[1,0,1] neg_lo:[1,0,0] neg_hi:[1,0,0]
	v_pk_fma_f32 v[142:143], v[106:107], v[8:9], v[142:143] op_sel:[0,1,0] op_sel_hi:[1,1,1] neg_lo:[1,0,0] neg_hi:[1,0,0]
	v_pk_fma_f32 v[142:143], v[108:109], v[10:11], v[142:143] op_sel_hi:[1,0,1] neg_lo:[1,0,0] neg_hi:[1,0,0]
	v_pk_fma_f32 v[142:143], v[110:111], v[10:11], v[142:143] op_sel:[0,1,0] op_sel_hi:[1,1,1] neg_lo:[1,0,0] neg_hi:[1,0,0]
	ds_read_b128 v[60:63], v228 offset:10368
	s_waitcnt lgkmcnt(11)
; #define LAS __attribute__((address_space(3)))
; __device__ __forceinline__ void phase_gdb(const int wvs, const Params& p, LAS unsigned char* lds, int nwg) {
;     ...
;     { float x[64]; const bool isw = t >= 64;
; #pragma unroll
;       for (int i = 0; i < 64; ++i) { const float v = (float)R[i * RP + t]; x[i] = v * bs[i] * (isw ? __expf(gcs[i]) : 1.0f); asm volatile("" : "+v"(x[i])); if ((i & 7) == 7) __builtin_amdgcn_sched_barrier(0); }
; #pragma unroll
;       for (int i = 1; i < 64; ++i) {
; #pragma unroll
;         for (int j4 = 0; j4 < (i + 3) / 4; ++j4) { const f32x4 m4 = *(const LAS f32x4*)(M + i * 64 + j4 * 4);
; #pragma unroll
;           for (int jj = 0; jj < 4; ++jj) if (j4 * 4 + jj < i) x[i] -= m4[jj] * x[j4 * 4 + jj]; }
;         __builtin_amdgcn_sched_barrier(0); }
; #pragma unroll
;       for (int i = 0; i < 64; ++i) R[i * RP + t] = (hf)x[i]; }
	v_pk_fma_f32 v[142:143], v[112:113], v[12:13], v[142:143] op_sel_hi:[1,0,1] neg_lo:[1,0,0] neg_hi:[1,0,0]
	v_pk_fma_f32 v[142:143], v[114:115], v[12:13], v[142:143] op_sel:[0,1,0] op_sel_hi:[1,1,1] neg_lo:[1,0,0] neg_hi:[1,0,0]
	v_pk_fma_f32 v[142:143], v[116:117], v[14:15], v[142:143] op_sel_hi:[1,0,1] neg_lo:[1,0,0] neg_hi:[1,0,0]
	v_pk_fma_f32 v[142:143], v[118:119], v[14:15], v[142:143] op_sel:[0,1,0] op_sel_hi:[1,1,1] neg_lo:[1,0,0] neg_hi:[1,0,0]
	ds_read_b128 v[244:247], v228 offset:10384
	v_pk_fma_f32 v[142:143], v[120:121], v[16:17], v[142:143] op_sel_hi:[1,0,1] neg_lo:[1,0,0] neg_hi:[1,0,0]
	v_pk_fma_f32 v[142:143], v[122:123], v[16:17], v[142:143] op_sel:[0,1,0] op_sel_hi:[1,1,1] neg_lo:[1,0,0] neg_hi:[1,0,0]
	v_pk_fma_f32 v[142:143], v[124:125], v[18:19], v[142:143] op_sel_hi:[1,0,1] neg_lo:[1,0,0] neg_hi:[1,0,0]
	v_pk_fma_f32 v[142:143], v[126:127], v[18:19], v[142:143] op_sel:[0,1,0] op_sel_hi:[1,1,1] neg_lo:[1,0,0] neg_hi:[1,0,0]
	ds_read_b128 v[248:251], v228 offset:10496
	v_pk_fma_f32 v[142:143], v[128:129], v[20:21], v[142:143] op_sel_hi:[1,0,1] neg_lo:[1,0,0] neg_hi:[1,0,0]
	v_pk_fma_f32 v[142:143], v[130:131], v[20:21], v[142:143] op_sel:[0,1,0] op_sel_hi:[1,1,1] neg_lo:[1,0,0] neg_hi:[1,0,0]
	v_pk_fma_f32 v[142:143], v[132:133], v[22:23], v[142:143] op_sel_hi:[1,0,1] neg_lo:[1,0,0] neg_hi:[1,0,0]
	v_pk_fma_f32 v[142:143], v[134:135], v[22:23], v[142:143] op_sel:[0,1,0] op_sel_hi:[1,1,1] neg_lo:[1,0,0] neg_hi:[1,0,0]
	ds_read_b128 v[4:7], v228 offset:10512
	v_pk_fma_f32 v[142:143], v[136:137], v[24:25], v[142:143] op_sel_hi:[1,0,1] neg_lo:[1,0,0] neg_hi:[1,0,0]
	v_pk_fma_f32 v[142:143], v[138:139], v[24:25], v[142:143] op_sel:[0,1,0] op_sel_hi:[1,1,1] neg_lo:[1,0,0] neg_hi:[1,0,0]
	v_fma_mixlo_f16 v0, -v140, v26, v142
	v_fma_mixlo_f16 v2, -v141, v26, v143
	v_pk_fma_f32 v[142:143], v[140:141], v[26:27], v[142:143] op_sel_hi:[1,0,1] neg_lo:[1,0,0] neg_hi:[1,0,0]
	ds_write_b16 v253, v0 offset:26992
	s_waitcnt lgkmcnt(14)
	ds_write_b16 v253, v2 offset:27120
	s_waitcnt lgkmcnt(14)
	ds_read_b128 v[8:11], v228 offset:10528
	v_pk_fma_f32 v[144:145], v[64:65], v[28:29], v[144:145] op_sel_hi:[1,0,1] neg_lo:[1,0,0] neg_hi:[1,0,0]
	v_pk_fma_f32 v[144:145], v[66:67], v[28:29], v[144:145] op_sel:[0,1,0] op_sel_hi:[1,1,1] neg_lo:[1,0,0] neg_hi:[1,0,0]
	v_pk_fma_f32 v[144:145], v[68:69], v[30:31], v[144:145] op_sel_hi:[1,0,1] neg_lo:[1,0,0] neg_hi:[1,0,0]
	v_pk_fma_f32 v[144:145], v[70:71], v[30:31], v[144:145] op_sel:[0,1,0] op_sel_hi:[1,1,1] neg_lo:[1,0,0] neg_hi:[1,0,0]
	s_waitcnt lgkmcnt(14)
	ds_read_b128 v[12:15], v228 offset:10544
	v_pk_fma_f32 v[144:145], v[72:73], v[32:33], v[144:145] op_sel_hi:[1,0,1] neg_lo:[1,0,0] neg_hi:[1,0,0]
	v_pk_fma_f32 v[144:145], v[74:75], v[32:33], v[144:145] op_sel:[0,1,0] op_sel_hi:[1,1,1] neg_lo:[1,0,0] neg_hi:[1,0,0]
	v_pk_fma_f32 v[144:145], v[76:77], v[34:35], v[144:145] op_sel_hi:[1,0,1] neg_lo:[1,0,0] neg_hi:[1,0,0]
	v_pk_fma_f32 v[144:145], v[78:79], v[34:35], v[144:145] op_sel:[0,1,0] op_sel_hi:[1,1,1] neg_lo:[1,0,0] neg_hi:[1,0,0]
	s_waitcnt lgkmcnt(14)
	ds_read_b128 v[16:19], v228 offset:10560
	s_waitcnt lgkmcnt(11)
	v_pk_fma_f32 v[144:145], v[80:81], v[36:37], v[144:145] op_sel_hi:[1,0,1] neg_lo:[1,0,0] neg_hi:[1,0,0]
	v_pk_fma_f32 v[144:145], v[82:83], v[36:37], v[144:145] op_sel:[0,1,0] op_sel_hi:[1,1,1] neg_lo:[1,0,0] neg_hi:[1,0,0]
	v_pk_fma_f32 v[144:145], v[84:85], v[38:39], v[144:145] op_sel_hi:[1,0,1] neg_lo:[1,0,0] neg_hi:[1,0,0]
	v_pk_fma_f32 v[144:145], v[86:87], v[38:39], v[144:145] op_sel:[0,1,0] op_sel_hi:[1,1,1] neg_lo:[1,0,0] neg_hi:[1,0,0]
	ds_read_b128 v[20:23], v228 offset:10576
	v_pk_fma_f32 v[144:145], v[88:89], v[40:41], v[144:145] op_sel_hi:[1,0,1] neg_lo:[1,0,0] neg_hi:[1,0,0]
	v_pk_fma_f32 v[144:145], v[90:91], v[40:41], v[144:145] op_sel:[0,1,0] op_sel_hi:[1,1,1] neg_lo:[1,0,0] neg_hi:[1,0,0]
	v_pk_fma_f32 v[144:145], v[92:93], v[42:43], v[144:145] op_sel_hi:[1,0,1] neg_lo:[1,0,0] neg_hi:[1,0,0]
	v_pk_fma_f32 v[144:145], v[94:95], v[42:43], v[144:145] op_sel:[0,1,0] op_sel_hi:[1,1,1] neg_lo:[1,0,0] neg_hi:[1,0,0]
	ds_read_b128 v[24:27], v228 offset:10592
	v_pk_fma_f32 v[144:145], v[96:97], v[44:45], v[144:145] op_sel_hi:[1,0,1] neg_lo:[1,0,0] neg_hi:[1,0,0]
	v_pk_fma_f32 v[144:145], v[98:99], v[44:45], v[144:145] op_sel:[0,1,0] op_sel_hi:[1,1,1] neg_lo:[1,0,0] neg_hi:[1,0,0]
	v_pk_fma_f32 v[144:145], v[100:101], v[46:47], v[144:145] op_sel_hi:[1,0,1] neg_lo:[1,0,0] neg_hi:[1,0,0]
	v_pk_fma_f32 v[144:145], v[102:103], v[46:47], v[144:145] op_sel:[0,1,0] op_sel_hi:[1,1,1] neg_lo:[1,0,0] neg_hi:[1,0,0]
	ds_read_b128 v[28:31], v228 offset:10608
	v_pk_fma_f32 v[144:145], v[104:105], v[48:49], v[144:145] op_sel_hi:[1,0,1] neg_lo:[1,0,0] neg_hi:[1,0,0]
	v_pk_fma_f32 v[144:145], v[106:107], v[48:49], v[144:145] op_sel:[0,1,0] op_sel_hi:[1,1,1] neg_lo:[1,0,0] neg_hi:[1,0,0]
	v_pk_fma_f32 v[144:145], v[108:109], v[50:51], v[144:145] op_sel_hi:[1,0,1] neg_lo:[1,0,0] neg_hi:[1,0,0]
	v_pk_fma_f32 v[144:145], v[110:111], v[50:51], v[144:145] op_sel:[0,1,0] op_sel_hi:[1,1,1] neg_lo:[1,0,0] neg_hi:[1,0,0]
	ds_read_b128 v[32:35], v228 offset:10624
	s_waitcnt lgkmcnt(11)
; #define LAS __attribute__((address_space(3)))
; __device__ __forceinline__ void phase_gdb(const int wvs, const Params& p, LAS unsigned char* lds, int nwg) {
;     ...
;     { float x[64]; const bool isw = t >= 64;
; #pragma unroll
;       for (int i = 0; i < 64; ++i) { const float v = (float)R[i * RP + t]; x[i] = v * bs[i] * (isw ? __expf(gcs[i]) : 1.0f); asm volatile("" : "+v"(x[i])); if ((i & 7) == 7) __builtin_amdgcn_sched_barrier(0); }
; #pragma unroll
;       for (int i = 1; i < 64; ++i) {
; #pragma unroll
;         for (int j4 = 0; j4 < (i + 3) / 4; ++j4) { const f32x4 m4 = *(const LAS f32x4*)(M + i * 64 + j4 * 4);
; #pragma unroll
;           for (int jj = 0; jj < 4; ++jj) if (j4 * 4 + jj < i) x[i] -= m4[jj] * x[j4 * 4 + jj]; }
;         __builtin_amdgcn_sched_barrier(0); }
; #pragma unroll
;       for (int i = 0; i < 64; ++i) R[i * RP + t] = (hf)x[i]; }
	v_pk_fma_f32 v[144:145], v[112:113], v[52:53], v[144:145] op_sel_hi:[1,0,1] neg_lo:[1,0,0] neg_hi:[1,0,0]
	v_pk_fma_f32 v[144:145], v[114:115], v[52:53], v[144:145] op_sel:[0,1,0] op_sel_hi:[1,1,1] neg_lo:[1,0,0] neg_hi:[1,0,0]
	v_pk_fma_f32 v[144:145], v[116:117], v[54:55], v[144:145] op_sel_hi:[1,0,1] neg_lo:[1,0,0] neg_hi:[1,0,0]
	v_pk_fma_f32 v[144:145], v[118:119], v[54:55], v[144:145] op_sel:[0,1,0] op_sel_hi:[1,1,1] neg_lo:[1,0,0] neg_hi:[1,0,0]
	ds_read_b128 v[36:39], v228 offset:10640
	v_pk_fma_f32 v[144:145], v[120:121], v[56:57], v[144:145] op_sel_hi:[1,0,1] neg_lo:[1,0,0] neg_hi:[1,0,0]
	v_pk_fma_f32 v[144:145], v[122:123], v[56:57], v[144:145] op_sel:[0,1,0] op_sel_hi:[1,1,1] neg_lo:[1,0,0] neg_hi:[1,0,0]
	v_pk_fma_f32 v[144:145], v[124:125], v[58:59], v[144:145] op_sel_hi:[1,0,1] neg_lo:[1,0,0] neg_hi:[1,0,0]
	v_pk_fma_f32 v[144:145], v[126:127], v[58:59], v[144:145] op_sel:[0,1,0] op_sel_hi:[1,1,1] neg_lo:[1,0,0] neg_hi:[1,0,0]
	ds_read_b128 v[40:43], v228 offset:10656
	v_pk_fma_f32 v[144:145], v[128:129], v[60:61], v[144:145] op_sel_hi:[1,0,1] neg_lo:[1,0,0] neg_hi:[1,0,0]
	v_pk_fma_f32 v[144:145], v[130:131], v[60:61], v[144:145] op_sel:[0,1,0] op_sel_hi:[1,1,1] neg_lo:[1,0,0] neg_hi:[1,0,0]
	v_pk_fma_f32 v[144:145], v[132:133], v[62:63], v[144:145] op_sel_hi:[1,0,1] neg_lo:[1,0,0] neg_hi:[1,0,0]
	v_pk_fma_f32 v[144:145], v[134:135], v[62:63], v[144:145] op_sel:[0,1,0] op_sel_hi:[1,1,1] neg_lo:[1,0,0] neg_hi:[1,0,0]
	ds_read_b128 v[44:47], v228 offset:10752
	v_pk_fma_f32 v[144:145], v[136:137], v[244:245], v[144:145] op_sel_hi:[1,0,1] neg_lo:[1,0,0] neg_hi:[1,0,0]
	v_pk_fma_f32 v[144:145], v[138:139], v[244:245], v[144:145] op_sel:[0,1,0] op_sel_hi:[1,1,1] neg_lo:[1,0,0] neg_hi:[1,0,0]
	v_pk_fma_f32 v[144:145], v[140:141], v[246:247], v[144:145] op_sel_hi:[1,0,1] neg_lo:[1,0,0] neg_hi:[1,0,0]
	v_fma_mixlo_f16 v3, -v142, v247, v144
	v_fma_mixlo_f16 v238, -v143, v247, v145
	v_pk_fma_f32 v[144:145], v[142:143], v[246:247], v[144:145] op_sel:[0,1,0] op_sel_hi:[1,1,1] neg_lo:[1,0,0] neg_hi:[1,0,0]
	ds_write_b16 v253, v3 offset:27264
	s_waitcnt lgkmcnt(14)
	ds_write_b16 v253, v238 offset:27392
	s_waitcnt lgkmcnt(14)
	ds_read_b128 v[48:51], v228 offset:10768
	v_pk_fma_f32 v[146:147], v[64:65], v[248:249], v[146:147] op_sel_hi:[1,0,1] neg_lo:[1,0,0] neg_hi:[1,0,0]
	v_pk_fma_f32 v[146:147], v[66:67], v[248:249], v[146:147] op_sel:[0,1,0] op_sel_hi:[1,1,1] neg_lo:[1,0,0] neg_hi:[1,0,0]
	v_pk_fma_f32 v[146:147], v[68:69], v[250:251], v[146:147] op_sel_hi:[1,0,1] neg_lo:[1,0,0] neg_hi:[1,0,0]
	v_pk_fma_f32 v[146:147], v[70:71], v[250:251], v[146:147] op_sel:[0,1,0] op_sel_hi:[1,1,1] neg_lo:[1,0,0] neg_hi:[1,0,0]
	s_waitcnt lgkmcnt(14)
	ds_read_b128 v[52:55], v228 offset:10784
	v_pk_fma_f32 v[146:147], v[72:73], v[4:5], v[146:147] op_sel_hi:[1,0,1] neg_lo:[1,0,0] neg_hi:[1,0,0]
	v_pk_fma_f32 v[146:147], v[74:75], v[4:5], v[146:147] op_sel:[0,1,0] op_sel_hi:[1,1,1] neg_lo:[1,0,0] neg_hi:[1,0,0]
	v_pk_fma_f32 v[146:147], v[76:77], v[6:7], v[146:147] op_sel_hi:[1,0,1] neg_lo:[1,0,0] neg_hi:[1,0,0]
	v_pk_fma_f32 v[146:147], v[78:79], v[6:7], v[146:147] op_sel:[0,1,0] op_sel_hi:[1,1,1] neg_lo:[1,0,0] neg_hi:[1,0,0]
	s_waitcnt lgkmcnt(14)
	ds_read_b128 v[56:59], v228 offset:10800
	s_waitcnt lgkmcnt(11)
	v_pk_fma_f32 v[146:147], v[80:81], v[8:9], v[146:147] op_sel_hi:[1,0,1] neg_lo:[1,0,0] neg_hi:[1,0,0]
	v_pk_fma_f32 v[146:147], v[82:83], v[8:9], v[146:147] op_sel:[0,1,0] op_sel_hi:[1,1,1] neg_lo:[1,0,0] neg_hi:[1,0,0]
	v_pk_fma_f32 v[146:147], v[84:85], v[10:11], v[146:147] op_sel_hi:[1,0,1] neg_lo:[1,0,0] neg_hi:[1,0,0]
	v_pk_fma_f32 v[146:147], v[86:87], v[10:11], v[146:147] op_sel:[0,1,0] op_sel_hi:[1,1,1] neg_lo:[1,0,0] neg_hi:[1,0,0]
	ds_read_b128 v[60:63], v228 offset:10816
	v_pk_fma_f32 v[146:147], v[88:89], v[12:13], v[146:147] op_sel_hi:[1,0,1] neg_lo:[1,0,0] neg_hi:[1,0,0]
	v_pk_fma_f32 v[146:147], v[90:91], v[12:13], v[146:147] op_sel:[0,1,0] op_sel_hi:[1,1,1] neg_lo:[1,0,0] neg_hi:[1,0,0]
	v_pk_fma_f32 v[146:147], v[92:93], v[14:15], v[146:147] op_sel_hi:[1,0,1] neg_lo:[1,0,0] neg_hi:[1,0,0]
	v_pk_fma_f32 v[146:147], v[94:95], v[14:15], v[146:147] op_sel:[0,1,0] op_sel_hi:[1,1,1] neg_lo:[1,0,0] neg_hi:[1,0,0]
	ds_read_b128 v[244:247], v228 offset:10832
	v_pk_fma_f32 v[146:147], v[96:97], v[16:17], v[146:147] op_sel_hi:[1,0,1] neg_lo:[1,0,0] neg_hi:[1,0,0]
	v_pk_fma_f32 v[146:147], v[98:99], v[16:17], v[146:147] op_sel:[0,1,0] op_sel_hi:[1,1,1] neg_lo:[1,0,0] neg_hi:[1,0,0]
	v_pk_fma_f32 v[146:147], v[100:101], v[18:19], v[146:147] op_sel_hi:[1,0,1] neg_lo:[1,0,0] neg_hi:[1,0,0]
	v_pk_fma_f32 v[146:147], v[102:103], v[18:19], v[146:147] op_sel:[0,1,0] op_sel_hi:[1,1,1] neg_lo:[1,0,0] neg_hi:[1,0,0]
	ds_read_b128 v[248:251], v228 offset:10848
	v_pk_fma_f32 v[146:147], v[104:105], v[20:21], v[146:147] op_sel_hi:[1,0,1] neg_lo:[1,0,0] neg_hi:[1,0,0]
	v_pk_fma_f32 v[146:147], v[106:107], v[20:21], v[146:147] op_sel:[0,1,0] op_sel_hi:[1,1,1] neg_lo:[1,0,0] neg_hi:[1,0,0]
	v_pk_fma_f32 v[146:147], v[108:109], v[22:23], v[146:147] op_sel_hi:[1,0,1] neg_lo:[1,0,0] neg_hi:[1,0,0]
	v_pk_fma_f32 v[146:147], v[110:111], v[22:23], v[146:147] op_sel:[0,1,0] op_sel_hi:[1,1,1] neg_lo:[1,0,0] neg_hi:[1,0,0]
	ds_read_b128 v[4:7], v228 offset:10864
	s_waitcnt lgkmcnt(11)
; #define LAS __attribute__((address_space(3)))
; __device__ __forceinline__ void phase_gdb(const int wvs, const Params& p, LAS unsigned char* lds, int nwg) {
;     ...
;     { float x[64]; const bool isw = t >= 64;
; #pragma unroll
;       for (int i = 0; i < 64; ++i) { const float v = (float)R[i * RP + t]; x[i] = v * bs[i] * (isw ? __expf(gcs[i]) : 1.0f); asm volatile("" : "+v"(x[i])); if ((i & 7) == 7) __builtin_amdgcn_sched_barrier(0); }
; #pragma unroll
;       for (int i = 1; i < 64; ++i) {
; #pragma unroll
;         for (int j4 = 0; j4 < (i + 3) / 4; ++j4) { const f32x4 m4 = *(const LAS f32x4*)(M + i * 64 + j4 * 4);
; #pragma unroll
;           for (int jj = 0; jj < 4; ++jj) if (j4 * 4 + jj < i) x[i] -= m4[jj] * x[j4 * 4 + jj]; }
;         __builtin_amdgcn_sched_barrier(0); }
; #pragma unroll
;       for (int i = 0; i < 64; ++i) R[i * RP + t] = (hf)x[i]; }
	v_pk_fma_f32 v[146:147], v[112:113], v[24:25], v[146:147] op_sel_hi:[1,0,1] neg_lo:[1,0,0] neg_hi:[1,0,0]
	v_pk_fma_f32 v[146:147], v[114:115], v[24:25], v[146:147] op_sel:[0,1,0] op_sel_hi:[1,1,1] neg_lo:[1,0,0] neg_hi:[1,0,0]
	v_pk_fma_f32 v[146:147], v[116:117], v[26:27], v[146:147] op_sel_hi:[1,0,1] neg_lo:[1,0,0] neg_hi:[1,0,0]
	v_pk_fma_f32 v[146:147], v[118:119], v[26:27], v[146:147] op_sel:[0,1,0] op_sel_hi:[1,1,1] neg_lo:[1,0,0] neg_hi:[1,0,0]
	ds_read_b128 v[8:11], v228 offset:10880
	v_pk_fma_f32 v[146:147], v[120:121], v[28:29], v[146:147] op_sel_hi:[1,0,1] neg_lo:[1,0,0] neg_hi:[1,0,0]
	v_pk_fma_f32 v[146:147], v[122:123], v[28:29], v[146:147] op_sel:[0,1,0] op_sel_hi:[1,1,1] neg_lo:[1,0,0] neg_hi:[1,0,0]
	v_pk_fma_f32 v[146:147], v[124:125], v[30:31], v[146:147] op_sel_hi:[1,0,1] neg_lo:[1,0,0] neg_hi:[1,0,0]
	v_pk_fma_f32 v[146:147], v[126:127], v[30:31], v[146:147] op_sel:[0,1,0] op_sel_hi:[1,1,1] neg_lo:[1,0,0] neg_hi:[1,0,0]
	ds_read_b128 v[12:15], v228 offset:10896
	v_pk_fma_f32 v[146:147], v[128:129], v[32:33], v[146:147] op_sel_hi:[1,0,1] neg_lo:[1,0,0] neg_hi:[1,0,0]
	v_pk_fma_f32 v[146:147], v[130:131], v[32:33], v[146:147] op_sel:[0,1,0] op_sel_hi:[1,1,1] neg_lo:[1,0,0] neg_hi:[1,0,0]
	v_pk_fma_f32 v[146:147], v[132:133], v[34:35], v[146:147] op_sel_hi:[1,0,1] neg_lo:[1,0,0] neg_hi:[1,0,0]
	v_pk_fma_f32 v[146:147], v[134:135], v[34:35], v[146:147] op_sel:[0,1,0] op_sel_hi:[1,1,1] neg_lo:[1,0,0] neg_hi:[1,0,0]
	ds_read_b128 v[16:19], v228 offset:10912
	v_pk_fma_f32 v[146:147], v[136:137], v[36:37], v[146:147] op_sel_hi:[1,0,1] neg_lo:[1,0,0] neg_hi:[1,0,0]
	v_pk_fma_f32 v[146:147], v[138:139], v[36:37], v[146:147] op_sel:[0,1,0] op_sel_hi:[1,1,1] neg_lo:[1,0,0] neg_hi:[1,0,0]
	v_pk_fma_f32 v[146:147], v[140:141], v[38:39], v[146:147] op_sel_hi:[1,0,1] neg_lo:[1,0,0] neg_hi:[1,0,0]
	v_pk_fma_f32 v[146:147], v[142:143], v[38:39], v[146:147] op_sel:[0,1,0] op_sel_hi:[1,1,1] neg_lo:[1,0,0] neg_hi:[1,0,0]
	ds_read_b128 v[20:23], v228 offset:11008
	s_waitcnt lgkmcnt(9)
	v_fma_mixlo_f16 v239, -v144, v40, v146
	v_fma_mixlo_f16 v240, -v145, v40, v147
	v_pk_fma_f32 v[146:147], v[144:145], v[40:41], v[146:147] op_sel_hi:[1,0,1] neg_lo:[1,0,0] neg_hi:[1,0,0]
	ds_write_b16 v253, v239 offset:27536
	ds_write_b16 v253, v240 offset:27664
	ds_read_b128 v[24:27], v228 offset:11024
	v_pk_fma_f32 v[148:149], v[64:65], v[44:45], v[148:149] op_sel_hi:[1,0,1] neg_lo:[1,0,0] neg_hi:[1,0,0]
	v_pk_fma_f32 v[148:149], v[66:67], v[44:45], v[148:149] op_sel:[0,1,0] op_sel_hi:[1,1,1] neg_lo:[1,0,0] neg_hi:[1,0,0]
	v_pk_fma_f32 v[148:149], v[68:69], v[46:47], v[148:149] op_sel_hi:[1,0,1] neg_lo:[1,0,0] neg_hi:[1,0,0]
	v_pk_fma_f32 v[148:149], v[70:71], v[46:47], v[148:149] op_sel:[0,1,0] op_sel_hi:[1,1,1] neg_lo:[1,0,0] neg_hi:[1,0,0]
	ds_read_b128 v[28:31], v228 offset:11040
	v_pk_fma_f32 v[148:149], v[72:73], v[48:49], v[148:149] op_sel_hi:[1,0,1] neg_lo:[1,0,0] neg_hi:[1,0,0]
	v_pk_fma_f32 v[148:149], v[74:75], v[48:49], v[148:149] op_sel:[0,1,0] op_sel_hi:[1,1,1] neg_lo:[1,0,0] neg_hi:[1,0,0]
	v_pk_fma_f32 v[148:149], v[76:77], v[50:51], v[148:149] op_sel_hi:[1,0,1] neg_lo:[1,0,0] neg_hi:[1,0,0]
	v_pk_fma_f32 v[148:149], v[78:79], v[50:51], v[148:149] op_sel:[0,1,0] op_sel_hi:[1,1,1] neg_lo:[1,0,0] neg_hi:[1,0,0]
	ds_read_b128 v[32:35], v228 offset:11056
	v_pk_fma_f32 v[148:149], v[80:81], v[52:53], v[148:149] op_sel_hi:[1,0,1] neg_lo:[1,0,0] neg_hi:[1,0,0]
	v_pk_fma_f32 v[148:149], v[82:83], v[52:53], v[148:149] op_sel:[0,1,0] op_sel_hi:[1,1,1] neg_lo:[1,0,0] neg_hi:[1,0,0]
	v_pk_fma_f32 v[148:149], v[84:85], v[54:55], v[148:149] op_sel_hi:[1,0,1] neg_lo:[1,0,0] neg_hi:[1,0,0]
	v_pk_fma_f32 v[148:149], v[86:87], v[54:55], v[148:149] op_sel:[0,1,0] op_sel_hi:[1,1,1] neg_lo:[1,0,0] neg_hi:[1,0,0]
	ds_read_b128 v[36:39], v228 offset:11072
	s_waitcnt lgkmcnt(11)
	v_pk_fma_f32 v[148:149], v[88:89], v[56:57], v[148:149] op_sel_hi:[1,0,1] neg_lo:[1,0,0] neg_hi:[1,0,0]
	v_pk_fma_f32 v[148:149], v[90:91], v[56:57], v[148:149] op_sel:[0,1,0] op_sel_hi:[1,1,1] neg_lo:[1,0,0] neg_hi:[1,0,0]
	v_pk_fma_f32 v[148:149], v[92:93], v[58:59], v[148:149] op_sel_hi:[1,0,1] neg_lo:[1,0,0] neg_hi:[1,0,0]
	v_pk_fma_f32 v[148:149], v[94:95], v[58:59], v[148:149] op_sel:[0,1,0] op_sel_hi:[1,1,1] neg_lo:[1,0,0] neg_hi:[1,0,0]
	ds_read_b128 v[40:43], v228 offset:11088
	v_pk_fma_f32 v[148:149], v[96:97], v[60:61], v[148:149] op_sel_hi:[1,0,1] neg_lo:[1,0,0] neg_hi:[1,0,0]
	v_pk_fma_f32 v[148:149], v[98:99], v[60:61], v[148:149] op_sel:[0,1,0] op_sel_hi:[1,1,1] neg_lo:[1,0,0] neg_hi:[1,0,0]
	v_pk_fma_f32 v[148:149], v[100:101], v[62:63], v[148:149] op_sel_hi:[1,0,1] neg_lo:[1,0,0] neg_hi:[1,0,0]
	v_pk_fma_f32 v[148:149], v[102:103], v[62:63], v[148:149] op_sel:[0,1,0] op_sel_hi:[1,1,1] neg_lo:[1,0,0] neg_hi:[1,0,0]
	ds_read_b128 v[44:47], v228 offset:11104
	v_pk_fma_f32 v[148:149], v[104:105], v[244:245], v[148:149] op_sel_hi:[1,0,1] neg_lo:[1,0,0] neg_hi:[1,0,0]
	v_pk_fma_f32 v[148:149], v[106:107], v[244:245], v[148:149] op_sel:[0,1,0] op_sel_hi:[1,1,1] neg_lo:[1,0,0] neg_hi:[1,0,0]
	v_pk_fma_f32 v[148:149], v[108:109], v[246:247], v[148:149] op_sel_hi:[1,0,1] neg_lo:[1,0,0] neg_hi:[1,0,0]
	v_pk_fma_f32 v[148:149], v[110:111], v[246:247], v[148:149] op_sel:[0,1,0] op_sel_hi:[1,1,1] neg_lo:[1,0,0] neg_hi:[1,0,0]
	ds_read_b128 v[48:51], v228 offset:11120
	v_pk_fma_f32 v[148:149], v[112:113], v[248:249], v[148:149] op_sel_hi:[1,0,1] neg_lo:[1,0,0] neg_hi:[1,0,0]
	v_pk_fma_f32 v[148:149], v[114:115], v[248:249], v[148:149] op_sel:[0,1,0] op_sel_hi:[1,1,1] neg_lo:[1,0,0] neg_hi:[1,0,0]
	v_pk_fma_f32 v[148:149], v[116:117], v[250:251], v[148:149] op_sel_hi:[1,0,1] neg_lo:[1,0,0] neg_hi:[1,0,0]
	v_pk_fma_f32 v[148:149], v[118:119], v[250:251], v[148:149] op_sel:[0,1,0] op_sel_hi:[1,1,1] neg_lo:[1,0,0] neg_hi:[1,0,0]
	ds_read_b128 v[52:55], v228 offset:11136
	s_waitcnt lgkmcnt(11)
; #define LAS __attribute__((address_space(3)))
; __device__ __forceinline__ void phase_gdb(const int wvs, const Params& p, LAS unsigned char* lds, int nwg) {
;     ...
;     { float x[64]; const bool isw = t >= 64;
; #pragma unroll
;       for (int i = 0; i < 64; ++i) { const float v = (float)R[i * RP + t]; x[i] = v * bs[i] * (isw ? __expf(gcs[i]) : 1.0f); asm volatile("" : "+v"(x[i])); if ((i & 7) == 7) __builtin_amdgcn_sched_barrier(0); }
; #pragma unroll
;       for (int i = 1; i < 64; ++i) {
; #pragma unroll
;         for (int j4 = 0; j4 < (i + 3) / 4; ++j4) { const f32x4 m4 = *(const LAS f32x4*)(M + i * 64 + j4 * 4);
; #pragma unroll
;           for (int jj = 0; jj < 4; ++jj) if (j4 * 4 + jj < i) x[i] -= m4[jj] * x[j4 * 4 + jj]; }
;         __builtin_amdgcn_sched_barrier(0); }
; #pragma unroll
;       for (int i = 0; i < 64; ++i) R[i * RP + t] = (hf)x[i]; }
	v_pk_fma_f32 v[148:149], v[120:121], v[4:5], v[148:149] op_sel_hi:[1,0,1] neg_lo:[1,0,0] neg_hi:[1,0,0]
	v_pk_fma_f32 v[148:149], v[122:123], v[4:5], v[148:149] op_sel:[0,1,0] op_sel_hi:[1,1,1] neg_lo:[1,0,0] neg_hi:[1,0,0]
	v_pk_fma_f32 v[148:149], v[124:125], v[6:7], v[148:149] op_sel_hi:[1,0,1] neg_lo:[1,0,0] neg_hi:[1,0,0]
	v_pk_fma_f32 v[148:149], v[126:127], v[6:7], v[148:149] op_sel:[0,1,0] op_sel_hi:[1,1,1] neg_lo:[1,0,0] neg_hi:[1,0,0]
	ds_read_b128 v[56:59], v228 offset:11152
	v_pk_fma_f32 v[148:149], v[128:129], v[8:9], v[148:149] op_sel_hi:[1,0,1] neg_lo:[1,0,0] neg_hi:[1,0,0]
	v_pk_fma_f32 v[148:149], v[130:131], v[8:9], v[148:149] op_sel:[0,1,0] op_sel_hi:[1,1,1] neg_lo:[1,0,0] neg_hi:[1,0,0]
	v_pk_fma_f32 v[148:149], v[132:133], v[10:11], v[148:149] op_sel_hi:[1,0,1] neg_lo:[1,0,0] neg_hi:[1,0,0]
	v_pk_fma_f32 v[148:149], v[134:135], v[10:11], v[148:149] op_sel:[0,1,0] op_sel_hi:[1,1,1] neg_lo:[1,0,0] neg_hi:[1,0,0]
	ds_read_b128 v[60:63], v228 offset:11168
	v_pk_fma_f32 v[148:149], v[136:137], v[12:13], v[148:149] op_sel_hi:[1,0,1] neg_lo:[1,0,0] neg_hi:[1,0,0]
	v_pk_fma_f32 v[148:149], v[138:139], v[12:13], v[148:149] op_sel:[0,1,0] op_sel_hi:[1,1,1] neg_lo:[1,0,0] neg_hi:[1,0,0]
	v_pk_fma_f32 v[148:149], v[140:141], v[14:15], v[148:149] op_sel_hi:[1,0,1] neg_lo:[1,0,0] neg_hi:[1,0,0]
	v_pk_fma_f32 v[148:149], v[142:143], v[14:15], v[148:149] op_sel:[0,1,0] op_sel_hi:[1,1,1] neg_lo:[1,0,0] neg_hi:[1,0,0]
	ds_read_b128 v[244:247], v228 offset:11264
	v_pk_fma_f32 v[148:149], v[144:145], v[16:17], v[148:149] op_sel_hi:[1,0,1] neg_lo:[1,0,0] neg_hi:[1,0,0]
	v_fma_mixlo_f16 v0, -v146, v17, v148
	v_fma_mixlo_f16 v2, -v147, v17, v149
	v_pk_fma_f32 v[148:149], v[146:147], v[16:17], v[148:149] op_sel:[0,1,0] op_sel_hi:[1,1,1] neg_lo:[1,0,0] neg_hi:[1,0,0]
	ds_write_b16 v253, v0 offset:27808
	s_waitcnt lgkmcnt(14)
	ds_write_b16 v253, v2 offset:27936
	s_waitcnt lgkmcnt(14)
	ds_read_b128 v[248:251], v228 offset:11280
	v_pk_fma_f32 v[150:151], v[64:65], v[20:21], v[150:151] op_sel_hi:[1,0,1] neg_lo:[1,0,0] neg_hi:[1,0,0]
	v_pk_fma_f32 v[150:151], v[66:67], v[20:21], v[150:151] op_sel:[0,1,0] op_sel_hi:[1,1,1] neg_lo:[1,0,0] neg_hi:[1,0,0]
	v_pk_fma_f32 v[150:151], v[68:69], v[22:23], v[150:151] op_sel_hi:[1,0,1] neg_lo:[1,0,0] neg_hi:[1,0,0]
	v_pk_fma_f32 v[150:151], v[70:71], v[22:23], v[150:151] op_sel:[0,1,0] op_sel_hi:[1,1,1] neg_lo:[1,0,0] neg_hi:[1,0,0]
	s_waitcnt lgkmcnt(14)
	ds_read_b128 v[4:7], v228 offset:11296
	s_waitcnt lgkmcnt(11)
	v_pk_fma_f32 v[150:151], v[72:73], v[24:25], v[150:151] op_sel_hi:[1,0,1] neg_lo:[1,0,0] neg_hi:[1,0,0]
	v_pk_fma_f32 v[150:151], v[74:75], v[24:25], v[150:151] op_sel:[0,1,0] op_sel_hi:[1,1,1] neg_lo:[1,0,0] neg_hi:[1,0,0]
	v_pk_fma_f32 v[150:151], v[76:77], v[26:27], v[150:151] op_sel_hi:[1,0,1] neg_lo:[1,0,0] neg_hi:[1,0,0]
	v_pk_fma_f32 v[150:151], v[78:79], v[26:27], v[150:151] op_sel:[0,1,0] op_sel_hi:[1,1,1] neg_lo:[1,0,0] neg_hi:[1,0,0]
	ds_read_b128 v[8:11], v228 offset:11312
	v_pk_fma_f32 v[150:151], v[80:81], v[28:29], v[150:151] op_sel_hi:[1,0,1] neg_lo:[1,0,0] neg_hi:[1,0,0]
	v_pk_fma_f32 v[150:151], v[82:83], v[28:29], v[150:151] op_sel:[0,1,0] op_sel_hi:[1,1,1] neg_lo:[1,0,0] neg_hi:[1,0,0]
	v_pk_fma_f32 v[150:151], v[84:85], v[30:31], v[150:151] op_sel_hi:[1,0,1] neg_lo:[1,0,0] neg_hi:[1,0,0]
	v_pk_fma_f32 v[150:151], v[86:87], v[30:31], v[150:151] op_sel:[0,1,0] op_sel_hi:[1,1,1] neg_lo:[1,0,0] neg_hi:[1,0,0]
	ds_read_b128 v[12:15], v228 offset:11328
	v_pk_fma_f32 v[150:151], v[88:89], v[32:33], v[150:151] op_sel_hi:[1,0,1] neg_lo:[1,0,0] neg_hi:[1,0,0]
	v_pk_fma_f32 v[150:151], v[90:91], v[32:33], v[150:151] op_sel:[0,1,0] op_sel_hi:[1,1,1] neg_lo:[1,0,0] neg_hi:[1,0,0]
	v_pk_fma_f32 v[150:151], v[92:93], v[34:35], v[150:151] op_sel_hi:[1,0,1] neg_lo:[1,0,0] neg_hi:[1,0,0]
	v_pk_fma_f32 v[150:151], v[94:95], v[34:35], v[150:151] op_sel:[0,1,0] op_sel_hi:[1,1,1] neg_lo:[1,0,0] neg_hi:[1,0,0]
	ds_read_b128 v[16:19], v228 offset:11344
	v_pk_fma_f32 v[150:151], v[96:97], v[36:37], v[150:151] op_sel_hi:[1,0,1] neg_lo:[1,0,0] neg_hi:[1,0,0]
	v_pk_fma_f32 v[150:151], v[98:99], v[36:37], v[150:151] op_sel:[0,1,0] op_sel_hi:[1,1,1] neg_lo:[1,0,0] neg_hi:[1,0,0]
	v_pk_fma_f32 v[150:151], v[100:101], v[38:39], v[150:151] op_sel_hi:[1,0,1] neg_lo:[1,0,0] neg_hi:[1,0,0]
	v_pk_fma_f32 v[150:151], v[102:103], v[38:39], v[150:151] op_sel:[0,1,0] op_sel_hi:[1,1,1] neg_lo:[1,0,0] neg_hi:[1,0,0]
	ds_read_b128 v[20:23], v228 offset:11360
	s_waitcnt lgkmcnt(11)
	v_pk_fma_f32 v[150:151], v[104:105], v[40:41], v[150:151] op_sel_hi:[1,0,1] neg_lo:[1,0,0] neg_hi:[1,0,0]
	v_pk_fma_f32 v[150:151], v[106:107], v[40:41], v[150:151] op_sel:[0,1,0] op_sel_hi:[1,1,1] neg_lo:[1,0,0] neg_hi:[1,0,0]
	v_pk_fma_f32 v[150:151], v[108:109], v[42:43], v[150:151] op_sel_hi:[1,0,1] neg_lo:[1,0,0] neg_hi:[1,0,0]
	v_pk_fma_f32 v[150:151], v[110:111], v[42:43], v[150:151] op_sel:[0,1,0] op_sel_hi:[1,1,1] neg_lo:[1,0,0] neg_hi:[1,0,0]
	ds_read_b128 v[24:27], v228 offset:11376
	v_pk_fma_f32 v[150:151], v[112:113], v[44:45], v[150:151] op_sel_hi:[1,0,1] neg_lo:[1,0,0] neg_hi:[1,0,0]
	v_pk_fma_f32 v[150:151], v[114:115], v[44:45], v[150:151] op_sel:[0,1,0] op_sel_hi:[1,1,1] neg_lo:[1,0,0] neg_hi:[1,0,0]
	v_pk_fma_f32 v[150:151], v[116:117], v[46:47], v[150:151] op_sel_hi:[1,0,1] neg_lo:[1,0,0] neg_hi:[1,0,0]
	v_pk_fma_f32 v[150:151], v[118:119], v[46:47], v[150:151] op_sel:[0,1,0] op_sel_hi:[1,1,1] neg_lo:[1,0,0] neg_hi:[1,0,0]
	ds_read_b128 v[28:31], v228 offset:11392
	v_pk_fma_f32 v[150:151], v[120:121], v[48:49], v[150:151] op_sel_hi:[1,0,1] neg_lo:[1,0,0] neg_hi:[1,0,0]
	v_pk_fma_f32 v[150:151], v[122:123], v[48:49], v[150:151] op_sel:[0,1,0] op_sel_hi:[1,1,1] neg_lo:[1,0,0] neg_hi:[1,0,0]
	v_pk_fma_f32 v[150:151], v[124:125], v[50:51], v[150:151] op_sel_hi:[1,0,1] neg_lo:[1,0,0] neg_hi:[1,0,0]
	v_pk_fma_f32 v[150:151], v[126:127], v[50:51], v[150:151] op_sel:[0,1,0] op_sel_hi:[1,1,1] neg_lo:[1,0,0] neg_hi:[1,0,0]
	ds_read_b128 v[32:35], v228 offset:11408
	v_pk_fma_f32 v[150:151], v[128:129], v[52:53], v[150:151] op_sel_hi:[1,0,1] neg_lo:[1,0,0] neg_hi:[1,0,0]
	v_pk_fma_f32 v[150:151], v[130:131], v[52:53], v[150:151] op_sel:[0,1,0] op_sel_hi:[1,1,1] neg_lo:[1,0,0] neg_hi:[1,0,0]
	v_pk_fma_f32 v[150:151], v[132:133], v[54:55], v[150:151] op_sel_hi:[1,0,1] neg_lo:[1,0,0] neg_hi:[1,0,0]
	v_pk_fma_f32 v[150:151], v[134:135], v[54:55], v[150:151] op_sel:[0,1,0] op_sel_hi:[1,1,1] neg_lo:[1,0,0] neg_hi:[1,0,0]
	ds_read_b128 v[36:39], v228 offset:11424
	s_waitcnt lgkmcnt(9)
; #define LAS __attribute__((address_space(3)))
; __device__ __forceinline__ void phase_gdb(const int wvs, const Params& p, LAS unsigned char* lds, int nwg) {
;     ...
;     { float x[64]; const bool isw = t >= 64;
; #pragma unroll
;       for (int i = 0; i < 64; ++i) { const float v = (float)R[i * RP + t]; x[i] = v * bs[i] * (isw ? __expf(gcs[i]) : 1.0f); asm volatile("" : "+v"(x[i])); if ((i & 7) == 7) __builtin_amdgcn_sched_barrier(0); }
; #pragma unroll
;       for (int i = 1; i < 64; ++i) {
; #pragma unroll
;         for (int j4 = 0; j4 < (i + 3) / 4; ++j4) { const f32x4 m4 = *(const LAS f32x4*)(M + i * 64 + j4 * 4);
; #pragma unroll
;           for (int jj = 0; jj < 4; ++jj) if (j4 * 4 + jj < i) x[i] -= m4[jj] * x[j4 * 4 + jj]; }
;         __builtin_amdgcn_sched_barrier(0); }
; #pragma unroll
;       for (int i = 0; i < 64; ++i) R[i * RP + t] = (hf)x[i]; }
	v_pk_fma_f32 v[150:151], v[136:137], v[56:57], v[150:151] op_sel_hi:[1,0,1] neg_lo:[1,0,0] neg_hi:[1,0,0]
	v_pk_fma_f32 v[150:151], v[138:139], v[56:57], v[150:151] op_sel:[0,1,0] op_sel_hi:[1,1,1] neg_lo:[1,0,0] neg_hi:[1,0,0]
	v_pk_fma_f32 v[150:151], v[140:141], v[58:59], v[150:151] op_sel_hi:[1,0,1] neg_lo:[1,0,0] neg_hi:[1,0,0]
	v_pk_fma_f32 v[150:151], v[142:143], v[58:59], v[150:151] op_sel:[0,1,0] op_sel_hi:[1,1,1] neg_lo:[1,0,0] neg_hi:[1,0,0]
	ds_read_b128 v[40:43], v228 offset:11520
	v_pk_fma_f32 v[150:151], v[144:145], v[60:61], v[150:151] op_sel_hi:[1,0,1] neg_lo:[1,0,0] neg_hi:[1,0,0]
	v_pk_fma_f32 v[150:151], v[146:147], v[60:61], v[150:151] op_sel:[0,1,0] op_sel_hi:[1,1,1] neg_lo:[1,0,0] neg_hi:[1,0,0]
	v_fma_mixlo_f16 v3, -v148, v62, v150
	v_fma_mixlo_f16 v238, -v149, v62, v151
	v_pk_fma_f32 v[150:151], v[148:149], v[62:63], v[150:151] op_sel_hi:[1,0,1] neg_lo:[1,0,0] neg_hi:[1,0,0]
	ds_write_b16 v253, v3 offset:28080
	ds_write_b16 v253, v238 offset:28208
	ds_read_b128 v[44:47], v228 offset:11536
	v_pk_fma_f32 v[152:153], v[64:65], v[244:245], v[152:153] op_sel_hi:[1,0,1] neg_lo:[1,0,0] neg_hi:[1,0,0]
	v_pk_fma_f32 v[152:153], v[66:67], v[244:245], v[152:153] op_sel:[0,1,0] op_sel_hi:[1,1,1] neg_lo:[1,0,0] neg_hi:[1,0,0]
	v_pk_fma_f32 v[152:153], v[68:69], v[246:247], v[152:153] op_sel_hi:[1,0,1] neg_lo:[1,0,0] neg_hi:[1,0,0]
	v_pk_fma_f32 v[152:153], v[70:71], v[246:247], v[152:153] op_sel:[0,1,0] op_sel_hi:[1,1,1] neg_lo:[1,0,0] neg_hi:[1,0,0]
	ds_read_b128 v[48:51], v228 offset:11552
	v_pk_fma_f32 v[152:153], v[72:73], v[248:249], v[152:153] op_sel_hi:[1,0,1] neg_lo:[1,0,0] neg_hi:[1,0,0]
	v_pk_fma_f32 v[152:153], v[74:75], v[248:249], v[152:153] op_sel:[0,1,0] op_sel_hi:[1,1,1] neg_lo:[1,0,0] neg_hi:[1,0,0]
	v_pk_fma_f32 v[152:153], v[76:77], v[250:251], v[152:153] op_sel_hi:[1,0,1] neg_lo:[1,0,0] neg_hi:[1,0,0]
	v_pk_fma_f32 v[152:153], v[78:79], v[250:251], v[152:153] op_sel:[0,1,0] op_sel_hi:[1,1,1] neg_lo:[1,0,0] neg_hi:[1,0,0]
	ds_read_b128 v[52:55], v228 offset:11568
	s_waitcnt lgkmcnt(11)
	v_pk_fma_f32 v[152:153], v[80:81], v[4:5], v[152:153] op_sel_hi:[1,0,1] neg_lo:[1,0,0] neg_hi:[1,0,0]
	v_pk_fma_f32 v[152:153], v[82:83], v[4:5], v[152:153] op_sel:[0,1,0] op_sel_hi:[1,1,1] neg_lo:[1,0,0] neg_hi:[1,0,0]
	v_pk_fma_f32 v[152:153], v[84:85], v[6:7], v[152:153] op_sel_hi:[1,0,1] neg_lo:[1,0,0] neg_hi:[1,0,0]
	v_pk_fma_f32 v[152:153], v[86:87], v[6:7], v[152:153] op_sel:[0,1,0] op_sel_hi:[1,1,1] neg_lo:[1,0,0] neg_hi:[1,0,0]
	ds_read_b128 v[56:59], v228 offset:11584
	v_pk_fma_f32 v[152:153], v[88:89], v[8:9], v[152:153] op_sel_hi:[1,0,1] neg_lo:[1,0,0] neg_hi:[1,0,0]
	v_pk_fma_f32 v[152:153], v[90:91], v[8:9], v[152:153] op_sel:[0,1,0] op_sel_hi:[1,1,1] neg_lo:[1,0,0] neg_hi:[1,0,0]
	v_pk_fma_f32 v[152:153], v[92:93], v[10:11], v[152:153] op_sel_hi:[1,0,1] neg_lo:[1,0,0] neg_hi:[1,0,0]
	v_pk_fma_f32 v[152:153], v[94:95], v[10:11], v[152:153] op_sel:[0,1,0] op_sel_hi:[1,1,1] neg_lo:[1,0,0] neg_hi:[1,0,0]
	ds_read_b128 v[60:63], v228 offset:11600
	v_pk_fma_f32 v[152:153], v[96:97], v[12:13], v[152:153] op_sel_hi:[1,0,1] neg_lo:[1,0,0] neg_hi:[1,0,0]
	v_pk_fma_f32 v[152:153], v[98:99], v[12:13], v[152:153] op_sel:[0,1,0] op_sel_hi:[1,1,1] neg_lo:[1,0,0] neg_hi:[1,0,0]
	v_pk_fma_f32 v[152:153], v[100:101], v[14:15], v[152:153] op_sel_hi:[1,0,1] neg_lo:[1,0,0] neg_hi:[1,0,0]
	v_pk_fma_f32 v[152:153], v[102:103], v[14:15], v[152:153] op_sel:[0,1,0] op_sel_hi:[1,1,1] neg_lo:[1,0,0] neg_hi:[1,0,0]
	ds_read_b128 v[244:247], v228 offset:11616
	v_pk_fma_f32 v[152:153], v[104:105], v[16:17], v[152:153] op_sel_hi:[1,0,1] neg_lo:[1,0,0] neg_hi:[1,0,0]
	v_pk_fma_f32 v[152:153], v[106:107], v[16:17], v[152:153] op_sel:[0,1,0] op_sel_hi:[1,1,1] neg_lo:[1,0,0] neg_hi:[1,0,0]
	v_pk_fma_f32 v[152:153], v[108:109], v[18:19], v[152:153] op_sel_hi:[1,0,1] neg_lo:[1,0,0] neg_hi:[1,0,0]
	v_pk_fma_f32 v[152:153], v[110:111], v[18:19], v[152:153] op_sel:[0,1,0] op_sel_hi:[1,1,1] neg_lo:[1,0,0] neg_hi:[1,0,0]
	ds_read_b128 v[248:251], v228 offset:11632
	s_waitcnt lgkmcnt(11)
	v_pk_fma_f32 v[152:153], v[112:113], v[20:21], v[152:153] op_sel_hi:[1,0,1] neg_lo:[1,0,0] neg_hi:[1,0,0]
	v_pk_fma_f32 v[152:153], v[114:115], v[20:21], v[152:153] op_sel:[0,1,0] op_sel_hi:[1,1,1] neg_lo:[1,0,0] neg_hi:[1,0,0]
	v_pk_fma_f32 v[152:153], v[116:117], v[22:23], v[152:153] op_sel_hi:[1,0,1] neg_lo:[1,0,0] neg_hi:[1,0,0]
	v_pk_fma_f32 v[152:153], v[118:119], v[22:23], v[152:153] op_sel:[0,1,0] op_sel_hi:[1,1,1] neg_lo:[1,0,0] neg_hi:[1,0,0]
	ds_read_b128 v[4:7], v228 offset:11648
	v_pk_fma_f32 v[152:153], v[120:121], v[24:25], v[152:153] op_sel_hi:[1,0,1] neg_lo:[1,0,0] neg_hi:[1,0,0]
	v_pk_fma_f32 v[152:153], v[122:123], v[24:25], v[152:153] op_sel:[0,1,0] op_sel_hi:[1,1,1] neg_lo:[1,0,0] neg_hi:[1,0,0]
	v_pk_fma_f32 v[152:153], v[124:125], v[26:27], v[152:153] op_sel_hi:[1,0,1] neg_lo:[1,0,0] neg_hi:[1,0,0]
	v_pk_fma_f32 v[152:153], v[126:127], v[26:27], v[152:153] op_sel:[0,1,0] op_sel_hi:[1,1,1] neg_lo:[1,0,0] neg_hi:[1,0,0]
	ds_read_b128 v[8:11], v228 offset:11664
	v_pk_fma_f32 v[152:153], v[128:129], v[28:29], v[152:153] op_sel_hi:[1,0,1] neg_lo:[1,0,0] neg_hi:[1,0,0]
	v_pk_fma_f32 v[152:153], v[130:131], v[28:29], v[152:153] op_sel:[0,1,0] op_sel_hi:[1,1,1] neg_lo:[1,0,0] neg_hi:[1,0,0]
	v_pk_fma_f32 v[152:153], v[132:133], v[30:31], v[152:153] op_sel_hi:[1,0,1] neg_lo:[1,0,0] neg_hi:[1,0,0]
	v_pk_fma_f32 v[152:153], v[134:135], v[30:31], v[152:153] op_sel:[0,1,0] op_sel_hi:[1,1,1] neg_lo:[1,0,0] neg_hi:[1,0,0]
	ds_read_b128 v[12:15], v228 offset:11680
	v_pk_fma_f32 v[152:153], v[136:137], v[32:33], v[152:153] op_sel_hi:[1,0,1] neg_lo:[1,0,0] neg_hi:[1,0,0]
	v_pk_fma_f32 v[152:153], v[138:139], v[32:33], v[152:153] op_sel:[0,1,0] op_sel_hi:[1,1,1] neg_lo:[1,0,0] neg_hi:[1,0,0]
	v_pk_fma_f32 v[152:153], v[140:141], v[34:35], v[152:153] op_sel_hi:[1,0,1] neg_lo:[1,0,0] neg_hi:[1,0,0]
	v_pk_fma_f32 v[152:153], v[142:143], v[34:35], v[152:153] op_sel:[0,1,0] op_sel_hi:[1,1,1] neg_lo:[1,0,0] neg_hi:[1,0,0]
	ds_read_b128 v[16:19], v228 offset:11696
	s_waitcnt lgkmcnt(9)
; #define LAS __attribute__((address_space(3)))
; __device__ __forceinline__ void phase_gdb(const int wvs, const Params& p, LAS unsigned char* lds, int nwg) {
;     ...
;     { float x[64]; const bool isw = t >= 64;
; #pragma unroll
;       for (int i = 0; i < 64; ++i) { const float v = (float)R[i * RP + t]; x[i] = v * bs[i] * (isw ? __expf(gcs[i]) : 1.0f); asm volatile("" : "+v"(x[i])); if ((i & 7) == 7) __builtin_amdgcn_sched_barrier(0); }
; #pragma unroll
;       for (int i = 1; i < 64; ++i) {
; #pragma unroll
;         for (int j4 = 0; j4 < (i + 3) / 4; ++j4) { const f32x4 m4 = *(const LAS f32x4*)(M + i * 64 + j4 * 4);
; #pragma unroll
;           for (int jj = 0; jj < 4; ++jj) if (j4 * 4 + jj < i) x[i] -= m4[jj] * x[j4 * 4 + jj]; }
;         __builtin_amdgcn_sched_barrier(0); }
; #pragma unroll
;       for (int i = 0; i < 64; ++i) R[i * RP + t] = (hf)x[i]; }
	v_pk_fma_f32 v[152:153], v[144:145], v[36:37], v[152:153] op_sel_hi:[1,0,1] neg_lo:[1,0,0] neg_hi:[1,0,0]
	v_pk_fma_f32 v[152:153], v[146:147], v[36:37], v[152:153] op_sel:[0,1,0] op_sel_hi:[1,1,1] neg_lo:[1,0,0] neg_hi:[1,0,0]
	v_pk_fma_f32 v[152:153], v[148:149], v[38:39], v[152:153] op_sel_hi:[1,0,1] neg_lo:[1,0,0] neg_hi:[1,0,0]
	v_fma_mixlo_f16 v239, -v150, v39, v152
	v_fma_mixlo_f16 v240, -v151, v39, v153
	v_pk_fma_f32 v[152:153], v[150:151], v[38:39], v[152:153] op_sel:[0,1,0] op_sel_hi:[1,1,1] neg_lo:[1,0,0] neg_hi:[1,0,0]
	ds_write_b16 v253, v239 offset:28352
	ds_write_b16 v253, v240 offset:28480
	ds_read_b128 v[20:23], v228 offset:11776
	v_pk_fma_f32 v[154:155], v[64:65], v[40:41], v[154:155] op_sel_hi:[1,0,1] neg_lo:[1,0,0] neg_hi:[1,0,0]
	v_pk_fma_f32 v[154:155], v[66:67], v[40:41], v[154:155] op_sel:[0,1,0] op_sel_hi:[1,1,1] neg_lo:[1,0,0] neg_hi:[1,0,0]
	v_pk_fma_f32 v[154:155], v[68:69], v[42:43], v[154:155] op_sel_hi:[1,0,1] neg_lo:[1,0,0] neg_hi:[1,0,0]
	v_pk_fma_f32 v[154:155], v[70:71], v[42:43], v[154:155] op_sel:[0,1,0] op_sel_hi:[1,1,1] neg_lo:[1,0,0] neg_hi:[1,0,0]
	ds_read_b128 v[24:27], v228 offset:11792
	v_pk_fma_f32 v[154:155], v[72:73], v[44:45], v[154:155] op_sel_hi:[1,0,1] neg_lo:[1,0,0] neg_hi:[1,0,0]
	v_pk_fma_f32 v[154:155], v[74:75], v[44:45], v[154:155] op_sel:[0,1,0] op_sel_hi:[1,1,1] neg_lo:[1,0,0] neg_hi:[1,0,0]
	v_pk_fma_f32 v[154:155], v[76:77], v[46:47], v[154:155] op_sel_hi:[1,0,1] neg_lo:[1,0,0] neg_hi:[1,0,0]
	v_pk_fma_f32 v[154:155], v[78:79], v[46:47], v[154:155] op_sel:[0,1,0] op_sel_hi:[1,1,1] neg_lo:[1,0,0] neg_hi:[1,0,0]
	ds_read_b128 v[28:31], v228 offset:11808
	v_pk_fma_f32 v[154:155], v[80:81], v[48:49], v[154:155] op_sel_hi:[1,0,1] neg_lo:[1,0,0] neg_hi:[1,0,0]
	v_pk_fma_f32 v[154:155], v[82:83], v[48:49], v[154:155] op_sel:[0,1,0] op_sel_hi:[1,1,1] neg_lo:[1,0,0] neg_hi:[1,0,0]
	v_pk_fma_f32 v[154:155], v[84:85], v[50:51], v[154:155] op_sel_hi:[1,0,1] neg_lo:[1,0,0] neg_hi:[1,0,0]
	v_pk_fma_f32 v[154:155], v[86:87], v[50:51], v[154:155] op_sel:[0,1,0] op_sel_hi:[1,1,1] neg_lo:[1,0,0] neg_hi:[1,0,0]
	ds_read_b128 v[32:35], v228 offset:11824
	s_waitcnt lgkmcnt(11)
	v_pk_fma_f32 v[154:155], v[88:89], v[52:53], v[154:155] op_sel_hi:[1,0,1] neg_lo:[1,0,0] neg_hi:[1,0,0]
	v_pk_fma_f32 v[154:155], v[90:91], v[52:53], v[154:155] op_sel:[0,1,0] op_sel_hi:[1,1,1] neg_lo:[1,0,0] neg_hi:[1,0,0]
	v_pk_fma_f32 v[154:155], v[92:93], v[54:55], v[154:155] op_sel_hi:[1,0,1] neg_lo:[1,0,0] neg_hi:[1,0,0]
	v_pk_fma_f32 v[154:155], v[94:95], v[54:55], v[154:155] op_sel:[0,1,0] op_sel_hi:[1,1,1] neg_lo:[1,0,0] neg_hi:[1,0,0]
	ds_read_b128 v[36:39], v228 offset:11840
	v_pk_fma_f32 v[154:155], v[96:97], v[56:57], v[154:155] op_sel_hi:[1,0,1] neg_lo:[1,0,0] neg_hi:[1,0,0]
	v_pk_fma_f32 v[154:155], v[98:99], v[56:57], v[154:155] op_sel:[0,1,0] op_sel_hi:[1,1,1] neg_lo:[1,0,0] neg_hi:[1,0,0]
	v_pk_fma_f32 v[154:155], v[100:101], v[58:59], v[154:155] op_sel_hi:[1,0,1] neg_lo:[1,0,0] neg_hi:[1,0,0]
	v_pk_fma_f32 v[154:155], v[102:103], v[58:59], v[154:155] op_sel:[0,1,0] op_sel_hi:[1,1,1] neg_lo:[1,0,0] neg_hi:[1,0,0]
	ds_read_b128 v[40:43], v228 offset:11856
	v_pk_fma_f32 v[154:155], v[104:105], v[60:61], v[154:155] op_sel_hi:[1,0,1] neg_lo:[1,0,0] neg_hi:[1,0,0]
	v_pk_fma_f32 v[154:155], v[106:107], v[60:61], v[154:155] op_sel:[0,1,0] op_sel_hi:[1,1,1] neg_lo:[1,0,0] neg_hi:[1,0,0]
	v_pk_fma_f32 v[154:155], v[108:109], v[62:63], v[154:155] op_sel_hi:[1,0,1] neg_lo:[1,0,0] neg_hi:[1,0,0]
	v_pk_fma_f32 v[154:155], v[110:111], v[62:63], v[154:155] op_sel:[0,1,0] op_sel_hi:[1,1,1] neg_lo:[1,0,0] neg_hi:[1,0,0]
	ds_read_b128 v[44:47], v228 offset:11872
	v_pk_fma_f32 v[154:155], v[112:113], v[244:245], v[154:155] op_sel_hi:[1,0,1] neg_lo:[1,0,0] neg_hi:[1,0,0]
	v_pk_fma_f32 v[154:155], v[114:115], v[244:245], v[154:155] op_sel:[0,1,0] op_sel_hi:[1,1,1] neg_lo:[1,0,0] neg_hi:[1,0,0]
	v_pk_fma_f32 v[154:155], v[116:117], v[246:247], v[154:155] op_sel_hi:[1,0,1] neg_lo:[1,0,0] neg_hi:[1,0,0]
	v_pk_fma_f32 v[154:155], v[118:119], v[246:247], v[154:155] op_sel:[0,1,0] op_sel_hi:[1,1,1] neg_lo:[1,0,0] neg_hi:[1,0,0]
	ds_read_b128 v[48:51], v228 offset:11888
	s_waitcnt lgkmcnt(11)
	v_pk_fma_f32 v[154:155], v[120:121], v[248:249], v[154:155] op_sel_hi:[1,0,1] neg_lo:[1,0,0] neg_hi:[1,0,0]
	v_pk_fma_f32 v[154:155], v[122:123], v[248:249], v[154:155] op_sel:[0,1,0] op_sel_hi:[1,1,1] neg_lo:[1,0,0] neg_hi:[1,0,0]
	v_pk_fma_f32 v[154:155], v[124:125], v[250:251], v[154:155] op_sel_hi:[1,0,1] neg_lo:[1,0,0] neg_hi:[1,0,0]
	v_pk_fma_f32 v[154:155], v[126:127], v[250:251], v[154:155] op_sel:[0,1,0] op_sel_hi:[1,1,1] neg_lo:[1,0,0] neg_hi:[1,0,0]
	ds_read_b128 v[52:55], v228 offset:11904
	v_pk_fma_f32 v[154:155], v[128:129], v[4:5], v[154:155] op_sel_hi:[1,0,1] neg_lo:[1,0,0] neg_hi:[1,0,0]
	v_pk_fma_f32 v[154:155], v[130:131], v[4:5], v[154:155] op_sel:[0,1,0] op_sel_hi:[1,1,1] neg_lo:[1,0,0] neg_hi:[1,0,0]
	v_pk_fma_f32 v[154:155], v[132:133], v[6:7], v[154:155] op_sel_hi:[1,0,1] neg_lo:[1,0,0] neg_hi:[1,0,0]
	v_pk_fma_f32 v[154:155], v[134:135], v[6:7], v[154:155] op_sel:[0,1,0] op_sel_hi:[1,1,1] neg_lo:[1,0,0] neg_hi:[1,0,0]
	ds_read_b128 v[56:59], v228 offset:11920
	v_pk_fma_f32 v[154:155], v[136:137], v[8:9], v[154:155] op_sel_hi:[1,0,1] neg_lo:[1,0,0] neg_hi:[1,0,0]
	v_pk_fma_f32 v[154:155], v[138:139], v[8:9], v[154:155] op_sel:[0,1,0] op_sel_hi:[1,1,1] neg_lo:[1,0,0] neg_hi:[1,0,0]
	v_pk_fma_f32 v[154:155], v[140:141], v[10:11], v[154:155] op_sel_hi:[1,0,1] neg_lo:[1,0,0] neg_hi:[1,0,0]
	v_pk_fma_f32 v[154:155], v[142:143], v[10:11], v[154:155] op_sel:[0,1,0] op_sel_hi:[1,1,1] neg_lo:[1,0,0] neg_hi:[1,0,0]
	ds_read_b128 v[60:63], v228 offset:11936
	v_pk_fma_f32 v[154:155], v[144:145], v[12:13], v[154:155] op_sel_hi:[1,0,1] neg_lo:[1,0,0] neg_hi:[1,0,0]
	v_pk_fma_f32 v[154:155], v[146:147], v[12:13], v[154:155] op_sel:[0,1,0] op_sel_hi:[1,1,1] neg_lo:[1,0,0] neg_hi:[1,0,0]
	v_pk_fma_f32 v[154:155], v[148:149], v[14:15], v[154:155] op_sel_hi:[1,0,1] neg_lo:[1,0,0] neg_hi:[1,0,0]
	v_pk_fma_f32 v[154:155], v[150:151], v[14:15], v[154:155] op_sel:[0,1,0] op_sel_hi:[1,1,1] neg_lo:[1,0,0] neg_hi:[1,0,0]
	ds_read_b128 v[244:247], v228 offset:11952
	s_waitcnt lgkmcnt(9)
; #define LAS __attribute__((address_space(3)))
; __device__ __forceinline__ void phase_gdb(const int wvs, const Params& p, LAS unsigned char* lds, int nwg) {
;     ...
;     { float x[64]; const bool isw = t >= 64;
; #pragma unroll
;       for (int i = 0; i < 64; ++i) { const float v = (float)R[i * RP + t]; x[i] = v * bs[i] * (isw ? __expf(gcs[i]) : 1.0f); asm volatile("" : "+v"(x[i])); if ((i & 7) == 7) __builtin_amdgcn_sched_barrier(0); }
; #pragma unroll
;       for (int i = 1; i < 64; ++i) {
; #pragma unroll
;         for (int j4 = 0; j4 < (i + 3) / 4; ++j4) { const f32x4 m4 = *(const LAS f32x4*)(M + i * 64 + j4 * 4);
; #pragma unroll
;           for (int jj = 0; jj < 4; ++jj) if (j4 * 4 + jj < i) x[i] -= m4[jj] * x[j4 * 4 + jj]; }
;         __builtin_amdgcn_sched_barrier(0); }
; #pragma unroll
;       for (int i = 0; i < 64; ++i) R[i * RP + t] = (hf)x[i]; }
	v_fma_mixlo_f16 v0, -v152, v16, v154
	v_fma_mixlo_f16 v2, -v153, v16, v155
	v_pk_fma_f32 v[154:155], v[152:153], v[16:17], v[154:155] op_sel_hi:[1,0,1] neg_lo:[1,0,0] neg_hi:[1,0,0]
	ds_write_b16 v253, v0 offset:28624
	ds_write_b16 v253, v2 offset:28752
	ds_read_b128 v[248:251], v228 offset:12032
	v_pk_fma_f32 v[156:157], v[64:65], v[20:21], v[156:157] op_sel_hi:[1,0,1] neg_lo:[1,0,0] neg_hi:[1,0,0]
	v_pk_fma_f32 v[156:157], v[66:67], v[20:21], v[156:157] op_sel:[0,1,0] op_sel_hi:[1,1,1] neg_lo:[1,0,0] neg_hi:[1,0,0]
	v_pk_fma_f32 v[156:157], v[68:69], v[22:23], v[156:157] op_sel_hi:[1,0,1] neg_lo:[1,0,0] neg_hi:[1,0,0]
	v_pk_fma_f32 v[156:157], v[70:71], v[22:23], v[156:157] op_sel:[0,1,0] op_sel_hi:[1,1,1] neg_lo:[1,0,0] neg_hi:[1,0,0]
	ds_read_b128 v[4:7], v228 offset:12048
	v_pk_fma_f32 v[156:157], v[72:73], v[24:25], v[156:157] op_sel_hi:[1,0,1] neg_lo:[1,0,0] neg_hi:[1,0,0]
	v_pk_fma_f32 v[156:157], v[74:75], v[24:25], v[156:157] op_sel:[0,1,0] op_sel_hi:[1,1,1] neg_lo:[1,0,0] neg_hi:[1,0,0]
	v_pk_fma_f32 v[156:157], v[76:77], v[26:27], v[156:157] op_sel_hi:[1,0,1] neg_lo:[1,0,0] neg_hi:[1,0,0]
	v_pk_fma_f32 v[156:157], v[78:79], v[26:27], v[156:157] op_sel:[0,1,0] op_sel_hi:[1,1,1] neg_lo:[1,0,0] neg_hi:[1,0,0]
	ds_read_b128 v[8:11], v228 offset:12064
	v_pk_fma_f32 v[156:157], v[80:81], v[28:29], v[156:157] op_sel_hi:[1,0,1] neg_lo:[1,0,0] neg_hi:[1,0,0]
	v_pk_fma_f32 v[156:157], v[82:83], v[28:29], v[156:157] op_sel:[0,1,0] op_sel_hi:[1,1,1] neg_lo:[1,0,0] neg_hi:[1,0,0]
	v_pk_fma_f32 v[156:157], v[84:85], v[30:31], v[156:157] op_sel_hi:[1,0,1] neg_lo:[1,0,0] neg_hi:[1,0,0]
	v_pk_fma_f32 v[156:157], v[86:87], v[30:31], v[156:157] op_sel:[0,1,0] op_sel_hi:[1,1,1] neg_lo:[1,0,0] neg_hi:[1,0,0]
	ds_read_b128 v[12:15], v228 offset:12080
	s_waitcnt lgkmcnt(11)
	v_pk_fma_f32 v[156:157], v[88:89], v[32:33], v[156:157] op_sel_hi:[1,0,1] neg_lo:[1,0,0] neg_hi:[1,0,0]
	v_pk_fma_f32 v[156:157], v[90:91], v[32:33], v[156:157] op_sel:[0,1,0] op_sel_hi:[1,1,1] neg_lo:[1,0,0] neg_hi:[1,0,0]
	v_pk_fma_f32 v[156:157], v[92:93], v[34:35], v[156:157] op_sel_hi:[1,0,1] neg_lo:[1,0,0] neg_hi:[1,0,0]
	v_pk_fma_f32 v[156:157], v[94:95], v[34:35], v[156:157] op_sel:[0,1,0] op_sel_hi:[1,1,1] neg_lo:[1,0,0] neg_hi:[1,0,0]
	ds_read_b128 v[16:19], v228 offset:12096
	v_pk_fma_f32 v[156:157], v[96:97], v[36:37], v[156:157] op_sel_hi:[1,0,1] neg_lo:[1,0,0] neg_hi:[1,0,0]
	v_pk_fma_f32 v[156:157], v[98:99], v[36:37], v[156:157] op_sel:[0,1,0] op_sel_hi:[1,1,1] neg_lo:[1,0,0] neg_hi:[1,0,0]
	v_pk_fma_f32 v[156:157], v[100:101], v[38:39], v[156:157] op_sel_hi:[1,0,1] neg_lo:[1,0,0] neg_hi:[1,0,0]
	v_pk_fma_f32 v[156:157], v[102:103], v[38:39], v[156:157] op_sel:[0,1,0] op_sel_hi:[1,1,1] neg_lo:[1,0,0] neg_hi:[1,0,0]
	ds_read_b128 v[20:23], v228 offset:12112
	v_pk_fma_f32 v[156:157], v[104:105], v[40:41], v[156:157] op_sel_hi:[1,0,1] neg_lo:[1,0,0] neg_hi:[1,0,0]
	v_pk_fma_f32 v[156:157], v[106:107], v[40:41], v[156:157] op_sel:[0,1,0] op_sel_hi:[1,1,1] neg_lo:[1,0,0] neg_hi:[1,0,0]
	v_pk_fma_f32 v[156:157], v[108:109], v[42:43], v[156:157] op_sel_hi:[1,0,1] neg_lo:[1,0,0] neg_hi:[1,0,0]
	v_pk_fma_f32 v[156:157], v[110:111], v[42:43], v[156:157] op_sel:[0,1,0] op_sel_hi:[1,1,1] neg_lo:[1,0,0] neg_hi:[1,0,0]
	ds_read_b128 v[24:27], v228 offset:12128
	v_pk_fma_f32 v[156:157], v[112:113], v[44:45], v[156:157] op_sel_hi:[1,0,1] neg_lo:[1,0,0] neg_hi:[1,0,0]
	v_pk_fma_f32 v[156:157], v[114:115], v[44:45], v[156:157] op_sel:[0,1,0] op_sel_hi:[1,1,1] neg_lo:[1,0,0] neg_hi:[1,0,0]
	v_pk_fma_f32 v[156:157], v[116:117], v[46:47], v[156:157] op_sel_hi:[1,0,1] neg_lo:[1,0,0] neg_hi:[1,0,0]
	v_pk_fma_f32 v[156:157], v[118:119], v[46:47], v[156:157] op_sel:[0,1,0] op_sel_hi:[1,1,1] neg_lo:[1,0,0] neg_hi:[1,0,0]
	ds_read_b128 v[28:31], v228 offset:12144
	s_waitcnt lgkmcnt(11)
	v_pk_fma_f32 v[156:157], v[120:121], v[48:49], v[156:157] op_sel_hi:[1,0,1] neg_lo:[1,0,0] neg_hi:[1,0,0]
	v_pk_fma_f32 v[156:157], v[122:123], v[48:49], v[156:157] op_sel:[0,1,0] op_sel_hi:[1,1,1] neg_lo:[1,0,0] neg_hi:[1,0,0]
	v_pk_fma_f32 v[156:157], v[124:125], v[50:51], v[156:157] op_sel_hi:[1,0,1] neg_lo:[1,0,0] neg_hi:[1,0,0]
	v_pk_fma_f32 v[156:157], v[126:127], v[50:51], v[156:157] op_sel:[0,1,0] op_sel_hi:[1,1,1] neg_lo:[1,0,0] neg_hi:[1,0,0]
	ds_read_b128 v[32:35], v228 offset:12160
	v_pk_fma_f32 v[156:157], v[128:129], v[52:53], v[156:157] op_sel_hi:[1,0,1] neg_lo:[1,0,0] neg_hi:[1,0,0]
	v_pk_fma_f32 v[156:157], v[130:131], v[52:53], v[156:157] op_sel:[0,1,0] op_sel_hi:[1,1,1] neg_lo:[1,0,0] neg_hi:[1,0,0]
	v_pk_fma_f32 v[156:157], v[132:133], v[54:55], v[156:157] op_sel_hi:[1,0,1] neg_lo:[1,0,0] neg_hi:[1,0,0]
	v_pk_fma_f32 v[156:157], v[134:135], v[54:55], v[156:157] op_sel:[0,1,0] op_sel_hi:[1,1,1] neg_lo:[1,0,0] neg_hi:[1,0,0]
	ds_read_b128 v[36:39], v228 offset:12176
	v_pk_fma_f32 v[156:157], v[136:137], v[56:57], v[156:157] op_sel_hi:[1,0,1] neg_lo:[1,0,0] neg_hi:[1,0,0]
	v_pk_fma_f32 v[156:157], v[138:139], v[56:57], v[156:157] op_sel:[0,1,0] op_sel_hi:[1,1,1] neg_lo:[1,0,0] neg_hi:[1,0,0]
	v_pk_fma_f32 v[156:157], v[140:141], v[58:59], v[156:157] op_sel_hi:[1,0,1] neg_lo:[1,0,0] neg_hi:[1,0,0]
	v_pk_fma_f32 v[156:157], v[142:143], v[58:59], v[156:157] op_sel:[0,1,0] op_sel_hi:[1,1,1] neg_lo:[1,0,0] neg_hi:[1,0,0]
	ds_read_b128 v[40:43], v228 offset:12192
	v_pk_fma_f32 v[156:157], v[144:145], v[60:61], v[156:157] op_sel_hi:[1,0,1] neg_lo:[1,0,0] neg_hi:[1,0,0]
	v_pk_fma_f32 v[156:157], v[146:147], v[60:61], v[156:157] op_sel:[0,1,0] op_sel_hi:[1,1,1] neg_lo:[1,0,0] neg_hi:[1,0,0]
	v_pk_fma_f32 v[156:157], v[148:149], v[62:63], v[156:157] op_sel_hi:[1,0,1] neg_lo:[1,0,0] neg_hi:[1,0,0]
	v_pk_fma_f32 v[156:157], v[150:151], v[62:63], v[156:157] op_sel:[0,1,0] op_sel_hi:[1,1,1] neg_lo:[1,0,0] neg_hi:[1,0,0]
	ds_read_b128 v[44:47], v228 offset:12208
	s_waitcnt lgkmcnt(9)
; #define LAS __attribute__((address_space(3)))
; __device__ __forceinline__ void phase_gdb(const int wvs, const Params& p, LAS unsigned char* lds, int nwg) {
;     ...
;     { float x[64]; const bool isw = t >= 64;
; #pragma unroll
;       for (int i = 0; i < 64; ++i) { const float v = (float)R[i * RP + t]; x[i] = v * bs[i] * (isw ? __expf(gcs[i]) : 1.0f); asm volatile("" : "+v"(x[i])); if ((i & 7) == 7) __builtin_amdgcn_sched_barrier(0); }
; #pragma unroll
;       for (int i = 1; i < 64; ++i) {
; #pragma unroll
;         for (int j4 = 0; j4 < (i + 3) / 4; ++j4) { const f32x4 m4 = *(const LAS f32x4*)(M + i * 64 + j4 * 4);
; #pragma unroll
;           for (int jj = 0; jj < 4; ++jj) if (j4 * 4 + jj < i) x[i] -= m4[jj] * x[j4 * 4 + jj]; }
;         __builtin_amdgcn_sched_barrier(0); }
; #pragma unroll
;       for (int i = 0; i < 64; ++i) R[i * RP + t] = (hf)x[i]; }
	v_pk_fma_f32 v[156:157], v[152:153], v[244:245], v[156:157] op_sel_hi:[1,0,1] neg_lo:[1,0,0] neg_hi:[1,0,0]
	v_fma_mixlo_f16 v3, -v154, v245, v156
	v_fma_mixlo_f16 v238, -v155, v245, v157
	v_pk_fma_f32 v[156:157], v[154:155], v[244:245], v[156:157] op_sel:[0,1,0] op_sel_hi:[1,1,1] neg_lo:[1,0,0] neg_hi:[1,0,0]
	ds_write_b16 v253, v3 offset:28896
	ds_write_b16 v253, v238 offset:29024
	ds_read_b128 v[48:51], v228 offset:12288
	v_pk_fma_f32 v[158:159], v[64:65], v[248:249], v[158:159] op_sel_hi:[1,0,1] neg_lo:[1,0,0] neg_hi:[1,0,0]
	v_pk_fma_f32 v[158:159], v[66:67], v[248:249], v[158:159] op_sel:[0,1,0] op_sel_hi:[1,1,1] neg_lo:[1,0,0] neg_hi:[1,0,0]
	v_pk_fma_f32 v[158:159], v[68:69], v[250:251], v[158:159] op_sel_hi:[1,0,1] neg_lo:[1,0,0] neg_hi:[1,0,0]
	v_pk_fma_f32 v[158:159], v[70:71], v[250:251], v[158:159] op_sel:[0,1,0] op_sel_hi:[1,1,1] neg_lo:[1,0,0] neg_hi:[1,0,0]
	ds_read_b128 v[52:55], v228 offset:12304
	v_pk_fma_f32 v[158:159], v[72:73], v[4:5], v[158:159] op_sel_hi:[1,0,1] neg_lo:[1,0,0] neg_hi:[1,0,0]
	v_pk_fma_f32 v[158:159], v[74:75], v[4:5], v[158:159] op_sel:[0,1,0] op_sel_hi:[1,1,1] neg_lo:[1,0,0] neg_hi:[1,0,0]
	v_pk_fma_f32 v[158:159], v[76:77], v[6:7], v[158:159] op_sel_hi:[1,0,1] neg_lo:[1,0,0] neg_hi:[1,0,0]
	v_pk_fma_f32 v[158:159], v[78:79], v[6:7], v[158:159] op_sel:[0,1,0] op_sel_hi:[1,1,1] neg_lo:[1,0,0] neg_hi:[1,0,0]
	ds_read_b128 v[56:59], v228 offset:12320
	v_pk_fma_f32 v[158:159], v[80:81], v[8:9], v[158:159] op_sel_hi:[1,0,1] neg_lo:[1,0,0] neg_hi:[1,0,0]
	v_pk_fma_f32 v[158:159], v[82:83], v[8:9], v[158:159] op_sel:[0,1,0] op_sel_hi:[1,1,1] neg_lo:[1,0,0] neg_hi:[1,0,0]
	v_pk_fma_f32 v[158:159], v[84:85], v[10:11], v[158:159] op_sel_hi:[1,0,1] neg_lo:[1,0,0] neg_hi:[1,0,0]
	v_pk_fma_f32 v[158:159], v[86:87], v[10:11], v[158:159] op_sel:[0,1,0] op_sel_hi:[1,1,1] neg_lo:[1,0,0] neg_hi:[1,0,0]
	ds_read_b128 v[60:63], v228 offset:12336
	s_waitcnt lgkmcnt(11)
	v_pk_fma_f32 v[158:159], v[88:89], v[12:13], v[158:159] op_sel_hi:[1,0,1] neg_lo:[1,0,0] neg_hi:[1,0,0]
	v_pk_fma_f32 v[158:159], v[90:91], v[12:13], v[158:159] op_sel:[0,1,0] op_sel_hi:[1,1,1] neg_lo:[1,0,0] neg_hi:[1,0,0]
	v_pk_fma_f32 v[158:159], v[92:93], v[14:15], v[158:159] op_sel_hi:[1,0,1] neg_lo:[1,0,0] neg_hi:[1,0,0]
	v_pk_fma_f32 v[158:159], v[94:95], v[14:15], v[158:159] op_sel:[0,1,0] op_sel_hi:[1,1,1] neg_lo:[1,0,0] neg_hi:[1,0,0]
	ds_read_b128 v[244:247], v228 offset:12352
	v_pk_fma_f32 v[158:159], v[96:97], v[16:17], v[158:159] op_sel_hi:[1,0,1] neg_lo:[1,0,0] neg_hi:[1,0,0]
	v_pk_fma_f32 v[158:159], v[98:99], v[16:17], v[158:159] op_sel:[0,1,0] op_sel_hi:[1,1,1] neg_lo:[1,0,0] neg_hi:[1,0,0]
	v_pk_fma_f32 v[158:159], v[100:101], v[18:19], v[158:159] op_sel_hi:[1,0,1] neg_lo:[1,0,0] neg_hi:[1,0,0]
	v_pk_fma_f32 v[158:159], v[102:103], v[18:19], v[158:159] op_sel:[0,1,0] op_sel_hi:[1,1,1] neg_lo:[1,0,0] neg_hi:[1,0,0]
	ds_read_b128 v[248:251], v228 offset:12368
	v_pk_fma_f32 v[158:159], v[104:105], v[20:21], v[158:159] op_sel_hi:[1,0,1] neg_lo:[1,0,0] neg_hi:[1,0,0]
	v_pk_fma_f32 v[158:159], v[106:107], v[20:21], v[158:159] op_sel:[0,1,0] op_sel_hi:[1,1,1] neg_lo:[1,0,0] neg_hi:[1,0,0]
	v_pk_fma_f32 v[158:159], v[108:109], v[22:23], v[158:159] op_sel_hi:[1,0,1] neg_lo:[1,0,0] neg_hi:[1,0,0]
	v_pk_fma_f32 v[158:159], v[110:111], v[22:23], v[158:159] op_sel:[0,1,0] op_sel_hi:[1,1,1] neg_lo:[1,0,0] neg_hi:[1,0,0]
	ds_read_b128 v[4:7], v228 offset:12384
	v_pk_fma_f32 v[158:159], v[112:113], v[24:25], v[158:159] op_sel_hi:[1,0,1] neg_lo:[1,0,0] neg_hi:[1,0,0]
	v_pk_fma_f32 v[158:159], v[114:115], v[24:25], v[158:159] op_sel:[0,1,0] op_sel_hi:[1,1,1] neg_lo:[1,0,0] neg_hi:[1,0,0]
	v_pk_fma_f32 v[158:159], v[116:117], v[26:27], v[158:159] op_sel_hi:[1,0,1] neg_lo:[1,0,0] neg_hi:[1,0,0]
	v_pk_fma_f32 v[158:159], v[118:119], v[26:27], v[158:159] op_sel:[0,1,0] op_sel_hi:[1,1,1] neg_lo:[1,0,0] neg_hi:[1,0,0]
	ds_read_b128 v[8:11], v228 offset:12400
	s_waitcnt lgkmcnt(11)
	v_pk_fma_f32 v[158:159], v[120:121], v[28:29], v[158:159] op_sel_hi:[1,0,1] neg_lo:[1,0,0] neg_hi:[1,0,0]
	v_pk_fma_f32 v[158:159], v[122:123], v[28:29], v[158:159] op_sel:[0,1,0] op_sel_hi:[1,1,1] neg_lo:[1,0,0] neg_hi:[1,0,0]
	v_pk_fma_f32 v[158:159], v[124:125], v[30:31], v[158:159] op_sel_hi:[1,0,1] neg_lo:[1,0,0] neg_hi:[1,0,0]
	v_pk_fma_f32 v[158:159], v[126:127], v[30:31], v[158:159] op_sel:[0,1,0] op_sel_hi:[1,1,1] neg_lo:[1,0,0] neg_hi:[1,0,0]
	ds_read_b128 v[12:15], v228 offset:12416
	v_pk_fma_f32 v[158:159], v[128:129], v[32:33], v[158:159] op_sel_hi:[1,0,1] neg_lo:[1,0,0] neg_hi:[1,0,0]
	v_pk_fma_f32 v[158:159], v[130:131], v[32:33], v[158:159] op_sel:[0,1,0] op_sel_hi:[1,1,1] neg_lo:[1,0,0] neg_hi:[1,0,0]
	v_pk_fma_f32 v[158:159], v[132:133], v[34:35], v[158:159] op_sel_hi:[1,0,1] neg_lo:[1,0,0] neg_hi:[1,0,0]
	v_pk_fma_f32 v[158:159], v[134:135], v[34:35], v[158:159] op_sel:[0,1,0] op_sel_hi:[1,1,1] neg_lo:[1,0,0] neg_hi:[1,0,0]
	ds_read_b128 v[16:19], v228 offset:12432
	v_pk_fma_f32 v[158:159], v[136:137], v[36:37], v[158:159] op_sel_hi:[1,0,1] neg_lo:[1,0,0] neg_hi:[1,0,0]
	v_pk_fma_f32 v[158:159], v[138:139], v[36:37], v[158:159] op_sel:[0,1,0] op_sel_hi:[1,1,1] neg_lo:[1,0,0] neg_hi:[1,0,0]
	v_pk_fma_f32 v[158:159], v[140:141], v[38:39], v[158:159] op_sel_hi:[1,0,1] neg_lo:[1,0,0] neg_hi:[1,0,0]
	v_pk_fma_f32 v[158:159], v[142:143], v[38:39], v[158:159] op_sel:[0,1,0] op_sel_hi:[1,1,1] neg_lo:[1,0,0] neg_hi:[1,0,0]
	ds_read_b128 v[20:23], v228 offset:12448
	v_pk_fma_f32 v[158:159], v[144:145], v[40:41], v[158:159] op_sel_hi:[1,0,1] neg_lo:[1,0,0] neg_hi:[1,0,0]
	v_pk_fma_f32 v[158:159], v[146:147], v[40:41], v[158:159] op_sel:[0,1,0] op_sel_hi:[1,1,1] neg_lo:[1,0,0] neg_hi:[1,0,0]
	v_pk_fma_f32 v[158:159], v[148:149], v[42:43], v[158:159] op_sel_hi:[1,0,1] neg_lo:[1,0,0] neg_hi:[1,0,0]
	v_pk_fma_f32 v[158:159], v[150:151], v[42:43], v[158:159] op_sel:[0,1,0] op_sel_hi:[1,1,1] neg_lo:[1,0,0] neg_hi:[1,0,0]
	ds_read_b128 v[24:27], v228 offset:12464
	s_waitcnt lgkmcnt(9)
; #define LAS __attribute__((address_space(3)))
; __device__ __forceinline__ void phase_gdb(const int wvs, const Params& p, LAS unsigned char* lds, int nwg) {
;     ...
;     { float x[64]; const bool isw = t >= 64;
; #pragma unroll
;       for (int i = 0; i < 64; ++i) { const float v = (float)R[i * RP + t]; x[i] = v * bs[i] * (isw ? __expf(gcs[i]) : 1.0f); asm volatile("" : "+v"(x[i])); if ((i & 7) == 7) __builtin_amdgcn_sched_barrier(0); }
; #pragma unroll
;       for (int i = 1; i < 64; ++i) {
; #pragma unroll
;         for (int j4 = 0; j4 < (i + 3) / 4; ++j4) { const f32x4 m4 = *(const LAS f32x4*)(M + i * 64 + j4 * 4);
; #pragma unroll
;           for (int jj = 0; jj < 4; ++jj) if (j4 * 4 + jj < i) x[i] -= m4[jj] * x[j4 * 4 + jj]; }
;         __builtin_amdgcn_sched_barrier(0); }
; #pragma unroll
;       for (int i = 0; i < 64; ++i) R[i * RP + t] = (hf)x[i]; }
	v_pk_fma_f32 v[158:159], v[152:153], v[44:45], v[158:159] op_sel_hi:[1,0,1] neg_lo:[1,0,0] neg_hi:[1,0,0]
	v_pk_fma_f32 v[158:159], v[154:155], v[44:45], v[158:159] op_sel:[0,1,0] op_sel_hi:[1,1,1] neg_lo:[1,0,0] neg_hi:[1,0,0]
	v_fma_mixlo_f16 v239, -v156, v46, v158
	v_fma_mixlo_f16 v240, -v157, v46, v159
	v_pk_fma_f32 v[158:159], v[156:157], v[46:47], v[158:159] op_sel_hi:[1,0,1] neg_lo:[1,0,0] neg_hi:[1,0,0]
	ds_write_b16 v253, v239 offset:29168
	ds_write_b16 v253, v240 offset:29296
	ds_read_b128 v[28:31], v228 offset:12544
	v_pk_fma_f32 v[160:161], v[64:65], v[48:49], v[160:161] op_sel_hi:[1,0,1] neg_lo:[1,0,0] neg_hi:[1,0,0]
	v_pk_fma_f32 v[160:161], v[66:67], v[48:49], v[160:161] op_sel:[0,1,0] op_sel_hi:[1,1,1] neg_lo:[1,0,0] neg_hi:[1,0,0]
	v_pk_fma_f32 v[160:161], v[68:69], v[50:51], v[160:161] op_sel_hi:[1,0,1] neg_lo:[1,0,0] neg_hi:[1,0,0]
	v_pk_fma_f32 v[160:161], v[70:71], v[50:51], v[160:161] op_sel:[0,1,0] op_sel_hi:[1,1,1] neg_lo:[1,0,0] neg_hi:[1,0,0]
	ds_read_b128 v[32:35], v228 offset:12560
	v_pk_fma_f32 v[160:161], v[72:73], v[52:53], v[160:161] op_sel_hi:[1,0,1] neg_lo:[1,0,0] neg_hi:[1,0,0]
	v_pk_fma_f32 v[160:161], v[74:75], v[52:53], v[160:161] op_sel:[0,1,0] op_sel_hi:[1,1,1] neg_lo:[1,0,0] neg_hi:[1,0,0]
	v_pk_fma_f32 v[160:161], v[76:77], v[54:55], v[160:161] op_sel_hi:[1,0,1] neg_lo:[1,0,0] neg_hi:[1,0,0]
	v_pk_fma_f32 v[160:161], v[78:79], v[54:55], v[160:161] op_sel:[0,1,0] op_sel_hi:[1,1,1] neg_lo:[1,0,0] neg_hi:[1,0,0]
	ds_read_b128 v[36:39], v228 offset:12576
	v_pk_fma_f32 v[160:161], v[80:81], v[56:57], v[160:161] op_sel_hi:[1,0,1] neg_lo:[1,0,0] neg_hi:[1,0,0]
	v_pk_fma_f32 v[160:161], v[82:83], v[56:57], v[160:161] op_sel:[0,1,0] op_sel_hi:[1,1,1] neg_lo:[1,0,0] neg_hi:[1,0,0]
	v_pk_fma_f32 v[160:161], v[84:85], v[58:59], v[160:161] op_sel_hi:[1,0,1] neg_lo:[1,0,0] neg_hi:[1,0,0]
	v_pk_fma_f32 v[160:161], v[86:87], v[58:59], v[160:161] op_sel:[0,1,0] op_sel_hi:[1,1,1] neg_lo:[1,0,0] neg_hi:[1,0,0]
	ds_read_b128 v[40:43], v228 offset:12592
	s_waitcnt lgkmcnt(11)
	v_pk_fma_f32 v[160:161], v[88:89], v[60:61], v[160:161] op_sel_hi:[1,0,1] neg_lo:[1,0,0] neg_hi:[1,0,0]
	v_pk_fma_f32 v[160:161], v[90:91], v[60:61], v[160:161] op_sel:[0,1,0] op_sel_hi:[1,1,1] neg_lo:[1,0,0] neg_hi:[1,0,0]
	v_pk_fma_f32 v[160:161], v[92:93], v[62:63], v[160:161] op_sel_hi:[1,0,1] neg_lo:[1,0,0] neg_hi:[1,0,0]
	v_pk_fma_f32 v[160:161], v[94:95], v[62:63], v[160:161] op_sel:[0,1,0] op_sel_hi:[1,1,1] neg_lo:[1,0,0] neg_hi:[1,0,0]
	ds_read_b128 v[44:47], v228 offset:12608
	v_pk_fma_f32 v[160:161], v[96:97], v[244:245], v[160:161] op_sel_hi:[1,0,1] neg_lo:[1,0,0] neg_hi:[1,0,0]
	v_pk_fma_f32 v[160:161], v[98:99], v[244:245], v[160:161] op_sel:[0,1,0] op_sel_hi:[1,1,1] neg_lo:[1,0,0] neg_hi:[1,0,0]
	v_pk_fma_f32 v[160:161], v[100:101], v[246:247], v[160:161] op_sel_hi:[1,0,1] neg_lo:[1,0,0] neg_hi:[1,0,0]
	v_pk_fma_f32 v[160:161], v[102:103], v[246:247], v[160:161] op_sel:[0,1,0] op_sel_hi:[1,1,1] neg_lo:[1,0,0] neg_hi:[1,0,0]
	ds_read_b128 v[48:51], v228 offset:12624
	v_pk_fma_f32 v[160:161], v[104:105], v[248:249], v[160:161] op_sel_hi:[1,0,1] neg_lo:[1,0,0] neg_hi:[1,0,0]
	v_pk_fma_f32 v[160:161], v[106:107], v[248:249], v[160:161] op_sel:[0,1,0] op_sel_hi:[1,1,1] neg_lo:[1,0,0] neg_hi:[1,0,0]
	v_pk_fma_f32 v[160:161], v[108:109], v[250:251], v[160:161] op_sel_hi:[1,0,1] neg_lo:[1,0,0] neg_hi:[1,0,0]
	v_pk_fma_f32 v[160:161], v[110:111], v[250:251], v[160:161] op_sel:[0,1,0] op_sel_hi:[1,1,1] neg_lo:[1,0,0] neg_hi:[1,0,0]
	ds_read_b128 v[52:55], v228 offset:12640
	v_pk_fma_f32 v[160:161], v[112:113], v[4:5], v[160:161] op_sel_hi:[1,0,1] neg_lo:[1,0,0] neg_hi:[1,0,0]
	v_pk_fma_f32 v[160:161], v[114:115], v[4:5], v[160:161] op_sel:[0,1,0] op_sel_hi:[1,1,1] neg_lo:[1,0,0] neg_hi:[1,0,0]
	v_pk_fma_f32 v[160:161], v[116:117], v[6:7], v[160:161] op_sel_hi:[1,0,1] neg_lo:[1,0,0] neg_hi:[1,0,0]
	v_pk_fma_f32 v[160:161], v[118:119], v[6:7], v[160:161] op_sel:[0,1,0] op_sel_hi:[1,1,1] neg_lo:[1,0,0] neg_hi:[1,0,0]
	ds_read_b128 v[56:59], v228 offset:12656
	s_waitcnt lgkmcnt(11)
	v_pk_fma_f32 v[160:161], v[120:121], v[8:9], v[160:161] op_sel_hi:[1,0,1] neg_lo:[1,0,0] neg_hi:[1,0,0]
	v_pk_fma_f32 v[160:161], v[122:123], v[8:9], v[160:161] op_sel:[0,1,0] op_sel_hi:[1,1,1] neg_lo:[1,0,0] neg_hi:[1,0,0]
	v_pk_fma_f32 v[160:161], v[124:125], v[10:11], v[160:161] op_sel_hi:[1,0,1] neg_lo:[1,0,0] neg_hi:[1,0,0]
	v_pk_fma_f32 v[160:161], v[126:127], v[10:11], v[160:161] op_sel:[0,1,0] op_sel_hi:[1,1,1] neg_lo:[1,0,0] neg_hi:[1,0,0]
	ds_read_b128 v[60:63], v228 offset:12672
	v_pk_fma_f32 v[160:161], v[128:129], v[12:13], v[160:161] op_sel_hi:[1,0,1] neg_lo:[1,0,0] neg_hi:[1,0,0]
	v_pk_fma_f32 v[160:161], v[130:131], v[12:13], v[160:161] op_sel:[0,1,0] op_sel_hi:[1,1,1] neg_lo:[1,0,0] neg_hi:[1,0,0]
	v_pk_fma_f32 v[160:161], v[132:133], v[14:15], v[160:161] op_sel_hi:[1,0,1] neg_lo:[1,0,0] neg_hi:[1,0,0]
	v_pk_fma_f32 v[160:161], v[134:135], v[14:15], v[160:161] op_sel:[0,1,0] op_sel_hi:[1,1,1] neg_lo:[1,0,0] neg_hi:[1,0,0]
	ds_read_b128 v[244:247], v228 offset:12688
	v_pk_fma_f32 v[160:161], v[136:137], v[16:17], v[160:161] op_sel_hi:[1,0,1] neg_lo:[1,0,0] neg_hi:[1,0,0]
	v_pk_fma_f32 v[160:161], v[138:139], v[16:17], v[160:161] op_sel:[0,1,0] op_sel_hi:[1,1,1] neg_lo:[1,0,0] neg_hi:[1,0,0]
	v_pk_fma_f32 v[160:161], v[140:141], v[18:19], v[160:161] op_sel_hi:[1,0,1] neg_lo:[1,0,0] neg_hi:[1,0,0]
	v_pk_fma_f32 v[160:161], v[142:143], v[18:19], v[160:161] op_sel:[0,1,0] op_sel_hi:[1,1,1] neg_lo:[1,0,0] neg_hi:[1,0,0]
	ds_read_b128 v[248:251], v228 offset:12704
	v_pk_fma_f32 v[160:161], v[144:145], v[20:21], v[160:161] op_sel_hi:[1,0,1] neg_lo:[1,0,0] neg_hi:[1,0,0]
	v_pk_fma_f32 v[160:161], v[146:147], v[20:21], v[160:161] op_sel:[0,1,0] op_sel_hi:[1,1,1] neg_lo:[1,0,0] neg_hi:[1,0,0]
	v_pk_fma_f32 v[160:161], v[148:149], v[22:23], v[160:161] op_sel_hi:[1,0,1] neg_lo:[1,0,0] neg_hi:[1,0,0]
	v_pk_fma_f32 v[160:161], v[150:151], v[22:23], v[160:161] op_sel:[0,1,0] op_sel_hi:[1,1,1] neg_lo:[1,0,0] neg_hi:[1,0,0]
	ds_read_b128 v[4:7], v228 offset:12720
	s_waitcnt lgkmcnt(9)
; #define LAS __attribute__((address_space(3)))
; __device__ __forceinline__ void phase_gdb(const int wvs, const Params& p, LAS unsigned char* lds, int nwg) {
;     ...
;     { float x[64]; const bool isw = t >= 64;
; #pragma unroll
;       for (int i = 0; i < 64; ++i) { const float v = (float)R[i * RP + t]; x[i] = v * bs[i] * (isw ? __expf(gcs[i]) : 1.0f); asm volatile("" : "+v"(x[i])); if ((i & 7) == 7) __builtin_amdgcn_sched_barrier(0); }
; #pragma unroll
;       for (int i = 1; i < 64; ++i) {
; #pragma unroll
;         for (int j4 = 0; j4 < (i + 3) / 4; ++j4) { const f32x4 m4 = *(const LAS f32x4*)(M + i * 64 + j4 * 4);
; #pragma unroll
;           for (int jj = 0; jj < 4; ++jj) if (j4 * 4 + jj < i) x[i] -= m4[jj] * x[j4 * 4 + jj]; }
;         __builtin_amdgcn_sched_barrier(0); }
; #pragma unroll
;       for (int i = 0; i < 64; ++i) R[i * RP + t] = (hf)x[i]; }
	v_pk_fma_f32 v[160:161], v[152:153], v[24:25], v[160:161] op_sel_hi:[1,0,1] neg_lo:[1,0,0] neg_hi:[1,0,0]
	v_pk_fma_f32 v[160:161], v[154:155], v[24:25], v[160:161] op_sel:[0,1,0] op_sel_hi:[1,1,1] neg_lo:[1,0,0] neg_hi:[1,0,0]
	v_pk_fma_f32 v[160:161], v[156:157], v[26:27], v[160:161] op_sel_hi:[1,0,1] neg_lo:[1,0,0] neg_hi:[1,0,0]
	v_fma_mixlo_f16 v0, -v158, v27, v160
	v_fma_mixlo_f16 v2, -v159, v27, v161
	v_pk_fma_f32 v[160:161], v[158:159], v[26:27], v[160:161] op_sel:[0,1,0] op_sel_hi:[1,1,1] neg_lo:[1,0,0] neg_hi:[1,0,0]
	ds_write_b16 v253, v0 offset:29440
	ds_write_b16 v253, v2 offset:29568
	ds_read_b128 v[8:11], v228 offset:12736
	v_pk_fma_f32 v[162:163], v[64:65], v[28:29], v[162:163] op_sel_hi:[1,0,1] neg_lo:[1,0,0] neg_hi:[1,0,0]
	v_pk_fma_f32 v[162:163], v[66:67], v[28:29], v[162:163] op_sel:[0,1,0] op_sel_hi:[1,1,1] neg_lo:[1,0,0] neg_hi:[1,0,0]
	v_pk_fma_f32 v[162:163], v[68:69], v[30:31], v[162:163] op_sel_hi:[1,0,1] neg_lo:[1,0,0] neg_hi:[1,0,0]
	v_pk_fma_f32 v[162:163], v[70:71], v[30:31], v[162:163] op_sel:[0,1,0] op_sel_hi:[1,1,1] neg_lo:[1,0,0] neg_hi:[1,0,0]
	ds_read_b128 v[12:15], v228 offset:12800
	v_pk_fma_f32 v[162:163], v[72:73], v[32:33], v[162:163] op_sel_hi:[1,0,1] neg_lo:[1,0,0] neg_hi:[1,0,0]
	v_pk_fma_f32 v[162:163], v[74:75], v[32:33], v[162:163] op_sel:[0,1,0] op_sel_hi:[1,1,1] neg_lo:[1,0,0] neg_hi:[1,0,0]
	v_pk_fma_f32 v[162:163], v[76:77], v[34:35], v[162:163] op_sel_hi:[1,0,1] neg_lo:[1,0,0] neg_hi:[1,0,0]
	v_pk_fma_f32 v[162:163], v[78:79], v[34:35], v[162:163] op_sel:[0,1,0] op_sel_hi:[1,1,1] neg_lo:[1,0,0] neg_hi:[1,0,0]
	ds_read_b128 v[16:19], v228 offset:12816
	v_pk_fma_f32 v[162:163], v[80:81], v[36:37], v[162:163] op_sel_hi:[1,0,1] neg_lo:[1,0,0] neg_hi:[1,0,0]
	v_pk_fma_f32 v[162:163], v[82:83], v[36:37], v[162:163] op_sel:[0,1,0] op_sel_hi:[1,1,1] neg_lo:[1,0,0] neg_hi:[1,0,0]
	v_pk_fma_f32 v[162:163], v[84:85], v[38:39], v[162:163] op_sel_hi:[1,0,1] neg_lo:[1,0,0] neg_hi:[1,0,0]
	v_pk_fma_f32 v[162:163], v[86:87], v[38:39], v[162:163] op_sel:[0,1,0] op_sel_hi:[1,1,1] neg_lo:[1,0,0] neg_hi:[1,0,0]
	ds_read_b128 v[20:23], v228 offset:12832
	s_waitcnt lgkmcnt(11)
	v_pk_fma_f32 v[162:163], v[88:89], v[40:41], v[162:163] op_sel_hi:[1,0,1] neg_lo:[1,0,0] neg_hi:[1,0,0]
	v_pk_fma_f32 v[162:163], v[90:91], v[40:41], v[162:163] op_sel:[0,1,0] op_sel_hi:[1,1,1] neg_lo:[1,0,0] neg_hi:[1,0,0]
	v_pk_fma_f32 v[162:163], v[92:93], v[42:43], v[162:163] op_sel_hi:[1,0,1] neg_lo:[1,0,0] neg_hi:[1,0,0]
	v_pk_fma_f32 v[162:163], v[94:95], v[42:43], v[162:163] op_sel:[0,1,0] op_sel_hi:[1,1,1] neg_lo:[1,0,0] neg_hi:[1,0,0]
	ds_read_b128 v[24:27], v228 offset:12848
	v_pk_fma_f32 v[162:163], v[96:97], v[44:45], v[162:163] op_sel_hi:[1,0,1] neg_lo:[1,0,0] neg_hi:[1,0,0]
	v_pk_fma_f32 v[162:163], v[98:99], v[44:45], v[162:163] op_sel:[0,1,0] op_sel_hi:[1,1,1] neg_lo:[1,0,0] neg_hi:[1,0,0]
	v_pk_fma_f32 v[162:163], v[100:101], v[46:47], v[162:163] op_sel_hi:[1,0,1] neg_lo:[1,0,0] neg_hi:[1,0,0]
	v_pk_fma_f32 v[162:163], v[102:103], v[46:47], v[162:163] op_sel:[0,1,0] op_sel_hi:[1,1,1] neg_lo:[1,0,0] neg_hi:[1,0,0]
	ds_read_b128 v[28:31], v228 offset:12864
	v_pk_fma_f32 v[162:163], v[104:105], v[48:49], v[162:163] op_sel_hi:[1,0,1] neg_lo:[1,0,0] neg_hi:[1,0,0]
	v_pk_fma_f32 v[162:163], v[106:107], v[48:49], v[162:163] op_sel:[0,1,0] op_sel_hi:[1,1,1] neg_lo:[1,0,0] neg_hi:[1,0,0]
	v_pk_fma_f32 v[162:163], v[108:109], v[50:51], v[162:163] op_sel_hi:[1,0,1] neg_lo:[1,0,0] neg_hi:[1,0,0]
	v_pk_fma_f32 v[162:163], v[110:111], v[50:51], v[162:163] op_sel:[0,1,0] op_sel_hi:[1,1,1] neg_lo:[1,0,0] neg_hi:[1,0,0]
	ds_read_b128 v[32:35], v228 offset:12880
	v_pk_fma_f32 v[162:163], v[112:113], v[52:53], v[162:163] op_sel_hi:[1,0,1] neg_lo:[1,0,0] neg_hi:[1,0,0]
	v_pk_fma_f32 v[162:163], v[114:115], v[52:53], v[162:163] op_sel:[0,1,0] op_sel_hi:[1,1,1] neg_lo:[1,0,0] neg_hi:[1,0,0]
	v_pk_fma_f32 v[162:163], v[116:117], v[54:55], v[162:163] op_sel_hi:[1,0,1] neg_lo:[1,0,0] neg_hi:[1,0,0]
	v_pk_fma_f32 v[162:163], v[118:119], v[54:55], v[162:163] op_sel:[0,1,0] op_sel_hi:[1,1,1] neg_lo:[1,0,0] neg_hi:[1,0,0]
	ds_read_b128 v[36:39], v228 offset:12896
	s_waitcnt lgkmcnt(11)
	v_pk_fma_f32 v[162:163], v[120:121], v[56:57], v[162:163] op_sel_hi:[1,0,1] neg_lo:[1,0,0] neg_hi:[1,0,0]
	v_pk_fma_f32 v[162:163], v[122:123], v[56:57], v[162:163] op_sel:[0,1,0] op_sel_hi:[1,1,1] neg_lo:[1,0,0] neg_hi:[1,0,0]
	v_pk_fma_f32 v[162:163], v[124:125], v[58:59], v[162:163] op_sel_hi:[1,0,1] neg_lo:[1,0,0] neg_hi:[1,0,0]
	v_pk_fma_f32 v[162:163], v[126:127], v[58:59], v[162:163] op_sel:[0,1,0] op_sel_hi:[1,1,1] neg_lo:[1,0,0] neg_hi:[1,0,0]
	ds_read_b128 v[40:43], v228 offset:12912
	v_pk_fma_f32 v[162:163], v[128:129], v[60:61], v[162:163] op_sel_hi:[1,0,1] neg_lo:[1,0,0] neg_hi:[1,0,0]
	v_pk_fma_f32 v[162:163], v[130:131], v[60:61], v[162:163] op_sel:[0,1,0] op_sel_hi:[1,1,1] neg_lo:[1,0,0] neg_hi:[1,0,0]
	v_pk_fma_f32 v[162:163], v[132:133], v[62:63], v[162:163] op_sel_hi:[1,0,1] neg_lo:[1,0,0] neg_hi:[1,0,0]
	v_pk_fma_f32 v[162:163], v[134:135], v[62:63], v[162:163] op_sel:[0,1,0] op_sel_hi:[1,1,1] neg_lo:[1,0,0] neg_hi:[1,0,0]
	ds_read_b128 v[44:47], v228 offset:12928
	v_pk_fma_f32 v[162:163], v[136:137], v[244:245], v[162:163] op_sel_hi:[1,0,1] neg_lo:[1,0,0] neg_hi:[1,0,0]
	v_pk_fma_f32 v[162:163], v[138:139], v[244:245], v[162:163] op_sel:[0,1,0] op_sel_hi:[1,1,1] neg_lo:[1,0,0] neg_hi:[1,0,0]
	v_pk_fma_f32 v[162:163], v[140:141], v[246:247], v[162:163] op_sel_hi:[1,0,1] neg_lo:[1,0,0] neg_hi:[1,0,0]
	v_pk_fma_f32 v[162:163], v[142:143], v[246:247], v[162:163] op_sel:[0,1,0] op_sel_hi:[1,1,1] neg_lo:[1,0,0] neg_hi:[1,0,0]
	ds_read_b128 v[48:51], v228 offset:12944
	v_pk_fma_f32 v[162:163], v[144:145], v[248:249], v[162:163] op_sel_hi:[1,0,1] neg_lo:[1,0,0] neg_hi:[1,0,0]
	v_pk_fma_f32 v[162:163], v[146:147], v[248:249], v[162:163] op_sel:[0,1,0] op_sel_hi:[1,1,1] neg_lo:[1,0,0] neg_hi:[1,0,0]
	v_pk_fma_f32 v[162:163], v[148:149], v[250:251], v[162:163] op_sel_hi:[1,0,1] neg_lo:[1,0,0] neg_hi:[1,0,0]
	v_pk_fma_f32 v[162:163], v[150:151], v[250:251], v[162:163] op_sel:[0,1,0] op_sel_hi:[1,1,1] neg_lo:[1,0,0] neg_hi:[1,0,0]
	ds_read_b128 v[52:55], v228 offset:12960
	s_waitcnt lgkmcnt(9)
; #define LAS __attribute__((address_space(3)))
; __device__ __forceinline__ void phase_gdb(const int wvs, const Params& p, LAS unsigned char* lds, int nwg) {
;     ...
;     { float x[64]; const bool isw = t >= 64;
; #pragma unroll
;       for (int i = 0; i < 64; ++i) { const float v = (float)R[i * RP + t]; x[i] = v * bs[i] * (isw ? __expf(gcs[i]) : 1.0f); asm volatile("" : "+v"(x[i])); if ((i & 7) == 7) __builtin_amdgcn_sched_barrier(0); }
; #pragma unroll
;       for (int i = 1; i < 64; ++i) {
; #pragma unroll
;         for (int j4 = 0; j4 < (i + 3) / 4; ++j4) { const f32x4 m4 = *(const LAS f32x4*)(M + i * 64 + j4 * 4);
; #pragma unroll
;           for (int jj = 0; jj < 4; ++jj) if (j4 * 4 + jj < i) x[i] -= m4[jj] * x[j4 * 4 + jj]; }
;         __builtin_amdgcn_sched_barrier(0); }
; #pragma unroll
;       for (int i = 0; i < 64; ++i) R[i * RP + t] = (hf)x[i]; }
	v_pk_fma_f32 v[162:163], v[152:153], v[4:5], v[162:163] op_sel_hi:[1,0,1] neg_lo:[1,0,0] neg_hi:[1,0,0]
	v_pk_fma_f32 v[162:163], v[154:155], v[4:5], v[162:163] op_sel:[0,1,0] op_sel_hi:[1,1,1] neg_lo:[1,0,0] neg_hi:[1,0,0]
	v_pk_fma_f32 v[162:163], v[156:157], v[6:7], v[162:163] op_sel_hi:[1,0,1] neg_lo:[1,0,0] neg_hi:[1,0,0]
	v_pk_fma_f32 v[162:163], v[158:159], v[6:7], v[162:163] op_sel:[0,1,0] op_sel_hi:[1,1,1] neg_lo:[1,0,0] neg_hi:[1,0,0]
	ds_read_b128 v[56:59], v228 offset:12976
	v_fma_mixlo_f16 v3, -v160, v8, v162
	v_fma_mixlo_f16 v238, -v161, v8, v163
	v_pk_fma_f32 v[162:163], v[160:161], v[8:9], v[162:163] op_sel_hi:[1,0,1] neg_lo:[1,0,0] neg_hi:[1,0,0]
	ds_write_b16 v253, v3 offset:29712
	ds_write_b16 v253, v238 offset:29840
	ds_read_b128 v[60:63], v228 offset:12992
	v_pk_fma_f32 v[164:165], v[64:65], v[12:13], v[164:165] op_sel_hi:[1,0,1] neg_lo:[1,0,0] neg_hi:[1,0,0]
	v_pk_fma_f32 v[164:165], v[66:67], v[12:13], v[164:165] op_sel:[0,1,0] op_sel_hi:[1,1,1] neg_lo:[1,0,0] neg_hi:[1,0,0]
	v_pk_fma_f32 v[164:165], v[68:69], v[14:15], v[164:165] op_sel_hi:[1,0,1] neg_lo:[1,0,0] neg_hi:[1,0,0]
	v_pk_fma_f32 v[164:165], v[70:71], v[14:15], v[164:165] op_sel:[0,1,0] op_sel_hi:[1,1,1] neg_lo:[1,0,0] neg_hi:[1,0,0]
	ds_read_b128 v[244:247], v228 offset:13056
	v_pk_fma_f32 v[164:165], v[72:73], v[16:17], v[164:165] op_sel_hi:[1,0,1] neg_lo:[1,0,0] neg_hi:[1,0,0]
	v_pk_fma_f32 v[164:165], v[74:75], v[16:17], v[164:165] op_sel:[0,1,0] op_sel_hi:[1,1,1] neg_lo:[1,0,0] neg_hi:[1,0,0]
	v_pk_fma_f32 v[164:165], v[76:77], v[18:19], v[164:165] op_sel_hi:[1,0,1] neg_lo:[1,0,0] neg_hi:[1,0,0]
	v_pk_fma_f32 v[164:165], v[78:79], v[18:19], v[164:165] op_sel:[0,1,0] op_sel_hi:[1,1,1] neg_lo:[1,0,0] neg_hi:[1,0,0]
	ds_read_b128 v[248:251], v228 offset:13072
	s_waitcnt lgkmcnt(11)
	v_pk_fma_f32 v[164:165], v[80:81], v[20:21], v[164:165] op_sel_hi:[1,0,1] neg_lo:[1,0,0] neg_hi:[1,0,0]
	v_pk_fma_f32 v[164:165], v[82:83], v[20:21], v[164:165] op_sel:[0,1,0] op_sel_hi:[1,1,1] neg_lo:[1,0,0] neg_hi:[1,0,0]
	v_pk_fma_f32 v[164:165], v[84:85], v[22:23], v[164:165] op_sel_hi:[1,0,1] neg_lo:[1,0,0] neg_hi:[1,0,0]
	v_pk_fma_f32 v[164:165], v[86:87], v[22:23], v[164:165] op_sel:[0,1,0] op_sel_hi:[1,1,1] neg_lo:[1,0,0] neg_hi:[1,0,0]
	ds_read_b128 v[4:7], v228 offset:13088
	v_pk_fma_f32 v[164:165], v[88:89], v[24:25], v[164:165] op_sel_hi:[1,0,1] neg_lo:[1,0,0] neg_hi:[1,0,0]
	v_pk_fma_f32 v[164:165], v[90:91], v[24:25], v[164:165] op_sel:[0,1,0] op_sel_hi:[1,1,1] neg_lo:[1,0,0] neg_hi:[1,0,0]
	v_pk_fma_f32 v[164:165], v[92:93], v[26:27], v[164:165] op_sel_hi:[1,0,1] neg_lo:[1,0,0] neg_hi:[1,0,0]
	v_pk_fma_f32 v[164:165], v[94:95], v[26:27], v[164:165] op_sel:[0,1,0] op_sel_hi:[1,1,1] neg_lo:[1,0,0] neg_hi:[1,0,0]
	ds_read_b128 v[8:11], v228 offset:13104
	v_pk_fma_f32 v[164:165], v[96:97], v[28:29], v[164:165] op_sel_hi:[1,0,1] neg_lo:[1,0,0] neg_hi:[1,0,0]
	v_pk_fma_f32 v[164:165], v[98:99], v[28:29], v[164:165] op_sel:[0,1,0] op_sel_hi:[1,1,1] neg_lo:[1,0,0] neg_hi:[1,0,0]
	v_pk_fma_f32 v[164:165], v[100:101], v[30:31], v[164:165] op_sel_hi:[1,0,1] neg_lo:[1,0,0] neg_hi:[1,0,0]
	v_pk_fma_f32 v[164:165], v[102:103], v[30:31], v[164:165] op_sel:[0,1,0] op_sel_hi:[1,1,1] neg_lo:[1,0,0] neg_hi:[1,0,0]
	ds_read_b128 v[12:15], v228 offset:13120
	v_pk_fma_f32 v[164:165], v[104:105], v[32:33], v[164:165] op_sel_hi:[1,0,1] neg_lo:[1,0,0] neg_hi:[1,0,0]
	v_pk_fma_f32 v[164:165], v[106:107], v[32:33], v[164:165] op_sel:[0,1,0] op_sel_hi:[1,1,1] neg_lo:[1,0,0] neg_hi:[1,0,0]
	v_pk_fma_f32 v[164:165], v[108:109], v[34:35], v[164:165] op_sel_hi:[1,0,1] neg_lo:[1,0,0] neg_hi:[1,0,0]
	v_pk_fma_f32 v[164:165], v[110:111], v[34:35], v[164:165] op_sel:[0,1,0] op_sel_hi:[1,1,1] neg_lo:[1,0,0] neg_hi:[1,0,0]
	ds_read_b128 v[16:19], v228 offset:13136
	s_waitcnt lgkmcnt(11)
	v_pk_fma_f32 v[164:165], v[112:113], v[36:37], v[164:165] op_sel_hi:[1,0,1] neg_lo:[1,0,0] neg_hi:[1,0,0]
	v_pk_fma_f32 v[164:165], v[114:115], v[36:37], v[164:165] op_sel:[0,1,0] op_sel_hi:[1,1,1] neg_lo:[1,0,0] neg_hi:[1,0,0]
	v_pk_fma_f32 v[164:165], v[116:117], v[38:39], v[164:165] op_sel_hi:[1,0,1] neg_lo:[1,0,0] neg_hi:[1,0,0]
	v_pk_fma_f32 v[164:165], v[118:119], v[38:39], v[164:165] op_sel:[0,1,0] op_sel_hi:[1,1,1] neg_lo:[1,0,0] neg_hi:[1,0,0]
	ds_read_b128 v[20:23], v228 offset:13152
	v_pk_fma_f32 v[164:165], v[120:121], v[40:41], v[164:165] op_sel_hi:[1,0,1] neg_lo:[1,0,0] neg_hi:[1,0,0]
	v_pk_fma_f32 v[164:165], v[122:123], v[40:41], v[164:165] op_sel:[0,1,0] op_sel_hi:[1,1,1] neg_lo:[1,0,0] neg_hi:[1,0,0]
	v_pk_fma_f32 v[164:165], v[124:125], v[42:43], v[164:165] op_sel_hi:[1,0,1] neg_lo:[1,0,0] neg_hi:[1,0,0]
	v_pk_fma_f32 v[164:165], v[126:127], v[42:43], v[164:165] op_sel:[0,1,0] op_sel_hi:[1,1,1] neg_lo:[1,0,0] neg_hi:[1,0,0]
	ds_read_b128 v[24:27], v228 offset:13168
	v_pk_fma_f32 v[164:165], v[128:129], v[44:45], v[164:165] op_sel_hi:[1,0,1] neg_lo:[1,0,0] neg_hi:[1,0,0]
	v_pk_fma_f32 v[164:165], v[130:131], v[44:45], v[164:165] op_sel:[0,1,0] op_sel_hi:[1,1,1] neg_lo:[1,0,0] neg_hi:[1,0,0]
	v_pk_fma_f32 v[164:165], v[132:133], v[46:47], v[164:165] op_sel_hi:[1,0,1] neg_lo:[1,0,0] neg_hi:[1,0,0]
	v_pk_fma_f32 v[164:165], v[134:135], v[46:47], v[164:165] op_sel:[0,1,0] op_sel_hi:[1,1,1] neg_lo:[1,0,0] neg_hi:[1,0,0]
	ds_read_b128 v[28:31], v228 offset:13184
	v_pk_fma_f32 v[164:165], v[136:137], v[48:49], v[164:165] op_sel_hi:[1,0,1] neg_lo:[1,0,0] neg_hi:[1,0,0]
	v_pk_fma_f32 v[164:165], v[138:139], v[48:49], v[164:165] op_sel:[0,1,0] op_sel_hi:[1,1,1] neg_lo:[1,0,0] neg_hi:[1,0,0]
	v_pk_fma_f32 v[164:165], v[140:141], v[50:51], v[164:165] op_sel_hi:[1,0,1] neg_lo:[1,0,0] neg_hi:[1,0,0]
	v_pk_fma_f32 v[164:165], v[142:143], v[50:51], v[164:165] op_sel:[0,1,0] op_sel_hi:[1,1,1] neg_lo:[1,0,0] neg_hi:[1,0,0]
	ds_read_b128 v[32:35], v228 offset:13200
	s_waitcnt lgkmcnt(9)
; #define LAS __attribute__((address_space(3)))
; __device__ __forceinline__ void phase_gdb(const int wvs, const Params& p, LAS unsigned char* lds, int nwg) {
;     ...
;     { float x[64]; const bool isw = t >= 64;
; #pragma unroll
;       for (int i = 0; i < 64; ++i) { const float v = (float)R[i * RP + t]; x[i] = v * bs[i] * (isw ? __expf(gcs[i]) : 1.0f); asm volatile("" : "+v"(x[i])); if ((i & 7) == 7) __builtin_amdgcn_sched_barrier(0); }
; #pragma unroll
;       for (int i = 1; i < 64; ++i) {
; #pragma unroll
;         for (int j4 = 0; j4 < (i + 3) / 4; ++j4) { const f32x4 m4 = *(const LAS f32x4*)(M + i * 64 + j4 * 4);
; #pragma unroll
;           for (int jj = 0; jj < 4; ++jj) if (j4 * 4 + jj < i) x[i] -= m4[jj] * x[j4 * 4 + jj]; }
;         __builtin_amdgcn_sched_barrier(0); }
; #pragma unroll
;       for (int i = 0; i < 64; ++i) R[i * RP + t] = (hf)x[i]; }
	v_pk_fma_f32 v[164:165], v[144:145], v[52:53], v[164:165] op_sel_hi:[1,0,1] neg_lo:[1,0,0] neg_hi:[1,0,0]
	v_pk_fma_f32 v[164:165], v[146:147], v[52:53], v[164:165] op_sel:[0,1,0] op_sel_hi:[1,1,1] neg_lo:[1,0,0] neg_hi:[1,0,0]
	v_pk_fma_f32 v[164:165], v[148:149], v[54:55], v[164:165] op_sel_hi:[1,0,1] neg_lo:[1,0,0] neg_hi:[1,0,0]
	v_pk_fma_f32 v[164:165], v[150:151], v[54:55], v[164:165] op_sel:[0,1,0] op_sel_hi:[1,1,1] neg_lo:[1,0,0] neg_hi:[1,0,0]
	ds_read_b128 v[36:39], v228 offset:13216
	v_pk_fma_f32 v[164:165], v[152:153], v[56:57], v[164:165] op_sel_hi:[1,0,1] neg_lo:[1,0,0] neg_hi:[1,0,0]
	v_pk_fma_f32 v[164:165], v[154:155], v[56:57], v[164:165] op_sel:[0,1,0] op_sel_hi:[1,1,1] neg_lo:[1,0,0] neg_hi:[1,0,0]
	v_pk_fma_f32 v[164:165], v[156:157], v[58:59], v[164:165] op_sel_hi:[1,0,1] neg_lo:[1,0,0] neg_hi:[1,0,0]
	v_pk_fma_f32 v[164:165], v[158:159], v[58:59], v[164:165] op_sel:[0,1,0] op_sel_hi:[1,1,1] neg_lo:[1,0,0] neg_hi:[1,0,0]
	ds_read_b128 v[40:43], v228 offset:13232
	v_pk_fma_f32 v[164:165], v[160:161], v[60:61], v[164:165] op_sel_hi:[1,0,1] neg_lo:[1,0,0] neg_hi:[1,0,0]
	v_fma_mixlo_f16 v239, -v162, v61, v164
	v_fma_mixlo_f16 v240, -v163, v61, v165
	v_pk_fma_f32 v[164:165], v[162:163], v[60:61], v[164:165] op_sel:[0,1,0] op_sel_hi:[1,1,1] neg_lo:[1,0,0] neg_hi:[1,0,0]
	ds_write_b16 v253, v239 offset:29984
	ds_write_b16 v253, v240 offset:30112
	ds_read_b128 v[44:47], v228 offset:13248
	v_pk_fma_f32 v[166:167], v[64:65], v[244:245], v[166:167] op_sel_hi:[1,0,1] neg_lo:[1,0,0] neg_hi:[1,0,0]
	v_pk_fma_f32 v[166:167], v[66:67], v[244:245], v[166:167] op_sel:[0,1,0] op_sel_hi:[1,1,1] neg_lo:[1,0,0] neg_hi:[1,0,0]
	v_pk_fma_f32 v[166:167], v[68:69], v[246:247], v[166:167] op_sel_hi:[1,0,1] neg_lo:[1,0,0] neg_hi:[1,0,0]
	v_pk_fma_f32 v[166:167], v[70:71], v[246:247], v[166:167] op_sel:[0,1,0] op_sel_hi:[1,1,1] neg_lo:[1,0,0] neg_hi:[1,0,0]
	ds_read_b128 v[48:51], v228 offset:13312
	s_waitcnt lgkmcnt(11)
	v_pk_fma_f32 v[166:167], v[72:73], v[248:249], v[166:167] op_sel_hi:[1,0,1] neg_lo:[1,0,0] neg_hi:[1,0,0]
	v_pk_fma_f32 v[166:167], v[74:75], v[248:249], v[166:167] op_sel:[0,1,0] op_sel_hi:[1,1,1] neg_lo:[1,0,0] neg_hi:[1,0,0]
	v_pk_fma_f32 v[166:167], v[76:77], v[250:251], v[166:167] op_sel_hi:[1,0,1] neg_lo:[1,0,0] neg_hi:[1,0,0]
	v_pk_fma_f32 v[166:167], v[78:79], v[250:251], v[166:167] op_sel:[0,1,0] op_sel_hi:[1,1,1] neg_lo:[1,0,0] neg_hi:[1,0,0]
	ds_read_b128 v[52:55], v228 offset:13328
	v_pk_fma_f32 v[166:167], v[80:81], v[4:5], v[166:167] op_sel_hi:[1,0,1] neg_lo:[1,0,0] neg_hi:[1,0,0]
	v_pk_fma_f32 v[166:167], v[82:83], v[4:5], v[166:167] op_sel:[0,1,0] op_sel_hi:[1,1,1] neg_lo:[1,0,0] neg_hi:[1,0,0]
	v_pk_fma_f32 v[166:167], v[84:85], v[6:7], v[166:167] op_sel_hi:[1,0,1] neg_lo:[1,0,0] neg_hi:[1,0,0]
	v_pk_fma_f32 v[166:167], v[86:87], v[6:7], v[166:167] op_sel:[0,1,0] op_sel_hi:[1,1,1] neg_lo:[1,0,0] neg_hi:[1,0,0]
	ds_read_b128 v[56:59], v228 offset:13344
	v_pk_fma_f32 v[166:167], v[88:89], v[8:9], v[166:167] op_sel_hi:[1,0,1] neg_lo:[1,0,0] neg_hi:[1,0,0]
	v_pk_fma_f32 v[166:167], v[90:91], v[8:9], v[166:167] op_sel:[0,1,0] op_sel_hi:[1,1,1] neg_lo:[1,0,0] neg_hi:[1,0,0]
	v_pk_fma_f32 v[166:167], v[92:93], v[10:11], v[166:167] op_sel_hi:[1,0,1] neg_lo:[1,0,0] neg_hi:[1,0,0]
	v_pk_fma_f32 v[166:167], v[94:95], v[10:11], v[166:167] op_sel:[0,1,0] op_sel_hi:[1,1,1] neg_lo:[1,0,0] neg_hi:[1,0,0]
	ds_read_b128 v[60:63], v228 offset:13360
	v_pk_fma_f32 v[166:167], v[96:97], v[12:13], v[166:167] op_sel_hi:[1,0,1] neg_lo:[1,0,0] neg_hi:[1,0,0]
	v_pk_fma_f32 v[166:167], v[98:99], v[12:13], v[166:167] op_sel:[0,1,0] op_sel_hi:[1,1,1] neg_lo:[1,0,0] neg_hi:[1,0,0]
	v_pk_fma_f32 v[166:167], v[100:101], v[14:15], v[166:167] op_sel_hi:[1,0,1] neg_lo:[1,0,0] neg_hi:[1,0,0]
	v_pk_fma_f32 v[166:167], v[102:103], v[14:15], v[166:167] op_sel:[0,1,0] op_sel_hi:[1,1,1] neg_lo:[1,0,0] neg_hi:[1,0,0]
	ds_read_b128 v[244:247], v228 offset:13376
	s_waitcnt lgkmcnt(11)
	v_pk_fma_f32 v[166:167], v[104:105], v[16:17], v[166:167] op_sel_hi:[1,0,1] neg_lo:[1,0,0] neg_hi:[1,0,0]
	v_pk_fma_f32 v[166:167], v[106:107], v[16:17], v[166:167] op_sel:[0,1,0] op_sel_hi:[1,1,1] neg_lo:[1,0,0] neg_hi:[1,0,0]
	v_pk_fma_f32 v[166:167], v[108:109], v[18:19], v[166:167] op_sel_hi:[1,0,1] neg_lo:[1,0,0] neg_hi:[1,0,0]
	v_pk_fma_f32 v[166:167], v[110:111], v[18:19], v[166:167] op_sel:[0,1,0] op_sel_hi:[1,1,1] neg_lo:[1,0,0] neg_hi:[1,0,0]
	ds_read_b128 v[248:251], v228 offset:13392
	v_pk_fma_f32 v[166:167], v[112:113], v[20:21], v[166:167] op_sel_hi:[1,0,1] neg_lo:[1,0,0] neg_hi:[1,0,0]
	v_pk_fma_f32 v[166:167], v[114:115], v[20:21], v[166:167] op_sel:[0,1,0] op_sel_hi:[1,1,1] neg_lo:[1,0,0] neg_hi:[1,0,0]
	v_pk_fma_f32 v[166:167], v[116:117], v[22:23], v[166:167] op_sel_hi:[1,0,1] neg_lo:[1,0,0] neg_hi:[1,0,0]
	v_pk_fma_f32 v[166:167], v[118:119], v[22:23], v[166:167] op_sel:[0,1,0] op_sel_hi:[1,1,1] neg_lo:[1,0,0] neg_hi:[1,0,0]
	ds_read_b128 v[4:7], v228 offset:13408
	v_pk_fma_f32 v[166:167], v[120:121], v[24:25], v[166:167] op_sel_hi:[1,0,1] neg_lo:[1,0,0] neg_hi:[1,0,0]
	v_pk_fma_f32 v[166:167], v[122:123], v[24:25], v[166:167] op_sel:[0,1,0] op_sel_hi:[1,1,1] neg_lo:[1,0,0] neg_hi:[1,0,0]
	v_pk_fma_f32 v[166:167], v[124:125], v[26:27], v[166:167] op_sel_hi:[1,0,1] neg_lo:[1,0,0] neg_hi:[1,0,0]
	v_pk_fma_f32 v[166:167], v[126:127], v[26:27], v[166:167] op_sel:[0,1,0] op_sel_hi:[1,1,1] neg_lo:[1,0,0] neg_hi:[1,0,0]
	ds_read_b128 v[8:11], v228 offset:13424
	v_pk_fma_f32 v[166:167], v[128:129], v[28:29], v[166:167] op_sel_hi:[1,0,1] neg_lo:[1,0,0] neg_hi:[1,0,0]
	v_pk_fma_f32 v[166:167], v[130:131], v[28:29], v[166:167] op_sel:[0,1,0] op_sel_hi:[1,1,1] neg_lo:[1,0,0] neg_hi:[1,0,0]
	v_pk_fma_f32 v[166:167], v[132:133], v[30:31], v[166:167] op_sel_hi:[1,0,1] neg_lo:[1,0,0] neg_hi:[1,0,0]
	v_pk_fma_f32 v[166:167], v[134:135], v[30:31], v[166:167] op_sel:[0,1,0] op_sel_hi:[1,1,1] neg_lo:[1,0,0] neg_hi:[1,0,0]
	ds_read_b128 v[12:15], v228 offset:13440
	s_waitcnt lgkmcnt(9)
; #define LAS __attribute__((address_space(3)))
; __device__ __forceinline__ void phase_gdb(const int wvs, const Params& p, LAS unsigned char* lds, int nwg) {
;     ...
;     { float x[64]; const bool isw = t >= 64;
; #pragma unroll
;       for (int i = 0; i < 64; ++i) { const float v = (float)R[i * RP + t]; x[i] = v * bs[i] * (isw ? __expf(gcs[i]) : 1.0f); asm volatile("" : "+v"(x[i])); if ((i & 7) == 7) __builtin_amdgcn_sched_barrier(0); }
; #pragma unroll
;       for (int i = 1; i < 64; ++i) {
; #pragma unroll
;         for (int j4 = 0; j4 < (i + 3) / 4; ++j4) { const f32x4 m4 = *(const LAS f32x4*)(M + i * 64 + j4 * 4);
; #pragma unroll
;           for (int jj = 0; jj < 4; ++jj) if (j4 * 4 + jj < i) x[i] -= m4[jj] * x[j4 * 4 + jj]; }
;         __builtin_amdgcn_sched_barrier(0); }
; #pragma unroll
;       for (int i = 0; i < 64; ++i) R[i * RP + t] = (hf)x[i]; }
	v_pk_fma_f32 v[166:167], v[136:137], v[32:33], v[166:167] op_sel_hi:[1,0,1] neg_lo:[1,0,0] neg_hi:[1,0,0]
	v_pk_fma_f32 v[166:167], v[138:139], v[32:33], v[166:167] op_sel:[0,1,0] op_sel_hi:[1,1,1] neg_lo:[1,0,0] neg_hi:[1,0,0]
	v_pk_fma_f32 v[166:167], v[140:141], v[34:35], v[166:167] op_sel_hi:[1,0,1] neg_lo:[1,0,0] neg_hi:[1,0,0]
	v_pk_fma_f32 v[166:167], v[142:143], v[34:35], v[166:167] op_sel:[0,1,0] op_sel_hi:[1,1,1] neg_lo:[1,0,0] neg_hi:[1,0,0]
	ds_read_b128 v[16:19], v228 offset:13456
	v_pk_fma_f32 v[166:167], v[144:145], v[36:37], v[166:167] op_sel_hi:[1,0,1] neg_lo:[1,0,0] neg_hi:[1,0,0]
	v_pk_fma_f32 v[166:167], v[146:147], v[36:37], v[166:167] op_sel:[0,1,0] op_sel_hi:[1,1,1] neg_lo:[1,0,0] neg_hi:[1,0,0]
	v_pk_fma_f32 v[166:167], v[148:149], v[38:39], v[166:167] op_sel_hi:[1,0,1] neg_lo:[1,0,0] neg_hi:[1,0,0]
	v_pk_fma_f32 v[166:167], v[150:151], v[38:39], v[166:167] op_sel:[0,1,0] op_sel_hi:[1,1,1] neg_lo:[1,0,0] neg_hi:[1,0,0]
	ds_read_b128 v[20:23], v228 offset:13472
	v_pk_fma_f32 v[166:167], v[152:153], v[40:41], v[166:167] op_sel_hi:[1,0,1] neg_lo:[1,0,0] neg_hi:[1,0,0]
	v_pk_fma_f32 v[166:167], v[154:155], v[40:41], v[166:167] op_sel:[0,1,0] op_sel_hi:[1,1,1] neg_lo:[1,0,0] neg_hi:[1,0,0]
	v_pk_fma_f32 v[166:167], v[156:157], v[42:43], v[166:167] op_sel_hi:[1,0,1] neg_lo:[1,0,0] neg_hi:[1,0,0]
	v_pk_fma_f32 v[166:167], v[158:159], v[42:43], v[166:167] op_sel:[0,1,0] op_sel_hi:[1,1,1] neg_lo:[1,0,0] neg_hi:[1,0,0]
	ds_read_b128 v[24:27], v228 offset:13488
	v_pk_fma_f32 v[166:167], v[160:161], v[44:45], v[166:167] op_sel_hi:[1,0,1] neg_lo:[1,0,0] neg_hi:[1,0,0]
	v_pk_fma_f32 v[166:167], v[162:163], v[44:45], v[166:167] op_sel:[0,1,0] op_sel_hi:[1,1,1] neg_lo:[1,0,0] neg_hi:[1,0,0]
	v_fma_mixlo_f16 v0, -v164, v46, v166
	v_fma_mixlo_f16 v2, -v165, v46, v167
	v_pk_fma_f32 v[166:167], v[164:165], v[46:47], v[166:167] op_sel_hi:[1,0,1] neg_lo:[1,0,0] neg_hi:[1,0,0]
	ds_write_b16 v253, v0 offset:30256
	ds_write_b16 v253, v2 offset:30384
	ds_read_b128 v[28:31], v228 offset:13504
	s_waitcnt lgkmcnt(11)
	v_pk_fma_f32 v[168:169], v[64:65], v[48:49], v[168:169] op_sel_hi:[1,0,1] neg_lo:[1,0,0] neg_hi:[1,0,0]
	v_pk_fma_f32 v[168:169], v[66:67], v[48:49], v[168:169] op_sel:[0,1,0] op_sel_hi:[1,1,1] neg_lo:[1,0,0] neg_hi:[1,0,0]
	v_pk_fma_f32 v[168:169], v[68:69], v[50:51], v[168:169] op_sel_hi:[1,0,1] neg_lo:[1,0,0] neg_hi:[1,0,0]
	v_pk_fma_f32 v[168:169], v[70:71], v[50:51], v[168:169] op_sel:[0,1,0] op_sel_hi:[1,1,1] neg_lo:[1,0,0] neg_hi:[1,0,0]
	ds_read_b128 v[32:35], v228 offset:13568
	v_pk_fma_f32 v[168:169], v[72:73], v[52:53], v[168:169] op_sel_hi:[1,0,1] neg_lo:[1,0,0] neg_hi:[1,0,0]
	v_pk_fma_f32 v[168:169], v[74:75], v[52:53], v[168:169] op_sel:[0,1,0] op_sel_hi:[1,1,1] neg_lo:[1,0,0] neg_hi:[1,0,0]
	v_pk_fma_f32 v[168:169], v[76:77], v[54:55], v[168:169] op_sel_hi:[1,0,1] neg_lo:[1,0,0] neg_hi:[1,0,0]
	v_pk_fma_f32 v[168:169], v[78:79], v[54:55], v[168:169] op_sel:[0,1,0] op_sel_hi:[1,1,1] neg_lo:[1,0,0] neg_hi:[1,0,0]
	ds_read_b128 v[36:39], v228 offset:13584
	v_pk_fma_f32 v[168:169], v[80:81], v[56:57], v[168:169] op_sel_hi:[1,0,1] neg_lo:[1,0,0] neg_hi:[1,0,0]
	v_pk_fma_f32 v[168:169], v[82:83], v[56:57], v[168:169] op_sel:[0,1,0] op_sel_hi:[1,1,1] neg_lo:[1,0,0] neg_hi:[1,0,0]
	v_pk_fma_f32 v[168:169], v[84:85], v[58:59], v[168:169] op_sel_hi:[1,0,1] neg_lo:[1,0,0] neg_hi:[1,0,0]
	v_pk_fma_f32 v[168:169], v[86:87], v[58:59], v[168:169] op_sel:[0,1,0] op_sel_hi:[1,1,1] neg_lo:[1,0,0] neg_hi:[1,0,0]
	ds_read_b128 v[40:43], v228 offset:13600
	v_pk_fma_f32 v[168:169], v[88:89], v[60:61], v[168:169] op_sel_hi:[1,0,1] neg_lo:[1,0,0] neg_hi:[1,0,0]
	v_pk_fma_f32 v[168:169], v[90:91], v[60:61], v[168:169] op_sel:[0,1,0] op_sel_hi:[1,1,1] neg_lo:[1,0,0] neg_hi:[1,0,0]
	v_pk_fma_f32 v[168:169], v[92:93], v[62:63], v[168:169] op_sel_hi:[1,0,1] neg_lo:[1,0,0] neg_hi:[1,0,0]
	v_pk_fma_f32 v[168:169], v[94:95], v[62:63], v[168:169] op_sel:[0,1,0] op_sel_hi:[1,1,1] neg_lo:[1,0,0] neg_hi:[1,0,0]
	ds_read_b128 v[44:47], v228 offset:13616
	s_waitcnt lgkmcnt(11)
	v_pk_fma_f32 v[168:169], v[96:97], v[244:245], v[168:169] op_sel_hi:[1,0,1] neg_lo:[1,0,0] neg_hi:[1,0,0]
	v_pk_fma_f32 v[168:169], v[98:99], v[244:245], v[168:169] op_sel:[0,1,0] op_sel_hi:[1,1,1] neg_lo:[1,0,0] neg_hi:[1,0,0]
	v_pk_fma_f32 v[168:169], v[100:101], v[246:247], v[168:169] op_sel_hi:[1,0,1] neg_lo:[1,0,0] neg_hi:[1,0,0]
	v_pk_fma_f32 v[168:169], v[102:103], v[246:247], v[168:169] op_sel:[0,1,0] op_sel_hi:[1,1,1] neg_lo:[1,0,0] neg_hi:[1,0,0]
	ds_read_b128 v[48:51], v228 offset:13632
	v_pk_fma_f32 v[168:169], v[104:105], v[248:249], v[168:169] op_sel_hi:[1,0,1] neg_lo:[1,0,0] neg_hi:[1,0,0]
	v_pk_fma_f32 v[168:169], v[106:107], v[248:249], v[168:169] op_sel:[0,1,0] op_sel_hi:[1,1,1] neg_lo:[1,0,0] neg_hi:[1,0,0]
	v_pk_fma_f32 v[168:169], v[108:109], v[250:251], v[168:169] op_sel_hi:[1,0,1] neg_lo:[1,0,0] neg_hi:[1,0,0]
	v_pk_fma_f32 v[168:169], v[110:111], v[250:251], v[168:169] op_sel:[0,1,0] op_sel_hi:[1,1,1] neg_lo:[1,0,0] neg_hi:[1,0,0]
	ds_read_b128 v[52:55], v228 offset:13648
	v_pk_fma_f32 v[168:169], v[112:113], v[4:5], v[168:169] op_sel_hi:[1,0,1] neg_lo:[1,0,0] neg_hi:[1,0,0]
	v_pk_fma_f32 v[168:169], v[114:115], v[4:5], v[168:169] op_sel:[0,1,0] op_sel_hi:[1,1,1] neg_lo:[1,0,0] neg_hi:[1,0,0]
	v_pk_fma_f32 v[168:169], v[116:117], v[6:7], v[168:169] op_sel_hi:[1,0,1] neg_lo:[1,0,0] neg_hi:[1,0,0]
	v_pk_fma_f32 v[168:169], v[118:119], v[6:7], v[168:169] op_sel:[0,1,0] op_sel_hi:[1,1,1] neg_lo:[1,0,0] neg_hi:[1,0,0]
	ds_read_b128 v[56:59], v228 offset:13664
	v_pk_fma_f32 v[168:169], v[120:121], v[8:9], v[168:169] op_sel_hi:[1,0,1] neg_lo:[1,0,0] neg_hi:[1,0,0]
	v_pk_fma_f32 v[168:169], v[122:123], v[8:9], v[168:169] op_sel:[0,1,0] op_sel_hi:[1,1,1] neg_lo:[1,0,0] neg_hi:[1,0,0]
	v_pk_fma_f32 v[168:169], v[124:125], v[10:11], v[168:169] op_sel_hi:[1,0,1] neg_lo:[1,0,0] neg_hi:[1,0,0]
	v_pk_fma_f32 v[168:169], v[126:127], v[10:11], v[168:169] op_sel:[0,1,0] op_sel_hi:[1,1,1] neg_lo:[1,0,0] neg_hi:[1,0,0]
	ds_read_b128 v[60:63], v228 offset:13680
	s_waitcnt lgkmcnt(11)
; #define LAS __attribute__((address_space(3)))
; __device__ __forceinline__ void phase_gdb(const int wvs, const Params& p, LAS unsigned char* lds, int nwg) {
;     ...
;     { float x[64]; const bool isw = t >= 64;
; #pragma unroll
;       for (int i = 0; i < 64; ++i) { const float v = (float)R[i * RP + t]; x[i] = v * bs[i] * (isw ? __expf(gcs[i]) : 1.0f); asm volatile("" : "+v"(x[i])); if ((i & 7) == 7) __builtin_amdgcn_sched_barrier(0); }
; #pragma unroll
;       for (int i = 1; i < 64; ++i) {
; #pragma unroll
;         for (int j4 = 0; j4 < (i + 3) / 4; ++j4) { const f32x4 m4 = *(const LAS f32x4*)(M + i * 64 + j4 * 4);
; #pragma unroll
;           for (int jj = 0; jj < 4; ++jj) if (j4 * 4 + jj < i) x[i] -= m4[jj] * x[j4 * 4 + jj]; }
;         __builtin_amdgcn_sched_barrier(0); }
; #pragma unroll
;       for (int i = 0; i < 64; ++i) R[i * RP + t] = (hf)x[i]; }
	v_pk_fma_f32 v[168:169], v[128:129], v[12:13], v[168:169] op_sel_hi:[1,0,1] neg_lo:[1,0,0] neg_hi:[1,0,0]
	v_pk_fma_f32 v[168:169], v[130:131], v[12:13], v[168:169] op_sel:[0,1,0] op_sel_hi:[1,1,1] neg_lo:[1,0,0] neg_hi:[1,0,0]
	v_pk_fma_f32 v[168:169], v[132:133], v[14:15], v[168:169] op_sel_hi:[1,0,1] neg_lo:[1,0,0] neg_hi:[1,0,0]
	v_pk_fma_f32 v[168:169], v[134:135], v[14:15], v[168:169] op_sel:[0,1,0] op_sel_hi:[1,1,1] neg_lo:[1,0,0] neg_hi:[1,0,0]
	ds_read_b128 v[244:247], v228 offset:13696
	v_pk_fma_f32 v[168:169], v[136:137], v[16:17], v[168:169] op_sel_hi:[1,0,1] neg_lo:[1,0,0] neg_hi:[1,0,0]
	v_pk_fma_f32 v[168:169], v[138:139], v[16:17], v[168:169] op_sel:[0,1,0] op_sel_hi:[1,1,1] neg_lo:[1,0,0] neg_hi:[1,0,0]
	v_pk_fma_f32 v[168:169], v[140:141], v[18:19], v[168:169] op_sel_hi:[1,0,1] neg_lo:[1,0,0] neg_hi:[1,0,0]
	v_pk_fma_f32 v[168:169], v[142:143], v[18:19], v[168:169] op_sel:[0,1,0] op_sel_hi:[1,1,1] neg_lo:[1,0,0] neg_hi:[1,0,0]
	ds_read_b128 v[248:251], v228 offset:13712
	v_pk_fma_f32 v[168:169], v[144:145], v[20:21], v[168:169] op_sel_hi:[1,0,1] neg_lo:[1,0,0] neg_hi:[1,0,0]
	v_pk_fma_f32 v[168:169], v[146:147], v[20:21], v[168:169] op_sel:[0,1,0] op_sel_hi:[1,1,1] neg_lo:[1,0,0] neg_hi:[1,0,0]
	v_pk_fma_f32 v[168:169], v[148:149], v[22:23], v[168:169] op_sel_hi:[1,0,1] neg_lo:[1,0,0] neg_hi:[1,0,0]
	v_pk_fma_f32 v[168:169], v[150:151], v[22:23], v[168:169] op_sel:[0,1,0] op_sel_hi:[1,1,1] neg_lo:[1,0,0] neg_hi:[1,0,0]
	ds_read_b128 v[4:7], v228 offset:13728
	v_pk_fma_f32 v[168:169], v[152:153], v[24:25], v[168:169] op_sel_hi:[1,0,1] neg_lo:[1,0,0] neg_hi:[1,0,0]
	v_pk_fma_f32 v[168:169], v[154:155], v[24:25], v[168:169] op_sel:[0,1,0] op_sel_hi:[1,1,1] neg_lo:[1,0,0] neg_hi:[1,0,0]
	v_pk_fma_f32 v[168:169], v[156:157], v[26:27], v[168:169] op_sel_hi:[1,0,1] neg_lo:[1,0,0] neg_hi:[1,0,0]
	v_pk_fma_f32 v[168:169], v[158:159], v[26:27], v[168:169] op_sel:[0,1,0] op_sel_hi:[1,1,1] neg_lo:[1,0,0] neg_hi:[1,0,0]
	ds_read_b128 v[8:11], v228 offset:13744
	s_waitcnt lgkmcnt(9)
	v_pk_fma_f32 v[168:169], v[160:161], v[28:29], v[168:169] op_sel_hi:[1,0,1] neg_lo:[1,0,0] neg_hi:[1,0,0]
	v_pk_fma_f32 v[168:169], v[162:163], v[28:29], v[168:169] op_sel:[0,1,0] op_sel_hi:[1,1,1] neg_lo:[1,0,0] neg_hi:[1,0,0]
	v_pk_fma_f32 v[168:169], v[164:165], v[30:31], v[168:169] op_sel_hi:[1,0,1] neg_lo:[1,0,0] neg_hi:[1,0,0]
	v_fma_mixlo_f16 v3, -v166, v31, v168
	v_fma_mixlo_f16 v238, -v167, v31, v169
	v_pk_fma_f32 v[168:169], v[166:167], v[30:31], v[168:169] op_sel:[0,1,0] op_sel_hi:[1,1,1] neg_lo:[1,0,0] neg_hi:[1,0,0]
	ds_write_b16 v253, v3 offset:30528
	ds_write_b16 v253, v238 offset:30656
	ds_read_b128 v[12:15], v228 offset:13760
	v_pk_fma_f32 v[170:171], v[64:65], v[32:33], v[170:171] op_sel_hi:[1,0,1] neg_lo:[1,0,0] neg_hi:[1,0,0]
	v_pk_fma_f32 v[170:171], v[66:67], v[32:33], v[170:171] op_sel:[0,1,0] op_sel_hi:[1,1,1] neg_lo:[1,0,0] neg_hi:[1,0,0]
	v_pk_fma_f32 v[170:171], v[68:69], v[34:35], v[170:171] op_sel_hi:[1,0,1] neg_lo:[1,0,0] neg_hi:[1,0,0]
	v_pk_fma_f32 v[170:171], v[70:71], v[34:35], v[170:171] op_sel:[0,1,0] op_sel_hi:[1,1,1] neg_lo:[1,0,0] neg_hi:[1,0,0]
	ds_read_b128 v[16:19], v228 offset:13776
	v_pk_fma_f32 v[170:171], v[72:73], v[36:37], v[170:171] op_sel_hi:[1,0,1] neg_lo:[1,0,0] neg_hi:[1,0,0]
	v_pk_fma_f32 v[170:171], v[74:75], v[36:37], v[170:171] op_sel:[0,1,0] op_sel_hi:[1,1,1] neg_lo:[1,0,0] neg_hi:[1,0,0]
	v_pk_fma_f32 v[170:171], v[76:77], v[38:39], v[170:171] op_sel_hi:[1,0,1] neg_lo:[1,0,0] neg_hi:[1,0,0]
	v_pk_fma_f32 v[170:171], v[78:79], v[38:39], v[170:171] op_sel:[0,1,0] op_sel_hi:[1,1,1] neg_lo:[1,0,0] neg_hi:[1,0,0]
	ds_read_b128 v[20:23], v228 offset:13824
	v_pk_fma_f32 v[170:171], v[80:81], v[40:41], v[170:171] op_sel_hi:[1,0,1] neg_lo:[1,0,0] neg_hi:[1,0,0]
	v_pk_fma_f32 v[170:171], v[82:83], v[40:41], v[170:171] op_sel:[0,1,0] op_sel_hi:[1,1,1] neg_lo:[1,0,0] neg_hi:[1,0,0]
	v_pk_fma_f32 v[170:171], v[84:85], v[42:43], v[170:171] op_sel_hi:[1,0,1] neg_lo:[1,0,0] neg_hi:[1,0,0]
	v_pk_fma_f32 v[170:171], v[86:87], v[42:43], v[170:171] op_sel:[0,1,0] op_sel_hi:[1,1,1] neg_lo:[1,0,0] neg_hi:[1,0,0]
	ds_read_b128 v[24:27], v228 offset:13840
	s_waitcnt lgkmcnt(11)
	v_pk_fma_f32 v[170:171], v[88:89], v[44:45], v[170:171] op_sel_hi:[1,0,1] neg_lo:[1,0,0] neg_hi:[1,0,0]
	v_pk_fma_f32 v[170:171], v[90:91], v[44:45], v[170:171] op_sel:[0,1,0] op_sel_hi:[1,1,1] neg_lo:[1,0,0] neg_hi:[1,0,0]
	v_pk_fma_f32 v[170:171], v[92:93], v[46:47], v[170:171] op_sel_hi:[1,0,1] neg_lo:[1,0,0] neg_hi:[1,0,0]
	v_pk_fma_f32 v[170:171], v[94:95], v[46:47], v[170:171] op_sel:[0,1,0] op_sel_hi:[1,1,1] neg_lo:[1,0,0] neg_hi:[1,0,0]
	ds_read_b128 v[28:31], v228 offset:13856
	v_pk_fma_f32 v[170:171], v[96:97], v[48:49], v[170:171] op_sel_hi:[1,0,1] neg_lo:[1,0,0] neg_hi:[1,0,0]
	v_pk_fma_f32 v[170:171], v[98:99], v[48:49], v[170:171] op_sel:[0,1,0] op_sel_hi:[1,1,1] neg_lo:[1,0,0] neg_hi:[1,0,0]
	v_pk_fma_f32 v[170:171], v[100:101], v[50:51], v[170:171] op_sel_hi:[1,0,1] neg_lo:[1,0,0] neg_hi:[1,0,0]
	v_pk_fma_f32 v[170:171], v[102:103], v[50:51], v[170:171] op_sel:[0,1,0] op_sel_hi:[1,1,1] neg_lo:[1,0,0] neg_hi:[1,0,0]
	ds_read_b128 v[32:35], v228 offset:13872
	v_pk_fma_f32 v[170:171], v[104:105], v[52:53], v[170:171] op_sel_hi:[1,0,1] neg_lo:[1,0,0] neg_hi:[1,0,0]
	v_pk_fma_f32 v[170:171], v[106:107], v[52:53], v[170:171] op_sel:[0,1,0] op_sel_hi:[1,1,1] neg_lo:[1,0,0] neg_hi:[1,0,0]
	v_pk_fma_f32 v[170:171], v[108:109], v[54:55], v[170:171] op_sel_hi:[1,0,1] neg_lo:[1,0,0] neg_hi:[1,0,0]
	v_pk_fma_f32 v[170:171], v[110:111], v[54:55], v[170:171] op_sel:[0,1,0] op_sel_hi:[1,1,1] neg_lo:[1,0,0] neg_hi:[1,0,0]
	ds_read_b128 v[36:39], v228 offset:13888
	v_pk_fma_f32 v[170:171], v[112:113], v[56:57], v[170:171] op_sel_hi:[1,0,1] neg_lo:[1,0,0] neg_hi:[1,0,0]
	v_pk_fma_f32 v[170:171], v[114:115], v[56:57], v[170:171] op_sel:[0,1,0] op_sel_hi:[1,1,1] neg_lo:[1,0,0] neg_hi:[1,0,0]
	v_pk_fma_f32 v[170:171], v[116:117], v[58:59], v[170:171] op_sel_hi:[1,0,1] neg_lo:[1,0,0] neg_hi:[1,0,0]
	v_pk_fma_f32 v[170:171], v[118:119], v[58:59], v[170:171] op_sel:[0,1,0] op_sel_hi:[1,1,1] neg_lo:[1,0,0] neg_hi:[1,0,0]
	ds_read_b128 v[40:43], v228 offset:13904
	s_waitcnt lgkmcnt(11)
; #define LAS __attribute__((address_space(3)))
; __device__ __forceinline__ void phase_gdb(const int wvs, const Params& p, LAS unsigned char* lds, int nwg) {
;     ...
;     { float x[64]; const bool isw = t >= 64;
; #pragma unroll
;       for (int i = 0; i < 64; ++i) { const float v = (float)R[i * RP + t]; x[i] = v * bs[i] * (isw ? __expf(gcs[i]) : 1.0f); asm volatile("" : "+v"(x[i])); if ((i & 7) == 7) __builtin_amdgcn_sched_barrier(0); }
; #pragma unroll
;       for (int i = 1; i < 64; ++i) {
; #pragma unroll
;         for (int j4 = 0; j4 < (i + 3) / 4; ++j4) { const f32x4 m4 = *(const LAS f32x4*)(M + i * 64 + j4 * 4);
; #pragma unroll
;           for (int jj = 0; jj < 4; ++jj) if (j4 * 4 + jj < i) x[i] -= m4[jj] * x[j4 * 4 + jj]; }
;         __builtin_amdgcn_sched_barrier(0); }
; #pragma unroll
;       for (int i = 0; i < 64; ++i) R[i * RP + t] = (hf)x[i]; }
	v_pk_fma_f32 v[170:171], v[120:121], v[60:61], v[170:171] op_sel_hi:[1,0,1] neg_lo:[1,0,0] neg_hi:[1,0,0]
	v_pk_fma_f32 v[170:171], v[122:123], v[60:61], v[170:171] op_sel:[0,1,0] op_sel_hi:[1,1,1] neg_lo:[1,0,0] neg_hi:[1,0,0]
	v_pk_fma_f32 v[170:171], v[124:125], v[62:63], v[170:171] op_sel_hi:[1,0,1] neg_lo:[1,0,0] neg_hi:[1,0,0]
	v_pk_fma_f32 v[170:171], v[126:127], v[62:63], v[170:171] op_sel:[0,1,0] op_sel_hi:[1,1,1] neg_lo:[1,0,0] neg_hi:[1,0,0]
	ds_read_b128 v[44:47], v228 offset:13920
	v_pk_fma_f32 v[170:171], v[128:129], v[244:245], v[170:171] op_sel_hi:[1,0,1] neg_lo:[1,0,0] neg_hi:[1,0,0]
	v_pk_fma_f32 v[170:171], v[130:131], v[244:245], v[170:171] op_sel:[0,1,0] op_sel_hi:[1,1,1] neg_lo:[1,0,0] neg_hi:[1,0,0]
	v_pk_fma_f32 v[170:171], v[132:133], v[246:247], v[170:171] op_sel_hi:[1,0,1] neg_lo:[1,0,0] neg_hi:[1,0,0]
	v_pk_fma_f32 v[170:171], v[134:135], v[246:247], v[170:171] op_sel:[0,1,0] op_sel_hi:[1,1,1] neg_lo:[1,0,0] neg_hi:[1,0,0]
	ds_read_b128 v[48:51], v228 offset:13936
	v_pk_fma_f32 v[170:171], v[136:137], v[248:249], v[170:171] op_sel_hi:[1,0,1] neg_lo:[1,0,0] neg_hi:[1,0,0]
	v_pk_fma_f32 v[170:171], v[138:139], v[248:249], v[170:171] op_sel:[0,1,0] op_sel_hi:[1,1,1] neg_lo:[1,0,0] neg_hi:[1,0,0]
	v_pk_fma_f32 v[170:171], v[140:141], v[250:251], v[170:171] op_sel_hi:[1,0,1] neg_lo:[1,0,0] neg_hi:[1,0,0]
	v_pk_fma_f32 v[170:171], v[142:143], v[250:251], v[170:171] op_sel:[0,1,0] op_sel_hi:[1,1,1] neg_lo:[1,0,0] neg_hi:[1,0,0]
	ds_read_b128 v[52:55], v228 offset:13952
	v_pk_fma_f32 v[170:171], v[144:145], v[4:5], v[170:171] op_sel_hi:[1,0,1] neg_lo:[1,0,0] neg_hi:[1,0,0]
	v_pk_fma_f32 v[170:171], v[146:147], v[4:5], v[170:171] op_sel:[0,1,0] op_sel_hi:[1,1,1] neg_lo:[1,0,0] neg_hi:[1,0,0]
	v_pk_fma_f32 v[170:171], v[148:149], v[6:7], v[170:171] op_sel_hi:[1,0,1] neg_lo:[1,0,0] neg_hi:[1,0,0]
	v_pk_fma_f32 v[170:171], v[150:151], v[6:7], v[170:171] op_sel:[0,1,0] op_sel_hi:[1,1,1] neg_lo:[1,0,0] neg_hi:[1,0,0]
	ds_read_b128 v[56:59], v228 offset:13968
	s_waitcnt lgkmcnt(9)
	v_pk_fma_f32 v[170:171], v[152:153], v[8:9], v[170:171] op_sel_hi:[1,0,1] neg_lo:[1,0,0] neg_hi:[1,0,0]
	v_pk_fma_f32 v[170:171], v[154:155], v[8:9], v[170:171] op_sel:[0,1,0] op_sel_hi:[1,1,1] neg_lo:[1,0,0] neg_hi:[1,0,0]
	v_pk_fma_f32 v[170:171], v[156:157], v[10:11], v[170:171] op_sel_hi:[1,0,1] neg_lo:[1,0,0] neg_hi:[1,0,0]
	v_pk_fma_f32 v[170:171], v[158:159], v[10:11], v[170:171] op_sel:[0,1,0] op_sel_hi:[1,1,1] neg_lo:[1,0,0] neg_hi:[1,0,0]
	ds_read_b128 v[60:63], v228 offset:13984
	v_pk_fma_f32 v[170:171], v[160:161], v[12:13], v[170:171] op_sel_hi:[1,0,1] neg_lo:[1,0,0] neg_hi:[1,0,0]
	v_pk_fma_f32 v[170:171], v[162:163], v[12:13], v[170:171] op_sel:[0,1,0] op_sel_hi:[1,1,1] neg_lo:[1,0,0] neg_hi:[1,0,0]
	v_pk_fma_f32 v[170:171], v[164:165], v[14:15], v[170:171] op_sel_hi:[1,0,1] neg_lo:[1,0,0] neg_hi:[1,0,0]
	v_pk_fma_f32 v[170:171], v[166:167], v[14:15], v[170:171] op_sel:[0,1,0] op_sel_hi:[1,1,1] neg_lo:[1,0,0] neg_hi:[1,0,0]
	ds_read_b128 v[244:247], v228 offset:14000
	v_fma_mixlo_f16 v239, -v168, v16, v170
	v_fma_mixlo_f16 v240, -v169, v16, v171
	v_pk_fma_f32 v[170:171], v[168:169], v[16:17], v[170:171] op_sel_hi:[1,0,1] neg_lo:[1,0,0] neg_hi:[1,0,0]
	ds_write_b16 v253, v239 offset:30800
	ds_write_b16 v253, v240 offset:30928
	ds_read_b128 v[248:251], v228 offset:14016
	v_pk_fma_f32 v[172:173], v[64:65], v[20:21], v[172:173] op_sel_hi:[1,0,1] neg_lo:[1,0,0] neg_hi:[1,0,0]
	v_pk_fma_f32 v[172:173], v[66:67], v[20:21], v[172:173] op_sel:[0,1,0] op_sel_hi:[1,1,1] neg_lo:[1,0,0] neg_hi:[1,0,0]
	v_pk_fma_f32 v[172:173], v[68:69], v[22:23], v[172:173] op_sel_hi:[1,0,1] neg_lo:[1,0,0] neg_hi:[1,0,0]
	v_pk_fma_f32 v[172:173], v[70:71], v[22:23], v[172:173] op_sel:[0,1,0] op_sel_hi:[1,1,1] neg_lo:[1,0,0] neg_hi:[1,0,0]
	ds_read_b128 v[4:7], v228 offset:14032
	s_waitcnt lgkmcnt(11)
	v_pk_fma_f32 v[172:173], v[72:73], v[24:25], v[172:173] op_sel_hi:[1,0,1] neg_lo:[1,0,0] neg_hi:[1,0,0]
	v_pk_fma_f32 v[172:173], v[74:75], v[24:25], v[172:173] op_sel:[0,1,0] op_sel_hi:[1,1,1] neg_lo:[1,0,0] neg_hi:[1,0,0]
	v_pk_fma_f32 v[172:173], v[76:77], v[26:27], v[172:173] op_sel_hi:[1,0,1] neg_lo:[1,0,0] neg_hi:[1,0,0]
	v_pk_fma_f32 v[172:173], v[78:79], v[26:27], v[172:173] op_sel:[0,1,0] op_sel_hi:[1,1,1] neg_lo:[1,0,0] neg_hi:[1,0,0]
	ds_read_b128 v[8:11], v228 offset:14080
	v_pk_fma_f32 v[172:173], v[80:81], v[28:29], v[172:173] op_sel_hi:[1,0,1] neg_lo:[1,0,0] neg_hi:[1,0,0]
	v_pk_fma_f32 v[172:173], v[82:83], v[28:29], v[172:173] op_sel:[0,1,0] op_sel_hi:[1,1,1] neg_lo:[1,0,0] neg_hi:[1,0,0]
	v_pk_fma_f32 v[172:173], v[84:85], v[30:31], v[172:173] op_sel_hi:[1,0,1] neg_lo:[1,0,0] neg_hi:[1,0,0]
	v_pk_fma_f32 v[172:173], v[86:87], v[30:31], v[172:173] op_sel:[0,1,0] op_sel_hi:[1,1,1] neg_lo:[1,0,0] neg_hi:[1,0,0]
	ds_read_b128 v[12:15], v228 offset:14096
	v_pk_fma_f32 v[172:173], v[88:89], v[32:33], v[172:173] op_sel_hi:[1,0,1] neg_lo:[1,0,0] neg_hi:[1,0,0]
	v_pk_fma_f32 v[172:173], v[90:91], v[32:33], v[172:173] op_sel:[0,1,0] op_sel_hi:[1,1,1] neg_lo:[1,0,0] neg_hi:[1,0,0]
	v_pk_fma_f32 v[172:173], v[92:93], v[34:35], v[172:173] op_sel_hi:[1,0,1] neg_lo:[1,0,0] neg_hi:[1,0,0]
	v_pk_fma_f32 v[172:173], v[94:95], v[34:35], v[172:173] op_sel:[0,1,0] op_sel_hi:[1,1,1] neg_lo:[1,0,0] neg_hi:[1,0,0]
	ds_read_b128 v[16:19], v228 offset:14112
	v_pk_fma_f32 v[172:173], v[96:97], v[36:37], v[172:173] op_sel_hi:[1,0,1] neg_lo:[1,0,0] neg_hi:[1,0,0]
	v_pk_fma_f32 v[172:173], v[98:99], v[36:37], v[172:173] op_sel:[0,1,0] op_sel_hi:[1,1,1] neg_lo:[1,0,0] neg_hi:[1,0,0]
	v_pk_fma_f32 v[172:173], v[100:101], v[38:39], v[172:173] op_sel_hi:[1,0,1] neg_lo:[1,0,0] neg_hi:[1,0,0]
	v_pk_fma_f32 v[172:173], v[102:103], v[38:39], v[172:173] op_sel:[0,1,0] op_sel_hi:[1,1,1] neg_lo:[1,0,0] neg_hi:[1,0,0]
	ds_read_b128 v[20:23], v228 offset:14128
	s_waitcnt lgkmcnt(11)
; #define LAS __attribute__((address_space(3)))
; __device__ __forceinline__ void phase_gdb(const int wvs, const Params& p, LAS unsigned char* lds, int nwg) {
;     ...
;     { float x[64]; const bool isw = t >= 64;
; #pragma unroll
;       for (int i = 0; i < 64; ++i) { const float v = (float)R[i * RP + t]; x[i] = v * bs[i] * (isw ? __expf(gcs[i]) : 1.0f); asm volatile("" : "+v"(x[i])); if ((i & 7) == 7) __builtin_amdgcn_sched_barrier(0); }
; #pragma unroll
;       for (int i = 1; i < 64; ++i) {
; #pragma unroll
;         for (int j4 = 0; j4 < (i + 3) / 4; ++j4) { const f32x4 m4 = *(const LAS f32x4*)(M + i * 64 + j4 * 4);
; #pragma unroll
;           for (int jj = 0; jj < 4; ++jj) if (j4 * 4 + jj < i) x[i] -= m4[jj] * x[j4 * 4 + jj]; }
;         __builtin_amdgcn_sched_barrier(0); }
; #pragma unroll
;       for (int i = 0; i < 64; ++i) R[i * RP + t] = (hf)x[i]; }
	v_pk_fma_f32 v[172:173], v[104:105], v[40:41], v[172:173] op_sel_hi:[1,0,1] neg_lo:[1,0,0] neg_hi:[1,0,0]
	v_pk_fma_f32 v[172:173], v[106:107], v[40:41], v[172:173] op_sel:[0,1,0] op_sel_hi:[1,1,1] neg_lo:[1,0,0] neg_hi:[1,0,0]
	v_pk_fma_f32 v[172:173], v[108:109], v[42:43], v[172:173] op_sel_hi:[1,0,1] neg_lo:[1,0,0] neg_hi:[1,0,0]
	v_pk_fma_f32 v[172:173], v[110:111], v[42:43], v[172:173] op_sel:[0,1,0] op_sel_hi:[1,1,1] neg_lo:[1,0,0] neg_hi:[1,0,0]
	ds_read_b128 v[24:27], v228 offset:14144
	v_pk_fma_f32 v[172:173], v[112:113], v[44:45], v[172:173] op_sel_hi:[1,0,1] neg_lo:[1,0,0] neg_hi:[1,0,0]
	v_pk_fma_f32 v[172:173], v[114:115], v[44:45], v[172:173] op_sel:[0,1,0] op_sel_hi:[1,1,1] neg_lo:[1,0,0] neg_hi:[1,0,0]
	v_pk_fma_f32 v[172:173], v[116:117], v[46:47], v[172:173] op_sel_hi:[1,0,1] neg_lo:[1,0,0] neg_hi:[1,0,0]
	v_pk_fma_f32 v[172:173], v[118:119], v[46:47], v[172:173] op_sel:[0,1,0] op_sel_hi:[1,1,1] neg_lo:[1,0,0] neg_hi:[1,0,0]
	ds_read_b128 v[28:31], v228 offset:14160
	v_pk_fma_f32 v[172:173], v[120:121], v[48:49], v[172:173] op_sel_hi:[1,0,1] neg_lo:[1,0,0] neg_hi:[1,0,0]
	v_pk_fma_f32 v[172:173], v[122:123], v[48:49], v[172:173] op_sel:[0,1,0] op_sel_hi:[1,1,1] neg_lo:[1,0,0] neg_hi:[1,0,0]
	v_pk_fma_f32 v[172:173], v[124:125], v[50:51], v[172:173] op_sel_hi:[1,0,1] neg_lo:[1,0,0] neg_hi:[1,0,0]
	v_pk_fma_f32 v[172:173], v[126:127], v[50:51], v[172:173] op_sel:[0,1,0] op_sel_hi:[1,1,1] neg_lo:[1,0,0] neg_hi:[1,0,0]
	ds_read_b128 v[32:35], v228 offset:14176
	v_pk_fma_f32 v[172:173], v[128:129], v[52:53], v[172:173] op_sel_hi:[1,0,1] neg_lo:[1,0,0] neg_hi:[1,0,0]
	v_pk_fma_f32 v[172:173], v[130:131], v[52:53], v[172:173] op_sel:[0,1,0] op_sel_hi:[1,1,1] neg_lo:[1,0,0] neg_hi:[1,0,0]
	v_pk_fma_f32 v[172:173], v[132:133], v[54:55], v[172:173] op_sel_hi:[1,0,1] neg_lo:[1,0,0] neg_hi:[1,0,0]
	v_pk_fma_f32 v[172:173], v[134:135], v[54:55], v[172:173] op_sel:[0,1,0] op_sel_hi:[1,1,1] neg_lo:[1,0,0] neg_hi:[1,0,0]
	ds_read_b128 v[36:39], v228 offset:14192
	s_waitcnt lgkmcnt(9)
	v_pk_fma_f32 v[172:173], v[136:137], v[56:57], v[172:173] op_sel_hi:[1,0,1] neg_lo:[1,0,0] neg_hi:[1,0,0]
	v_pk_fma_f32 v[172:173], v[138:139], v[56:57], v[172:173] op_sel:[0,1,0] op_sel_hi:[1,1,1] neg_lo:[1,0,0] neg_hi:[1,0,0]
	v_pk_fma_f32 v[172:173], v[140:141], v[58:59], v[172:173] op_sel_hi:[1,0,1] neg_lo:[1,0,0] neg_hi:[1,0,0]
	v_pk_fma_f32 v[172:173], v[142:143], v[58:59], v[172:173] op_sel:[0,1,0] op_sel_hi:[1,1,1] neg_lo:[1,0,0] neg_hi:[1,0,0]
	ds_read_b128 v[40:43], v228 offset:14208
	v_pk_fma_f32 v[172:173], v[144:145], v[60:61], v[172:173] op_sel_hi:[1,0,1] neg_lo:[1,0,0] neg_hi:[1,0,0]
	v_pk_fma_f32 v[172:173], v[146:147], v[60:61], v[172:173] op_sel:[0,1,0] op_sel_hi:[1,1,1] neg_lo:[1,0,0] neg_hi:[1,0,0]
	v_pk_fma_f32 v[172:173], v[148:149], v[62:63], v[172:173] op_sel_hi:[1,0,1] neg_lo:[1,0,0] neg_hi:[1,0,0]
	v_pk_fma_f32 v[172:173], v[150:151], v[62:63], v[172:173] op_sel:[0,1,0] op_sel_hi:[1,1,1] neg_lo:[1,0,0] neg_hi:[1,0,0]
	ds_read_b128 v[44:47], v228 offset:14224
	v_pk_fma_f32 v[172:173], v[152:153], v[244:245], v[172:173] op_sel_hi:[1,0,1] neg_lo:[1,0,0] neg_hi:[1,0,0]
	v_pk_fma_f32 v[172:173], v[154:155], v[244:245], v[172:173] op_sel:[0,1,0] op_sel_hi:[1,1,1] neg_lo:[1,0,0] neg_hi:[1,0,0]
	v_pk_fma_f32 v[172:173], v[156:157], v[246:247], v[172:173] op_sel_hi:[1,0,1] neg_lo:[1,0,0] neg_hi:[1,0,0]
	v_pk_fma_f32 v[172:173], v[158:159], v[246:247], v[172:173] op_sel:[0,1,0] op_sel_hi:[1,1,1] neg_lo:[1,0,0] neg_hi:[1,0,0]
	ds_read_b128 v[48:51], v228 offset:14240
	v_pk_fma_f32 v[172:173], v[160:161], v[248:249], v[172:173] op_sel_hi:[1,0,1] neg_lo:[1,0,0] neg_hi:[1,0,0]
	v_pk_fma_f32 v[172:173], v[162:163], v[248:249], v[172:173] op_sel:[0,1,0] op_sel_hi:[1,1,1] neg_lo:[1,0,0] neg_hi:[1,0,0]
	v_pk_fma_f32 v[172:173], v[164:165], v[250:251], v[172:173] op_sel_hi:[1,0,1] neg_lo:[1,0,0] neg_hi:[1,0,0]
	v_pk_fma_f32 v[172:173], v[166:167], v[250:251], v[172:173] op_sel:[0,1,0] op_sel_hi:[1,1,1] neg_lo:[1,0,0] neg_hi:[1,0,0]
	ds_read_b128 v[52:55], v228 offset:14256
	s_waitcnt lgkmcnt(9)
	v_pk_fma_f32 v[172:173], v[168:169], v[4:5], v[172:173] op_sel_hi:[1,0,1] neg_lo:[1,0,0] neg_hi:[1,0,0]
	v_fma_mixlo_f16 v0, -v170, v5, v172
	v_fma_mixlo_f16 v2, -v171, v5, v173
	v_pk_fma_f32 v[172:173], v[170:171], v[4:5], v[172:173] op_sel:[0,1,0] op_sel_hi:[1,1,1] neg_lo:[1,0,0] neg_hi:[1,0,0]
	ds_write_b16 v253, v0 offset:31072
	ds_write_b16 v253, v2 offset:31200
	ds_read_b128 v[56:59], v228 offset:14272
	v_pk_fma_f32 v[174:175], v[64:65], v[8:9], v[174:175] op_sel_hi:[1,0,1] neg_lo:[1,0,0] neg_hi:[1,0,0]
	v_pk_fma_f32 v[174:175], v[66:67], v[8:9], v[174:175] op_sel:[0,1,0] op_sel_hi:[1,1,1] neg_lo:[1,0,0] neg_hi:[1,0,0]
	v_pk_fma_f32 v[174:175], v[68:69], v[10:11], v[174:175] op_sel_hi:[1,0,1] neg_lo:[1,0,0] neg_hi:[1,0,0]
	v_pk_fma_f32 v[174:175], v[70:71], v[10:11], v[174:175] op_sel:[0,1,0] op_sel_hi:[1,1,1] neg_lo:[1,0,0] neg_hi:[1,0,0]
	ds_read_b128 v[60:63], v228 offset:14288
	v_pk_fma_f32 v[174:175], v[72:73], v[12:13], v[174:175] op_sel_hi:[1,0,1] neg_lo:[1,0,0] neg_hi:[1,0,0]
	v_pk_fma_f32 v[174:175], v[74:75], v[12:13], v[174:175] op_sel:[0,1,0] op_sel_hi:[1,1,1] neg_lo:[1,0,0] neg_hi:[1,0,0]
	v_pk_fma_f32 v[174:175], v[76:77], v[14:15], v[174:175] op_sel_hi:[1,0,1] neg_lo:[1,0,0] neg_hi:[1,0,0]
	v_pk_fma_f32 v[174:175], v[78:79], v[14:15], v[174:175] op_sel:[0,1,0] op_sel_hi:[1,1,1] neg_lo:[1,0,0] neg_hi:[1,0,0]
	ds_read_b128 v[244:247], v228 offset:14336
	v_pk_fma_f32 v[174:175], v[80:81], v[16:17], v[174:175] op_sel_hi:[1,0,1] neg_lo:[1,0,0] neg_hi:[1,0,0]
	v_pk_fma_f32 v[174:175], v[82:83], v[16:17], v[174:175] op_sel:[0,1,0] op_sel_hi:[1,1,1] neg_lo:[1,0,0] neg_hi:[1,0,0]
	v_pk_fma_f32 v[174:175], v[84:85], v[18:19], v[174:175] op_sel_hi:[1,0,1] neg_lo:[1,0,0] neg_hi:[1,0,0]
	v_pk_fma_f32 v[174:175], v[86:87], v[18:19], v[174:175] op_sel:[0,1,0] op_sel_hi:[1,1,1] neg_lo:[1,0,0] neg_hi:[1,0,0]
	ds_read_b128 v[248:251], v228 offset:14352
	s_waitcnt lgkmcnt(11)
; #define LAS __attribute__((address_space(3)))
; __device__ __forceinline__ void phase_gdb(const int wvs, const Params& p, LAS unsigned char* lds, int nwg) {
;     ...
;     { float x[64]; const bool isw = t >= 64;
; #pragma unroll
;       for (int i = 0; i < 64; ++i) { const float v = (float)R[i * RP + t]; x[i] = v * bs[i] * (isw ? __expf(gcs[i]) : 1.0f); asm volatile("" : "+v"(x[i])); if ((i & 7) == 7) __builtin_amdgcn_sched_barrier(0); }
; #pragma unroll
;       for (int i = 1; i < 64; ++i) {
; #pragma unroll
;         for (int j4 = 0; j4 < (i + 3) / 4; ++j4) { const f32x4 m4 = *(const LAS f32x4*)(M + i * 64 + j4 * 4);
; #pragma unroll
;           for (int jj = 0; jj < 4; ++jj) if (j4 * 4 + jj < i) x[i] -= m4[jj] * x[j4 * 4 + jj]; }
;         __builtin_amdgcn_sched_barrier(0); }
; #pragma unroll
;       for (int i = 0; i < 64; ++i) R[i * RP + t] = (hf)x[i]; }
	v_pk_fma_f32 v[174:175], v[88:89], v[20:21], v[174:175] op_sel_hi:[1,0,1] neg_lo:[1,0,0] neg_hi:[1,0,0]
	v_pk_fma_f32 v[174:175], v[90:91], v[20:21], v[174:175] op_sel:[0,1,0] op_sel_hi:[1,1,1] neg_lo:[1,0,0] neg_hi:[1,0,0]
	v_pk_fma_f32 v[174:175], v[92:93], v[22:23], v[174:175] op_sel_hi:[1,0,1] neg_lo:[1,0,0] neg_hi:[1,0,0]
	v_pk_fma_f32 v[174:175], v[94:95], v[22:23], v[174:175] op_sel:[0,1,0] op_sel_hi:[1,1,1] neg_lo:[1,0,0] neg_hi:[1,0,0]
	ds_read_b128 v[4:7], v228 offset:14368
	v_pk_fma_f32 v[174:175], v[96:97], v[24:25], v[174:175] op_sel_hi:[1,0,1] neg_lo:[1,0,0] neg_hi:[1,0,0]
	v_pk_fma_f32 v[174:175], v[98:99], v[24:25], v[174:175] op_sel:[0,1,0] op_sel_hi:[1,1,1] neg_lo:[1,0,0] neg_hi:[1,0,0]
	v_pk_fma_f32 v[174:175], v[100:101], v[26:27], v[174:175] op_sel_hi:[1,0,1] neg_lo:[1,0,0] neg_hi:[1,0,0]
	v_pk_fma_f32 v[174:175], v[102:103], v[26:27], v[174:175] op_sel:[0,1,0] op_sel_hi:[1,1,1] neg_lo:[1,0,0] neg_hi:[1,0,0]
	ds_read_b128 v[8:11], v228 offset:14384
	v_pk_fma_f32 v[174:175], v[104:105], v[28:29], v[174:175] op_sel_hi:[1,0,1] neg_lo:[1,0,0] neg_hi:[1,0,0]
	v_pk_fma_f32 v[174:175], v[106:107], v[28:29], v[174:175] op_sel:[0,1,0] op_sel_hi:[1,1,1] neg_lo:[1,0,0] neg_hi:[1,0,0]
	v_pk_fma_f32 v[174:175], v[108:109], v[30:31], v[174:175] op_sel_hi:[1,0,1] neg_lo:[1,0,0] neg_hi:[1,0,0]
	v_pk_fma_f32 v[174:175], v[110:111], v[30:31], v[174:175] op_sel:[0,1,0] op_sel_hi:[1,1,1] neg_lo:[1,0,0] neg_hi:[1,0,0]
	ds_read_b128 v[12:15], v228 offset:14400
	v_pk_fma_f32 v[174:175], v[112:113], v[32:33], v[174:175] op_sel_hi:[1,0,1] neg_lo:[1,0,0] neg_hi:[1,0,0]
	v_pk_fma_f32 v[174:175], v[114:115], v[32:33], v[174:175] op_sel:[0,1,0] op_sel_hi:[1,1,1] neg_lo:[1,0,0] neg_hi:[1,0,0]
	v_pk_fma_f32 v[174:175], v[116:117], v[34:35], v[174:175] op_sel_hi:[1,0,1] neg_lo:[1,0,0] neg_hi:[1,0,0]
	v_pk_fma_f32 v[174:175], v[118:119], v[34:35], v[174:175] op_sel:[0,1,0] op_sel_hi:[1,1,1] neg_lo:[1,0,0] neg_hi:[1,0,0]
	ds_read_b128 v[16:19], v228 offset:14416
	s_waitcnt lgkmcnt(11)
	v_pk_fma_f32 v[174:175], v[120:121], v[36:37], v[174:175] op_sel_hi:[1,0,1] neg_lo:[1,0,0] neg_hi:[1,0,0]
	v_pk_fma_f32 v[174:175], v[122:123], v[36:37], v[174:175] op_sel:[0,1,0] op_sel_hi:[1,1,1] neg_lo:[1,0,0] neg_hi:[1,0,0]
	v_pk_fma_f32 v[174:175], v[124:125], v[38:39], v[174:175] op_sel_hi:[1,0,1] neg_lo:[1,0,0] neg_hi:[1,0,0]
	v_pk_fma_f32 v[174:175], v[126:127], v[38:39], v[174:175] op_sel:[0,1,0] op_sel_hi:[1,1,1] neg_lo:[1,0,0] neg_hi:[1,0,0]
	ds_read_b128 v[20:23], v228 offset:14432
	v_pk_fma_f32 v[174:175], v[128:129], v[40:41], v[174:175] op_sel_hi:[1,0,1] neg_lo:[1,0,0] neg_hi:[1,0,0]
	v_pk_fma_f32 v[174:175], v[130:131], v[40:41], v[174:175] op_sel:[0,1,0] op_sel_hi:[1,1,1] neg_lo:[1,0,0] neg_hi:[1,0,0]
	v_pk_fma_f32 v[174:175], v[132:133], v[42:43], v[174:175] op_sel_hi:[1,0,1] neg_lo:[1,0,0] neg_hi:[1,0,0]
	v_pk_fma_f32 v[174:175], v[134:135], v[42:43], v[174:175] op_sel:[0,1,0] op_sel_hi:[1,1,1] neg_lo:[1,0,0] neg_hi:[1,0,0]
	ds_read_b128 v[24:27], v228 offset:14448
	v_pk_fma_f32 v[174:175], v[136:137], v[44:45], v[174:175] op_sel_hi:[1,0,1] neg_lo:[1,0,0] neg_hi:[1,0,0]
	v_pk_fma_f32 v[174:175], v[138:139], v[44:45], v[174:175] op_sel:[0,1,0] op_sel_hi:[1,1,1] neg_lo:[1,0,0] neg_hi:[1,0,0]
	v_pk_fma_f32 v[174:175], v[140:141], v[46:47], v[174:175] op_sel_hi:[1,0,1] neg_lo:[1,0,0] neg_hi:[1,0,0]
	v_pk_fma_f32 v[174:175], v[142:143], v[46:47], v[174:175] op_sel:[0,1,0] op_sel_hi:[1,1,1] neg_lo:[1,0,0] neg_hi:[1,0,0]
	ds_read_b128 v[28:31], v228 offset:14464
	v_pk_fma_f32 v[174:175], v[144:145], v[48:49], v[174:175] op_sel_hi:[1,0,1] neg_lo:[1,0,0] neg_hi:[1,0,0]
	v_pk_fma_f32 v[174:175], v[146:147], v[48:49], v[174:175] op_sel:[0,1,0] op_sel_hi:[1,1,1] neg_lo:[1,0,0] neg_hi:[1,0,0]
	v_pk_fma_f32 v[174:175], v[148:149], v[50:51], v[174:175] op_sel_hi:[1,0,1] neg_lo:[1,0,0] neg_hi:[1,0,0]
	v_pk_fma_f32 v[174:175], v[150:151], v[50:51], v[174:175] op_sel:[0,1,0] op_sel_hi:[1,1,1] neg_lo:[1,0,0] neg_hi:[1,0,0]
	ds_read_b128 v[32:35], v228 offset:14480
	s_waitcnt lgkmcnt(9)
	v_pk_fma_f32 v[174:175], v[152:153], v[52:53], v[174:175] op_sel_hi:[1,0,1] neg_lo:[1,0,0] neg_hi:[1,0,0]
	v_pk_fma_f32 v[174:175], v[154:155], v[52:53], v[174:175] op_sel:[0,1,0] op_sel_hi:[1,1,1] neg_lo:[1,0,0] neg_hi:[1,0,0]
	v_pk_fma_f32 v[174:175], v[156:157], v[54:55], v[174:175] op_sel_hi:[1,0,1] neg_lo:[1,0,0] neg_hi:[1,0,0]
	v_pk_fma_f32 v[174:175], v[158:159], v[54:55], v[174:175] op_sel:[0,1,0] op_sel_hi:[1,1,1] neg_lo:[1,0,0] neg_hi:[1,0,0]
	ds_read_b128 v[36:39], v228 offset:14496
	v_pk_fma_f32 v[174:175], v[160:161], v[56:57], v[174:175] op_sel_hi:[1,0,1] neg_lo:[1,0,0] neg_hi:[1,0,0]
	v_pk_fma_f32 v[174:175], v[162:163], v[56:57], v[174:175] op_sel:[0,1,0] op_sel_hi:[1,1,1] neg_lo:[1,0,0] neg_hi:[1,0,0]
	v_pk_fma_f32 v[174:175], v[164:165], v[58:59], v[174:175] op_sel_hi:[1,0,1] neg_lo:[1,0,0] neg_hi:[1,0,0]
	v_pk_fma_f32 v[174:175], v[166:167], v[58:59], v[174:175] op_sel:[0,1,0] op_sel_hi:[1,1,1] neg_lo:[1,0,0] neg_hi:[1,0,0]
	ds_read_b128 v[40:43], v228 offset:14512
	v_pk_fma_f32 v[174:175], v[168:169], v[60:61], v[174:175] op_sel_hi:[1,0,1] neg_lo:[1,0,0] neg_hi:[1,0,0]
	v_pk_fma_f32 v[174:175], v[170:171], v[60:61], v[174:175] op_sel:[0,1,0] op_sel_hi:[1,1,1] neg_lo:[1,0,0] neg_hi:[1,0,0]
	v_fma_mixlo_f16 v3, -v172, v62, v174
	v_fma_mixlo_f16 v238, -v173, v62, v175
	v_pk_fma_f32 v[174:175], v[172:173], v[62:63], v[174:175] op_sel_hi:[1,0,1] neg_lo:[1,0,0] neg_hi:[1,0,0]
	ds_write_b16 v253, v3 offset:31344
	ds_write_b16 v253, v238 offset:31472
	ds_read_b128 v[44:47], v228 offset:14528
	v_pk_fma_f32 v[176:177], v[64:65], v[244:245], v[176:177] op_sel_hi:[1,0,1] neg_lo:[1,0,0] neg_hi:[1,0,0]
	v_pk_fma_f32 v[176:177], v[66:67], v[244:245], v[176:177] op_sel:[0,1,0] op_sel_hi:[1,1,1] neg_lo:[1,0,0] neg_hi:[1,0,0]
	v_pk_fma_f32 v[176:177], v[68:69], v[246:247], v[176:177] op_sel_hi:[1,0,1] neg_lo:[1,0,0] neg_hi:[1,0,0]
	v_pk_fma_f32 v[176:177], v[70:71], v[246:247], v[176:177] op_sel:[0,1,0] op_sel_hi:[1,1,1] neg_lo:[1,0,0] neg_hi:[1,0,0]
	ds_read_b128 v[48:51], v228 offset:14544
	s_waitcnt lgkmcnt(11)
; #define LAS __attribute__((address_space(3)))
; __device__ __forceinline__ void phase_gdb(const int wvs, const Params& p, LAS unsigned char* lds, int nwg) {
;     ...
;     { float x[64]; const bool isw = t >= 64;
; #pragma unroll
;       for (int i = 0; i < 64; ++i) { const float v = (float)R[i * RP + t]; x[i] = v * bs[i] * (isw ? __expf(gcs[i]) : 1.0f); asm volatile("" : "+v"(x[i])); if ((i & 7) == 7) __builtin_amdgcn_sched_barrier(0); }
; #pragma unroll
;       for (int i = 1; i < 64; ++i) {
; #pragma unroll
;         for (int j4 = 0; j4 < (i + 3) / 4; ++j4) { const f32x4 m4 = *(const LAS f32x4*)(M + i * 64 + j4 * 4);
; #pragma unroll
;           for (int jj = 0; jj < 4; ++jj) if (j4 * 4 + jj < i) x[i] -= m4[jj] * x[j4 * 4 + jj]; }
;         __builtin_amdgcn_sched_barrier(0); }
; #pragma unroll
;       for (int i = 0; i < 64; ++i) R[i * RP + t] = (hf)x[i]; }
	v_pk_fma_f32 v[176:177], v[72:73], v[248:249], v[176:177] op_sel_hi:[1,0,1] neg_lo:[1,0,0] neg_hi:[1,0,0]
	v_pk_fma_f32 v[176:177], v[74:75], v[248:249], v[176:177] op_sel:[0,1,0] op_sel_hi:[1,1,1] neg_lo:[1,0,0] neg_hi:[1,0,0]
	v_pk_fma_f32 v[176:177], v[76:77], v[250:251], v[176:177] op_sel_hi:[1,0,1] neg_lo:[1,0,0] neg_hi:[1,0,0]
	v_pk_fma_f32 v[176:177], v[78:79], v[250:251], v[176:177] op_sel:[0,1,0] op_sel_hi:[1,1,1] neg_lo:[1,0,0] neg_hi:[1,0,0]
	ds_read_b128 v[52:55], v228 offset:14592
	v_pk_fma_f32 v[176:177], v[80:81], v[4:5], v[176:177] op_sel_hi:[1,0,1] neg_lo:[1,0,0] neg_hi:[1,0,0]
	v_pk_fma_f32 v[176:177], v[82:83], v[4:5], v[176:177] op_sel:[0,1,0] op_sel_hi:[1,1,1] neg_lo:[1,0,0] neg_hi:[1,0,0]
	v_pk_fma_f32 v[176:177], v[84:85], v[6:7], v[176:177] op_sel_hi:[1,0,1] neg_lo:[1,0,0] neg_hi:[1,0,0]
	v_pk_fma_f32 v[176:177], v[86:87], v[6:7], v[176:177] op_sel:[0,1,0] op_sel_hi:[1,1,1] neg_lo:[1,0,0] neg_hi:[1,0,0]
	ds_read_b128 v[56:59], v228 offset:14608
	v_pk_fma_f32 v[176:177], v[88:89], v[8:9], v[176:177] op_sel_hi:[1,0,1] neg_lo:[1,0,0] neg_hi:[1,0,0]
	v_pk_fma_f32 v[176:177], v[90:91], v[8:9], v[176:177] op_sel:[0,1,0] op_sel_hi:[1,1,1] neg_lo:[1,0,0] neg_hi:[1,0,0]
	v_pk_fma_f32 v[176:177], v[92:93], v[10:11], v[176:177] op_sel_hi:[1,0,1] neg_lo:[1,0,0] neg_hi:[1,0,0]
	v_pk_fma_f32 v[176:177], v[94:95], v[10:11], v[176:177] op_sel:[0,1,0] op_sel_hi:[1,1,1] neg_lo:[1,0,0] neg_hi:[1,0,0]
	ds_read_b128 v[60:63], v228 offset:14624
	v_pk_fma_f32 v[176:177], v[96:97], v[12:13], v[176:177] op_sel_hi:[1,0,1] neg_lo:[1,0,0] neg_hi:[1,0,0]
	v_pk_fma_f32 v[176:177], v[98:99], v[12:13], v[176:177] op_sel:[0,1,0] op_sel_hi:[1,1,1] neg_lo:[1,0,0] neg_hi:[1,0,0]
	v_pk_fma_f32 v[176:177], v[100:101], v[14:15], v[176:177] op_sel_hi:[1,0,1] neg_lo:[1,0,0] neg_hi:[1,0,0]
	v_pk_fma_f32 v[176:177], v[102:103], v[14:15], v[176:177] op_sel:[0,1,0] op_sel_hi:[1,1,1] neg_lo:[1,0,0] neg_hi:[1,0,0]
	ds_read_b128 v[244:247], v228 offset:14640
	s_waitcnt lgkmcnt(11)
	v_pk_fma_f32 v[176:177], v[104:105], v[16:17], v[176:177] op_sel_hi:[1,0,1] neg_lo:[1,0,0] neg_hi:[1,0,0]
	v_pk_fma_f32 v[176:177], v[106:107], v[16:17], v[176:177] op_sel:[0,1,0] op_sel_hi:[1,1,1] neg_lo:[1,0,0] neg_hi:[1,0,0]
	v_pk_fma_f32 v[176:177], v[108:109], v[18:19], v[176:177] op_sel_hi:[1,0,1] neg_lo:[1,0,0] neg_hi:[1,0,0]
	v_pk_fma_f32 v[176:177], v[110:111], v[18:19], v[176:177] op_sel:[0,1,0] op_sel_hi:[1,1,1] neg_lo:[1,0,0] neg_hi:[1,0,0]
	ds_read_b128 v[248:251], v228 offset:14656
	v_pk_fma_f32 v[176:177], v[112:113], v[20:21], v[176:177] op_sel_hi:[1,0,1] neg_lo:[1,0,0] neg_hi:[1,0,0]
	v_pk_fma_f32 v[176:177], v[114:115], v[20:21], v[176:177] op_sel:[0,1,0] op_sel_hi:[1,1,1] neg_lo:[1,0,0] neg_hi:[1,0,0]
	v_pk_fma_f32 v[176:177], v[116:117], v[22:23], v[176:177] op_sel_hi:[1,0,1] neg_lo:[1,0,0] neg_hi:[1,0,0]
	v_pk_fma_f32 v[176:177], v[118:119], v[22:23], v[176:177] op_sel:[0,1,0] op_sel_hi:[1,1,1] neg_lo:[1,0,0] neg_hi:[1,0,0]
	ds_read_b128 v[4:7], v228 offset:14672
	v_pk_fma_f32 v[176:177], v[120:121], v[24:25], v[176:177] op_sel_hi:[1,0,1] neg_lo:[1,0,0] neg_hi:[1,0,0]
	v_pk_fma_f32 v[176:177], v[122:123], v[24:25], v[176:177] op_sel:[0,1,0] op_sel_hi:[1,1,1] neg_lo:[1,0,0] neg_hi:[1,0,0]
	v_pk_fma_f32 v[176:177], v[124:125], v[26:27], v[176:177] op_sel_hi:[1,0,1] neg_lo:[1,0,0] neg_hi:[1,0,0]
	v_pk_fma_f32 v[176:177], v[126:127], v[26:27], v[176:177] op_sel:[0,1,0] op_sel_hi:[1,1,1] neg_lo:[1,0,0] neg_hi:[1,0,0]
	ds_read_b128 v[8:11], v228 offset:14688
	v_pk_fma_f32 v[176:177], v[128:129], v[28:29], v[176:177] op_sel_hi:[1,0,1] neg_lo:[1,0,0] neg_hi:[1,0,0]
	v_pk_fma_f32 v[176:177], v[130:131], v[28:29], v[176:177] op_sel:[0,1,0] op_sel_hi:[1,1,1] neg_lo:[1,0,0] neg_hi:[1,0,0]
	v_pk_fma_f32 v[176:177], v[132:133], v[30:31], v[176:177] op_sel_hi:[1,0,1] neg_lo:[1,0,0] neg_hi:[1,0,0]
	v_pk_fma_f32 v[176:177], v[134:135], v[30:31], v[176:177] op_sel:[0,1,0] op_sel_hi:[1,1,1] neg_lo:[1,0,0] neg_hi:[1,0,0]
	ds_read_b128 v[12:15], v228 offset:14704
	s_waitcnt lgkmcnt(9)
	v_pk_fma_f32 v[176:177], v[136:137], v[32:33], v[176:177] op_sel_hi:[1,0,1] neg_lo:[1,0,0] neg_hi:[1,0,0]
	v_pk_fma_f32 v[176:177], v[138:139], v[32:33], v[176:177] op_sel:[0,1,0] op_sel_hi:[1,1,1] neg_lo:[1,0,0] neg_hi:[1,0,0]
	v_pk_fma_f32 v[176:177], v[140:141], v[34:35], v[176:177] op_sel_hi:[1,0,1] neg_lo:[1,0,0] neg_hi:[1,0,0]
	v_pk_fma_f32 v[176:177], v[142:143], v[34:35], v[176:177] op_sel:[0,1,0] op_sel_hi:[1,1,1] neg_lo:[1,0,0] neg_hi:[1,0,0]
	ds_read_b128 v[16:19], v228 offset:14720
	v_pk_fma_f32 v[176:177], v[144:145], v[36:37], v[176:177] op_sel_hi:[1,0,1] neg_lo:[1,0,0] neg_hi:[1,0,0]
	v_pk_fma_f32 v[176:177], v[146:147], v[36:37], v[176:177] op_sel:[0,1,0] op_sel_hi:[1,1,1] neg_lo:[1,0,0] neg_hi:[1,0,0]
	v_pk_fma_f32 v[176:177], v[148:149], v[38:39], v[176:177] op_sel_hi:[1,0,1] neg_lo:[1,0,0] neg_hi:[1,0,0]
	v_pk_fma_f32 v[176:177], v[150:151], v[38:39], v[176:177] op_sel:[0,1,0] op_sel_hi:[1,1,1] neg_lo:[1,0,0] neg_hi:[1,0,0]
	ds_read_b128 v[20:23], v228 offset:14736
	v_pk_fma_f32 v[176:177], v[152:153], v[40:41], v[176:177] op_sel_hi:[1,0,1] neg_lo:[1,0,0] neg_hi:[1,0,0]
	v_pk_fma_f32 v[176:177], v[154:155], v[40:41], v[176:177] op_sel:[0,1,0] op_sel_hi:[1,1,1] neg_lo:[1,0,0] neg_hi:[1,0,0]
	v_pk_fma_f32 v[176:177], v[156:157], v[42:43], v[176:177] op_sel_hi:[1,0,1] neg_lo:[1,0,0] neg_hi:[1,0,0]
	v_pk_fma_f32 v[176:177], v[158:159], v[42:43], v[176:177] op_sel:[0,1,0] op_sel_hi:[1,1,1] neg_lo:[1,0,0] neg_hi:[1,0,0]
	ds_read_b128 v[24:27], v228 offset:14752
	v_pk_fma_f32 v[176:177], v[160:161], v[44:45], v[176:177] op_sel_hi:[1,0,1] neg_lo:[1,0,0] neg_hi:[1,0,0]
	v_pk_fma_f32 v[176:177], v[162:163], v[44:45], v[176:177] op_sel:[0,1,0] op_sel_hi:[1,1,1] neg_lo:[1,0,0] neg_hi:[1,0,0]
	v_pk_fma_f32 v[176:177], v[164:165], v[46:47], v[176:177] op_sel_hi:[1,0,1] neg_lo:[1,0,0] neg_hi:[1,0,0]
	v_pk_fma_f32 v[176:177], v[166:167], v[46:47], v[176:177] op_sel:[0,1,0] op_sel_hi:[1,1,1] neg_lo:[1,0,0] neg_hi:[1,0,0]
	ds_read_b128 v[28:31], v228 offset:14768
	s_waitcnt lgkmcnt(9)
; #define LAS __attribute__((address_space(3)))
; __device__ __forceinline__ void phase_gdb(const int wvs, const Params& p, LAS unsigned char* lds, int nwg) {
;     ...
;     { float x[64]; const bool isw = t >= 64;
; #pragma unroll
;       for (int i = 0; i < 64; ++i) { const float v = (float)R[i * RP + t]; x[i] = v * bs[i] * (isw ? __expf(gcs[i]) : 1.0f); asm volatile("" : "+v"(x[i])); if ((i & 7) == 7) __builtin_amdgcn_sched_barrier(0); }
; #pragma unroll
;       for (int i = 1; i < 64; ++i) {
; #pragma unroll
;         for (int j4 = 0; j4 < (i + 3) / 4; ++j4) { const f32x4 m4 = *(const LAS f32x4*)(M + i * 64 + j4 * 4);
; #pragma unroll
;           for (int jj = 0; jj < 4; ++jj) if (j4 * 4 + jj < i) x[i] -= m4[jj] * x[j4 * 4 + jj]; }
;         __builtin_amdgcn_sched_barrier(0); }
; #pragma unroll
;       for (int i = 0; i < 64; ++i) R[i * RP + t] = (hf)x[i]; }
	v_pk_fma_f32 v[176:177], v[168:169], v[48:49], v[176:177] op_sel_hi:[1,0,1] neg_lo:[1,0,0] neg_hi:[1,0,0]
	v_pk_fma_f32 v[176:177], v[170:171], v[48:49], v[176:177] op_sel:[0,1,0] op_sel_hi:[1,1,1] neg_lo:[1,0,0] neg_hi:[1,0,0]
	v_pk_fma_f32 v[176:177], v[172:173], v[50:51], v[176:177] op_sel_hi:[1,0,1] neg_lo:[1,0,0] neg_hi:[1,0,0]
	v_fma_mixlo_f16 v239, -v174, v51, v176
	v_fma_mixlo_f16 v240, -v175, v51, v177
	v_pk_fma_f32 v[176:177], v[174:175], v[50:51], v[176:177] op_sel:[0,1,0] op_sel_hi:[1,1,1] neg_lo:[1,0,0] neg_hi:[1,0,0]
	ds_write_b16 v253, v239 offset:31616
	ds_write_b16 v253, v240 offset:31744
	ds_read_b128 v[32:35], v228 offset:14784
	v_pk_fma_f32 v[178:179], v[64:65], v[52:53], v[178:179] op_sel_hi:[1,0,1] neg_lo:[1,0,0] neg_hi:[1,0,0]
	v_pk_fma_f32 v[178:179], v[66:67], v[52:53], v[178:179] op_sel:[0,1,0] op_sel_hi:[1,1,1] neg_lo:[1,0,0] neg_hi:[1,0,0]
	v_pk_fma_f32 v[178:179], v[68:69], v[54:55], v[178:179] op_sel_hi:[1,0,1] neg_lo:[1,0,0] neg_hi:[1,0,0]
	v_pk_fma_f32 v[178:179], v[70:71], v[54:55], v[178:179] op_sel:[0,1,0] op_sel_hi:[1,1,1] neg_lo:[1,0,0] neg_hi:[1,0,0]
	ds_read_b128 v[36:39], v228 offset:14800
	v_pk_fma_f32 v[178:179], v[72:73], v[56:57], v[178:179] op_sel_hi:[1,0,1] neg_lo:[1,0,0] neg_hi:[1,0,0]
	v_pk_fma_f32 v[178:179], v[74:75], v[56:57], v[178:179] op_sel:[0,1,0] op_sel_hi:[1,1,1] neg_lo:[1,0,0] neg_hi:[1,0,0]
	v_pk_fma_f32 v[178:179], v[76:77], v[58:59], v[178:179] op_sel_hi:[1,0,1] neg_lo:[1,0,0] neg_hi:[1,0,0]
	v_pk_fma_f32 v[178:179], v[78:79], v[58:59], v[178:179] op_sel:[0,1,0] op_sel_hi:[1,1,1] neg_lo:[1,0,0] neg_hi:[1,0,0]
	ds_read_b128 v[40:43], v228 offset:14816
	v_pk_fma_f32 v[178:179], v[80:81], v[60:61], v[178:179] op_sel_hi:[1,0,1] neg_lo:[1,0,0] neg_hi:[1,0,0]
	v_pk_fma_f32 v[178:179], v[82:83], v[60:61], v[178:179] op_sel:[0,1,0] op_sel_hi:[1,1,1] neg_lo:[1,0,0] neg_hi:[1,0,0]
	v_pk_fma_f32 v[178:179], v[84:85], v[62:63], v[178:179] op_sel_hi:[1,0,1] neg_lo:[1,0,0] neg_hi:[1,0,0]
	v_pk_fma_f32 v[178:179], v[86:87], v[62:63], v[178:179] op_sel:[0,1,0] op_sel_hi:[1,1,1] neg_lo:[1,0,0] neg_hi:[1,0,0]
	ds_read_b128 v[44:47], v228 offset:14848
	s_waitcnt lgkmcnt(11)
	v_pk_fma_f32 v[178:179], v[88:89], v[244:245], v[178:179] op_sel_hi:[1,0,1] neg_lo:[1,0,0] neg_hi:[1,0,0]
	v_pk_fma_f32 v[178:179], v[90:91], v[244:245], v[178:179] op_sel:[0,1,0] op_sel_hi:[1,1,1] neg_lo:[1,0,0] neg_hi:[1,0,0]
	v_pk_fma_f32 v[178:179], v[92:93], v[246:247], v[178:179] op_sel_hi:[1,0,1] neg_lo:[1,0,0] neg_hi:[1,0,0]
	v_pk_fma_f32 v[178:179], v[94:95], v[246:247], v[178:179] op_sel:[0,1,0] op_sel_hi:[1,1,1] neg_lo:[1,0,0] neg_hi:[1,0,0]
	ds_read_b128 v[48:51], v228 offset:14864
	v_pk_fma_f32 v[178:179], v[96:97], v[248:249], v[178:179] op_sel_hi:[1,0,1] neg_lo:[1,0,0] neg_hi:[1,0,0]
	v_pk_fma_f32 v[178:179], v[98:99], v[248:249], v[178:179] op_sel:[0,1,0] op_sel_hi:[1,1,1] neg_lo:[1,0,0] neg_hi:[1,0,0]
	v_pk_fma_f32 v[178:179], v[100:101], v[250:251], v[178:179] op_sel_hi:[1,0,1] neg_lo:[1,0,0] neg_hi:[1,0,0]
	v_pk_fma_f32 v[178:179], v[102:103], v[250:251], v[178:179] op_sel:[0,1,0] op_sel_hi:[1,1,1] neg_lo:[1,0,0] neg_hi:[1,0,0]
	ds_read_b128 v[52:55], v228 offset:14880
	v_pk_fma_f32 v[178:179], v[104:105], v[4:5], v[178:179] op_sel_hi:[1,0,1] neg_lo:[1,0,0] neg_hi:[1,0,0]
	v_pk_fma_f32 v[178:179], v[106:107], v[4:5], v[178:179] op_sel:[0,1,0] op_sel_hi:[1,1,1] neg_lo:[1,0,0] neg_hi:[1,0,0]
	v_pk_fma_f32 v[178:179], v[108:109], v[6:7], v[178:179] op_sel_hi:[1,0,1] neg_lo:[1,0,0] neg_hi:[1,0,0]
	v_pk_fma_f32 v[178:179], v[110:111], v[6:7], v[178:179] op_sel:[0,1,0] op_sel_hi:[1,1,1] neg_lo:[1,0,0] neg_hi:[1,0,0]
	ds_read_b128 v[56:59], v228 offset:14896
	v_pk_fma_f32 v[178:179], v[112:113], v[8:9], v[178:179] op_sel_hi:[1,0,1] neg_lo:[1,0,0] neg_hi:[1,0,0]
	v_pk_fma_f32 v[178:179], v[114:115], v[8:9], v[178:179] op_sel:[0,1,0] op_sel_hi:[1,1,1] neg_lo:[1,0,0] neg_hi:[1,0,0]
	v_pk_fma_f32 v[178:179], v[116:117], v[10:11], v[178:179] op_sel_hi:[1,0,1] neg_lo:[1,0,0] neg_hi:[1,0,0]
	v_pk_fma_f32 v[178:179], v[118:119], v[10:11], v[178:179] op_sel:[0,1,0] op_sel_hi:[1,1,1] neg_lo:[1,0,0] neg_hi:[1,0,0]
	ds_read_b128 v[60:63], v228 offset:14912
	s_waitcnt lgkmcnt(11)
	v_pk_fma_f32 v[178:179], v[120:121], v[12:13], v[178:179] op_sel_hi:[1,0,1] neg_lo:[1,0,0] neg_hi:[1,0,0]
	v_pk_fma_f32 v[178:179], v[122:123], v[12:13], v[178:179] op_sel:[0,1,0] op_sel_hi:[1,1,1] neg_lo:[1,0,0] neg_hi:[1,0,0]
	v_pk_fma_f32 v[178:179], v[124:125], v[14:15], v[178:179] op_sel_hi:[1,0,1] neg_lo:[1,0,0] neg_hi:[1,0,0]
	v_pk_fma_f32 v[178:179], v[126:127], v[14:15], v[178:179] op_sel:[0,1,0] op_sel_hi:[1,1,1] neg_lo:[1,0,0] neg_hi:[1,0,0]
	ds_read_b128 v[244:247], v228 offset:14928
	v_pk_fma_f32 v[178:179], v[128:129], v[16:17], v[178:179] op_sel_hi:[1,0,1] neg_lo:[1,0,0] neg_hi:[1,0,0]
	v_pk_fma_f32 v[178:179], v[130:131], v[16:17], v[178:179] op_sel:[0,1,0] op_sel_hi:[1,1,1] neg_lo:[1,0,0] neg_hi:[1,0,0]
	v_pk_fma_f32 v[178:179], v[132:133], v[18:19], v[178:179] op_sel_hi:[1,0,1] neg_lo:[1,0,0] neg_hi:[1,0,0]
	v_pk_fma_f32 v[178:179], v[134:135], v[18:19], v[178:179] op_sel:[0,1,0] op_sel_hi:[1,1,1] neg_lo:[1,0,0] neg_hi:[1,0,0]
	ds_read_b128 v[248:251], v228 offset:14944
	v_pk_fma_f32 v[178:179], v[136:137], v[20:21], v[178:179] op_sel_hi:[1,0,1] neg_lo:[1,0,0] neg_hi:[1,0,0]
	v_pk_fma_f32 v[178:179], v[138:139], v[20:21], v[178:179] op_sel:[0,1,0] op_sel_hi:[1,1,1] neg_lo:[1,0,0] neg_hi:[1,0,0]
	v_pk_fma_f32 v[178:179], v[140:141], v[22:23], v[178:179] op_sel_hi:[1,0,1] neg_lo:[1,0,0] neg_hi:[1,0,0]
	v_pk_fma_f32 v[178:179], v[142:143], v[22:23], v[178:179] op_sel:[0,1,0] op_sel_hi:[1,1,1] neg_lo:[1,0,0] neg_hi:[1,0,0]
	ds_read_b128 v[4:7], v228 offset:14960
	v_pk_fma_f32 v[178:179], v[144:145], v[24:25], v[178:179] op_sel_hi:[1,0,1] neg_lo:[1,0,0] neg_hi:[1,0,0]
	v_pk_fma_f32 v[178:179], v[146:147], v[24:25], v[178:179] op_sel:[0,1,0] op_sel_hi:[1,1,1] neg_lo:[1,0,0] neg_hi:[1,0,0]
	v_pk_fma_f32 v[178:179], v[148:149], v[26:27], v[178:179] op_sel_hi:[1,0,1] neg_lo:[1,0,0] neg_hi:[1,0,0]
	v_pk_fma_f32 v[178:179], v[150:151], v[26:27], v[178:179] op_sel:[0,1,0] op_sel_hi:[1,1,1] neg_lo:[1,0,0] neg_hi:[1,0,0]
	ds_read_b128 v[8:11], v228 offset:14976
	s_waitcnt lgkmcnt(9)
; #define LAS __attribute__((address_space(3)))
; __device__ __forceinline__ void phase_gdb(const int wvs, const Params& p, LAS unsigned char* lds, int nwg) {
;     ...
;     { float x[64]; const bool isw = t >= 64;
; #pragma unroll
;       for (int i = 0; i < 64; ++i) { const float v = (float)R[i * RP + t]; x[i] = v * bs[i] * (isw ? __expf(gcs[i]) : 1.0f); asm volatile("" : "+v"(x[i])); if ((i & 7) == 7) __builtin_amdgcn_sched_barrier(0); }
; #pragma unroll
;       for (int i = 1; i < 64; ++i) {
; #pragma unroll
;         for (int j4 = 0; j4 < (i + 3) / 4; ++j4) { const f32x4 m4 = *(const LAS f32x4*)(M + i * 64 + j4 * 4);
; #pragma unroll
;           for (int jj = 0; jj < 4; ++jj) if (j4 * 4 + jj < i) x[i] -= m4[jj] * x[j4 * 4 + jj]; }
;         __builtin_amdgcn_sched_barrier(0); }
; #pragma unroll
;       for (int i = 0; i < 64; ++i) R[i * RP + t] = (hf)x[i]; }
	v_pk_fma_f32 v[178:179], v[152:153], v[28:29], v[178:179] op_sel_hi:[1,0,1] neg_lo:[1,0,0] neg_hi:[1,0,0]
	v_pk_fma_f32 v[178:179], v[154:155], v[28:29], v[178:179] op_sel:[0,1,0] op_sel_hi:[1,1,1] neg_lo:[1,0,0] neg_hi:[1,0,0]
	v_pk_fma_f32 v[178:179], v[156:157], v[30:31], v[178:179] op_sel_hi:[1,0,1] neg_lo:[1,0,0] neg_hi:[1,0,0]
	v_pk_fma_f32 v[178:179], v[158:159], v[30:31], v[178:179] op_sel:[0,1,0] op_sel_hi:[1,1,1] neg_lo:[1,0,0] neg_hi:[1,0,0]
	ds_read_b128 v[12:15], v228 offset:14992
	v_pk_fma_f32 v[178:179], v[160:161], v[32:33], v[178:179] op_sel_hi:[1,0,1] neg_lo:[1,0,0] neg_hi:[1,0,0]
	v_pk_fma_f32 v[178:179], v[162:163], v[32:33], v[178:179] op_sel:[0,1,0] op_sel_hi:[1,1,1] neg_lo:[1,0,0] neg_hi:[1,0,0]
	v_pk_fma_f32 v[178:179], v[164:165], v[34:35], v[178:179] op_sel_hi:[1,0,1] neg_lo:[1,0,0] neg_hi:[1,0,0]
	v_pk_fma_f32 v[178:179], v[166:167], v[34:35], v[178:179] op_sel:[0,1,0] op_sel_hi:[1,1,1] neg_lo:[1,0,0] neg_hi:[1,0,0]
	ds_read_b128 v[16:19], v228 offset:15008
	v_pk_fma_f32 v[178:179], v[168:169], v[36:37], v[178:179] op_sel_hi:[1,0,1] neg_lo:[1,0,0] neg_hi:[1,0,0]
	v_pk_fma_f32 v[178:179], v[170:171], v[36:37], v[178:179] op_sel:[0,1,0] op_sel_hi:[1,1,1] neg_lo:[1,0,0] neg_hi:[1,0,0]
	v_pk_fma_f32 v[178:179], v[172:173], v[38:39], v[178:179] op_sel_hi:[1,0,1] neg_lo:[1,0,0] neg_hi:[1,0,0]
	v_pk_fma_f32 v[178:179], v[174:175], v[38:39], v[178:179] op_sel:[0,1,0] op_sel_hi:[1,1,1] neg_lo:[1,0,0] neg_hi:[1,0,0]
	ds_read_b128 v[20:23], v228 offset:15024
	v_fma_mixlo_f16 v0, -v176, v40, v178
	v_fma_mixlo_f16 v2, -v177, v40, v179
	v_pk_fma_f32 v[178:179], v[176:177], v[40:41], v[178:179] op_sel_hi:[1,0,1] neg_lo:[1,0,0] neg_hi:[1,0,0]
	ds_write_b16 v253, v0 offset:31888
	ds_write_b16 v253, v2 offset:32016
	ds_read_b128 v[24:27], v228 offset:15040
	s_waitcnt lgkmcnt(11)
	v_pk_fma_f32 v[180:181], v[64:65], v[44:45], v[180:181] op_sel_hi:[1,0,1] neg_lo:[1,0,0] neg_hi:[1,0,0]
	v_pk_fma_f32 v[180:181], v[66:67], v[44:45], v[180:181] op_sel:[0,1,0] op_sel_hi:[1,1,1] neg_lo:[1,0,0] neg_hi:[1,0,0]
	v_pk_fma_f32 v[180:181], v[68:69], v[46:47], v[180:181] op_sel_hi:[1,0,1] neg_lo:[1,0,0] neg_hi:[1,0,0]
	v_pk_fma_f32 v[180:181], v[70:71], v[46:47], v[180:181] op_sel:[0,1,0] op_sel_hi:[1,1,1] neg_lo:[1,0,0] neg_hi:[1,0,0]
	ds_read_b128 v[28:31], v228 offset:15056
	v_pk_fma_f32 v[180:181], v[72:73], v[48:49], v[180:181] op_sel_hi:[1,0,1] neg_lo:[1,0,0] neg_hi:[1,0,0]
	v_pk_fma_f32 v[180:181], v[74:75], v[48:49], v[180:181] op_sel:[0,1,0] op_sel_hi:[1,1,1] neg_lo:[1,0,0] neg_hi:[1,0,0]
	v_pk_fma_f32 v[180:181], v[76:77], v[50:51], v[180:181] op_sel_hi:[1,0,1] neg_lo:[1,0,0] neg_hi:[1,0,0]
	v_pk_fma_f32 v[180:181], v[78:79], v[50:51], v[180:181] op_sel:[0,1,0] op_sel_hi:[1,1,1] neg_lo:[1,0,0] neg_hi:[1,0,0]
	ds_read_b128 v[32:35], v228 offset:15072
	v_pk_fma_f32 v[180:181], v[80:81], v[52:53], v[180:181] op_sel_hi:[1,0,1] neg_lo:[1,0,0] neg_hi:[1,0,0]
	v_pk_fma_f32 v[180:181], v[82:83], v[52:53], v[180:181] op_sel:[0,1,0] op_sel_hi:[1,1,1] neg_lo:[1,0,0] neg_hi:[1,0,0]
	v_pk_fma_f32 v[180:181], v[84:85], v[54:55], v[180:181] op_sel_hi:[1,0,1] neg_lo:[1,0,0] neg_hi:[1,0,0]
	v_pk_fma_f32 v[180:181], v[86:87], v[54:55], v[180:181] op_sel:[0,1,0] op_sel_hi:[1,1,1] neg_lo:[1,0,0] neg_hi:[1,0,0]
	ds_read_b128 v[36:39], v228 offset:15104
	v_pk_fma_f32 v[180:181], v[88:89], v[56:57], v[180:181] op_sel_hi:[1,0,1] neg_lo:[1,0,0] neg_hi:[1,0,0]
	v_pk_fma_f32 v[180:181], v[90:91], v[56:57], v[180:181] op_sel:[0,1,0] op_sel_hi:[1,1,1] neg_lo:[1,0,0] neg_hi:[1,0,0]
	v_pk_fma_f32 v[180:181], v[92:93], v[58:59], v[180:181] op_sel_hi:[1,0,1] neg_lo:[1,0,0] neg_hi:[1,0,0]
	v_pk_fma_f32 v[180:181], v[94:95], v[58:59], v[180:181] op_sel:[0,1,0] op_sel_hi:[1,1,1] neg_lo:[1,0,0] neg_hi:[1,0,0]
	ds_read_b128 v[40:43], v228 offset:15120
	s_waitcnt lgkmcnt(11)
	v_pk_fma_f32 v[180:181], v[96:97], v[60:61], v[180:181] op_sel_hi:[1,0,1] neg_lo:[1,0,0] neg_hi:[1,0,0]
	v_pk_fma_f32 v[180:181], v[98:99], v[60:61], v[180:181] op_sel:[0,1,0] op_sel_hi:[1,1,1] neg_lo:[1,0,0] neg_hi:[1,0,0]
	v_pk_fma_f32 v[180:181], v[100:101], v[62:63], v[180:181] op_sel_hi:[1,0,1] neg_lo:[1,0,0] neg_hi:[1,0,0]
	v_pk_fma_f32 v[180:181], v[102:103], v[62:63], v[180:181] op_sel:[0,1,0] op_sel_hi:[1,1,1] neg_lo:[1,0,0] neg_hi:[1,0,0]
	ds_read_b128 v[44:47], v228 offset:15136
	v_pk_fma_f32 v[180:181], v[104:105], v[244:245], v[180:181] op_sel_hi:[1,0,1] neg_lo:[1,0,0] neg_hi:[1,0,0]
	v_pk_fma_f32 v[180:181], v[106:107], v[244:245], v[180:181] op_sel:[0,1,0] op_sel_hi:[1,1,1] neg_lo:[1,0,0] neg_hi:[1,0,0]
	v_pk_fma_f32 v[180:181], v[108:109], v[246:247], v[180:181] op_sel_hi:[1,0,1] neg_lo:[1,0,0] neg_hi:[1,0,0]
	v_pk_fma_f32 v[180:181], v[110:111], v[246:247], v[180:181] op_sel:[0,1,0] op_sel_hi:[1,1,1] neg_lo:[1,0,0] neg_hi:[1,0,0]
	ds_read_b128 v[48:51], v228 offset:15152
	v_pk_fma_f32 v[180:181], v[112:113], v[248:249], v[180:181] op_sel_hi:[1,0,1] neg_lo:[1,0,0] neg_hi:[1,0,0]
	v_pk_fma_f32 v[180:181], v[114:115], v[248:249], v[180:181] op_sel:[0,1,0] op_sel_hi:[1,1,1] neg_lo:[1,0,0] neg_hi:[1,0,0]
	v_pk_fma_f32 v[180:181], v[116:117], v[250:251], v[180:181] op_sel_hi:[1,0,1] neg_lo:[1,0,0] neg_hi:[1,0,0]
	v_pk_fma_f32 v[180:181], v[118:119], v[250:251], v[180:181] op_sel:[0,1,0] op_sel_hi:[1,1,1] neg_lo:[1,0,0] neg_hi:[1,0,0]
	ds_read_b128 v[52:55], v228 offset:15168
	v_pk_fma_f32 v[180:181], v[120:121], v[4:5], v[180:181] op_sel_hi:[1,0,1] neg_lo:[1,0,0] neg_hi:[1,0,0]
	v_pk_fma_f32 v[180:181], v[122:123], v[4:5], v[180:181] op_sel:[0,1,0] op_sel_hi:[1,1,1] neg_lo:[1,0,0] neg_hi:[1,0,0]
	v_pk_fma_f32 v[180:181], v[124:125], v[6:7], v[180:181] op_sel_hi:[1,0,1] neg_lo:[1,0,0] neg_hi:[1,0,0]
	v_pk_fma_f32 v[180:181], v[126:127], v[6:7], v[180:181] op_sel:[0,1,0] op_sel_hi:[1,1,1] neg_lo:[1,0,0] neg_hi:[1,0,0]
	ds_read_b128 v[56:59], v228 offset:15184
	s_waitcnt lgkmcnt(11)
; #define LAS __attribute__((address_space(3)))
; __device__ __forceinline__ void phase_gdb(const int wvs, const Params& p, LAS unsigned char* lds, int nwg) {
;     ...
;     { float x[64]; const bool isw = t >= 64;
; #pragma unroll
;       for (int i = 0; i < 64; ++i) { const float v = (float)R[i * RP + t]; x[i] = v * bs[i] * (isw ? __expf(gcs[i]) : 1.0f); asm volatile("" : "+v"(x[i])); if ((i & 7) == 7) __builtin_amdgcn_sched_barrier(0); }
; #pragma unroll
;       for (int i = 1; i < 64; ++i) {
; #pragma unroll
;         for (int j4 = 0; j4 < (i + 3) / 4; ++j4) { const f32x4 m4 = *(const LAS f32x4*)(M + i * 64 + j4 * 4);
; #pragma unroll
;           for (int jj = 0; jj < 4; ++jj) if (j4 * 4 + jj < i) x[i] -= m4[jj] * x[j4 * 4 + jj]; }
;         __builtin_amdgcn_sched_barrier(0); }
; #pragma unroll
;       for (int i = 0; i < 64; ++i) R[i * RP + t] = (hf)x[i]; }
	v_pk_fma_f32 v[180:181], v[128:129], v[8:9], v[180:181] op_sel_hi:[1,0,1] neg_lo:[1,0,0] neg_hi:[1,0,0]
	v_pk_fma_f32 v[180:181], v[130:131], v[8:9], v[180:181] op_sel:[0,1,0] op_sel_hi:[1,1,1] neg_lo:[1,0,0] neg_hi:[1,0,0]
	v_pk_fma_f32 v[180:181], v[132:133], v[10:11], v[180:181] op_sel_hi:[1,0,1] neg_lo:[1,0,0] neg_hi:[1,0,0]
	v_pk_fma_f32 v[180:181], v[134:135], v[10:11], v[180:181] op_sel:[0,1,0] op_sel_hi:[1,1,1] neg_lo:[1,0,0] neg_hi:[1,0,0]
	ds_read_b128 v[60:63], v228 offset:15200
	v_pk_fma_f32 v[180:181], v[136:137], v[12:13], v[180:181] op_sel_hi:[1,0,1] neg_lo:[1,0,0] neg_hi:[1,0,0]
	v_pk_fma_f32 v[180:181], v[138:139], v[12:13], v[180:181] op_sel:[0,1,0] op_sel_hi:[1,1,1] neg_lo:[1,0,0] neg_hi:[1,0,0]
	v_pk_fma_f32 v[180:181], v[140:141], v[14:15], v[180:181] op_sel_hi:[1,0,1] neg_lo:[1,0,0] neg_hi:[1,0,0]
	v_pk_fma_f32 v[180:181], v[142:143], v[14:15], v[180:181] op_sel:[0,1,0] op_sel_hi:[1,1,1] neg_lo:[1,0,0] neg_hi:[1,0,0]
	ds_read_b128 v[244:247], v228 offset:15216
	v_pk_fma_f32 v[180:181], v[144:145], v[16:17], v[180:181] op_sel_hi:[1,0,1] neg_lo:[1,0,0] neg_hi:[1,0,0]
	v_pk_fma_f32 v[180:181], v[146:147], v[16:17], v[180:181] op_sel:[0,1,0] op_sel_hi:[1,1,1] neg_lo:[1,0,0] neg_hi:[1,0,0]
	v_pk_fma_f32 v[180:181], v[148:149], v[18:19], v[180:181] op_sel_hi:[1,0,1] neg_lo:[1,0,0] neg_hi:[1,0,0]
	v_pk_fma_f32 v[180:181], v[150:151], v[18:19], v[180:181] op_sel:[0,1,0] op_sel_hi:[1,1,1] neg_lo:[1,0,0] neg_hi:[1,0,0]
	ds_read_b128 v[248:251], v228 offset:15232
	v_pk_fma_f32 v[180:181], v[152:153], v[20:21], v[180:181] op_sel_hi:[1,0,1] neg_lo:[1,0,0] neg_hi:[1,0,0]
	v_pk_fma_f32 v[180:181], v[154:155], v[20:21], v[180:181] op_sel:[0,1,0] op_sel_hi:[1,1,1] neg_lo:[1,0,0] neg_hi:[1,0,0]
	v_pk_fma_f32 v[180:181], v[156:157], v[22:23], v[180:181] op_sel_hi:[1,0,1] neg_lo:[1,0,0] neg_hi:[1,0,0]
	v_pk_fma_f32 v[180:181], v[158:159], v[22:23], v[180:181] op_sel:[0,1,0] op_sel_hi:[1,1,1] neg_lo:[1,0,0] neg_hi:[1,0,0]
	ds_read_b128 v[4:7], v228 offset:15248
	s_waitcnt lgkmcnt(9)
	v_pk_fma_f32 v[180:181], v[160:161], v[24:25], v[180:181] op_sel_hi:[1,0,1] neg_lo:[1,0,0] neg_hi:[1,0,0]
	v_pk_fma_f32 v[180:181], v[162:163], v[24:25], v[180:181] op_sel:[0,1,0] op_sel_hi:[1,1,1] neg_lo:[1,0,0] neg_hi:[1,0,0]
	v_pk_fma_f32 v[180:181], v[164:165], v[26:27], v[180:181] op_sel_hi:[1,0,1] neg_lo:[1,0,0] neg_hi:[1,0,0]
	v_pk_fma_f32 v[180:181], v[166:167], v[26:27], v[180:181] op_sel:[0,1,0] op_sel_hi:[1,1,1] neg_lo:[1,0,0] neg_hi:[1,0,0]
	ds_read_b128 v[8:11], v228 offset:15264
	v_pk_fma_f32 v[180:181], v[168:169], v[28:29], v[180:181] op_sel_hi:[1,0,1] neg_lo:[1,0,0] neg_hi:[1,0,0]
	v_pk_fma_f32 v[180:181], v[170:171], v[28:29], v[180:181] op_sel:[0,1,0] op_sel_hi:[1,1,1] neg_lo:[1,0,0] neg_hi:[1,0,0]
	v_pk_fma_f32 v[180:181], v[172:173], v[30:31], v[180:181] op_sel_hi:[1,0,1] neg_lo:[1,0,0] neg_hi:[1,0,0]
	v_pk_fma_f32 v[180:181], v[174:175], v[30:31], v[180:181] op_sel:[0,1,0] op_sel_hi:[1,1,1] neg_lo:[1,0,0] neg_hi:[1,0,0]
	ds_read_b128 v[12:15], v228 offset:15280
	v_pk_fma_f32 v[180:181], v[176:177], v[32:33], v[180:181] op_sel_hi:[1,0,1] neg_lo:[1,0,0] neg_hi:[1,0,0]
	v_fma_mixlo_f16 v3, -v178, v33, v180
	v_fma_mixlo_f16 v238, -v179, v33, v181
	v_pk_fma_f32 v[180:181], v[178:179], v[32:33], v[180:181] op_sel:[0,1,0] op_sel_hi:[1,1,1] neg_lo:[1,0,0] neg_hi:[1,0,0]
	ds_write_b16 v253, v3 offset:32160
	ds_write_b16 v253, v238 offset:32288
	ds_read_b128 v[16:19], v228 offset:15296
	v_pk_fma_f32 v[182:183], v[64:65], v[36:37], v[182:183] op_sel_hi:[1,0,1] neg_lo:[1,0,0] neg_hi:[1,0,0]
	v_pk_fma_f32 v[182:183], v[66:67], v[36:37], v[182:183] op_sel:[0,1,0] op_sel_hi:[1,1,1] neg_lo:[1,0,0] neg_hi:[1,0,0]
	v_pk_fma_f32 v[182:183], v[68:69], v[38:39], v[182:183] op_sel_hi:[1,0,1] neg_lo:[1,0,0] neg_hi:[1,0,0]
	v_pk_fma_f32 v[182:183], v[70:71], v[38:39], v[182:183] op_sel:[0,1,0] op_sel_hi:[1,1,1] neg_lo:[1,0,0] neg_hi:[1,0,0]
	ds_read_b128 v[20:23], v228 offset:15312
	s_waitcnt lgkmcnt(11)
	v_pk_fma_f32 v[182:183], v[72:73], v[40:41], v[182:183] op_sel_hi:[1,0,1] neg_lo:[1,0,0] neg_hi:[1,0,0]
	v_pk_fma_f32 v[182:183], v[74:75], v[40:41], v[182:183] op_sel:[0,1,0] op_sel_hi:[1,1,1] neg_lo:[1,0,0] neg_hi:[1,0,0]
	v_pk_fma_f32 v[182:183], v[76:77], v[42:43], v[182:183] op_sel_hi:[1,0,1] neg_lo:[1,0,0] neg_hi:[1,0,0]
	v_pk_fma_f32 v[182:183], v[78:79], v[42:43], v[182:183] op_sel:[0,1,0] op_sel_hi:[1,1,1] neg_lo:[1,0,0] neg_hi:[1,0,0]
	ds_read_b128 v[24:27], v228 offset:15328
	v_pk_fma_f32 v[182:183], v[80:81], v[44:45], v[182:183] op_sel_hi:[1,0,1] neg_lo:[1,0,0] neg_hi:[1,0,0]
	v_pk_fma_f32 v[182:183], v[82:83], v[44:45], v[182:183] op_sel:[0,1,0] op_sel_hi:[1,1,1] neg_lo:[1,0,0] neg_hi:[1,0,0]
	v_pk_fma_f32 v[182:183], v[84:85], v[46:47], v[182:183] op_sel_hi:[1,0,1] neg_lo:[1,0,0] neg_hi:[1,0,0]
	v_pk_fma_f32 v[182:183], v[86:87], v[46:47], v[182:183] op_sel:[0,1,0] op_sel_hi:[1,1,1] neg_lo:[1,0,0] neg_hi:[1,0,0]
	ds_read_b128 v[28:31], v228 offset:15360
	v_pk_fma_f32 v[182:183], v[88:89], v[48:49], v[182:183] op_sel_hi:[1,0,1] neg_lo:[1,0,0] neg_hi:[1,0,0]
	v_pk_fma_f32 v[182:183], v[90:91], v[48:49], v[182:183] op_sel:[0,1,0] op_sel_hi:[1,1,1] neg_lo:[1,0,0] neg_hi:[1,0,0]
	v_pk_fma_f32 v[182:183], v[92:93], v[50:51], v[182:183] op_sel_hi:[1,0,1] neg_lo:[1,0,0] neg_hi:[1,0,0]
	v_pk_fma_f32 v[182:183], v[94:95], v[50:51], v[182:183] op_sel:[0,1,0] op_sel_hi:[1,1,1] neg_lo:[1,0,0] neg_hi:[1,0,0]
	ds_read_b128 v[32:35], v228 offset:15376
	v_pk_fma_f32 v[182:183], v[96:97], v[52:53], v[182:183] op_sel_hi:[1,0,1] neg_lo:[1,0,0] neg_hi:[1,0,0]
	v_pk_fma_f32 v[182:183], v[98:99], v[52:53], v[182:183] op_sel:[0,1,0] op_sel_hi:[1,1,1] neg_lo:[1,0,0] neg_hi:[1,0,0]
	v_pk_fma_f32 v[182:183], v[100:101], v[54:55], v[182:183] op_sel_hi:[1,0,1] neg_lo:[1,0,0] neg_hi:[1,0,0]
	v_pk_fma_f32 v[182:183], v[102:103], v[54:55], v[182:183] op_sel:[0,1,0] op_sel_hi:[1,1,1] neg_lo:[1,0,0] neg_hi:[1,0,0]
	ds_read_b128 v[36:39], v228 offset:15392
	s_waitcnt lgkmcnt(11)
; #define LAS __attribute__((address_space(3)))
; __device__ __forceinline__ void phase_gdb(const int wvs, const Params& p, LAS unsigned char* lds, int nwg) {
;     ...
;     { float x[64]; const bool isw = t >= 64;
; #pragma unroll
;       for (int i = 0; i < 64; ++i) { const float v = (float)R[i * RP + t]; x[i] = v * bs[i] * (isw ? __expf(gcs[i]) : 1.0f); asm volatile("" : "+v"(x[i])); if ((i & 7) == 7) __builtin_amdgcn_sched_barrier(0); }
; #pragma unroll
;       for (int i = 1; i < 64; ++i) {
; #pragma unroll
;         for (int j4 = 0; j4 < (i + 3) / 4; ++j4) { const f32x4 m4 = *(const LAS f32x4*)(M + i * 64 + j4 * 4);
; #pragma unroll
;           for (int jj = 0; jj < 4; ++jj) if (j4 * 4 + jj < i) x[i] -= m4[jj] * x[j4 * 4 + jj]; }
;         __builtin_amdgcn_sched_barrier(0); }
; #pragma unroll
;       for (int i = 0; i < 64; ++i) R[i * RP + t] = (hf)x[i]; }
	v_pk_fma_f32 v[182:183], v[104:105], v[56:57], v[182:183] op_sel_hi:[1,0,1] neg_lo:[1,0,0] neg_hi:[1,0,0]
	v_pk_fma_f32 v[182:183], v[106:107], v[56:57], v[182:183] op_sel:[0,1,0] op_sel_hi:[1,1,1] neg_lo:[1,0,0] neg_hi:[1,0,0]
	v_pk_fma_f32 v[182:183], v[108:109], v[58:59], v[182:183] op_sel_hi:[1,0,1] neg_lo:[1,0,0] neg_hi:[1,0,0]
	v_pk_fma_f32 v[182:183], v[110:111], v[58:59], v[182:183] op_sel:[0,1,0] op_sel_hi:[1,1,1] neg_lo:[1,0,0] neg_hi:[1,0,0]
	ds_read_b128 v[40:43], v228 offset:15408
	v_pk_fma_f32 v[182:183], v[112:113], v[60:61], v[182:183] op_sel_hi:[1,0,1] neg_lo:[1,0,0] neg_hi:[1,0,0]
	v_pk_fma_f32 v[182:183], v[114:115], v[60:61], v[182:183] op_sel:[0,1,0] op_sel_hi:[1,1,1] neg_lo:[1,0,0] neg_hi:[1,0,0]
	v_pk_fma_f32 v[182:183], v[116:117], v[62:63], v[182:183] op_sel_hi:[1,0,1] neg_lo:[1,0,0] neg_hi:[1,0,0]
	v_pk_fma_f32 v[182:183], v[118:119], v[62:63], v[182:183] op_sel:[0,1,0] op_sel_hi:[1,1,1] neg_lo:[1,0,0] neg_hi:[1,0,0]
	ds_read_b128 v[44:47], v228 offset:15424
	v_pk_fma_f32 v[182:183], v[120:121], v[244:245], v[182:183] op_sel_hi:[1,0,1] neg_lo:[1,0,0] neg_hi:[1,0,0]
	v_pk_fma_f32 v[182:183], v[122:123], v[244:245], v[182:183] op_sel:[0,1,0] op_sel_hi:[1,1,1] neg_lo:[1,0,0] neg_hi:[1,0,0]
	v_pk_fma_f32 v[182:183], v[124:125], v[246:247], v[182:183] op_sel_hi:[1,0,1] neg_lo:[1,0,0] neg_hi:[1,0,0]
	v_pk_fma_f32 v[182:183], v[126:127], v[246:247], v[182:183] op_sel:[0,1,0] op_sel_hi:[1,1,1] neg_lo:[1,0,0] neg_hi:[1,0,0]
	ds_read_b128 v[48:51], v228 offset:15440
	v_pk_fma_f32 v[182:183], v[128:129], v[248:249], v[182:183] op_sel_hi:[1,0,1] neg_lo:[1,0,0] neg_hi:[1,0,0]
	v_pk_fma_f32 v[182:183], v[130:131], v[248:249], v[182:183] op_sel:[0,1,0] op_sel_hi:[1,1,1] neg_lo:[1,0,0] neg_hi:[1,0,0]
	v_pk_fma_f32 v[182:183], v[132:133], v[250:251], v[182:183] op_sel_hi:[1,0,1] neg_lo:[1,0,0] neg_hi:[1,0,0]
	v_pk_fma_f32 v[182:183], v[134:135], v[250:251], v[182:183] op_sel:[0,1,0] op_sel_hi:[1,1,1] neg_lo:[1,0,0] neg_hi:[1,0,0]
	ds_read_b128 v[52:55], v228 offset:15456
	s_waitcnt lgkmcnt(9)
	v_pk_fma_f32 v[182:183], v[136:137], v[4:5], v[182:183] op_sel_hi:[1,0,1] neg_lo:[1,0,0] neg_hi:[1,0,0]
	v_pk_fma_f32 v[182:183], v[138:139], v[4:5], v[182:183] op_sel:[0,1,0] op_sel_hi:[1,1,1] neg_lo:[1,0,0] neg_hi:[1,0,0]
	v_pk_fma_f32 v[182:183], v[140:141], v[6:7], v[182:183] op_sel_hi:[1,0,1] neg_lo:[1,0,0] neg_hi:[1,0,0]
	v_pk_fma_f32 v[182:183], v[142:143], v[6:7], v[182:183] op_sel:[0,1,0] op_sel_hi:[1,1,1] neg_lo:[1,0,0] neg_hi:[1,0,0]
	ds_read_b128 v[56:59], v228 offset:15472
	v_pk_fma_f32 v[182:183], v[144:145], v[8:9], v[182:183] op_sel_hi:[1,0,1] neg_lo:[1,0,0] neg_hi:[1,0,0]
	v_pk_fma_f32 v[182:183], v[146:147], v[8:9], v[182:183] op_sel:[0,1,0] op_sel_hi:[1,1,1] neg_lo:[1,0,0] neg_hi:[1,0,0]
	v_pk_fma_f32 v[182:183], v[148:149], v[10:11], v[182:183] op_sel_hi:[1,0,1] neg_lo:[1,0,0] neg_hi:[1,0,0]
	v_pk_fma_f32 v[182:183], v[150:151], v[10:11], v[182:183] op_sel:[0,1,0] op_sel_hi:[1,1,1] neg_lo:[1,0,0] neg_hi:[1,0,0]
	ds_read_b128 v[60:63], v228 offset:15488
	v_pk_fma_f32 v[182:183], v[152:153], v[12:13], v[182:183] op_sel_hi:[1,0,1] neg_lo:[1,0,0] neg_hi:[1,0,0]
	v_pk_fma_f32 v[182:183], v[154:155], v[12:13], v[182:183] op_sel:[0,1,0] op_sel_hi:[1,1,1] neg_lo:[1,0,0] neg_hi:[1,0,0]
	v_pk_fma_f32 v[182:183], v[156:157], v[14:15], v[182:183] op_sel_hi:[1,0,1] neg_lo:[1,0,0] neg_hi:[1,0,0]
	v_pk_fma_f32 v[182:183], v[158:159], v[14:15], v[182:183] op_sel:[0,1,0] op_sel_hi:[1,1,1] neg_lo:[1,0,0] neg_hi:[1,0,0]
	ds_read_b128 v[244:247], v228 offset:15504
	v_pk_fma_f32 v[182:183], v[160:161], v[16:17], v[182:183] op_sel_hi:[1,0,1] neg_lo:[1,0,0] neg_hi:[1,0,0]
	v_pk_fma_f32 v[182:183], v[162:163], v[16:17], v[182:183] op_sel:[0,1,0] op_sel_hi:[1,1,1] neg_lo:[1,0,0] neg_hi:[1,0,0]
	v_pk_fma_f32 v[182:183], v[164:165], v[18:19], v[182:183] op_sel_hi:[1,0,1] neg_lo:[1,0,0] neg_hi:[1,0,0]
	v_pk_fma_f32 v[182:183], v[166:167], v[18:19], v[182:183] op_sel:[0,1,0] op_sel_hi:[1,1,1] neg_lo:[1,0,0] neg_hi:[1,0,0]
	ds_read_b128 v[248:251], v228 offset:15520
	s_waitcnt lgkmcnt(9)
	v_pk_fma_f32 v[182:183], v[168:169], v[20:21], v[182:183] op_sel_hi:[1,0,1] neg_lo:[1,0,0] neg_hi:[1,0,0]
	v_pk_fma_f32 v[182:183], v[170:171], v[20:21], v[182:183] op_sel:[0,1,0] op_sel_hi:[1,1,1] neg_lo:[1,0,0] neg_hi:[1,0,0]
	v_pk_fma_f32 v[182:183], v[172:173], v[22:23], v[182:183] op_sel_hi:[1,0,1] neg_lo:[1,0,0] neg_hi:[1,0,0]
	v_pk_fma_f32 v[182:183], v[174:175], v[22:23], v[182:183] op_sel:[0,1,0] op_sel_hi:[1,1,1] neg_lo:[1,0,0] neg_hi:[1,0,0]
	ds_read_b128 v[4:7], v228 offset:15536
	v_pk_fma_f32 v[182:183], v[176:177], v[24:25], v[182:183] op_sel_hi:[1,0,1] neg_lo:[1,0,0] neg_hi:[1,0,0]
	v_pk_fma_f32 v[182:183], v[178:179], v[24:25], v[182:183] op_sel:[0,1,0] op_sel_hi:[1,1,1] neg_lo:[1,0,0] neg_hi:[1,0,0]
	v_fma_mixlo_f16 v239, -v180, v26, v182
	v_fma_mixlo_f16 v240, -v181, v26, v183
	v_pk_fma_f32 v[182:183], v[180:181], v[26:27], v[182:183] op_sel_hi:[1,0,1] neg_lo:[1,0,0] neg_hi:[1,0,0]
	ds_write_b16 v253, v239 offset:32432
	ds_write_b16 v253, v240 offset:32560
	ds_read_b128 v[8:11], v228 offset:15552
	v_pk_fma_f32 v[184:185], v[64:65], v[28:29], v[184:185] op_sel_hi:[1,0,1] neg_lo:[1,0,0] neg_hi:[1,0,0]
	v_pk_fma_f32 v[184:185], v[66:67], v[28:29], v[184:185] op_sel:[0,1,0] op_sel_hi:[1,1,1] neg_lo:[1,0,0] neg_hi:[1,0,0]
	v_pk_fma_f32 v[184:185], v[68:69], v[30:31], v[184:185] op_sel_hi:[1,0,1] neg_lo:[1,0,0] neg_hi:[1,0,0]
	v_pk_fma_f32 v[184:185], v[70:71], v[30:31], v[184:185] op_sel:[0,1,0] op_sel_hi:[1,1,1] neg_lo:[1,0,0] neg_hi:[1,0,0]
	ds_read_b128 v[12:15], v228 offset:15568
	v_pk_fma_f32 v[184:185], v[72:73], v[32:33], v[184:185] op_sel_hi:[1,0,1] neg_lo:[1,0,0] neg_hi:[1,0,0]
	v_pk_fma_f32 v[184:185], v[74:75], v[32:33], v[184:185] op_sel:[0,1,0] op_sel_hi:[1,1,1] neg_lo:[1,0,0] neg_hi:[1,0,0]
	v_pk_fma_f32 v[184:185], v[76:77], v[34:35], v[184:185] op_sel_hi:[1,0,1] neg_lo:[1,0,0] neg_hi:[1,0,0]
	v_pk_fma_f32 v[184:185], v[78:79], v[34:35], v[184:185] op_sel:[0,1,0] op_sel_hi:[1,1,1] neg_lo:[1,0,0] neg_hi:[1,0,0]
	ds_read_b128 v[16:19], v228 offset:15584
	s_waitcnt lgkmcnt(11)
; #define LAS __attribute__((address_space(3)))
; __device__ __forceinline__ void phase_gdb(const int wvs, const Params& p, LAS unsigned char* lds, int nwg) {
;     ...
;     { float x[64]; const bool isw = t >= 64;
; #pragma unroll
;       for (int i = 0; i < 64; ++i) { const float v = (float)R[i * RP + t]; x[i] = v * bs[i] * (isw ? __expf(gcs[i]) : 1.0f); asm volatile("" : "+v"(x[i])); if ((i & 7) == 7) __builtin_amdgcn_sched_barrier(0); }
; #pragma unroll
;       for (int i = 1; i < 64; ++i) {
; #pragma unroll
;         for (int j4 = 0; j4 < (i + 3) / 4; ++j4) { const f32x4 m4 = *(const LAS f32x4*)(M + i * 64 + j4 * 4);
; #pragma unroll
;           for (int jj = 0; jj < 4; ++jj) if (j4 * 4 + jj < i) x[i] -= m4[jj] * x[j4 * 4 + jj]; }
;         __builtin_amdgcn_sched_barrier(0); }
; #pragma unroll
;       for (int i = 0; i < 64; ++i) R[i * RP + t] = (hf)x[i]; }
	v_pk_fma_f32 v[184:185], v[80:81], v[36:37], v[184:185] op_sel_hi:[1,0,1] neg_lo:[1,0,0] neg_hi:[1,0,0]
	v_pk_fma_f32 v[184:185], v[82:83], v[36:37], v[184:185] op_sel:[0,1,0] op_sel_hi:[1,1,1] neg_lo:[1,0,0] neg_hi:[1,0,0]
	v_pk_fma_f32 v[184:185], v[84:85], v[38:39], v[184:185] op_sel_hi:[1,0,1] neg_lo:[1,0,0] neg_hi:[1,0,0]
	v_pk_fma_f32 v[184:185], v[86:87], v[38:39], v[184:185] op_sel:[0,1,0] op_sel_hi:[1,1,1] neg_lo:[1,0,0] neg_hi:[1,0,0]
	ds_read_b128 v[20:23], v228 offset:15616
	v_pk_fma_f32 v[184:185], v[88:89], v[40:41], v[184:185] op_sel_hi:[1,0,1] neg_lo:[1,0,0] neg_hi:[1,0,0]
	v_pk_fma_f32 v[184:185], v[90:91], v[40:41], v[184:185] op_sel:[0,1,0] op_sel_hi:[1,1,1] neg_lo:[1,0,0] neg_hi:[1,0,0]
	v_pk_fma_f32 v[184:185], v[92:93], v[42:43], v[184:185] op_sel_hi:[1,0,1] neg_lo:[1,0,0] neg_hi:[1,0,0]
	v_pk_fma_f32 v[184:185], v[94:95], v[42:43], v[184:185] op_sel:[0,1,0] op_sel_hi:[1,1,1] neg_lo:[1,0,0] neg_hi:[1,0,0]
	ds_read_b128 v[24:27], v228 offset:15632
	v_pk_fma_f32 v[184:185], v[96:97], v[44:45], v[184:185] op_sel_hi:[1,0,1] neg_lo:[1,0,0] neg_hi:[1,0,0]
	v_pk_fma_f32 v[184:185], v[98:99], v[44:45], v[184:185] op_sel:[0,1,0] op_sel_hi:[1,1,1] neg_lo:[1,0,0] neg_hi:[1,0,0]
	v_pk_fma_f32 v[184:185], v[100:101], v[46:47], v[184:185] op_sel_hi:[1,0,1] neg_lo:[1,0,0] neg_hi:[1,0,0]
	v_pk_fma_f32 v[184:185], v[102:103], v[46:47], v[184:185] op_sel:[0,1,0] op_sel_hi:[1,1,1] neg_lo:[1,0,0] neg_hi:[1,0,0]
	ds_read_b128 v[28:31], v228 offset:15648
	v_pk_fma_f32 v[184:185], v[104:105], v[48:49], v[184:185] op_sel_hi:[1,0,1] neg_lo:[1,0,0] neg_hi:[1,0,0]
	v_pk_fma_f32 v[184:185], v[106:107], v[48:49], v[184:185] op_sel:[0,1,0] op_sel_hi:[1,1,1] neg_lo:[1,0,0] neg_hi:[1,0,0]
	v_pk_fma_f32 v[184:185], v[108:109], v[50:51], v[184:185] op_sel_hi:[1,0,1] neg_lo:[1,0,0] neg_hi:[1,0,0]
	v_pk_fma_f32 v[184:185], v[110:111], v[50:51], v[184:185] op_sel:[0,1,0] op_sel_hi:[1,1,1] neg_lo:[1,0,0] neg_hi:[1,0,0]
	ds_read_b128 v[32:35], v228 offset:15664
	s_waitcnt lgkmcnt(11)
	v_pk_fma_f32 v[184:185], v[112:113], v[52:53], v[184:185] op_sel_hi:[1,0,1] neg_lo:[1,0,0] neg_hi:[1,0,0]
	v_pk_fma_f32 v[184:185], v[114:115], v[52:53], v[184:185] op_sel:[0,1,0] op_sel_hi:[1,1,1] neg_lo:[1,0,0] neg_hi:[1,0,0]
	v_pk_fma_f32 v[184:185], v[116:117], v[54:55], v[184:185] op_sel_hi:[1,0,1] neg_lo:[1,0,0] neg_hi:[1,0,0]
	v_pk_fma_f32 v[184:185], v[118:119], v[54:55], v[184:185] op_sel:[0,1,0] op_sel_hi:[1,1,1] neg_lo:[1,0,0] neg_hi:[1,0,0]
	ds_read_b128 v[36:39], v228 offset:15680
	v_pk_fma_f32 v[184:185], v[120:121], v[56:57], v[184:185] op_sel_hi:[1,0,1] neg_lo:[1,0,0] neg_hi:[1,0,0]
	v_pk_fma_f32 v[184:185], v[122:123], v[56:57], v[184:185] op_sel:[0,1,0] op_sel_hi:[1,1,1] neg_lo:[1,0,0] neg_hi:[1,0,0]
	v_pk_fma_f32 v[184:185], v[124:125], v[58:59], v[184:185] op_sel_hi:[1,0,1] neg_lo:[1,0,0] neg_hi:[1,0,0]
	v_pk_fma_f32 v[184:185], v[126:127], v[58:59], v[184:185] op_sel:[0,1,0] op_sel_hi:[1,1,1] neg_lo:[1,0,0] neg_hi:[1,0,0]
	ds_read_b128 v[40:43], v228 offset:15696
	v_pk_fma_f32 v[184:185], v[128:129], v[60:61], v[184:185] op_sel_hi:[1,0,1] neg_lo:[1,0,0] neg_hi:[1,0,0]
	v_pk_fma_f32 v[184:185], v[130:131], v[60:61], v[184:185] op_sel:[0,1,0] op_sel_hi:[1,1,1] neg_lo:[1,0,0] neg_hi:[1,0,0]
	v_pk_fma_f32 v[184:185], v[132:133], v[62:63], v[184:185] op_sel_hi:[1,0,1] neg_lo:[1,0,0] neg_hi:[1,0,0]
	v_pk_fma_f32 v[184:185], v[134:135], v[62:63], v[184:185] op_sel:[0,1,0] op_sel_hi:[1,1,1] neg_lo:[1,0,0] neg_hi:[1,0,0]
	ds_read_b128 v[44:47], v228 offset:15712
	v_pk_fma_f32 v[184:185], v[136:137], v[244:245], v[184:185] op_sel_hi:[1,0,1] neg_lo:[1,0,0] neg_hi:[1,0,0]
	v_pk_fma_f32 v[184:185], v[138:139], v[244:245], v[184:185] op_sel:[0,1,0] op_sel_hi:[1,1,1] neg_lo:[1,0,0] neg_hi:[1,0,0]
	v_pk_fma_f32 v[184:185], v[140:141], v[246:247], v[184:185] op_sel_hi:[1,0,1] neg_lo:[1,0,0] neg_hi:[1,0,0]
	v_pk_fma_f32 v[184:185], v[142:143], v[246:247], v[184:185] op_sel:[0,1,0] op_sel_hi:[1,1,1] neg_lo:[1,0,0] neg_hi:[1,0,0]
	ds_read_b128 v[48:51], v228 offset:15728
	s_waitcnt lgkmcnt(9)
	v_pk_fma_f32 v[184:185], v[144:145], v[248:249], v[184:185] op_sel_hi:[1,0,1] neg_lo:[1,0,0] neg_hi:[1,0,0]
	v_pk_fma_f32 v[184:185], v[146:147], v[248:249], v[184:185] op_sel:[0,1,0] op_sel_hi:[1,1,1] neg_lo:[1,0,0] neg_hi:[1,0,0]
	v_pk_fma_f32 v[184:185], v[148:149], v[250:251], v[184:185] op_sel_hi:[1,0,1] neg_lo:[1,0,0] neg_hi:[1,0,0]
	v_pk_fma_f32 v[184:185], v[150:151], v[250:251], v[184:185] op_sel:[0,1,0] op_sel_hi:[1,1,1] neg_lo:[1,0,0] neg_hi:[1,0,0]
	ds_read_b128 v[52:55], v228 offset:15744
	v_pk_fma_f32 v[184:185], v[152:153], v[4:5], v[184:185] op_sel_hi:[1,0,1] neg_lo:[1,0,0] neg_hi:[1,0,0]
	v_pk_fma_f32 v[184:185], v[154:155], v[4:5], v[184:185] op_sel:[0,1,0] op_sel_hi:[1,1,1] neg_lo:[1,0,0] neg_hi:[1,0,0]
	v_pk_fma_f32 v[184:185], v[156:157], v[6:7], v[184:185] op_sel_hi:[1,0,1] neg_lo:[1,0,0] neg_hi:[1,0,0]
	v_pk_fma_f32 v[184:185], v[158:159], v[6:7], v[184:185] op_sel:[0,1,0] op_sel_hi:[1,1,1] neg_lo:[1,0,0] neg_hi:[1,0,0]
	ds_read_b128 v[56:59], v228 offset:15760
	v_pk_fma_f32 v[184:185], v[160:161], v[8:9], v[184:185] op_sel_hi:[1,0,1] neg_lo:[1,0,0] neg_hi:[1,0,0]
	v_pk_fma_f32 v[184:185], v[162:163], v[8:9], v[184:185] op_sel:[0,1,0] op_sel_hi:[1,1,1] neg_lo:[1,0,0] neg_hi:[1,0,0]
	v_pk_fma_f32 v[184:185], v[164:165], v[10:11], v[184:185] op_sel_hi:[1,0,1] neg_lo:[1,0,0] neg_hi:[1,0,0]
	v_pk_fma_f32 v[184:185], v[166:167], v[10:11], v[184:185] op_sel:[0,1,0] op_sel_hi:[1,1,1] neg_lo:[1,0,0] neg_hi:[1,0,0]
	ds_read_b128 v[60:63], v228 offset:15776
	v_pk_fma_f32 v[184:185], v[168:169], v[12:13], v[184:185] op_sel_hi:[1,0,1] neg_lo:[1,0,0] neg_hi:[1,0,0]
	v_pk_fma_f32 v[184:185], v[170:171], v[12:13], v[184:185] op_sel:[0,1,0] op_sel_hi:[1,1,1] neg_lo:[1,0,0] neg_hi:[1,0,0]
	v_pk_fma_f32 v[184:185], v[172:173], v[14:15], v[184:185] op_sel_hi:[1,0,1] neg_lo:[1,0,0] neg_hi:[1,0,0]
	v_pk_fma_f32 v[184:185], v[174:175], v[14:15], v[184:185] op_sel:[0,1,0] op_sel_hi:[1,1,1] neg_lo:[1,0,0] neg_hi:[1,0,0]
	ds_read_b128 v[244:247], v228 offset:15792
	s_waitcnt lgkmcnt(9)
; #define LAS __attribute__((address_space(3)))
; __device__ __forceinline__ void phase_gdb(const int wvs, const Params& p, LAS unsigned char* lds, int nwg) {
;     ...
;     { float x[64]; const bool isw = t >= 64;
; #pragma unroll
;       for (int i = 0; i < 64; ++i) { const float v = (float)R[i * RP + t]; x[i] = v * bs[i] * (isw ? __expf(gcs[i]) : 1.0f); asm volatile("" : "+v"(x[i])); if ((i & 7) == 7) __builtin_amdgcn_sched_barrier(0); }
; #pragma unroll
;       for (int i = 1; i < 64; ++i) {
; #pragma unroll
;         for (int j4 = 0; j4 < (i + 3) / 4; ++j4) { const f32x4 m4 = *(const LAS f32x4*)(M + i * 64 + j4 * 4);
; #pragma unroll
;           for (int jj = 0; jj < 4; ++jj) if (j4 * 4 + jj < i) x[i] -= m4[jj] * x[j4 * 4 + jj]; }
;         __builtin_amdgcn_sched_barrier(0); }
; #pragma unroll
;       for (int i = 0; i < 64; ++i) R[i * RP + t] = (hf)x[i]; }
	v_pk_fma_f32 v[184:185], v[176:177], v[16:17], v[184:185] op_sel_hi:[1,0,1] neg_lo:[1,0,0] neg_hi:[1,0,0]
	v_pk_fma_f32 v[184:185], v[178:179], v[16:17], v[184:185] op_sel:[0,1,0] op_sel_hi:[1,1,1] neg_lo:[1,0,0] neg_hi:[1,0,0]
	v_pk_fma_f32 v[184:185], v[180:181], v[18:19], v[184:185] op_sel_hi:[1,0,1] neg_lo:[1,0,0] neg_hi:[1,0,0]
	v_fma_mixlo_f16 v0, -v182, v19, v184
	v_fma_mixlo_f16 v2, -v183, v19, v185
	v_pk_fma_f32 v[184:185], v[182:183], v[18:19], v[184:185] op_sel:[0,1,0] op_sel_hi:[1,1,1] neg_lo:[1,0,0] neg_hi:[1,0,0]
	ds_write_b16 v253, v0 offset:32704
	ds_write_b16 v253, v2 offset:32832
	ds_read_b128 v[248:251], v228 offset:15808
	v_pk_fma_f32 v[186:187], v[64:65], v[20:21], v[186:187] op_sel_hi:[1,0,1] neg_lo:[1,0,0] neg_hi:[1,0,0]
	v_pk_fma_f32 v[186:187], v[66:67], v[20:21], v[186:187] op_sel:[0,1,0] op_sel_hi:[1,1,1] neg_lo:[1,0,0] neg_hi:[1,0,0]
	v_pk_fma_f32 v[186:187], v[68:69], v[22:23], v[186:187] op_sel_hi:[1,0,1] neg_lo:[1,0,0] neg_hi:[1,0,0]
	v_pk_fma_f32 v[186:187], v[70:71], v[22:23], v[186:187] op_sel:[0,1,0] op_sel_hi:[1,1,1] neg_lo:[1,0,0] neg_hi:[1,0,0]
	ds_read_b128 v[4:7], v228 offset:15824
	v_pk_fma_f32 v[186:187], v[72:73], v[24:25], v[186:187] op_sel_hi:[1,0,1] neg_lo:[1,0,0] neg_hi:[1,0,0]
	v_pk_fma_f32 v[186:187], v[74:75], v[24:25], v[186:187] op_sel:[0,1,0] op_sel_hi:[1,1,1] neg_lo:[1,0,0] neg_hi:[1,0,0]
	v_pk_fma_f32 v[186:187], v[76:77], v[26:27], v[186:187] op_sel_hi:[1,0,1] neg_lo:[1,0,0] neg_hi:[1,0,0]
	v_pk_fma_f32 v[186:187], v[78:79], v[26:27], v[186:187] op_sel:[0,1,0] op_sel_hi:[1,1,1] neg_lo:[1,0,0] neg_hi:[1,0,0]
	ds_read_b128 v[8:11], v228 offset:15840
	v_pk_fma_f32 v[186:187], v[80:81], v[28:29], v[186:187] op_sel_hi:[1,0,1] neg_lo:[1,0,0] neg_hi:[1,0,0]
	v_pk_fma_f32 v[186:187], v[82:83], v[28:29], v[186:187] op_sel:[0,1,0] op_sel_hi:[1,1,1] neg_lo:[1,0,0] neg_hi:[1,0,0]
	v_pk_fma_f32 v[186:187], v[84:85], v[30:31], v[186:187] op_sel_hi:[1,0,1] neg_lo:[1,0,0] neg_hi:[1,0,0]
	v_pk_fma_f32 v[186:187], v[86:87], v[30:31], v[186:187] op_sel:[0,1,0] op_sel_hi:[1,1,1] neg_lo:[1,0,0] neg_hi:[1,0,0]
	ds_read_b128 v[12:15], v228 offset:15856
	s_waitcnt lgkmcnt(11)
	v_pk_fma_f32 v[186:187], v[88:89], v[32:33], v[186:187] op_sel_hi:[1,0,1] neg_lo:[1,0,0] neg_hi:[1,0,0]
	v_pk_fma_f32 v[186:187], v[90:91], v[32:33], v[186:187] op_sel:[0,1,0] op_sel_hi:[1,1,1] neg_lo:[1,0,0] neg_hi:[1,0,0]
	v_pk_fma_f32 v[186:187], v[92:93], v[34:35], v[186:187] op_sel_hi:[1,0,1] neg_lo:[1,0,0] neg_hi:[1,0,0]
	v_pk_fma_f32 v[186:187], v[94:95], v[34:35], v[186:187] op_sel:[0,1,0] op_sel_hi:[1,1,1] neg_lo:[1,0,0] neg_hi:[1,0,0]
	ds_read_b128 v[16:19], v228 offset:15872
	v_pk_fma_f32 v[186:187], v[96:97], v[36:37], v[186:187] op_sel_hi:[1,0,1] neg_lo:[1,0,0] neg_hi:[1,0,0]
	v_pk_fma_f32 v[186:187], v[98:99], v[36:37], v[186:187] op_sel:[0,1,0] op_sel_hi:[1,1,1] neg_lo:[1,0,0] neg_hi:[1,0,0]
	v_pk_fma_f32 v[186:187], v[100:101], v[38:39], v[186:187] op_sel_hi:[1,0,1] neg_lo:[1,0,0] neg_hi:[1,0,0]
	v_pk_fma_f32 v[186:187], v[102:103], v[38:39], v[186:187] op_sel:[0,1,0] op_sel_hi:[1,1,1] neg_lo:[1,0,0] neg_hi:[1,0,0]
	ds_read_b128 v[20:23], v228 offset:15888
	v_pk_fma_f32 v[186:187], v[104:105], v[40:41], v[186:187] op_sel_hi:[1,0,1] neg_lo:[1,0,0] neg_hi:[1,0,0]
	v_pk_fma_f32 v[186:187], v[106:107], v[40:41], v[186:187] op_sel:[0,1,0] op_sel_hi:[1,1,1] neg_lo:[1,0,0] neg_hi:[1,0,0]
	v_pk_fma_f32 v[186:187], v[108:109], v[42:43], v[186:187] op_sel_hi:[1,0,1] neg_lo:[1,0,0] neg_hi:[1,0,0]
	v_pk_fma_f32 v[186:187], v[110:111], v[42:43], v[186:187] op_sel:[0,1,0] op_sel_hi:[1,1,1] neg_lo:[1,0,0] neg_hi:[1,0,0]
	ds_read_b128 v[24:27], v228 offset:15904
	v_pk_fma_f32 v[186:187], v[112:113], v[44:45], v[186:187] op_sel_hi:[1,0,1] neg_lo:[1,0,0] neg_hi:[1,0,0]
	v_pk_fma_f32 v[186:187], v[114:115], v[44:45], v[186:187] op_sel:[0,1,0] op_sel_hi:[1,1,1] neg_lo:[1,0,0] neg_hi:[1,0,0]
	v_pk_fma_f32 v[186:187], v[116:117], v[46:47], v[186:187] op_sel_hi:[1,0,1] neg_lo:[1,0,0] neg_hi:[1,0,0]
	v_pk_fma_f32 v[186:187], v[118:119], v[46:47], v[186:187] op_sel:[0,1,0] op_sel_hi:[1,1,1] neg_lo:[1,0,0] neg_hi:[1,0,0]
	ds_read_b128 v[28:31], v228 offset:15920
	s_waitcnt lgkmcnt(11)
	v_pk_fma_f32 v[186:187], v[120:121], v[48:49], v[186:187] op_sel_hi:[1,0,1] neg_lo:[1,0,0] neg_hi:[1,0,0]
	v_pk_fma_f32 v[186:187], v[122:123], v[48:49], v[186:187] op_sel:[0,1,0] op_sel_hi:[1,1,1] neg_lo:[1,0,0] neg_hi:[1,0,0]
	v_pk_fma_f32 v[186:187], v[124:125], v[50:51], v[186:187] op_sel_hi:[1,0,1] neg_lo:[1,0,0] neg_hi:[1,0,0]
	v_pk_fma_f32 v[186:187], v[126:127], v[50:51], v[186:187] op_sel:[0,1,0] op_sel_hi:[1,1,1] neg_lo:[1,0,0] neg_hi:[1,0,0]
	ds_read_b128 v[32:35], v228 offset:15936
	v_pk_fma_f32 v[186:187], v[128:129], v[52:53], v[186:187] op_sel_hi:[1,0,1] neg_lo:[1,0,0] neg_hi:[1,0,0]
	v_pk_fma_f32 v[186:187], v[130:131], v[52:53], v[186:187] op_sel:[0,1,0] op_sel_hi:[1,1,1] neg_lo:[1,0,0] neg_hi:[1,0,0]
	v_pk_fma_f32 v[186:187], v[132:133], v[54:55], v[186:187] op_sel_hi:[1,0,1] neg_lo:[1,0,0] neg_hi:[1,0,0]
	v_pk_fma_f32 v[186:187], v[134:135], v[54:55], v[186:187] op_sel:[0,1,0] op_sel_hi:[1,1,1] neg_lo:[1,0,0] neg_hi:[1,0,0]
	ds_read_b128 v[36:39], v228 offset:15952
	v_pk_fma_f32 v[186:187], v[136:137], v[56:57], v[186:187] op_sel_hi:[1,0,1] neg_lo:[1,0,0] neg_hi:[1,0,0]
	v_pk_fma_f32 v[186:187], v[138:139], v[56:57], v[186:187] op_sel:[0,1,0] op_sel_hi:[1,1,1] neg_lo:[1,0,0] neg_hi:[1,0,0]
	v_pk_fma_f32 v[186:187], v[140:141], v[58:59], v[186:187] op_sel_hi:[1,0,1] neg_lo:[1,0,0] neg_hi:[1,0,0]
	v_pk_fma_f32 v[186:187], v[142:143], v[58:59], v[186:187] op_sel:[0,1,0] op_sel_hi:[1,1,1] neg_lo:[1,0,0] neg_hi:[1,0,0]
	ds_read_b128 v[40:43], v228 offset:15968
	v_pk_fma_f32 v[186:187], v[144:145], v[60:61], v[186:187] op_sel_hi:[1,0,1] neg_lo:[1,0,0] neg_hi:[1,0,0]
	v_pk_fma_f32 v[186:187], v[146:147], v[60:61], v[186:187] op_sel:[0,1,0] op_sel_hi:[1,1,1] neg_lo:[1,0,0] neg_hi:[1,0,0]
	v_pk_fma_f32 v[186:187], v[148:149], v[62:63], v[186:187] op_sel_hi:[1,0,1] neg_lo:[1,0,0] neg_hi:[1,0,0]
	v_pk_fma_f32 v[186:187], v[150:151], v[62:63], v[186:187] op_sel:[0,1,0] op_sel_hi:[1,1,1] neg_lo:[1,0,0] neg_hi:[1,0,0]
	ds_read_b128 v[44:47], v228 offset:15984
	s_waitcnt lgkmcnt(9)
; #define LAS __attribute__((address_space(3)))
; __device__ __forceinline__ void phase_gdb(const int wvs, const Params& p, LAS unsigned char* lds, int nwg) {
;     ...
;     { float x[64]; const bool isw = t >= 64;
; #pragma unroll
;       for (int i = 0; i < 64; ++i) { const float v = (float)R[i * RP + t]; x[i] = v * bs[i] * (isw ? __expf(gcs[i]) : 1.0f); asm volatile("" : "+v"(x[i])); if ((i & 7) == 7) __builtin_amdgcn_sched_barrier(0); }
; #pragma unroll
;       for (int i = 1; i < 64; ++i) {
; #pragma unroll
;         for (int j4 = 0; j4 < (i + 3) / 4; ++j4) { const f32x4 m4 = *(const LAS f32x4*)(M + i * 64 + j4 * 4);
; #pragma unroll
;           for (int jj = 0; jj < 4; ++jj) if (j4 * 4 + jj < i) x[i] -= m4[jj] * x[j4 * 4 + jj]; }
;         __builtin_amdgcn_sched_barrier(0); }
; #pragma unroll
;       for (int i = 0; i < 64; ++i) R[i * RP + t] = (hf)x[i]; }
	v_pk_fma_f32 v[186:187], v[152:153], v[244:245], v[186:187] op_sel_hi:[1,0,1] neg_lo:[1,0,0] neg_hi:[1,0,0]
	v_pk_fma_f32 v[186:187], v[154:155], v[244:245], v[186:187] op_sel:[0,1,0] op_sel_hi:[1,1,1] neg_lo:[1,0,0] neg_hi:[1,0,0]
	v_pk_fma_f32 v[186:187], v[156:157], v[246:247], v[186:187] op_sel_hi:[1,0,1] neg_lo:[1,0,0] neg_hi:[1,0,0]
	v_pk_fma_f32 v[186:187], v[158:159], v[246:247], v[186:187] op_sel:[0,1,0] op_sel_hi:[1,1,1] neg_lo:[1,0,0] neg_hi:[1,0,0]
	ds_read_b128 v[48:51], v228 offset:16000
	v_pk_fma_f32 v[186:187], v[160:161], v[248:249], v[186:187] op_sel_hi:[1,0,1] neg_lo:[1,0,0] neg_hi:[1,0,0]
	v_pk_fma_f32 v[186:187], v[162:163], v[248:249], v[186:187] op_sel:[0,1,0] op_sel_hi:[1,1,1] neg_lo:[1,0,0] neg_hi:[1,0,0]
	v_pk_fma_f32 v[186:187], v[164:165], v[250:251], v[186:187] op_sel_hi:[1,0,1] neg_lo:[1,0,0] neg_hi:[1,0,0]
	v_pk_fma_f32 v[186:187], v[166:167], v[250:251], v[186:187] op_sel:[0,1,0] op_sel_hi:[1,1,1] neg_lo:[1,0,0] neg_hi:[1,0,0]
	ds_read_b128 v[52:55], v228 offset:16016
	v_pk_fma_f32 v[186:187], v[168:169], v[4:5], v[186:187] op_sel_hi:[1,0,1] neg_lo:[1,0,0] neg_hi:[1,0,0]
	v_pk_fma_f32 v[186:187], v[170:171], v[4:5], v[186:187] op_sel:[0,1,0] op_sel_hi:[1,1,1] neg_lo:[1,0,0] neg_hi:[1,0,0]
	v_pk_fma_f32 v[186:187], v[172:173], v[6:7], v[186:187] op_sel_hi:[1,0,1] neg_lo:[1,0,0] neg_hi:[1,0,0]
	v_pk_fma_f32 v[186:187], v[174:175], v[6:7], v[186:187] op_sel:[0,1,0] op_sel_hi:[1,1,1] neg_lo:[1,0,0] neg_hi:[1,0,0]
	ds_read_b128 v[56:59], v228 offset:16032
	v_pk_fma_f32 v[186:187], v[176:177], v[8:9], v[186:187] op_sel_hi:[1,0,1] neg_lo:[1,0,0] neg_hi:[1,0,0]
	v_pk_fma_f32 v[186:187], v[178:179], v[8:9], v[186:187] op_sel:[0,1,0] op_sel_hi:[1,1,1] neg_lo:[1,0,0] neg_hi:[1,0,0]
	v_pk_fma_f32 v[186:187], v[180:181], v[10:11], v[186:187] op_sel_hi:[1,0,1] neg_lo:[1,0,0] neg_hi:[1,0,0]
	v_pk_fma_f32 v[186:187], v[182:183], v[10:11], v[186:187] op_sel:[0,1,0] op_sel_hi:[1,1,1] neg_lo:[1,0,0] neg_hi:[1,0,0]
	ds_read_b128 v[60:63], v228 offset:16048
	s_waitcnt lgkmcnt(9)
	v_fma_mixlo_f16 v3, -v184, v12, v186
	v_fma_mixlo_f16 v238, -v185, v12, v187
	v_pk_fma_f32 v[186:187], v[184:185], v[12:13], v[186:187] op_sel_hi:[1,0,1] neg_lo:[1,0,0] neg_hi:[1,0,0]
	ds_write_b16 v253, v3 offset:32976
	ds_write_b16 v253, v238 offset:33104
	ds_read_b128 v[244:247], v228 offset:16064
	v_pk_fma_f32 v[188:189], v[64:65], v[16:17], v[188:189] op_sel_hi:[1,0,1] neg_lo:[1,0,0] neg_hi:[1,0,0]
	v_pk_fma_f32 v[188:189], v[66:67], v[16:17], v[188:189] op_sel:[0,1,0] op_sel_hi:[1,1,1] neg_lo:[1,0,0] neg_hi:[1,0,0]
	v_pk_fma_f32 v[188:189], v[68:69], v[18:19], v[188:189] op_sel_hi:[1,0,1] neg_lo:[1,0,0] neg_hi:[1,0,0]
	v_pk_fma_f32 v[188:189], v[70:71], v[18:19], v[188:189] op_sel:[0,1,0] op_sel_hi:[1,1,1] neg_lo:[1,0,0] neg_hi:[1,0,0]
	ds_read_b128 v[248:251], v228 offset:16080
	v_pk_fma_f32 v[188:189], v[72:73], v[20:21], v[188:189] op_sel_hi:[1,0,1] neg_lo:[1,0,0] neg_hi:[1,0,0]
	v_pk_fma_f32 v[188:189], v[74:75], v[20:21], v[188:189] op_sel:[0,1,0] op_sel_hi:[1,1,1] neg_lo:[1,0,0] neg_hi:[1,0,0]
	v_pk_fma_f32 v[188:189], v[76:77], v[22:23], v[188:189] op_sel_hi:[1,0,1] neg_lo:[1,0,0] neg_hi:[1,0,0]
	v_pk_fma_f32 v[188:189], v[78:79], v[22:23], v[188:189] op_sel:[0,1,0] op_sel_hi:[1,1,1] neg_lo:[1,0,0] neg_hi:[1,0,0]
	ds_read_b128 v[4:7], v228 offset:16096
	v_pk_fma_f32 v[188:189], v[80:81], v[24:25], v[188:189] op_sel_hi:[1,0,1] neg_lo:[1,0,0] neg_hi:[1,0,0]
	v_pk_fma_f32 v[188:189], v[82:83], v[24:25], v[188:189] op_sel:[0,1,0] op_sel_hi:[1,1,1] neg_lo:[1,0,0] neg_hi:[1,0,0]
	v_pk_fma_f32 v[188:189], v[84:85], v[26:27], v[188:189] op_sel_hi:[1,0,1] neg_lo:[1,0,0] neg_hi:[1,0,0]
	v_pk_fma_f32 v[188:189], v[86:87], v[26:27], v[188:189] op_sel:[0,1,0] op_sel_hi:[1,1,1] neg_lo:[1,0,0] neg_hi:[1,0,0]
	ds_read_b128 v[8:11], v228 offset:16112
	s_waitcnt lgkmcnt(11)
	v_pk_fma_f32 v[188:189], v[88:89], v[28:29], v[188:189] op_sel_hi:[1,0,1] neg_lo:[1,0,0] neg_hi:[1,0,0]
	v_pk_fma_f32 v[188:189], v[90:91], v[28:29], v[188:189] op_sel:[0,1,0] op_sel_hi:[1,1,1] neg_lo:[1,0,0] neg_hi:[1,0,0]
	v_pk_fma_f32 v[188:189], v[92:93], v[30:31], v[188:189] op_sel_hi:[1,0,1] neg_lo:[1,0,0] neg_hi:[1,0,0]
	v_pk_fma_f32 v[188:189], v[94:95], v[30:31], v[188:189] op_sel:[0,1,0] op_sel_hi:[1,1,1] neg_lo:[1,0,0] neg_hi:[1,0,0]
	ds_read_b128 v[12:15], v228 offset:16128
	v_pk_fma_f32 v[188:189], v[96:97], v[32:33], v[188:189] op_sel_hi:[1,0,1] neg_lo:[1,0,0] neg_hi:[1,0,0]
	v_pk_fma_f32 v[188:189], v[98:99], v[32:33], v[188:189] op_sel:[0,1,0] op_sel_hi:[1,1,1] neg_lo:[1,0,0] neg_hi:[1,0,0]
	v_pk_fma_f32 v[188:189], v[100:101], v[34:35], v[188:189] op_sel_hi:[1,0,1] neg_lo:[1,0,0] neg_hi:[1,0,0]
	v_pk_fma_f32 v[188:189], v[102:103], v[34:35], v[188:189] op_sel:[0,1,0] op_sel_hi:[1,1,1] neg_lo:[1,0,0] neg_hi:[1,0,0]
	ds_read_b128 v[16:19], v228 offset:16144
	v_pk_fma_f32 v[188:189], v[104:105], v[36:37], v[188:189] op_sel_hi:[1,0,1] neg_lo:[1,0,0] neg_hi:[1,0,0]
	v_pk_fma_f32 v[188:189], v[106:107], v[36:37], v[188:189] op_sel:[0,1,0] op_sel_hi:[1,1,1] neg_lo:[1,0,0] neg_hi:[1,0,0]
	v_pk_fma_f32 v[188:189], v[108:109], v[38:39], v[188:189] op_sel_hi:[1,0,1] neg_lo:[1,0,0] neg_hi:[1,0,0]
	v_pk_fma_f32 v[188:189], v[110:111], v[38:39], v[188:189] op_sel:[0,1,0] op_sel_hi:[1,1,1] neg_lo:[1,0,0] neg_hi:[1,0,0]
	ds_read_b128 v[20:23], v228 offset:16160
	v_pk_fma_f32 v[188:189], v[112:113], v[40:41], v[188:189] op_sel_hi:[1,0,1] neg_lo:[1,0,0] neg_hi:[1,0,0]
	v_pk_fma_f32 v[188:189], v[114:115], v[40:41], v[188:189] op_sel:[0,1,0] op_sel_hi:[1,1,1] neg_lo:[1,0,0] neg_hi:[1,0,0]
	v_pk_fma_f32 v[188:189], v[116:117], v[42:43], v[188:189] op_sel_hi:[1,0,1] neg_lo:[1,0,0] neg_hi:[1,0,0]
	v_pk_fma_f32 v[188:189], v[118:119], v[42:43], v[188:189] op_sel:[0,1,0] op_sel_hi:[1,1,1] neg_lo:[1,0,0] neg_hi:[1,0,0]
	ds_read_b128 v[24:27], v228 offset:16176
	s_waitcnt lgkmcnt(11)
; #define LAS __attribute__((address_space(3)))
; __device__ __forceinline__ void phase_gdb(const int wvs, const Params& p, LAS unsigned char* lds, int nwg) {
;     ...
;     { float x[64]; const bool isw = t >= 64;
; #pragma unroll
;       for (int i = 0; i < 64; ++i) { const float v = (float)R[i * RP + t]; x[i] = v * bs[i] * (isw ? __expf(gcs[i]) : 1.0f); asm volatile("" : "+v"(x[i])); if ((i & 7) == 7) __builtin_amdgcn_sched_barrier(0); }
; #pragma unroll
;       for (int i = 1; i < 64; ++i) {
; #pragma unroll
;         for (int j4 = 0; j4 < (i + 3) / 4; ++j4) { const f32x4 m4 = *(const LAS f32x4*)(M + i * 64 + j4 * 4);
; #pragma unroll
;           for (int jj = 0; jj < 4; ++jj) if (j4 * 4 + jj < i) x[i] -= m4[jj] * x[j4 * 4 + jj]; }
;         __builtin_amdgcn_sched_barrier(0); }
; #pragma unroll
;       for (int i = 0; i < 64; ++i) R[i * RP + t] = (hf)x[i]; }
	v_pk_fma_f32 v[188:189], v[120:121], v[44:45], v[188:189] op_sel_hi:[1,0,1] neg_lo:[1,0,0] neg_hi:[1,0,0]
	v_pk_fma_f32 v[188:189], v[122:123], v[44:45], v[188:189] op_sel:[0,1,0] op_sel_hi:[1,1,1] neg_lo:[1,0,0] neg_hi:[1,0,0]
	v_pk_fma_f32 v[188:189], v[124:125], v[46:47], v[188:189] op_sel_hi:[1,0,1] neg_lo:[1,0,0] neg_hi:[1,0,0]
	v_pk_fma_f32 v[188:189], v[126:127], v[46:47], v[188:189] op_sel:[0,1,0] op_sel_hi:[1,1,1] neg_lo:[1,0,0] neg_hi:[1,0,0]
	ds_read_b128 v[28:31], v228 offset:16192
	v_pk_fma_f32 v[188:189], v[128:129], v[48:49], v[188:189] op_sel_hi:[1,0,1] neg_lo:[1,0,0] neg_hi:[1,0,0]
	v_pk_fma_f32 v[188:189], v[130:131], v[48:49], v[188:189] op_sel:[0,1,0] op_sel_hi:[1,1,1] neg_lo:[1,0,0] neg_hi:[1,0,0]
	v_pk_fma_f32 v[188:189], v[132:133], v[50:51], v[188:189] op_sel_hi:[1,0,1] neg_lo:[1,0,0] neg_hi:[1,0,0]
	v_pk_fma_f32 v[188:189], v[134:135], v[50:51], v[188:189] op_sel:[0,1,0] op_sel_hi:[1,1,1] neg_lo:[1,0,0] neg_hi:[1,0,0]
	ds_read_b128 v[32:35], v228 offset:16208
	v_pk_fma_f32 v[188:189], v[136:137], v[52:53], v[188:189] op_sel_hi:[1,0,1] neg_lo:[1,0,0] neg_hi:[1,0,0]
	v_pk_fma_f32 v[188:189], v[138:139], v[52:53], v[188:189] op_sel:[0,1,0] op_sel_hi:[1,1,1] neg_lo:[1,0,0] neg_hi:[1,0,0]
	v_pk_fma_f32 v[188:189], v[140:141], v[54:55], v[188:189] op_sel_hi:[1,0,1] neg_lo:[1,0,0] neg_hi:[1,0,0]
	v_pk_fma_f32 v[188:189], v[142:143], v[54:55], v[188:189] op_sel:[0,1,0] op_sel_hi:[1,1,1] neg_lo:[1,0,0] neg_hi:[1,0,0]
	ds_read_b128 v[36:39], v228 offset:16224
	v_pk_fma_f32 v[188:189], v[144:145], v[56:57], v[188:189] op_sel_hi:[1,0,1] neg_lo:[1,0,0] neg_hi:[1,0,0]
	v_pk_fma_f32 v[188:189], v[146:147], v[56:57], v[188:189] op_sel:[0,1,0] op_sel_hi:[1,1,1] neg_lo:[1,0,0] neg_hi:[1,0,0]
	v_pk_fma_f32 v[188:189], v[148:149], v[58:59], v[188:189] op_sel_hi:[1,0,1] neg_lo:[1,0,0] neg_hi:[1,0,0]
	v_pk_fma_f32 v[188:189], v[150:151], v[58:59], v[188:189] op_sel:[0,1,0] op_sel_hi:[1,1,1] neg_lo:[1,0,0] neg_hi:[1,0,0]
	ds_read_b128 v[40:43], v228 offset:16240
	s_waitcnt lgkmcnt(9)
	v_pk_fma_f32 v[188:189], v[152:153], v[60:61], v[188:189] op_sel_hi:[1,0,1] neg_lo:[1,0,0] neg_hi:[1,0,0]
	v_pk_fma_f32 v[188:189], v[154:155], v[60:61], v[188:189] op_sel:[0,1,0] op_sel_hi:[1,1,1] neg_lo:[1,0,0] neg_hi:[1,0,0]
	v_pk_fma_f32 v[188:189], v[156:157], v[62:63], v[188:189] op_sel_hi:[1,0,1] neg_lo:[1,0,0] neg_hi:[1,0,0]
	v_pk_fma_f32 v[188:189], v[158:159], v[62:63], v[188:189] op_sel:[0,1,0] op_sel_hi:[1,1,1] neg_lo:[1,0,0] neg_hi:[1,0,0]
	ds_read_b128 v[44:47], v228 offset:16256
	v_pk_fma_f32 v[188:189], v[160:161], v[244:245], v[188:189] op_sel_hi:[1,0,1] neg_lo:[1,0,0] neg_hi:[1,0,0]
	v_pk_fma_f32 v[188:189], v[162:163], v[244:245], v[188:189] op_sel:[0,1,0] op_sel_hi:[1,1,1] neg_lo:[1,0,0] neg_hi:[1,0,0]
	v_pk_fma_f32 v[188:189], v[164:165], v[246:247], v[188:189] op_sel_hi:[1,0,1] neg_lo:[1,0,0] neg_hi:[1,0,0]
	v_pk_fma_f32 v[188:189], v[166:167], v[246:247], v[188:189] op_sel:[0,1,0] op_sel_hi:[1,1,1] neg_lo:[1,0,0] neg_hi:[1,0,0]
	ds_read_b128 v[48:51], v228 offset:16272
	v_pk_fma_f32 v[188:189], v[168:169], v[248:249], v[188:189] op_sel_hi:[1,0,1] neg_lo:[1,0,0] neg_hi:[1,0,0]
	v_pk_fma_f32 v[188:189], v[170:171], v[248:249], v[188:189] op_sel:[0,1,0] op_sel_hi:[1,1,1] neg_lo:[1,0,0] neg_hi:[1,0,0]
	v_pk_fma_f32 v[188:189], v[172:173], v[250:251], v[188:189] op_sel_hi:[1,0,1] neg_lo:[1,0,0] neg_hi:[1,0,0]
	v_pk_fma_f32 v[188:189], v[174:175], v[250:251], v[188:189] op_sel:[0,1,0] op_sel_hi:[1,1,1] neg_lo:[1,0,0] neg_hi:[1,0,0]
	ds_read_b128 v[52:55], v228 offset:16288
	v_pk_fma_f32 v[188:189], v[176:177], v[4:5], v[188:189] op_sel_hi:[1,0,1] neg_lo:[1,0,0] neg_hi:[1,0,0]
	v_pk_fma_f32 v[188:189], v[178:179], v[4:5], v[188:189] op_sel:[0,1,0] op_sel_hi:[1,1,1] neg_lo:[1,0,0] neg_hi:[1,0,0]
	v_pk_fma_f32 v[188:189], v[180:181], v[6:7], v[188:189] op_sel_hi:[1,0,1] neg_lo:[1,0,0] neg_hi:[1,0,0]
	v_pk_fma_f32 v[188:189], v[182:183], v[6:7], v[188:189] op_sel:[0,1,0] op_sel_hi:[1,1,1] neg_lo:[1,0,0] neg_hi:[1,0,0]
	ds_read_b128 v[56:59], v228 offset:16304
	s_waitcnt lgkmcnt(9)
	v_pk_fma_f32 v[188:189], v[184:185], v[8:9], v[188:189] op_sel_hi:[1,0,1] neg_lo:[1,0,0] neg_hi:[1,0,0]
	v_fma_mixlo_f16 v239, -v186, v9, v188
	v_fma_mixlo_f16 v240, -v187, v9, v189
	v_pk_fma_f32 v[188:189], v[186:187], v[8:9], v[188:189] op_sel:[0,1,0] op_sel_hi:[1,1,1] neg_lo:[1,0,0] neg_hi:[1,0,0]
	ds_write_b16 v253, v239 offset:33248
	ds_write_b16 v253, v240 offset:33376
	ds_read_b128 v[60:63], v228 offset:16320
	v_pk_fma_f32 v[190:191], v[64:65], v[12:13], v[190:191] op_sel_hi:[1,0,1] neg_lo:[1,0,0] neg_hi:[1,0,0]
	v_pk_fma_f32 v[190:191], v[66:67], v[12:13], v[190:191] op_sel:[0,1,0] op_sel_hi:[1,1,1] neg_lo:[1,0,0] neg_hi:[1,0,0]
	v_pk_fma_f32 v[190:191], v[68:69], v[14:15], v[190:191] op_sel_hi:[1,0,1] neg_lo:[1,0,0] neg_hi:[1,0,0]
	v_pk_fma_f32 v[190:191], v[70:71], v[14:15], v[190:191] op_sel:[0,1,0] op_sel_hi:[1,1,1] neg_lo:[1,0,0] neg_hi:[1,0,0]
	ds_read_b128 v[244:247], v228 offset:16336
	v_pk_fma_f32 v[190:191], v[72:73], v[16:17], v[190:191] op_sel_hi:[1,0,1] neg_lo:[1,0,0] neg_hi:[1,0,0]
	v_pk_fma_f32 v[190:191], v[74:75], v[16:17], v[190:191] op_sel:[0,1,0] op_sel_hi:[1,1,1] neg_lo:[1,0,0] neg_hi:[1,0,0]
	v_pk_fma_f32 v[190:191], v[76:77], v[18:19], v[190:191] op_sel_hi:[1,0,1] neg_lo:[1,0,0] neg_hi:[1,0,0]
	v_pk_fma_f32 v[190:191], v[78:79], v[18:19], v[190:191] op_sel:[0,1,0] op_sel_hi:[1,1,1] neg_lo:[1,0,0] neg_hi:[1,0,0]
	ds_read_b128 v[248:251], v228 offset:16352
	v_pk_fma_f32 v[190:191], v[80:81], v[20:21], v[190:191] op_sel_hi:[1,0,1] neg_lo:[1,0,0] neg_hi:[1,0,0]
	v_pk_fma_f32 v[190:191], v[82:83], v[20:21], v[190:191] op_sel:[0,1,0] op_sel_hi:[1,1,1] neg_lo:[1,0,0] neg_hi:[1,0,0]
	v_pk_fma_f32 v[190:191], v[84:85], v[22:23], v[190:191] op_sel_hi:[1,0,1] neg_lo:[1,0,0] neg_hi:[1,0,0]
	v_pk_fma_f32 v[190:191], v[86:87], v[22:23], v[190:191] op_sel:[0,1,0] op_sel_hi:[1,1,1] neg_lo:[1,0,0] neg_hi:[1,0,0]
	ds_read_b128 v[4:7], v228 offset:16368
	s_waitcnt lgkmcnt(11)
; #define LAS __attribute__((address_space(3)))
; __device__ __forceinline__ void phase_gdb(const int wvs, const Params& p, LAS unsigned char* lds, int nwg) {
;     ...
;     { float x[64]; const bool isw = t >= 64;
; #pragma unroll
;       for (int i = 0; i < 64; ++i) { const float v = (float)R[i * RP + t]; x[i] = v * bs[i] * (isw ? __expf(gcs[i]) : 1.0f); asm volatile("" : "+v"(x[i])); if ((i & 7) == 7) __builtin_amdgcn_sched_barrier(0); }
; #pragma unroll
;       for (int i = 1; i < 64; ++i) {
; #pragma unroll
;         for (int j4 = 0; j4 < (i + 3) / 4; ++j4) { const f32x4 m4 = *(const LAS f32x4*)(M + i * 64 + j4 * 4);
; #pragma unroll
;           for (int jj = 0; jj < 4; ++jj) if (j4 * 4 + jj < i) x[i] -= m4[jj] * x[j4 * 4 + jj]; }
;         __builtin_amdgcn_sched_barrier(0); }
; #pragma unroll
;       for (int i = 0; i < 64; ++i) R[i * RP + t] = (hf)x[i]; }
	v_pk_fma_f32 v[190:191], v[88:89], v[24:25], v[190:191] op_sel_hi:[1,0,1] neg_lo:[1,0,0] neg_hi:[1,0,0]
	v_pk_fma_f32 v[190:191], v[90:91], v[24:25], v[190:191] op_sel:[0,1,0] op_sel_hi:[1,1,1] neg_lo:[1,0,0] neg_hi:[1,0,0]
	v_pk_fma_f32 v[190:191], v[92:93], v[26:27], v[190:191] op_sel_hi:[1,0,1] neg_lo:[1,0,0] neg_hi:[1,0,0]
	v_pk_fma_f32 v[190:191], v[94:95], v[26:27], v[190:191] op_sel:[0,1,0] op_sel_hi:[1,1,1] neg_lo:[1,0,0] neg_hi:[1,0,0]
	v_pk_fma_f32 v[190:191], v[96:97], v[28:29], v[190:191] op_sel_hi:[1,0,1] neg_lo:[1,0,0] neg_hi:[1,0,0]
	v_pk_fma_f32 v[190:191], v[98:99], v[28:29], v[190:191] op_sel:[0,1,0] op_sel_hi:[1,1,1] neg_lo:[1,0,0] neg_hi:[1,0,0]
	v_pk_fma_f32 v[190:191], v[100:101], v[30:31], v[190:191] op_sel_hi:[1,0,1] neg_lo:[1,0,0] neg_hi:[1,0,0]
	v_pk_fma_f32 v[190:191], v[102:103], v[30:31], v[190:191] op_sel:[0,1,0] op_sel_hi:[1,1,1] neg_lo:[1,0,0] neg_hi:[1,0,0]
	v_pk_fma_f32 v[190:191], v[104:105], v[32:33], v[190:191] op_sel_hi:[1,0,1] neg_lo:[1,0,0] neg_hi:[1,0,0]
	v_pk_fma_f32 v[190:191], v[106:107], v[32:33], v[190:191] op_sel:[0,1,0] op_sel_hi:[1,1,1] neg_lo:[1,0,0] neg_hi:[1,0,0]
	v_pk_fma_f32 v[190:191], v[108:109], v[34:35], v[190:191] op_sel_hi:[1,0,1] neg_lo:[1,0,0] neg_hi:[1,0,0]
	v_pk_fma_f32 v[190:191], v[110:111], v[34:35], v[190:191] op_sel:[0,1,0] op_sel_hi:[1,1,1] neg_lo:[1,0,0] neg_hi:[1,0,0]
	v_pk_fma_f32 v[190:191], v[112:113], v[36:37], v[190:191] op_sel_hi:[1,0,1] neg_lo:[1,0,0] neg_hi:[1,0,0]
	v_pk_fma_f32 v[190:191], v[114:115], v[36:37], v[190:191] op_sel:[0,1,0] op_sel_hi:[1,1,1] neg_lo:[1,0,0] neg_hi:[1,0,0]
	v_pk_fma_f32 v[190:191], v[116:117], v[38:39], v[190:191] op_sel_hi:[1,0,1] neg_lo:[1,0,0] neg_hi:[1,0,0]
	v_pk_fma_f32 v[190:191], v[118:119], v[38:39], v[190:191] op_sel:[0,1,0] op_sel_hi:[1,1,1] neg_lo:[1,0,0] neg_hi:[1,0,0]
	s_waitcnt lgkmcnt(7)
	v_pk_fma_f32 v[190:191], v[120:121], v[40:41], v[190:191] op_sel_hi:[1,0,1] neg_lo:[1,0,0] neg_hi:[1,0,0]
	v_pk_fma_f32 v[190:191], v[122:123], v[40:41], v[190:191] op_sel:[0,1,0] op_sel_hi:[1,1,1] neg_lo:[1,0,0] neg_hi:[1,0,0]
	v_pk_fma_f32 v[190:191], v[124:125], v[42:43], v[190:191] op_sel_hi:[1,0,1] neg_lo:[1,0,0] neg_hi:[1,0,0]
	v_pk_fma_f32 v[190:191], v[126:127], v[42:43], v[190:191] op_sel:[0,1,0] op_sel_hi:[1,1,1] neg_lo:[1,0,0] neg_hi:[1,0,0]
	v_pk_fma_f32 v[190:191], v[128:129], v[44:45], v[190:191] op_sel_hi:[1,0,1] neg_lo:[1,0,0] neg_hi:[1,0,0]
	v_pk_fma_f32 v[190:191], v[130:131], v[44:45], v[190:191] op_sel:[0,1,0] op_sel_hi:[1,1,1] neg_lo:[1,0,0] neg_hi:[1,0,0]
	v_pk_fma_f32 v[190:191], v[132:133], v[46:47], v[190:191] op_sel_hi:[1,0,1] neg_lo:[1,0,0] neg_hi:[1,0,0]
	v_pk_fma_f32 v[190:191], v[134:135], v[46:47], v[190:191] op_sel:[0,1,0] op_sel_hi:[1,1,1] neg_lo:[1,0,0] neg_hi:[1,0,0]
	v_pk_fma_f32 v[190:191], v[136:137], v[48:49], v[190:191] op_sel_hi:[1,0,1] neg_lo:[1,0,0] neg_hi:[1,0,0]
	v_pk_fma_f32 v[190:191], v[138:139], v[48:49], v[190:191] op_sel:[0,1,0] op_sel_hi:[1,1,1] neg_lo:[1,0,0] neg_hi:[1,0,0]
	v_pk_fma_f32 v[190:191], v[140:141], v[50:51], v[190:191] op_sel_hi:[1,0,1] neg_lo:[1,0,0] neg_hi:[1,0,0]
	v_pk_fma_f32 v[190:191], v[142:143], v[50:51], v[190:191] op_sel:[0,1,0] op_sel_hi:[1,1,1] neg_lo:[1,0,0] neg_hi:[1,0,0]
	v_pk_fma_f32 v[190:191], v[144:145], v[52:53], v[190:191] op_sel_hi:[1,0,1] neg_lo:[1,0,0] neg_hi:[1,0,0]
	v_pk_fma_f32 v[190:191], v[146:147], v[52:53], v[190:191] op_sel:[0,1,0] op_sel_hi:[1,1,1] neg_lo:[1,0,0] neg_hi:[1,0,0]
	v_pk_fma_f32 v[190:191], v[148:149], v[54:55], v[190:191] op_sel_hi:[1,0,1] neg_lo:[1,0,0] neg_hi:[1,0,0]
	v_pk_fma_f32 v[190:191], v[150:151], v[54:55], v[190:191] op_sel:[0,1,0] op_sel_hi:[1,1,1] neg_lo:[1,0,0] neg_hi:[1,0,0]
	s_waitcnt lgkmcnt(1)
	v_pk_fma_f32 v[190:191], v[152:153], v[56:57], v[190:191] op_sel_hi:[1,0,1] neg_lo:[1,0,0] neg_hi:[1,0,0]
	v_pk_fma_f32 v[190:191], v[154:155], v[56:57], v[190:191] op_sel:[0,1,0] op_sel_hi:[1,1,1] neg_lo:[1,0,0] neg_hi:[1,0,0]
	v_pk_fma_f32 v[190:191], v[156:157], v[58:59], v[190:191] op_sel_hi:[1,0,1] neg_lo:[1,0,0] neg_hi:[1,0,0]
	v_pk_fma_f32 v[190:191], v[158:159], v[58:59], v[190:191] op_sel:[0,1,0] op_sel_hi:[1,1,1] neg_lo:[1,0,0] neg_hi:[1,0,0]
	v_pk_fma_f32 v[190:191], v[160:161], v[60:61], v[190:191] op_sel_hi:[1,0,1] neg_lo:[1,0,0] neg_hi:[1,0,0]
	v_pk_fma_f32 v[190:191], v[162:163], v[60:61], v[190:191] op_sel:[0,1,0] op_sel_hi:[1,1,1] neg_lo:[1,0,0] neg_hi:[1,0,0]
	v_pk_fma_f32 v[190:191], v[164:165], v[62:63], v[190:191] op_sel_hi:[1,0,1] neg_lo:[1,0,0] neg_hi:[1,0,0]
	v_pk_fma_f32 v[190:191], v[166:167], v[62:63], v[190:191] op_sel:[0,1,0] op_sel_hi:[1,1,1] neg_lo:[1,0,0] neg_hi:[1,0,0]
	v_pk_fma_f32 v[190:191], v[168:169], v[244:245], v[190:191] op_sel_hi:[1,0,1] neg_lo:[1,0,0] neg_hi:[1,0,0]
	v_pk_fma_f32 v[190:191], v[170:171], v[244:245], v[190:191] op_sel:[0,1,0] op_sel_hi:[1,1,1] neg_lo:[1,0,0] neg_hi:[1,0,0]
	v_pk_fma_f32 v[190:191], v[172:173], v[246:247], v[190:191] op_sel_hi:[1,0,1] neg_lo:[1,0,0] neg_hi:[1,0,0]
	v_pk_fma_f32 v[190:191], v[174:175], v[246:247], v[190:191] op_sel:[0,1,0] op_sel_hi:[1,1,1] neg_lo:[1,0,0] neg_hi:[1,0,0]
	v_pk_fma_f32 v[190:191], v[176:177], v[248:249], v[190:191] op_sel_hi:[1,0,1] neg_lo:[1,0,0] neg_hi:[1,0,0]
	v_pk_fma_f32 v[190:191], v[178:179], v[248:249], v[190:191] op_sel:[0,1,0] op_sel_hi:[1,1,1] neg_lo:[1,0,0] neg_hi:[1,0,0]
	v_pk_fma_f32 v[190:191], v[180:181], v[250:251], v[190:191] op_sel_hi:[1,0,1] neg_lo:[1,0,0] neg_hi:[1,0,0]
	v_pk_fma_f32 v[190:191], v[182:183], v[250:251], v[190:191] op_sel:[0,1,0] op_sel_hi:[1,1,1] neg_lo:[1,0,0] neg_hi:[1,0,0]
	s_waitcnt lgkmcnt(0)
	v_pk_fma_f32 v[190:191], v[184:185], v[4:5], v[190:191] op_sel_hi:[1,0,1] neg_lo:[1,0,0] neg_hi:[1,0,0]
	v_pk_fma_f32 v[190:191], v[186:187], v[4:5], v[190:191] op_sel:[0,1,0] op_sel_hi:[1,1,1] neg_lo:[1,0,0] neg_hi:[1,0,0]
	v_fma_mixlo_f16 v0, -v188, v6, v190
	v_fma_mixlo_f16 v2, -v189, v6, v191
	v_pk_fma_f32 v[190:191], v[188:189], v[6:7], v[190:191] op_sel_hi:[1,0,1] neg_lo:[1,0,0] neg_hi:[1,0,0]
	ds_write_b16 v253, v0 offset:33520
	ds_write_b16 v253, v2 offset:33648
; #define LAS __attribute__((address_space(3)))
; __device__ __forceinline__ void phase_gdb(const int wvs, const Params& p, LAS unsigned char* lds, int nwg) {
;     ...
;     __syncthreads();
;     ...
;     { int tid2 = tid; asm volatile("" : "+v"(tid2));
;       const int tq2 = tid2 >> 7, t2 = tid2 & 127, rr2 = t2 >> 4, cc2 = (t2 & 15) * 8; LAS hf* R2 = (LAS hf*)(lds + tq2 * SLOT + 16384);
;       const int task2 = grp * 4 + tq2, d2 = task2 & 1, h2 = (task2 >> 1) % 6, n2 = (task2 / 12) % NCH64, b2 = task2 / (12 * NCH64); const size_t tokbase2 = (size_t)b2 * TPB + n2 * 64;
; #pragma unroll 1
;       for (int ps = 0; ps < 8; ++ps) { const int i = ps * 8 + rr2; const h8 v = *(const LAS h8*)(R2 + i * RP + cc2); const size_t tk = tokbase2 + (d2 ? 63 - i : i);
;         hf* dst = cc2 < 64 ? P + tk * PP + (d2 ? PC_GV : PC_GQ) + h2 * 64 + cc2 : (d2 == 0 ? P + tk * PP + PC_GK + h2 * 64 + cc2 - 64 : WB + tk * 384 + h2 * 64 + cc2 - 64);
;         *(h8*)dst = v; } }
.Lgdb_wskip:
	v_mov_b32_e32 v14, v224
	s_waitcnt lgkmcnt(0)
	s_barrier
	s_mov_b32 s2, 0x8700
	v_ashrrev_i32_e32 v0, 7, v14
	v_lshlrev_b32_e32 v2, 3, v14
	v_mul_lo_u32 v16, v0, s2
	v_add_u32_e32 v0, s12, v0
	v_and_b32_e32 v8, 0x78, v2
	v_ashrrev_i32_e32 v2, 1, v0
	v_mul_hi_i32 v3, v2, s52
	v_lshrrev_b32_e32 v4, 31, v3
	v_add_u32_e32 v3, v3, v4
	v_mul_lo_u32 v3, v3, 6
	v_sub_u32_e32 v9, v2, v3
	v_mul_hi_i32 v2, v0, s52
	v_lshrrev_b32_e32 v3, 31, v2
	v_ashrrev_i32_e32 v2, 1, v2
	v_add_u32_e32 v2, v2, v3
	v_mul_hi_i32 v3, v2, s89
	v_lshrrev_b32_e32 v4, 31, v3
	v_lshrrev_b32_e32 v3, 5, v3
	v_add_u32_e32 v3, v3, v4
	v_mul_lo_u32 v3, v3, s35
	s_mov_b32 s2, 0xa0a0a0a1
	v_sub_u32_e32 v4, v2, v3
	v_mul_hi_i32 v2, v0, s2
	v_add_u32_e32 v0, v2, v0
	v_lshrrev_b32_e32 v2, 31, v0
	v_ashrrev_i32_e32 v0, 9, v0
	v_add_u32_e32 v0, v0, v2
	v_lshlrev_b32_e32 v4, 6, v4
	v_mul_hi_i32_i24_e32 v3, 0x1100, v0
	v_mul_i32_i24_e32 v2, 0x1100, v0
	v_ashrrev_i32_e32 v5, 31, v4
	v_lshl_add_u64 v[6:7], v[2:3], 0, v[4:5]
	v_lshlrev_b32_e32 v2, 6, v9
	v_ashrrev_i32_e32 v3, 31, v2
	v_and_b32_e32 v0, 0x80, v14
	v_lshlrev_b64 v[2:3], 1, v[2:3]
	v_cmp_ne_u32_e64 s[8:9], 0, v0
	v_lshl_add_u64 v[4:5], s[14:15], 0, v[2:3]
	v_lshlrev_b32_e32 v0, 1, v8
	v_and_b32_e32 v12, 0x80, v14
	v_cmp_lt_u32_e64 s[10:11], 63, v8
	v_lshl_add_u64 v[8:9], v[4:5], 0, v[0:1]
	v_lshl_add_u64 v[4:5], s[16:17], 0, v[2:3]
	v_lshl_add_u64 v[10:11], v[4:5], 0, v[0:1]
	v_cmp_eq_u32_e64 s[12:13], 0, v12
	v_mov_b32_e32 v4, 0x800
	v_mov_b32_e32 v5, 0x200
	v_cndmask_b32_e64 v4, v4, v5, s[12:13]
	v_mov_b32_e32 v5, v1
	v_lshl_add_u64 v[4:5], s[16:17], 0, v[4:5]
	v_lshl_add_u64 v[2:3], v[4:5], 0, v[2:3]
	v_bfe_u32 v18, v14, 4, 3
	v_lshl_add_u64 v[12:13], v[2:3], 0, v[0:1]
	v_and_b32_e32 v2, 15, v14
	v_lshrrev_b32_e32 v15, 4, v14
	v_mad_u32_u24 v0, v18, s67, v16
	v_lshlrev_b32_e32 v2, 4, v2
	s_add_i32 s18, 0, 0x4000
	s_mov_b32 s2, 0
	v_bitop3_b32 v19, v15, 63, 7 bitop3:0x6c
	v_add3_u32 v20, v0, v2, s18
	s_branch .LBB0_1029
